# on top of v15: extra s_setprio 0/1 flip every 8 MFMAs inside each 32-MFMA GEMM block (28 K-loops)
# speedup vs baseline: 1.0431x; 1.0431x over previous
.LBB0_274:
	ds_read_b128 v[146:149], v153
	ds_read_b128 v[156:159], v153 offset:1024
	ds_read_b128 v[160:163], v153 offset:2048
	ds_read_b128 v[164:167], v153 offset:3072
	ds_read_b128 v[168:171], v154
	ds_read_b128 v[172:175], v154 offset:1024
	ds_read_b128 v[176:179], v154 offset:2048
	ds_read_b128 v[180:183], v154 offset:3072
	s_add_u32 s34, s76, 0xfff80080
	s_addc_u32 s35, s77, -1
	s_cmp_eq_u32 s85, 28
	s_cselect_b32 s79, s0, s35
	s_cselect_b32 s78, s1, s34
	s_cselect_b32 s35, s67, s84
	s_cselect_b32 s34, s69, s83
	v_lshl_add_u64 v[218:219], s[76:77], 0, v[138:139]
	s_add_i32 m0, s54, 0xc000
	ds_read_b128 v[184:187], v155
	ds_read_b128 v[188:191], v155 offset:1024
	ds_read_b128 v[192:195], v155 offset:2048
	ds_read_b128 v[196:199], v155 offset:3072
	ds_read_b128 v[200:203], v155 offset:4096
	ds_read_b128 v[204:207], v155 offset:5120
	ds_read_b128 v[208:211], v155 offset:6144
	ds_read_b128 v[212:215], v155 offset:7168
	global_load_lds_dwordx4 v[218:219], off
	v_lshl_add_u64 v[218:219], s[76:77], 0, v[140:141]
	s_add_i32 m0, s54, 0xe000
	s_nop 0
	global_load_lds_dwordx4 v[218:219], off
	s_waitcnt vmcnt(8)
	s_waitcnt lgkmcnt(0)
	s_barrier
	s_setprio 1
	s_waitcnt lgkmcnt(0)
	v_mfma_f32_16x16x32_bf16 v[126:129], v[146:149], v[184:187], v[126:129]
	v_mfma_f32_16x16x32_bf16 v[118:121], v[160:163], v[184:187], v[118:121]
	v_mfma_f32_16x16x32_bf16 v[110:113], v[146:149], v[192:195], v[110:113]
	v_mfma_f32_16x16x32_bf16 v[102:105], v[160:163], v[192:195], v[102:105]
	v_mfma_f32_16x16x32_bf16 v[94:97], v[146:149], v[200:203], v[94:97]
	v_mfma_f32_16x16x32_bf16 v[86:89], v[160:163], v[200:203], v[86:89]
	v_mfma_f32_16x16x32_bf16 v[78:81], v[146:149], v[208:211], v[78:81]
	v_mfma_f32_16x16x32_bf16 v[70:73], v[160:163], v[208:211], v[70:73]
	s_setprio 0
	s_setprio 1
	v_mfma_f32_16x16x32_bf16 v[126:129], v[156:159], v[188:191], v[126:129]
	v_mfma_f32_16x16x32_bf16 v[118:121], v[164:167], v[188:191], v[118:121]
	v_mfma_f32_16x16x32_bf16 v[110:113], v[156:159], v[196:199], v[110:113]
	v_mfma_f32_16x16x32_bf16 v[102:105], v[164:167], v[196:199], v[102:105]
	v_mfma_f32_16x16x32_bf16 v[94:97], v[156:159], v[204:207], v[94:97]
	v_mfma_f32_16x16x32_bf16 v[86:89], v[164:167], v[204:207], v[86:89]
	v_mfma_f32_16x16x32_bf16 v[78:81], v[156:159], v[212:215], v[78:81]
	v_mfma_f32_16x16x32_bf16 v[70:73], v[164:167], v[212:215], v[70:73]
	s_setprio 0
	s_setprio 1
	v_mfma_f32_16x16x32_bf16 v[122:125], v[168:171], v[184:187], v[122:125]
	v_mfma_f32_16x16x32_bf16 v[114:117], v[176:179], v[184:187], v[114:117]
	v_mfma_f32_16x16x32_bf16 v[106:109], v[168:171], v[192:195], v[106:109]
	v_mfma_f32_16x16x32_bf16 v[98:101], v[176:179], v[192:195], v[98:101]
	v_mfma_f32_16x16x32_bf16 v[90:93], v[168:171], v[200:203], v[90:93]
	v_mfma_f32_16x16x32_bf16 v[82:85], v[176:179], v[200:203], v[82:85]
	v_mfma_f32_16x16x32_bf16 v[74:77], v[168:171], v[208:211], v[74:77]
	v_mfma_f32_16x16x32_bf16 v[66:69], v[176:179], v[208:211], v[66:69]
	s_setprio 0
	s_setprio 1
	v_mfma_f32_16x16x32_bf16 v[122:125], v[172:175], v[188:191], v[122:125]
	v_mfma_f32_16x16x32_bf16 v[114:117], v[180:183], v[188:191], v[114:117]
	v_mfma_f32_16x16x32_bf16 v[106:109], v[172:175], v[196:199], v[106:109]
	v_mfma_f32_16x16x32_bf16 v[98:101], v[180:183], v[196:199], v[98:101]
	v_mfma_f32_16x16x32_bf16 v[90:93], v[172:175], v[204:207], v[90:93]
	v_mfma_f32_16x16x32_bf16 v[82:85], v[180:183], v[204:207], v[82:85]
	v_mfma_f32_16x16x32_bf16 v[74:77], v[172:175], v[212:215], v[74:77]
	v_mfma_f32_16x16x32_bf16 v[66:69], v[180:183], v[212:215], v[66:69]
	s_setprio 0
	s_barrier
	s_add_i32 s62, s75, s33
	v_lshl_add_u64 v[218:219], s[34:35], 0, v[134:135]
	s_mov_b32 m0, s62
	ds_read_b128 v[184:187], v155 offset:16384
	ds_read_b128 v[188:191], v155 offset:17408
	ds_read_b128 v[192:195], v155 offset:18432
	ds_read_b128 v[196:199], v155 offset:19456
	ds_read_b128 v[200:203], v155 offset:20480
	ds_read_b128 v[204:207], v155 offset:21504
	ds_read_b128 v[208:211], v155 offset:22528
	ds_read_b128 v[212:215], v155 offset:23552
	global_load_lds_dwordx4 v[218:219], off
	s_add_i32 m0, s62, 0x2000
	s_add_u32 s62, s34, 0x80000
	v_lshl_add_u64 v[220:221], s[34:35], 0, v[130:131]
	s_addc_u32 s63, s35, 0
	s_add_i32 s86, s80, s33
	global_load_lds_dwordx4 v[220:221], off
	v_lshl_add_u64 v[222:223], s[62:63], 0, v[134:135]
	s_mov_b32 m0, s86
	v_lshl_add_u64 v[224:225], s[78:79], 0, v[132:133]
	global_load_lds_dwordx4 v[222:223], off
	v_lshl_add_u64 v[222:223], s[62:63], 0, v[130:131]
	s_add_i32 m0, s86, 0x2000
	s_nop 0
	global_load_lds_dwordx4 v[222:223], off
	v_lshl_add_u64 v[222:223], s[78:79], 0, v[136:137]
	s_mov_b32 m0, s54
	s_nop 0
	global_load_lds_dwordx4 v[222:223], off
	s_mov_b32 m0, s55
	s_nop 0
	global_load_lds_dwordx4 v[224:225], off
	s_waitcnt vmcnt(8)
	s_waitcnt lgkmcnt(0)
	s_barrier
	s_setprio 1
	s_waitcnt lgkmcnt(0)
	v_mfma_f32_16x16x32_bf16 v[62:65], v[146:149], v[184:187], v[62:65]
	v_mfma_f32_16x16x32_bf16 v[54:57], v[160:163], v[184:187], v[54:57]
	v_mfma_f32_16x16x32_bf16 v[46:49], v[146:149], v[192:195], v[46:49]
	v_mfma_f32_16x16x32_bf16 v[38:41], v[160:163], v[192:195], v[38:41]
	v_mfma_f32_16x16x32_bf16 v[30:33], v[146:149], v[200:203], v[30:33]
	v_mfma_f32_16x16x32_bf16 v[22:25], v[160:163], v[200:203], v[22:25]
	v_mfma_f32_16x16x32_bf16 v[14:17], v[146:149], v[208:211], v[14:17]
	v_mfma_f32_16x16x32_bf16 v[6:9], v[160:163], v[208:211], v[6:9]
	s_setprio 0
	s_setprio 1
	v_mfma_f32_16x16x32_bf16 v[62:65], v[156:159], v[188:191], v[62:65]
	v_mfma_f32_16x16x32_bf16 v[54:57], v[164:167], v[188:191], v[54:57]
	v_mfma_f32_16x16x32_bf16 v[46:49], v[156:159], v[196:199], v[46:49]
	v_mfma_f32_16x16x32_bf16 v[38:41], v[164:167], v[196:199], v[38:41]
	v_mfma_f32_16x16x32_bf16 v[30:33], v[156:159], v[204:207], v[30:33]
	v_mfma_f32_16x16x32_bf16 v[22:25], v[164:167], v[204:207], v[22:25]
	v_mfma_f32_16x16x32_bf16 v[14:17], v[156:159], v[212:215], v[14:17]
	v_mfma_f32_16x16x32_bf16 v[6:9], v[164:167], v[212:215], v[6:9]
	s_setprio 0
	s_setprio 1
	v_mfma_f32_16x16x32_bf16 v[58:61], v[168:171], v[184:187], v[58:61]
	v_mfma_f32_16x16x32_bf16 v[50:53], v[176:179], v[184:187], v[50:53]
	v_mfma_f32_16x16x32_bf16 v[42:45], v[168:171], v[192:195], v[42:45]
	v_mfma_f32_16x16x32_bf16 v[34:37], v[176:179], v[192:195], v[34:37]
	v_mfma_f32_16x16x32_bf16 v[26:29], v[168:171], v[200:203], v[26:29]
	v_mfma_f32_16x16x32_bf16 v[18:21], v[176:179], v[200:203], v[18:21]
	v_mfma_f32_16x16x32_bf16 v[10:13], v[168:171], v[208:211], v[10:13]
	v_mfma_f32_16x16x32_bf16 v[2:5], v[176:179], v[208:211], v[2:5]
	s_setprio 0
	s_setprio 1
	v_mfma_f32_16x16x32_bf16 v[58:61], v[172:175], v[188:191], v[58:61]
	v_mfma_f32_16x16x32_bf16 v[50:53], v[180:183], v[188:191], v[50:53]
	v_mfma_f32_16x16x32_bf16 v[42:45], v[172:175], v[196:199], v[42:45]
	v_mfma_f32_16x16x32_bf16 v[34:37], v[180:183], v[196:199], v[34:37]
	v_mfma_f32_16x16x32_bf16 v[26:29], v[172:175], v[204:207], v[26:29]
	v_mfma_f32_16x16x32_bf16 v[18:21], v[180:183], v[204:207], v[18:21]
	v_mfma_f32_16x16x32_bf16 v[10:13], v[172:175], v[212:215], v[10:13]
	v_mfma_f32_16x16x32_bf16 v[2:5], v[180:183], v[212:215], v[2:5]
	s_setprio 0
	s_barrier
	s_add_i32 s86, 0, 0x18000
	s_add_i32 s87, 0, 0x1c000
	v_add_u32_e32 v164, s86, v151
	v_add_u32_e32 v180, s87, v151
	ds_read_b128 v[146:149], v164
	ds_read_b128 v[156:159], v164 offset:1024
	ds_read_b128 v[160:163], v164 offset:2048
	ds_read_b128 v[164:167], v164 offset:3072
	ds_read_b128 v[168:171], v180
	ds_read_b128 v[172:175], v180 offset:1024
	ds_read_b128 v[176:179], v180 offset:2048
	ds_read_b128 v[180:183], v180 offset:3072
	s_add_u32 s62, s78, 0x80000
	s_addc_u32 s63, s79, 0
	s_mov_b32 m0, s56
	v_lshl_add_u64 v[226:227], s[62:63], 0, v[136:137]
	ds_read_b128 v[184:187], v155 offset:32768
	ds_read_b128 v[188:191], v155 offset:33792
	ds_read_b128 v[192:195], v155 offset:34816
	ds_read_b128 v[196:199], v155 offset:35840
	ds_read_b128 v[200:203], v155 offset:36864
	ds_read_b128 v[204:207], v155 offset:37888
	ds_read_b128 v[208:211], v155 offset:38912
	ds_read_b128 v[212:215], v155 offset:39936
	global_load_lds_dwordx4 v[226:227], off
	v_lshl_add_u64 v[226:227], s[62:63], 0, v[132:133]
	s_mov_b32 m0, s57
	s_nop 0
	global_load_lds_dwordx4 v[226:227], off
	s_waitcnt vmcnt(8)
	s_waitcnt lgkmcnt(0)
	s_barrier
	s_setprio 1
	s_waitcnt lgkmcnt(0)
	v_mfma_f32_16x16x32_bf16 v[126:129], v[146:149], v[184:187], v[126:129]
	v_mfma_f32_16x16x32_bf16 v[118:121], v[160:163], v[184:187], v[118:121]
	v_mfma_f32_16x16x32_bf16 v[110:113], v[146:149], v[192:195], v[110:113]
	v_mfma_f32_16x16x32_bf16 v[102:105], v[160:163], v[192:195], v[102:105]
	v_mfma_f32_16x16x32_bf16 v[94:97], v[146:149], v[200:203], v[94:97]
	v_mfma_f32_16x16x32_bf16 v[86:89], v[160:163], v[200:203], v[86:89]
	v_mfma_f32_16x16x32_bf16 v[78:81], v[146:149], v[208:211], v[78:81]
	v_mfma_f32_16x16x32_bf16 v[70:73], v[160:163], v[208:211], v[70:73]
	s_setprio 0
	s_setprio 1
	v_mfma_f32_16x16x32_bf16 v[126:129], v[156:159], v[188:191], v[126:129]
	v_mfma_f32_16x16x32_bf16 v[118:121], v[164:167], v[188:191], v[118:121]
	v_mfma_f32_16x16x32_bf16 v[110:113], v[156:159], v[196:199], v[110:113]
	v_mfma_f32_16x16x32_bf16 v[102:105], v[164:167], v[196:199], v[102:105]
	v_mfma_f32_16x16x32_bf16 v[94:97], v[156:159], v[204:207], v[94:97]
	v_mfma_f32_16x16x32_bf16 v[86:89], v[164:167], v[204:207], v[86:89]
	v_mfma_f32_16x16x32_bf16 v[78:81], v[156:159], v[212:215], v[78:81]
	v_mfma_f32_16x16x32_bf16 v[70:73], v[164:167], v[212:215], v[70:73]
	s_setprio 0
	s_setprio 1
	v_mfma_f32_16x16x32_bf16 v[122:125], v[168:171], v[184:187], v[122:125]
	v_mfma_f32_16x16x32_bf16 v[114:117], v[176:179], v[184:187], v[114:117]
	v_mfma_f32_16x16x32_bf16 v[106:109], v[168:171], v[192:195], v[106:109]
	v_mfma_f32_16x16x32_bf16 v[98:101], v[176:179], v[192:195], v[98:101]
	v_mfma_f32_16x16x32_bf16 v[90:93], v[168:171], v[200:203], v[90:93]
	v_mfma_f32_16x16x32_bf16 v[82:85], v[176:179], v[200:203], v[82:85]
	v_mfma_f32_16x16x32_bf16 v[74:77], v[168:171], v[208:211], v[74:77]
	v_mfma_f32_16x16x32_bf16 v[66:69], v[176:179], v[208:211], v[66:69]
	s_setprio 0
	s_setprio 1
	v_mfma_f32_16x16x32_bf16 v[122:125], v[172:175], v[188:191], v[122:125]
	v_mfma_f32_16x16x32_bf16 v[114:117], v[180:183], v[188:191], v[114:117]
	v_mfma_f32_16x16x32_bf16 v[106:109], v[172:175], v[196:199], v[106:109]
	v_mfma_f32_16x16x32_bf16 v[98:101], v[180:183], v[196:199], v[98:101]
	v_mfma_f32_16x16x32_bf16 v[90:93], v[172:175], v[204:207], v[90:93]
	v_mfma_f32_16x16x32_bf16 v[82:85], v[180:183], v[204:207], v[82:85]
	v_mfma_f32_16x16x32_bf16 v[74:77], v[172:175], v[212:215], v[74:77]
	v_mfma_f32_16x16x32_bf16 v[66:69], v[180:183], v[212:215], v[66:69]
	s_setprio 0
	s_barrier
	s_add_i32 s62, s86, s33
	v_lshl_add_u64 v[218:219], v[218:219], 0, s[8:9]
	s_mov_b32 m0, s62
	ds_read_b128 v[184:187], v155 offset:49152
	ds_read_b128 v[188:191], v155 offset:50176
	ds_read_b128 v[192:195], v155 offset:51200
	ds_read_b128 v[196:199], v155 offset:52224
	ds_read_b128 v[200:203], v155 offset:53248
	ds_read_b128 v[204:207], v155 offset:54272
	ds_read_b128 v[208:211], v155 offset:55296
	ds_read_b128 v[212:215], v155 offset:56320
	global_load_lds_dwordx4 v[218:219], off
	s_add_i32 m0, s62, 0x2000
	s_add_u32 s34, s34, 0x80080
	v_lshl_add_u64 v[218:219], v[220:221], 0, s[8:9]
	s_addc_u32 s35, s35, 0
	s_add_i32 s62, s87, s33
	global_load_lds_dwordx4 v[218:219], off
	v_lshl_add_u64 v[218:219], s[34:35], 0, v[134:135]
	s_mov_b32 m0, s62
	s_nop 0
	global_load_lds_dwordx4 v[218:219], off
	v_lshl_add_u64 v[218:219], s[34:35], 0, v[130:131]
	s_add_i32 m0, s62, 0x2000
	s_nop 0
	global_load_lds_dwordx4 v[218:219], off
	v_lshl_add_u64 v[218:219], v[222:223], 0, s[8:9]
	s_mov_b32 m0, s59
	s_nop 0
	global_load_lds_dwordx4 v[218:219], off
	v_lshl_add_u64 v[218:219], v[224:225], 0, s[8:9]
	s_mov_b32 m0, s60
	s_nop 0
	global_load_lds_dwordx4 v[218:219], off
	s_waitcnt vmcnt(8)
	s_waitcnt lgkmcnt(0)
	s_barrier
	s_setprio 1
	s_waitcnt lgkmcnt(0)
	v_mfma_f32_16x16x32_bf16 v[62:65], v[146:149], v[184:187], v[62:65]
	v_mfma_f32_16x16x32_bf16 v[54:57], v[160:163], v[184:187], v[54:57]
	v_mfma_f32_16x16x32_bf16 v[46:49], v[146:149], v[192:195], v[46:49]
	v_mfma_f32_16x16x32_bf16 v[38:41], v[160:163], v[192:195], v[38:41]
	v_mfma_f32_16x16x32_bf16 v[30:33], v[146:149], v[200:203], v[30:33]
	v_mfma_f32_16x16x32_bf16 v[22:25], v[160:163], v[200:203], v[22:25]
	v_mfma_f32_16x16x32_bf16 v[14:17], v[146:149], v[208:211], v[14:17]
	v_mfma_f32_16x16x32_bf16 v[6:9], v[160:163], v[208:211], v[6:9]
	s_setprio 0
	s_setprio 1
	v_mfma_f32_16x16x32_bf16 v[62:65], v[156:159], v[188:191], v[62:65]
	v_mfma_f32_16x16x32_bf16 v[54:57], v[164:167], v[188:191], v[54:57]
	v_mfma_f32_16x16x32_bf16 v[46:49], v[156:159], v[196:199], v[46:49]
	v_mfma_f32_16x16x32_bf16 v[38:41], v[164:167], v[196:199], v[38:41]
	v_mfma_f32_16x16x32_bf16 v[30:33], v[156:159], v[204:207], v[30:33]
	v_mfma_f32_16x16x32_bf16 v[22:25], v[164:167], v[204:207], v[22:25]
	v_mfma_f32_16x16x32_bf16 v[14:17], v[156:159], v[212:215], v[14:17]
	v_mfma_f32_16x16x32_bf16 v[6:9], v[164:167], v[212:215], v[6:9]
	s_setprio 0
	s_setprio 1
	v_mfma_f32_16x16x32_bf16 v[58:61], v[168:171], v[184:187], v[58:61]
	v_mfma_f32_16x16x32_bf16 v[50:53], v[176:179], v[184:187], v[50:53]
	v_mfma_f32_16x16x32_bf16 v[42:45], v[168:171], v[192:195], v[42:45]
	v_mfma_f32_16x16x32_bf16 v[34:37], v[176:179], v[192:195], v[34:37]
	v_mfma_f32_16x16x32_bf16 v[26:29], v[168:171], v[200:203], v[26:29]
	v_mfma_f32_16x16x32_bf16 v[18:21], v[176:179], v[200:203], v[18:21]
	v_mfma_f32_16x16x32_bf16 v[10:13], v[168:171], v[208:211], v[10:13]
	v_mfma_f32_16x16x32_bf16 v[2:5], v[176:179], v[208:211], v[2:5]
	s_setprio 0
	s_setprio 1
	v_mfma_f32_16x16x32_bf16 v[58:61], v[172:175], v[188:191], v[58:61]
	v_mfma_f32_16x16x32_bf16 v[50:53], v[180:183], v[188:191], v[50:53]
	v_mfma_f32_16x16x32_bf16 v[42:45], v[172:175], v[196:199], v[42:45]
	v_mfma_f32_16x16x32_bf16 v[34:37], v[180:183], v[196:199], v[34:37]
	v_mfma_f32_16x16x32_bf16 v[26:29], v[172:175], v[204:207], v[26:29]
	v_mfma_f32_16x16x32_bf16 v[18:21], v[180:183], v[204:207], v[18:21]
	v_mfma_f32_16x16x32_bf16 v[10:13], v[172:175], v[212:215], v[10:13]
	v_mfma_f32_16x16x32_bf16 v[2:5], v[180:183], v[212:215], v[2:5]
	s_setprio 0
	s_barrier
	s_add_i32 s85, s85, 2
	s_add_u32 s76, s76, 0x100
	s_addc_u32 s77, s77, 0
	s_add_u32 s83, s83, 0x100
	s_addc_u32 s84, s84, 0
	s_cmp_gt_u32 s85, 29
	s_cbranch_scc0 .LBB0_274
	s_and_b64 vcc, exec, s[64:65]
	s_cbranch_vccz .LBB0_277
	s_barrier

.LBB0_387:
	ds_read_b128 v[146:149], v154
	ds_read_b128 v[158:161], v154 offset:1024
	ds_read_b128 v[162:165], v154 offset:2048
	ds_read_b128 v[166:169], v154 offset:3072
	ds_read_b128 v[170:173], v155
	ds_read_b128 v[174:177], v155 offset:1024
	ds_read_b128 v[178:181], v155 offset:2048
	ds_read_b128 v[182:185], v155 offset:3072
	s_add_u32 s34, s72, 0xffea0080
	s_addc_u32 s35, s73, -1
	s_cmpk_eq_i32 s81, 0x54
	s_cselect_b32 s75, s5, s35
	s_cselect_b32 s74, s4, s34
	s_cselect_b32 s35, s71, s1
	s_cselect_b32 s34, s70, s0
	v_lshl_add_u64 v[150:151], s[72:73], 0, v[138:139]
	s_add_i32 m0, s53, 0xc000
	ds_read_b128 v[186:189], v156
	ds_read_b128 v[190:193], v156 offset:1024
	ds_read_b128 v[194:197], v156 offset:2048
	ds_read_b128 v[198:201], v156 offset:3072
	ds_read_b128 v[202:205], v156 offset:4096
	ds_read_b128 v[206:209], v156 offset:5120
	ds_read_b128 v[210:213], v156 offset:6144
	ds_read_b128 v[218:221], v156 offset:7168
	global_load_lds_dwordx4 v[150:151], off
	v_lshl_add_u64 v[150:151], s[72:73], 0, v[140:141]
	s_add_i32 m0, s53, 0xe000
	s_nop 0
	global_load_lds_dwordx4 v[150:151], off
	s_waitcnt vmcnt(8)
	s_waitcnt lgkmcnt(0)
	s_barrier
	s_setprio 1
	s_waitcnt lgkmcnt(0)
	v_mfma_f32_16x16x32_bf16 v[126:129], v[146:149], v[186:189], v[126:129]
	v_mfma_f32_16x16x32_bf16 v[122:125], v[162:165], v[186:189], v[122:125]
	v_mfma_f32_16x16x32_bf16 v[118:121], v[146:149], v[194:197], v[118:121]
	v_mfma_f32_16x16x32_bf16 v[114:117], v[162:165], v[194:197], v[114:117]
	v_mfma_f32_16x16x32_bf16 v[94:97], v[146:149], v[202:205], v[94:97]
	v_mfma_f32_16x16x32_bf16 v[90:93], v[162:165], v[202:205], v[90:93]
	v_mfma_f32_16x16x32_bf16 v[86:89], v[146:149], v[210:213], v[86:89]
	v_mfma_f32_16x16x32_bf16 v[82:85], v[162:165], v[210:213], v[82:85]
	s_setprio 0
	s_setprio 1
	v_mfma_f32_16x16x32_bf16 v[126:129], v[158:161], v[190:193], v[126:129]
	v_mfma_f32_16x16x32_bf16 v[122:125], v[166:169], v[190:193], v[122:125]
	v_mfma_f32_16x16x32_bf16 v[118:121], v[158:161], v[198:201], v[118:121]
	v_mfma_f32_16x16x32_bf16 v[114:117], v[166:169], v[198:201], v[114:117]
	v_mfma_f32_16x16x32_bf16 v[94:97], v[158:161], v[206:209], v[94:97]
	v_mfma_f32_16x16x32_bf16 v[90:93], v[166:169], v[206:209], v[90:93]
	v_mfma_f32_16x16x32_bf16 v[86:89], v[158:161], v[218:221], v[86:89]
	v_mfma_f32_16x16x32_bf16 v[82:85], v[166:169], v[218:221], v[82:85]
	s_setprio 0
	s_setprio 1
	v_mfma_f32_16x16x32_bf16 v[110:113], v[170:173], v[186:189], v[110:113]
	v_mfma_f32_16x16x32_bf16 v[106:109], v[178:181], v[186:189], v[106:109]
	v_mfma_f32_16x16x32_bf16 v[102:105], v[170:173], v[194:197], v[102:105]
	v_mfma_f32_16x16x32_bf16 v[98:101], v[178:181], v[194:197], v[98:101]
	v_mfma_f32_16x16x32_bf16 v[78:81], v[170:173], v[202:205], v[78:81]
	v_mfma_f32_16x16x32_bf16 v[74:77], v[178:181], v[202:205], v[74:77]
	v_mfma_f32_16x16x32_bf16 v[70:73], v[170:173], v[210:213], v[70:73]
	v_mfma_f32_16x16x32_bf16 v[66:69], v[178:181], v[210:213], v[66:69]
	s_setprio 0
	s_setprio 1
	v_mfma_f32_16x16x32_bf16 v[110:113], v[174:177], v[190:193], v[110:113]
	v_mfma_f32_16x16x32_bf16 v[106:109], v[182:185], v[190:193], v[106:109]
	v_mfma_f32_16x16x32_bf16 v[102:105], v[174:177], v[198:201], v[102:105]
	v_mfma_f32_16x16x32_bf16 v[98:101], v[182:185], v[198:201], v[98:101]
	v_mfma_f32_16x16x32_bf16 v[78:81], v[174:177], v[206:209], v[78:81]
	v_mfma_f32_16x16x32_bf16 v[74:77], v[182:185], v[206:209], v[74:77]
	v_mfma_f32_16x16x32_bf16 v[70:73], v[174:177], v[218:221], v[70:73]
	v_mfma_f32_16x16x32_bf16 v[66:69], v[182:185], v[218:221], v[66:69]
	s_setprio 0
	s_barrier
	s_add_i32 s62, s61, s52
	v_lshl_add_u64 v[150:151], s[34:35], 0, v[132:133]
	s_mov_b32 m0, s62
	ds_read_b128 v[186:189], v156 offset:16384
	ds_read_b128 v[190:193], v156 offset:17408
	ds_read_b128 v[194:197], v156 offset:18432
	ds_read_b128 v[198:201], v156 offset:19456
	ds_read_b128 v[202:205], v156 offset:20480
	ds_read_b128 v[206:209], v156 offset:21504
	ds_read_b128 v[210:213], v156 offset:22528
	ds_read_b128 v[218:221], v156 offset:23552
	global_load_lds_dwordx4 v[150:151], off
	s_add_i32 m0, s62, 0x2000
	s_add_u32 s62, s34, 0x160000
	v_lshl_add_u64 v[214:215], s[34:35], 0, v[136:137]
	s_addc_u32 s63, s35, 0
	s_add_i32 s82, s76, s52
	global_load_lds_dwordx4 v[214:215], off
	v_lshl_add_u64 v[222:223], s[62:63], 0, v[132:133]
	s_mov_b32 m0, s82
	v_lshl_add_u64 v[224:225], s[74:75], 0, v[134:135]
	global_load_lds_dwordx4 v[222:223], off
	v_lshl_add_u64 v[222:223], s[62:63], 0, v[136:137]
	s_add_i32 m0, s82, 0x2000
	s_nop 0
	global_load_lds_dwordx4 v[222:223], off
	v_lshl_add_u64 v[222:223], s[74:75], 0, v[130:131]
	s_mov_b32 m0, s53
	s_nop 0
	global_load_lds_dwordx4 v[222:223], off
	s_mov_b32 m0, s54
	s_nop 0
	global_load_lds_dwordx4 v[224:225], off
	s_waitcnt vmcnt(8)
	s_waitcnt lgkmcnt(0)
	s_barrier
	s_setprio 1
	s_waitcnt lgkmcnt(0)
	v_mfma_f32_16x16x32_bf16 v[62:65], v[146:149], v[186:189], v[62:65]
	v_mfma_f32_16x16x32_bf16 v[58:61], v[162:165], v[186:189], v[58:61]
	v_mfma_f32_16x16x32_bf16 v[54:57], v[146:149], v[194:197], v[54:57]
	v_mfma_f32_16x16x32_bf16 v[50:53], v[162:165], v[194:197], v[50:53]
	v_mfma_f32_16x16x32_bf16 v[30:33], v[146:149], v[202:205], v[30:33]
	v_mfma_f32_16x16x32_bf16 v[26:29], v[162:165], v[202:205], v[26:29]
	v_mfma_f32_16x16x32_bf16 v[22:25], v[146:149], v[210:213], v[22:25]
	v_mfma_f32_16x16x32_bf16 v[18:21], v[162:165], v[210:213], v[18:21]
	s_setprio 0
	s_setprio 1
	v_mfma_f32_16x16x32_bf16 v[62:65], v[158:161], v[190:193], v[62:65]
	v_mfma_f32_16x16x32_bf16 v[58:61], v[166:169], v[190:193], v[58:61]
	v_mfma_f32_16x16x32_bf16 v[54:57], v[158:161], v[198:201], v[54:57]
	v_mfma_f32_16x16x32_bf16 v[50:53], v[166:169], v[198:201], v[50:53]
	v_mfma_f32_16x16x32_bf16 v[30:33], v[158:161], v[206:209], v[30:33]
	v_mfma_f32_16x16x32_bf16 v[26:29], v[166:169], v[206:209], v[26:29]
	v_mfma_f32_16x16x32_bf16 v[22:25], v[158:161], v[218:221], v[22:25]
	v_mfma_f32_16x16x32_bf16 v[18:21], v[166:169], v[218:221], v[18:21]
	s_setprio 0
	s_setprio 1
	v_mfma_f32_16x16x32_bf16 v[46:49], v[170:173], v[186:189], v[46:49]
	v_mfma_f32_16x16x32_bf16 v[42:45], v[178:181], v[186:189], v[42:45]
	v_mfma_f32_16x16x32_bf16 v[38:41], v[170:173], v[194:197], v[38:41]
	v_mfma_f32_16x16x32_bf16 v[34:37], v[178:181], v[194:197], v[34:37]
	v_mfma_f32_16x16x32_bf16 v[14:17], v[170:173], v[202:205], v[14:17]
	v_mfma_f32_16x16x32_bf16 v[10:13], v[178:181], v[202:205], v[10:13]
	v_mfma_f32_16x16x32_bf16 v[6:9], v[170:173], v[210:213], v[6:9]
	v_mfma_f32_16x16x32_bf16 v[2:5], v[178:181], v[210:213], v[2:5]
	s_setprio 0
	s_setprio 1
	v_mfma_f32_16x16x32_bf16 v[46:49], v[174:177], v[190:193], v[46:49]
	v_mfma_f32_16x16x32_bf16 v[42:45], v[182:185], v[190:193], v[42:45]
	v_mfma_f32_16x16x32_bf16 v[38:41], v[174:177], v[198:201], v[38:41]
	v_mfma_f32_16x16x32_bf16 v[34:37], v[182:185], v[198:201], v[34:37]
	v_mfma_f32_16x16x32_bf16 v[14:17], v[174:177], v[206:209], v[14:17]
	v_mfma_f32_16x16x32_bf16 v[10:13], v[182:185], v[206:209], v[10:13]
	v_mfma_f32_16x16x32_bf16 v[6:9], v[174:177], v[218:221], v[6:9]
	v_mfma_f32_16x16x32_bf16 v[2:5], v[182:185], v[218:221], v[2:5]
	s_setprio 0
	s_barrier
	s_add_i32 s82, 0, 0x18000
	v_add_u32_e32 v157, s82, v152
	s_add_i32 s83, 0, 0x1c000
	ds_read_b128 v[146:149], v157
	ds_read_b128 v[158:161], v157 offset:1024
	ds_read_b128 v[162:165], v157 offset:2048
	ds_read_b128 v[166:169], v157 offset:3072
	v_add_u32_e32 v157, s83, v152
	ds_read_b128 v[170:173], v157
	ds_read_b128 v[174:177], v157 offset:1024
	ds_read_b128 v[178:181], v157 offset:2048
	ds_read_b128 v[182:185], v157 offset:3072
	s_add_u32 s62, s74, 0x160000
	s_addc_u32 s63, s75, 0
	s_mov_b32 m0, s55
	v_lshl_add_u64 v[226:227], s[62:63], 0, v[130:131]
	ds_read_b128 v[186:189], v156 offset:32768
	ds_read_b128 v[190:193], v156 offset:33792
	ds_read_b128 v[194:197], v156 offset:34816
	ds_read_b128 v[198:201], v156 offset:35840
	ds_read_b128 v[202:205], v156 offset:36864
	ds_read_b128 v[206:209], v156 offset:37888
	ds_read_b128 v[210:213], v156 offset:38912
	ds_read_b128 v[218:221], v156 offset:39936
	global_load_lds_dwordx4 v[226:227], off
	v_lshl_add_u64 v[226:227], s[62:63], 0, v[134:135]
	s_mov_b32 m0, s56
	s_nop 0
	global_load_lds_dwordx4 v[226:227], off
	s_waitcnt vmcnt(8)
	s_waitcnt lgkmcnt(0)
	s_barrier
	s_setprio 1
	s_waitcnt lgkmcnt(0)
	v_mfma_f32_16x16x32_bf16 v[126:129], v[146:149], v[186:189], v[126:129]
	v_mfma_f32_16x16x32_bf16 v[122:125], v[162:165], v[186:189], v[122:125]
	v_mfma_f32_16x16x32_bf16 v[118:121], v[146:149], v[194:197], v[118:121]
	v_mfma_f32_16x16x32_bf16 v[114:117], v[162:165], v[194:197], v[114:117]
	v_mfma_f32_16x16x32_bf16 v[94:97], v[146:149], v[202:205], v[94:97]
	v_mfma_f32_16x16x32_bf16 v[90:93], v[162:165], v[202:205], v[90:93]
	v_mfma_f32_16x16x32_bf16 v[86:89], v[146:149], v[210:213], v[86:89]
	v_mfma_f32_16x16x32_bf16 v[82:85], v[162:165], v[210:213], v[82:85]
	s_setprio 0
	s_setprio 1
	v_mfma_f32_16x16x32_bf16 v[126:129], v[158:161], v[190:193], v[126:129]
	v_mfma_f32_16x16x32_bf16 v[122:125], v[166:169], v[190:193], v[122:125]
	v_mfma_f32_16x16x32_bf16 v[118:121], v[158:161], v[198:201], v[118:121]
	v_mfma_f32_16x16x32_bf16 v[114:117], v[166:169], v[198:201], v[114:117]
	v_mfma_f32_16x16x32_bf16 v[94:97], v[158:161], v[206:209], v[94:97]
	v_mfma_f32_16x16x32_bf16 v[90:93], v[166:169], v[206:209], v[90:93]
	v_mfma_f32_16x16x32_bf16 v[86:89], v[158:161], v[218:221], v[86:89]
	v_mfma_f32_16x16x32_bf16 v[82:85], v[166:169], v[218:221], v[82:85]
	s_setprio 0
	s_setprio 1
	v_mfma_f32_16x16x32_bf16 v[110:113], v[170:173], v[186:189], v[110:113]
	v_mfma_f32_16x16x32_bf16 v[106:109], v[178:181], v[186:189], v[106:109]
	v_mfma_f32_16x16x32_bf16 v[102:105], v[170:173], v[194:197], v[102:105]
	v_mfma_f32_16x16x32_bf16 v[98:101], v[178:181], v[194:197], v[98:101]
	v_mfma_f32_16x16x32_bf16 v[78:81], v[170:173], v[202:205], v[78:81]
	v_mfma_f32_16x16x32_bf16 v[74:77], v[178:181], v[202:205], v[74:77]
	v_mfma_f32_16x16x32_bf16 v[70:73], v[170:173], v[210:213], v[70:73]
	v_mfma_f32_16x16x32_bf16 v[66:69], v[178:181], v[210:213], v[66:69]
	s_setprio 0
	s_setprio 1
	v_mfma_f32_16x16x32_bf16 v[110:113], v[174:177], v[190:193], v[110:113]
	v_mfma_f32_16x16x32_bf16 v[106:109], v[182:185], v[190:193], v[106:109]
	v_mfma_f32_16x16x32_bf16 v[102:105], v[174:177], v[198:201], v[102:105]
	v_mfma_f32_16x16x32_bf16 v[98:101], v[182:185], v[198:201], v[98:101]
	v_mfma_f32_16x16x32_bf16 v[78:81], v[174:177], v[206:209], v[78:81]
	v_mfma_f32_16x16x32_bf16 v[74:77], v[182:185], v[206:209], v[74:77]
	v_mfma_f32_16x16x32_bf16 v[70:73], v[174:177], v[218:221], v[70:73]
	v_mfma_f32_16x16x32_bf16 v[66:69], v[182:185], v[218:221], v[66:69]
	s_setprio 0
	s_barrier
	s_add_i32 s62, s82, s52
	v_lshl_add_u64 v[150:151], v[150:151], 0, s[66:67]
	s_mov_b32 m0, s62
	ds_read_b128 v[186:189], v156 offset:49152
	ds_read_b128 v[190:193], v156 offset:50176
	ds_read_b128 v[194:197], v156 offset:51200
	ds_read_b128 v[198:201], v156 offset:52224
	ds_read_b128 v[202:205], v156 offset:53248
	ds_read_b128 v[206:209], v156 offset:54272
	ds_read_b128 v[210:213], v156 offset:55296
	ds_read_b128 v[218:221], v156 offset:56320
	global_load_lds_dwordx4 v[150:151], off
	s_add_i32 m0, s62, 0x2000
	s_add_u32 s34, s34, 0x160080
	v_lshl_add_u64 v[150:151], v[214:215], 0, s[66:67]
	s_addc_u32 s35, s35, 0
	s_add_i32 s62, s83, s52
	global_load_lds_dwordx4 v[150:151], off
	v_lshl_add_u64 v[150:151], s[34:35], 0, v[132:133]
	s_mov_b32 m0, s62
	s_nop 0
	global_load_lds_dwordx4 v[150:151], off
	v_lshl_add_u64 v[150:151], s[34:35], 0, v[136:137]
	s_add_i32 m0, s62, 0x2000
	s_nop 0
	global_load_lds_dwordx4 v[150:151], off
	v_lshl_add_u64 v[150:151], v[222:223], 0, s[66:67]
	s_mov_b32 m0, s58
	s_nop 0
	global_load_lds_dwordx4 v[150:151], off
	v_lshl_add_u64 v[150:151], v[224:225], 0, s[66:67]
	s_mov_b32 m0, s59
	s_nop 0
	global_load_lds_dwordx4 v[150:151], off
	s_waitcnt vmcnt(8)
	s_waitcnt lgkmcnt(0)
	s_barrier
	s_setprio 1
	s_waitcnt lgkmcnt(0)
	v_mfma_f32_16x16x32_bf16 v[62:65], v[146:149], v[186:189], v[62:65]
	v_mfma_f32_16x16x32_bf16 v[58:61], v[162:165], v[186:189], v[58:61]
	v_mfma_f32_16x16x32_bf16 v[54:57], v[146:149], v[194:197], v[54:57]
	v_mfma_f32_16x16x32_bf16 v[50:53], v[162:165], v[194:197], v[50:53]
	v_mfma_f32_16x16x32_bf16 v[30:33], v[146:149], v[202:205], v[30:33]
	v_mfma_f32_16x16x32_bf16 v[26:29], v[162:165], v[202:205], v[26:29]
	v_mfma_f32_16x16x32_bf16 v[22:25], v[146:149], v[210:213], v[22:25]
	v_mfma_f32_16x16x32_bf16 v[18:21], v[162:165], v[210:213], v[18:21]
	s_setprio 0
	s_setprio 1
	v_mfma_f32_16x16x32_bf16 v[62:65], v[158:161], v[190:193], v[62:65]
	v_mfma_f32_16x16x32_bf16 v[58:61], v[166:169], v[190:193], v[58:61]
	v_mfma_f32_16x16x32_bf16 v[54:57], v[158:161], v[198:201], v[54:57]
	v_mfma_f32_16x16x32_bf16 v[50:53], v[166:169], v[198:201], v[50:53]
	v_mfma_f32_16x16x32_bf16 v[30:33], v[158:161], v[206:209], v[30:33]
	v_mfma_f32_16x16x32_bf16 v[26:29], v[166:169], v[206:209], v[26:29]
	v_mfma_f32_16x16x32_bf16 v[22:25], v[158:161], v[218:221], v[22:25]
	v_mfma_f32_16x16x32_bf16 v[18:21], v[166:169], v[218:221], v[18:21]
	s_setprio 0
	s_setprio 1
	v_mfma_f32_16x16x32_bf16 v[46:49], v[170:173], v[186:189], v[46:49]
	v_mfma_f32_16x16x32_bf16 v[42:45], v[178:181], v[186:189], v[42:45]
	v_mfma_f32_16x16x32_bf16 v[38:41], v[170:173], v[194:197], v[38:41]
	v_mfma_f32_16x16x32_bf16 v[34:37], v[178:181], v[194:197], v[34:37]
	v_mfma_f32_16x16x32_bf16 v[14:17], v[170:173], v[202:205], v[14:17]
	v_mfma_f32_16x16x32_bf16 v[10:13], v[178:181], v[202:205], v[10:13]
	v_mfma_f32_16x16x32_bf16 v[6:9], v[170:173], v[210:213], v[6:9]
	v_mfma_f32_16x16x32_bf16 v[2:5], v[178:181], v[210:213], v[2:5]
	s_setprio 0
	s_setprio 1
	v_mfma_f32_16x16x32_bf16 v[46:49], v[174:177], v[190:193], v[46:49]
	v_mfma_f32_16x16x32_bf16 v[42:45], v[182:185], v[190:193], v[42:45]
	v_mfma_f32_16x16x32_bf16 v[38:41], v[174:177], v[198:201], v[38:41]
	v_mfma_f32_16x16x32_bf16 v[34:37], v[182:185], v[198:201], v[34:37]
	v_mfma_f32_16x16x32_bf16 v[14:17], v[174:177], v[206:209], v[14:17]
	v_mfma_f32_16x16x32_bf16 v[10:13], v[182:185], v[206:209], v[10:13]
	v_mfma_f32_16x16x32_bf16 v[6:9], v[174:177], v[218:221], v[6:9]
	v_mfma_f32_16x16x32_bf16 v[2:5], v[182:185], v[218:221], v[2:5]
	s_setprio 0
	s_barrier
	s_add_i32 s81, s81, 2
	s_add_u32 s72, s72, 0x100
	s_addc_u32 s73, s73, 0
	s_add_u32 s0, s0, 0x100
	s_addc_u32 s1, s1, 0
	s_cmpk_gt_u32 s81, 0x55
	s_cbranch_scc0 .LBB0_387
	s_and_b64 vcc, exec, s[68:69]
	s_cbranch_vccz .LBB0_390
	s_barrier

.LBB0_518:
	ds_read_b128 v[160:163], v155
	ds_read_b128 v[164:167], v155 offset:1024
	ds_read_b128 v[168:171], v155 offset:2048
	ds_read_b128 v[172:175], v155 offset:3072
	ds_read_b128 v[176:179], v156
	ds_read_b128 v[180:183], v156 offset:1024
	ds_read_b128 v[184:187], v156 offset:2048
	ds_read_b128 v[188:191], v156 offset:3072
	s_add_u32 s34, s90, 0xfff80080
	s_addc_u32 s35, s91, -1
	s_cmp_eq_u32 s83, 28
	s_cselect_b32 s93, s0, s35
	s_cselect_b32 s92, s1, s34
	s_cselect_b32 s35, s7, s68
	s_cselect_b32 s34, s9, s52
	v_lshl_add_u64 v[152:153], s[90:91], 0, v[144:145]
	s_add_i32 m0, s56, 0xc000
	ds_read_b128 v[192:195], v157
	ds_read_b128 v[196:199], v157 offset:1024
	ds_read_b128 v[200:203], v157 offset:2048
	ds_read_b128 v[204:207], v157 offset:3072
	ds_read_b128 v[208:211], v157 offset:4096
	ds_read_b128 v[212:215], v157 offset:5120
	ds_read_b128 v[218:221], v157 offset:6144
	ds_read_b128 v[222:225], v157 offset:7168
	global_load_lds_dwordx4 v[152:153], off
	v_lshl_add_u64 v[152:153], s[90:91], 0, v[146:147]
	s_add_i32 m0, s56, 0xe000
	s_nop 0
	global_load_lds_dwordx4 v[152:153], off
	s_waitcnt vmcnt(8)
	s_waitcnt lgkmcnt(0)
	s_barrier
	s_setprio 1
	s_waitcnt lgkmcnt(0)
	v_mfma_f32_16x16x32_bf16 v[126:129], v[160:163], v[192:195], v[126:129]
	v_mfma_f32_16x16x32_bf16 v[122:125], v[168:171], v[192:195], v[122:125]
	v_mfma_f32_16x16x32_bf16 v[110:113], v[160:163], v[200:203], v[110:113]
	v_mfma_f32_16x16x32_bf16 v[106:109], v[168:171], v[200:203], v[106:109]
	v_mfma_f32_16x16x32_bf16 v[94:97], v[160:163], v[208:211], v[94:97]
	v_mfma_f32_16x16x32_bf16 v[90:93], v[168:171], v[208:211], v[90:93]
	v_mfma_f32_16x16x32_bf16 v[78:81], v[160:163], v[218:221], v[78:81]
	v_mfma_f32_16x16x32_bf16 v[74:77], v[168:171], v[218:221], v[74:77]
	s_setprio 0
	s_setprio 1
	v_mfma_f32_16x16x32_bf16 v[126:129], v[164:167], v[196:199], v[126:129]
	v_mfma_f32_16x16x32_bf16 v[122:125], v[172:175], v[196:199], v[122:125]
	v_mfma_f32_16x16x32_bf16 v[110:113], v[164:167], v[204:207], v[110:113]
	v_mfma_f32_16x16x32_bf16 v[106:109], v[172:175], v[204:207], v[106:109]
	v_mfma_f32_16x16x32_bf16 v[94:97], v[164:167], v[212:215], v[94:97]
	v_mfma_f32_16x16x32_bf16 v[90:93], v[172:175], v[212:215], v[90:93]
	v_mfma_f32_16x16x32_bf16 v[78:81], v[164:167], v[222:225], v[78:81]
	v_mfma_f32_16x16x32_bf16 v[74:77], v[172:175], v[222:225], v[74:77]
	s_setprio 0
	s_setprio 1
	v_mfma_f32_16x16x32_bf16 v[118:121], v[176:179], v[192:195], v[118:121]
	v_mfma_f32_16x16x32_bf16 v[114:117], v[184:187], v[192:195], v[114:117]
	v_mfma_f32_16x16x32_bf16 v[102:105], v[176:179], v[200:203], v[102:105]
	v_mfma_f32_16x16x32_bf16 v[98:101], v[184:187], v[200:203], v[98:101]
	v_mfma_f32_16x16x32_bf16 v[86:89], v[176:179], v[208:211], v[86:89]
	v_mfma_f32_16x16x32_bf16 v[82:85], v[184:187], v[208:211], v[82:85]
	v_mfma_f32_16x16x32_bf16 v[70:73], v[176:179], v[218:221], v[70:73]
	v_mfma_f32_16x16x32_bf16 v[66:69], v[184:187], v[218:221], v[66:69]
	s_setprio 0
	s_setprio 1
	v_mfma_f32_16x16x32_bf16 v[118:121], v[180:183], v[196:199], v[118:121]
	v_mfma_f32_16x16x32_bf16 v[114:117], v[188:191], v[196:199], v[114:117]
	v_mfma_f32_16x16x32_bf16 v[102:105], v[180:183], v[204:207], v[102:105]
	v_mfma_f32_16x16x32_bf16 v[98:101], v[188:191], v[204:207], v[98:101]
	v_mfma_f32_16x16x32_bf16 v[86:89], v[180:183], v[212:215], v[86:89]
	v_mfma_f32_16x16x32_bf16 v[82:85], v[188:191], v[212:215], v[82:85]
	v_mfma_f32_16x16x32_bf16 v[70:73], v[180:183], v[222:225], v[70:73]
	v_mfma_f32_16x16x32_bf16 v[66:69], v[188:191], v[222:225], v[66:69]
	s_setprio 0
	s_barrier
	s_add_i32 s53, s75, s30
	v_lshl_add_u64 v[152:153], s[34:35], 0, v[132:133]
	s_mov_b32 m0, s53
	ds_read_b128 v[192:195], v157 offset:16384
	ds_read_b128 v[196:199], v157 offset:17408
	ds_read_b128 v[200:203], v157 offset:18432
	ds_read_b128 v[204:207], v157 offset:19456
	ds_read_b128 v[208:211], v157 offset:20480
	ds_read_b128 v[212:215], v157 offset:21504
	ds_read_b128 v[218:221], v157 offset:22528
	ds_read_b128 v[222:225], v157 offset:23552
	global_load_lds_dwordx4 v[152:153], off
	s_add_i32 m0, s53, 0x2000
	s_add_u32 s54, s34, 0x80000
	v_lshl_add_u64 v[226:227], s[34:35], 0, v[136:137]
	s_addc_u32 s55, s35, 0
	s_add_i32 s53, s94, s30
	global_load_lds_dwordx4 v[226:227], off
	v_lshl_add_u64 v[228:229], s[54:55], 0, v[132:133]
	s_mov_b32 m0, s53
	v_lshl_add_u64 v[230:231], s[92:93], 0, v[134:135]
	global_load_lds_dwordx4 v[228:229], off
	v_lshl_add_u64 v[228:229], s[54:55], 0, v[136:137]
	s_add_i32 m0, s53, 0x2000
	s_nop 0
	global_load_lds_dwordx4 v[228:229], off
	v_lshl_add_u64 v[228:229], s[92:93], 0, v[130:131]
	s_mov_b32 m0, s56
	s_nop 0
	global_load_lds_dwordx4 v[228:229], off
	s_mov_b32 m0, s57
	s_nop 0
	global_load_lds_dwordx4 v[230:231], off
	s_waitcnt vmcnt(8)
	s_waitcnt lgkmcnt(0)
	s_barrier
	s_setprio 1
	s_waitcnt lgkmcnt(0)
	v_mfma_f32_16x16x32_bf16 v[62:65], v[160:163], v[192:195], v[62:65]
	v_mfma_f32_16x16x32_bf16 v[58:61], v[168:171], v[192:195], v[58:61]
	v_mfma_f32_16x16x32_bf16 v[46:49], v[160:163], v[200:203], v[46:49]
	v_mfma_f32_16x16x32_bf16 v[42:45], v[168:171], v[200:203], v[42:45]
	v_mfma_f32_16x16x32_bf16 v[30:33], v[160:163], v[208:211], v[30:33]
	v_mfma_f32_16x16x32_bf16 v[26:29], v[168:171], v[208:211], v[26:29]
	v_mfma_f32_16x16x32_bf16 v[14:17], v[160:163], v[218:221], v[14:17]
	v_mfma_f32_16x16x32_bf16 v[10:13], v[168:171], v[218:221], v[10:13]
	s_setprio 0
	s_setprio 1
	v_mfma_f32_16x16x32_bf16 v[62:65], v[164:167], v[196:199], v[62:65]
	v_mfma_f32_16x16x32_bf16 v[58:61], v[172:175], v[196:199], v[58:61]
	v_mfma_f32_16x16x32_bf16 v[46:49], v[164:167], v[204:207], v[46:49]
	v_mfma_f32_16x16x32_bf16 v[42:45], v[172:175], v[204:207], v[42:45]
	v_mfma_f32_16x16x32_bf16 v[30:33], v[164:167], v[212:215], v[30:33]
	v_mfma_f32_16x16x32_bf16 v[26:29], v[172:175], v[212:215], v[26:29]
	v_mfma_f32_16x16x32_bf16 v[14:17], v[164:167], v[222:225], v[14:17]
	v_mfma_f32_16x16x32_bf16 v[10:13], v[172:175], v[222:225], v[10:13]
	s_setprio 0
	s_setprio 1
	v_mfma_f32_16x16x32_bf16 v[54:57], v[176:179], v[192:195], v[54:57]
	v_mfma_f32_16x16x32_bf16 v[50:53], v[184:187], v[192:195], v[50:53]
	v_mfma_f32_16x16x32_bf16 v[38:41], v[176:179], v[200:203], v[38:41]
	v_mfma_f32_16x16x32_bf16 v[34:37], v[184:187], v[200:203], v[34:37]
	v_mfma_f32_16x16x32_bf16 v[22:25], v[176:179], v[208:211], v[22:25]
	v_mfma_f32_16x16x32_bf16 v[18:21], v[184:187], v[208:211], v[18:21]
	v_mfma_f32_16x16x32_bf16 v[6:9], v[176:179], v[218:221], v[6:9]
	v_mfma_f32_16x16x32_bf16 v[2:5], v[184:187], v[218:221], v[2:5]
	s_setprio 0
	s_setprio 1
	v_mfma_f32_16x16x32_bf16 v[54:57], v[180:183], v[196:199], v[54:57]
	v_mfma_f32_16x16x32_bf16 v[50:53], v[188:191], v[196:199], v[50:53]
	v_mfma_f32_16x16x32_bf16 v[38:41], v[180:183], v[204:207], v[38:41]
	v_mfma_f32_16x16x32_bf16 v[34:37], v[188:191], v[204:207], v[34:37]
	v_mfma_f32_16x16x32_bf16 v[22:25], v[180:183], v[212:215], v[22:25]
	v_mfma_f32_16x16x32_bf16 v[18:21], v[188:191], v[212:215], v[18:21]
	v_mfma_f32_16x16x32_bf16 v[6:9], v[180:183], v[222:225], v[6:9]
	v_mfma_f32_16x16x32_bf16 v[2:5], v[188:191], v[222:225], v[2:5]
	s_setprio 0
	s_barrier
	s_add_i32 s53, 0, 0x18000
	v_add_u32_e32 v138, s53, v154
	s_add_i32 s62, 0, 0x1c000
	ds_read_b128 v[160:163], v138
	ds_read_b128 v[164:167], v138 offset:1024
	ds_read_b128 v[168:171], v138 offset:2048
	ds_read_b128 v[172:175], v138 offset:3072
	v_add_u32_e32 v138, s62, v154
	ds_read_b128 v[176:179], v138
	ds_read_b128 v[180:183], v138 offset:1024
	ds_read_b128 v[184:187], v138 offset:2048
	ds_read_b128 v[188:191], v138 offset:3072
	s_add_u32 s54, s92, 0x80000
	s_addc_u32 s55, s93, 0
	s_mov_b32 m0, s58
	v_lshl_add_u64 v[232:233], s[54:55], 0, v[130:131]
	ds_read_b128 v[192:195], v157 offset:32768
	ds_read_b128 v[196:199], v157 offset:33792
	ds_read_b128 v[200:203], v157 offset:34816
	ds_read_b128 v[204:207], v157 offset:35840
	ds_read_b128 v[208:211], v157 offset:36864
	ds_read_b128 v[212:215], v157 offset:37888
	ds_read_b128 v[218:221], v157 offset:38912
	ds_read_b128 v[222:225], v157 offset:39936
	global_load_lds_dwordx4 v[232:233], off
	v_lshl_add_u64 v[232:233], s[54:55], 0, v[134:135]
	s_mov_b32 m0, s59
	s_nop 0
	global_load_lds_dwordx4 v[232:233], off
	s_waitcnt vmcnt(8)
	s_waitcnt lgkmcnt(0)
	s_barrier
	s_setprio 1
	s_waitcnt lgkmcnt(0)
	v_mfma_f32_16x16x32_bf16 v[126:129], v[160:163], v[192:195], v[126:129]
	v_mfma_f32_16x16x32_bf16 v[122:125], v[168:171], v[192:195], v[122:125]
	v_mfma_f32_16x16x32_bf16 v[110:113], v[160:163], v[200:203], v[110:113]
	v_mfma_f32_16x16x32_bf16 v[106:109], v[168:171], v[200:203], v[106:109]
	v_mfma_f32_16x16x32_bf16 v[94:97], v[160:163], v[208:211], v[94:97]
	v_mfma_f32_16x16x32_bf16 v[90:93], v[168:171], v[208:211], v[90:93]
	v_mfma_f32_16x16x32_bf16 v[78:81], v[160:163], v[218:221], v[78:81]
	v_mfma_f32_16x16x32_bf16 v[74:77], v[168:171], v[218:221], v[74:77]
	s_setprio 0
	s_setprio 1
	v_mfma_f32_16x16x32_bf16 v[126:129], v[164:167], v[196:199], v[126:129]
	v_mfma_f32_16x16x32_bf16 v[122:125], v[172:175], v[196:199], v[122:125]
	v_mfma_f32_16x16x32_bf16 v[110:113], v[164:167], v[204:207], v[110:113]
	v_mfma_f32_16x16x32_bf16 v[106:109], v[172:175], v[204:207], v[106:109]
	v_mfma_f32_16x16x32_bf16 v[94:97], v[164:167], v[212:215], v[94:97]
	v_mfma_f32_16x16x32_bf16 v[90:93], v[172:175], v[212:215], v[90:93]
	v_mfma_f32_16x16x32_bf16 v[78:81], v[164:167], v[222:225], v[78:81]
	v_mfma_f32_16x16x32_bf16 v[74:77], v[172:175], v[222:225], v[74:77]
	s_setprio 0
	s_setprio 1
	v_mfma_f32_16x16x32_bf16 v[118:121], v[176:179], v[192:195], v[118:121]
	v_mfma_f32_16x16x32_bf16 v[114:117], v[184:187], v[192:195], v[114:117]
	v_mfma_f32_16x16x32_bf16 v[102:105], v[176:179], v[200:203], v[102:105]
	v_mfma_f32_16x16x32_bf16 v[98:101], v[184:187], v[200:203], v[98:101]
	v_mfma_f32_16x16x32_bf16 v[86:89], v[176:179], v[208:211], v[86:89]
	v_mfma_f32_16x16x32_bf16 v[82:85], v[184:187], v[208:211], v[82:85]
	v_mfma_f32_16x16x32_bf16 v[70:73], v[176:179], v[218:221], v[70:73]
	v_mfma_f32_16x16x32_bf16 v[66:69], v[184:187], v[218:221], v[66:69]
	s_setprio 0
	s_setprio 1
	v_mfma_f32_16x16x32_bf16 v[118:121], v[180:183], v[196:199], v[118:121]
	v_mfma_f32_16x16x32_bf16 v[114:117], v[188:191], v[196:199], v[114:117]
	v_mfma_f32_16x16x32_bf16 v[102:105], v[180:183], v[204:207], v[102:105]
	v_mfma_f32_16x16x32_bf16 v[98:101], v[188:191], v[204:207], v[98:101]
	v_mfma_f32_16x16x32_bf16 v[86:89], v[180:183], v[212:215], v[86:89]
	v_mfma_f32_16x16x32_bf16 v[82:85], v[188:191], v[212:215], v[82:85]
	v_mfma_f32_16x16x32_bf16 v[70:73], v[180:183], v[222:225], v[70:73]
	v_mfma_f32_16x16x32_bf16 v[66:69], v[188:191], v[222:225], v[66:69]
	s_setprio 0
	s_barrier
	s_add_i32 s53, s53, s30
	v_lshl_add_u64 v[152:153], v[152:153], 0, s[76:77]
	s_mov_b32 m0, s53
	ds_read_b128 v[192:195], v157 offset:49152
	ds_read_b128 v[196:199], v157 offset:50176
	ds_read_b128 v[200:203], v157 offset:51200
	ds_read_b128 v[204:207], v157 offset:52224
	ds_read_b128 v[208:211], v157 offset:53248
	ds_read_b128 v[212:215], v157 offset:54272
	ds_read_b128 v[218:221], v157 offset:55296
	ds_read_b128 v[222:225], v157 offset:56320
	global_load_lds_dwordx4 v[152:153], off
	s_add_i32 m0, s53, 0x2000
	s_add_u32 s34, s34, 0x80080
	v_lshl_add_u64 v[152:153], v[226:227], 0, s[76:77]
	s_addc_u32 s35, s35, 0
	s_add_i32 s53, s62, s30
	global_load_lds_dwordx4 v[152:153], off
	v_lshl_add_u64 v[152:153], s[34:35], 0, v[132:133]
	s_mov_b32 m0, s53
	s_nop 0
	global_load_lds_dwordx4 v[152:153], off
	v_lshl_add_u64 v[152:153], s[34:35], 0, v[136:137]
	s_add_i32 m0, s53, 0x2000
	s_nop 0
	global_load_lds_dwordx4 v[152:153], off
	v_lshl_add_u64 v[152:153], v[228:229], 0, s[76:77]
	s_mov_b32 m0, s61
	s_nop 0
	global_load_lds_dwordx4 v[152:153], off
	v_lshl_add_u64 v[152:153], v[230:231], 0, s[76:77]
	s_mov_b32 m0, s72
	s_nop 0
	global_load_lds_dwordx4 v[152:153], off
	s_waitcnt vmcnt(8)
	s_waitcnt lgkmcnt(0)
	s_barrier
	s_setprio 1
	s_waitcnt lgkmcnt(0)
	v_mfma_f32_16x16x32_bf16 v[62:65], v[160:163], v[192:195], v[62:65]
	v_mfma_f32_16x16x32_bf16 v[58:61], v[168:171], v[192:195], v[58:61]
	v_mfma_f32_16x16x32_bf16 v[46:49], v[160:163], v[200:203], v[46:49]
	v_mfma_f32_16x16x32_bf16 v[42:45], v[168:171], v[200:203], v[42:45]
	v_mfma_f32_16x16x32_bf16 v[30:33], v[160:163], v[208:211], v[30:33]
	v_mfma_f32_16x16x32_bf16 v[26:29], v[168:171], v[208:211], v[26:29]
	v_mfma_f32_16x16x32_bf16 v[14:17], v[160:163], v[218:221], v[14:17]
	v_mfma_f32_16x16x32_bf16 v[10:13], v[168:171], v[218:221], v[10:13]
	s_setprio 0
	s_setprio 1
	v_mfma_f32_16x16x32_bf16 v[62:65], v[164:167], v[196:199], v[62:65]
	v_mfma_f32_16x16x32_bf16 v[58:61], v[172:175], v[196:199], v[58:61]
	v_mfma_f32_16x16x32_bf16 v[46:49], v[164:167], v[204:207], v[46:49]
	v_mfma_f32_16x16x32_bf16 v[42:45], v[172:175], v[204:207], v[42:45]
	v_mfma_f32_16x16x32_bf16 v[30:33], v[164:167], v[212:215], v[30:33]
	v_mfma_f32_16x16x32_bf16 v[26:29], v[172:175], v[212:215], v[26:29]
	v_mfma_f32_16x16x32_bf16 v[14:17], v[164:167], v[222:225], v[14:17]
	v_mfma_f32_16x16x32_bf16 v[10:13], v[172:175], v[222:225], v[10:13]
	s_setprio 0
	s_setprio 1
	v_mfma_f32_16x16x32_bf16 v[54:57], v[176:179], v[192:195], v[54:57]
	v_mfma_f32_16x16x32_bf16 v[50:53], v[184:187], v[192:195], v[50:53]
	v_mfma_f32_16x16x32_bf16 v[38:41], v[176:179], v[200:203], v[38:41]
	v_mfma_f32_16x16x32_bf16 v[34:37], v[184:187], v[200:203], v[34:37]
	v_mfma_f32_16x16x32_bf16 v[22:25], v[176:179], v[208:211], v[22:25]
	v_mfma_f32_16x16x32_bf16 v[18:21], v[184:187], v[208:211], v[18:21]
	v_mfma_f32_16x16x32_bf16 v[6:9], v[176:179], v[218:221], v[6:9]
	v_mfma_f32_16x16x32_bf16 v[2:5], v[184:187], v[218:221], v[2:5]
	s_setprio 0
	s_setprio 1
	v_mfma_f32_16x16x32_bf16 v[54:57], v[180:183], v[196:199], v[54:57]
	v_mfma_f32_16x16x32_bf16 v[50:53], v[188:191], v[196:199], v[50:53]
	v_mfma_f32_16x16x32_bf16 v[38:41], v[180:183], v[204:207], v[38:41]
	v_mfma_f32_16x16x32_bf16 v[34:37], v[188:191], v[204:207], v[34:37]
	v_mfma_f32_16x16x32_bf16 v[22:25], v[180:183], v[212:215], v[22:25]
	v_mfma_f32_16x16x32_bf16 v[18:21], v[188:191], v[212:215], v[18:21]
	v_mfma_f32_16x16x32_bf16 v[6:9], v[180:183], v[222:225], v[6:9]
	v_mfma_f32_16x16x32_bf16 v[2:5], v[188:191], v[222:225], v[2:5]
	s_setprio 0
	s_barrier
	s_add_i32 s83, s83, 2
	s_add_u32 s90, s90, 0x100
	s_addc_u32 s91, s91, 0
	s_add_u32 s52, s52, 0x100
	s_addc_u32 s68, s68, 0
	s_cmp_gt_u32 s83, 29
	s_cbranch_scc0 .LBB0_518
	s_and_b64 vcc, exec, s[78:79]
	s_cbranch_vccz .LBB0_521
	s_barrier

.LBB0_685:
	ds_read_b128 v[146:149], v165
	ds_read_b128 v[150:153], v165 offset:1024
	ds_read_b128 v[168:171], v165 offset:2048
	ds_read_b128 v[172:175], v165 offset:3072
	ds_read_b128 v[176:179], v166
	ds_read_b128 v[180:183], v166 offset:1024
	ds_read_b128 v[184:187], v166 offset:2048
	ds_read_b128 v[188:191], v166 offset:3072
	s_add_u32 s34, s84, 0xfffe0080
	s_addc_u32 s35, s85, -1
	s_cmp_eq_u32 s89, 4
	s_cselect_b32 s87, s0, s35
	s_cselect_b32 s86, s1, s34
	s_cselect_b32 s35, s52, s88
	s_cselect_b32 s34, s71, s77
	v_lshl_add_u64 v[226:227], s[84:85], 0, v[138:139]
	s_add_i32 m0, s33, 0xc000
	ds_read_b128 v[192:195], v167
	ds_read_b128 v[196:199], v167 offset:1024
	ds_read_b128 v[200:203], v167 offset:2048
	ds_read_b128 v[204:207], v167 offset:3072
	ds_read_b128 v[208:211], v167 offset:4096
	ds_read_b128 v[212:215], v167 offset:5120
	ds_read_b128 v[218:221], v167 offset:6144
	ds_read_b128 v[222:225], v167 offset:7168
	global_load_lds_dwordx4 v[226:227], off
	v_lshl_add_u64 v[226:227], s[84:85], 0, v[140:141]
	s_add_i32 m0, s33, 0xe000
	s_nop 0
	global_load_lds_dwordx4 v[226:227], off
	s_waitcnt vmcnt(8)
	s_waitcnt lgkmcnt(0)
	s_barrier
	s_setprio 1
	s_waitcnt lgkmcnt(0)
	v_mfma_f32_16x16x32_bf16 v[126:129], v[146:149], v[192:195], v[126:129]
	v_mfma_f32_16x16x32_bf16 v[122:125], v[168:171], v[192:195], v[122:125]
	v_mfma_f32_16x16x32_bf16 v[114:117], v[146:149], v[200:203], v[114:117]
	v_mfma_f32_16x16x32_bf16 v[106:109], v[168:171], v[200:203], v[106:109]
	v_mfma_f32_16x16x32_bf16 v[98:101], v[146:149], v[208:211], v[98:101]
	v_mfma_f32_16x16x32_bf16 v[90:93], v[168:171], v[208:211], v[90:93]
	v_mfma_f32_16x16x32_bf16 v[82:85], v[146:149], v[218:221], v[82:85]
	v_mfma_f32_16x16x32_bf16 v[74:77], v[168:171], v[218:221], v[74:77]
	s_setprio 0
	s_setprio 1
	v_mfma_f32_16x16x32_bf16 v[126:129], v[150:153], v[196:199], v[126:129]
	v_mfma_f32_16x16x32_bf16 v[122:125], v[172:175], v[196:199], v[122:125]
	v_mfma_f32_16x16x32_bf16 v[114:117], v[150:153], v[204:207], v[114:117]
	v_mfma_f32_16x16x32_bf16 v[106:109], v[172:175], v[204:207], v[106:109]
	v_mfma_f32_16x16x32_bf16 v[98:101], v[150:153], v[212:215], v[98:101]
	v_mfma_f32_16x16x32_bf16 v[90:93], v[172:175], v[212:215], v[90:93]
	v_mfma_f32_16x16x32_bf16 v[82:85], v[150:153], v[222:225], v[82:85]
	v_mfma_f32_16x16x32_bf16 v[74:77], v[172:175], v[222:225], v[74:77]
	s_setprio 0
	s_setprio 1
	v_mfma_f32_16x16x32_bf16 v[118:121], v[176:179], v[192:195], v[118:121]
	v_mfma_f32_16x16x32_bf16 v[110:113], v[184:187], v[192:195], v[110:113]
	v_mfma_f32_16x16x32_bf16 v[102:105], v[176:179], v[200:203], v[102:105]
	v_mfma_f32_16x16x32_bf16 v[94:97], v[184:187], v[200:203], v[94:97]
	v_mfma_f32_16x16x32_bf16 v[86:89], v[176:179], v[208:211], v[86:89]
	v_mfma_f32_16x16x32_bf16 v[78:81], v[184:187], v[208:211], v[78:81]
	v_mfma_f32_16x16x32_bf16 v[70:73], v[176:179], v[218:221], v[70:73]
	v_mfma_f32_16x16x32_bf16 v[66:69], v[184:187], v[218:221], v[66:69]
	s_setprio 0
	s_setprio 1
	v_mfma_f32_16x16x32_bf16 v[118:121], v[180:183], v[196:199], v[118:121]
	v_mfma_f32_16x16x32_bf16 v[110:113], v[188:191], v[196:199], v[110:113]
	v_mfma_f32_16x16x32_bf16 v[102:105], v[180:183], v[204:207], v[102:105]
	v_mfma_f32_16x16x32_bf16 v[94:97], v[188:191], v[204:207], v[94:97]
	v_mfma_f32_16x16x32_bf16 v[86:89], v[180:183], v[212:215], v[86:89]
	v_mfma_f32_16x16x32_bf16 v[78:81], v[188:191], v[212:215], v[78:81]
	v_mfma_f32_16x16x32_bf16 v[70:73], v[180:183], v[222:225], v[70:73]
	v_mfma_f32_16x16x32_bf16 v[66:69], v[188:191], v[222:225], v[66:69]
	s_setprio 0
	s_barrier
	s_add_i32 s53, s73, s12
	v_lshl_add_u64 v[226:227], s[34:35], 0, v[132:133]
	s_mov_b32 m0, s53
	ds_read_b128 v[192:195], v167 offset:16384
	ds_read_b128 v[196:199], v167 offset:17408
	ds_read_b128 v[200:203], v167 offset:18432
	ds_read_b128 v[204:207], v167 offset:19456
	ds_read_b128 v[208:211], v167 offset:20480
	ds_read_b128 v[212:215], v167 offset:21504
	ds_read_b128 v[218:221], v167 offset:22528
	ds_read_b128 v[222:225], v167 offset:23552
	global_load_lds_dwordx4 v[226:227], off
	s_add_i32 m0, s53, 0x2000
	s_add_u32 s54, s34, 0x20000
	v_lshl_add_u64 v[228:229], s[34:35], 0, v[136:137]
	s_addc_u32 s55, s35, 0
	s_add_i32 s53, s74, s12
	global_load_lds_dwordx4 v[228:229], off
	v_lshl_add_u64 v[230:231], s[54:55], 0, v[132:133]
	s_mov_b32 m0, s53
	v_lshl_add_u64 v[232:233], s[86:87], 0, v[134:135]
	global_load_lds_dwordx4 v[230:231], off
	v_lshl_add_u64 v[230:231], s[54:55], 0, v[136:137]
	s_add_i32 m0, s53, 0x2000
	s_nop 0
	global_load_lds_dwordx4 v[230:231], off
	v_lshl_add_u64 v[230:231], s[86:87], 0, v[130:131]
	s_mov_b32 m0, s33
	s_nop 0
	global_load_lds_dwordx4 v[230:231], off
	s_mov_b32 m0, s56
	s_nop 0
	global_load_lds_dwordx4 v[232:233], off
	s_waitcnt vmcnt(8)
	s_waitcnt lgkmcnt(0)
	s_barrier
	s_setprio 1
	s_waitcnt lgkmcnt(0)
	v_mfma_f32_16x16x32_bf16 v[62:65], v[146:149], v[192:195], v[62:65]
	v_mfma_f32_16x16x32_bf16 v[58:61], v[168:171], v[192:195], v[58:61]
	v_mfma_f32_16x16x32_bf16 v[50:53], v[146:149], v[200:203], v[50:53]
	v_mfma_f32_16x16x32_bf16 v[42:45], v[168:171], v[200:203], v[42:45]
	v_mfma_f32_16x16x32_bf16 v[34:37], v[146:149], v[208:211], v[34:37]
	v_mfma_f32_16x16x32_bf16 v[26:29], v[168:171], v[208:211], v[26:29]
	v_mfma_f32_16x16x32_bf16 v[18:21], v[146:149], v[218:221], v[18:21]
	v_mfma_f32_16x16x32_bf16 v[10:13], v[168:171], v[218:221], v[10:13]
	s_setprio 0
	s_setprio 1
	v_mfma_f32_16x16x32_bf16 v[62:65], v[150:153], v[196:199], v[62:65]
	v_mfma_f32_16x16x32_bf16 v[58:61], v[172:175], v[196:199], v[58:61]
	v_mfma_f32_16x16x32_bf16 v[50:53], v[150:153], v[204:207], v[50:53]
	v_mfma_f32_16x16x32_bf16 v[42:45], v[172:175], v[204:207], v[42:45]
	v_mfma_f32_16x16x32_bf16 v[34:37], v[150:153], v[212:215], v[34:37]
	v_mfma_f32_16x16x32_bf16 v[26:29], v[172:175], v[212:215], v[26:29]
	v_mfma_f32_16x16x32_bf16 v[18:21], v[150:153], v[222:225], v[18:21]
	v_mfma_f32_16x16x32_bf16 v[10:13], v[172:175], v[222:225], v[10:13]
	s_setprio 0
	s_setprio 1
	v_mfma_f32_16x16x32_bf16 v[54:57], v[176:179], v[192:195], v[54:57]
	v_mfma_f32_16x16x32_bf16 v[46:49], v[184:187], v[192:195], v[46:49]
	v_mfma_f32_16x16x32_bf16 v[38:41], v[176:179], v[200:203], v[38:41]
	v_mfma_f32_16x16x32_bf16 v[30:33], v[184:187], v[200:203], v[30:33]
	v_mfma_f32_16x16x32_bf16 v[22:25], v[176:179], v[208:211], v[22:25]
	v_mfma_f32_16x16x32_bf16 v[14:17], v[184:187], v[208:211], v[14:17]
	v_mfma_f32_16x16x32_bf16 v[6:9], v[176:179], v[218:221], v[6:9]
	v_mfma_f32_16x16x32_bf16 v[2:5], v[184:187], v[218:221], v[2:5]
	s_setprio 0
	s_setprio 1
	v_mfma_f32_16x16x32_bf16 v[54:57], v[180:183], v[196:199], v[54:57]
	v_mfma_f32_16x16x32_bf16 v[46:49], v[188:191], v[196:199], v[46:49]
	v_mfma_f32_16x16x32_bf16 v[38:41], v[180:183], v[204:207], v[38:41]
	v_mfma_f32_16x16x32_bf16 v[30:33], v[188:191], v[204:207], v[30:33]
	v_mfma_f32_16x16x32_bf16 v[22:25], v[180:183], v[212:215], v[22:25]
	v_mfma_f32_16x16x32_bf16 v[14:17], v[188:191], v[212:215], v[14:17]
	v_mfma_f32_16x16x32_bf16 v[6:9], v[180:183], v[222:225], v[6:9]
	v_mfma_f32_16x16x32_bf16 v[2:5], v[188:191], v[222:225], v[2:5]
	s_setprio 0
	s_barrier
	s_add_i32 s53, 0, 0x18000
	s_add_i32 s62, 0, 0x1c000
	v_add_u32_e32 v172, s53, v162
	v_add_u32_e32 v188, s62, v162
	ds_read_b128 v[146:149], v172
	ds_read_b128 v[150:153], v172 offset:1024
	ds_read_b128 v[168:171], v172 offset:2048
	ds_read_b128 v[172:175], v172 offset:3072
	ds_read_b128 v[176:179], v188
	ds_read_b128 v[180:183], v188 offset:1024
	ds_read_b128 v[184:187], v188 offset:2048
	ds_read_b128 v[188:191], v188 offset:3072
	s_add_u32 s54, s86, 0x20000
	s_addc_u32 s55, s87, 0
	s_mov_b32 m0, s57
	v_lshl_add_u64 v[234:235], s[54:55], 0, v[130:131]
	ds_read_b128 v[192:195], v167 offset:32768
	ds_read_b128 v[196:199], v167 offset:33792
	ds_read_b128 v[200:203], v167 offset:34816
	ds_read_b128 v[204:207], v167 offset:35840
	ds_read_b128 v[208:211], v167 offset:36864
	ds_read_b128 v[212:215], v167 offset:37888
	ds_read_b128 v[218:221], v167 offset:38912
	ds_read_b128 v[222:225], v167 offset:39936
	global_load_lds_dwordx4 v[234:235], off
	v_lshl_add_u64 v[234:235], s[54:55], 0, v[134:135]
	s_mov_b32 m0, s58
	s_nop 0
	global_load_lds_dwordx4 v[234:235], off
	s_waitcnt vmcnt(8)
	s_waitcnt lgkmcnt(0)
	s_barrier
	s_setprio 1
	s_waitcnt lgkmcnt(0)
	v_mfma_f32_16x16x32_bf16 v[126:129], v[146:149], v[192:195], v[126:129]
	v_mfma_f32_16x16x32_bf16 v[122:125], v[168:171], v[192:195], v[122:125]
	v_mfma_f32_16x16x32_bf16 v[114:117], v[146:149], v[200:203], v[114:117]
	v_mfma_f32_16x16x32_bf16 v[106:109], v[168:171], v[200:203], v[106:109]
	v_mfma_f32_16x16x32_bf16 v[98:101], v[146:149], v[208:211], v[98:101]
	v_mfma_f32_16x16x32_bf16 v[90:93], v[168:171], v[208:211], v[90:93]
	v_mfma_f32_16x16x32_bf16 v[82:85], v[146:149], v[218:221], v[82:85]
	v_mfma_f32_16x16x32_bf16 v[74:77], v[168:171], v[218:221], v[74:77]
	s_setprio 0
	s_setprio 1
	v_mfma_f32_16x16x32_bf16 v[126:129], v[150:153], v[196:199], v[126:129]
	v_mfma_f32_16x16x32_bf16 v[122:125], v[172:175], v[196:199], v[122:125]
	v_mfma_f32_16x16x32_bf16 v[114:117], v[150:153], v[204:207], v[114:117]
	v_mfma_f32_16x16x32_bf16 v[106:109], v[172:175], v[204:207], v[106:109]
	v_mfma_f32_16x16x32_bf16 v[98:101], v[150:153], v[212:215], v[98:101]
	v_mfma_f32_16x16x32_bf16 v[90:93], v[172:175], v[212:215], v[90:93]
	v_mfma_f32_16x16x32_bf16 v[82:85], v[150:153], v[222:225], v[82:85]
	v_mfma_f32_16x16x32_bf16 v[74:77], v[172:175], v[222:225], v[74:77]
	s_setprio 0
	s_setprio 1
	v_mfma_f32_16x16x32_bf16 v[118:121], v[176:179], v[192:195], v[118:121]
	v_mfma_f32_16x16x32_bf16 v[110:113], v[184:187], v[192:195], v[110:113]
	v_mfma_f32_16x16x32_bf16 v[102:105], v[176:179], v[200:203], v[102:105]
	v_mfma_f32_16x16x32_bf16 v[94:97], v[184:187], v[200:203], v[94:97]
	v_mfma_f32_16x16x32_bf16 v[86:89], v[176:179], v[208:211], v[86:89]
	v_mfma_f32_16x16x32_bf16 v[78:81], v[184:187], v[208:211], v[78:81]
	v_mfma_f32_16x16x32_bf16 v[70:73], v[176:179], v[218:221], v[70:73]
	v_mfma_f32_16x16x32_bf16 v[66:69], v[184:187], v[218:221], v[66:69]
	s_setprio 0
	s_setprio 1
	v_mfma_f32_16x16x32_bf16 v[118:121], v[180:183], v[196:199], v[118:121]
	v_mfma_f32_16x16x32_bf16 v[110:113], v[188:191], v[196:199], v[110:113]
	v_mfma_f32_16x16x32_bf16 v[102:105], v[180:183], v[204:207], v[102:105]
	v_mfma_f32_16x16x32_bf16 v[94:97], v[188:191], v[204:207], v[94:97]
	v_mfma_f32_16x16x32_bf16 v[86:89], v[180:183], v[212:215], v[86:89]
	v_mfma_f32_16x16x32_bf16 v[78:81], v[188:191], v[212:215], v[78:81]
	v_mfma_f32_16x16x32_bf16 v[70:73], v[180:183], v[222:225], v[70:73]
	v_mfma_f32_16x16x32_bf16 v[66:69], v[188:191], v[222:225], v[66:69]
	s_setprio 0
	s_barrier
	s_add_i32 s53, s53, s12
	v_lshl_add_u64 v[226:227], v[226:227], 0, s[8:9]
	s_mov_b32 m0, s53
	ds_read_b128 v[192:195], v167 offset:49152
	ds_read_b128 v[196:199], v167 offset:50176
	ds_read_b128 v[200:203], v167 offset:51200
	ds_read_b128 v[204:207], v167 offset:52224
	ds_read_b128 v[208:211], v167 offset:53248
	ds_read_b128 v[212:215], v167 offset:54272
	ds_read_b128 v[218:221], v167 offset:55296
	ds_read_b128 v[222:225], v167 offset:56320
	global_load_lds_dwordx4 v[226:227], off
	s_add_i32 m0, s53, 0x2000
	s_add_u32 s34, s34, 0x20080
	v_lshl_add_u64 v[226:227], v[228:229], 0, s[8:9]
	s_addc_u32 s35, s35, 0
	s_add_i32 s53, s62, s12
	global_load_lds_dwordx4 v[226:227], off
	v_lshl_add_u64 v[226:227], s[34:35], 0, v[132:133]
	s_mov_b32 m0, s53
	s_nop 0
	global_load_lds_dwordx4 v[226:227], off
	v_lshl_add_u64 v[226:227], s[34:35], 0, v[136:137]
	s_add_i32 m0, s53, 0x2000
	s_nop 0
	global_load_lds_dwordx4 v[226:227], off
	v_lshl_add_u64 v[226:227], v[230:231], 0, s[8:9]
	s_mov_b32 m0, s60
	s_nop 0
	global_load_lds_dwordx4 v[226:227], off
	v_lshl_add_u64 v[226:227], v[232:233], 0, s[8:9]
	s_mov_b32 m0, s61
	s_nop 0
	global_load_lds_dwordx4 v[226:227], off
	s_waitcnt vmcnt(8)
	s_waitcnt lgkmcnt(0)
	s_barrier
	s_setprio 1
	s_waitcnt lgkmcnt(0)
	v_mfma_f32_16x16x32_bf16 v[62:65], v[146:149], v[192:195], v[62:65]
	v_mfma_f32_16x16x32_bf16 v[58:61], v[168:171], v[192:195], v[58:61]
	v_mfma_f32_16x16x32_bf16 v[50:53], v[146:149], v[200:203], v[50:53]
	v_mfma_f32_16x16x32_bf16 v[42:45], v[168:171], v[200:203], v[42:45]
	v_mfma_f32_16x16x32_bf16 v[34:37], v[146:149], v[208:211], v[34:37]
	v_mfma_f32_16x16x32_bf16 v[26:29], v[168:171], v[208:211], v[26:29]
	v_mfma_f32_16x16x32_bf16 v[18:21], v[146:149], v[218:221], v[18:21]
	v_mfma_f32_16x16x32_bf16 v[10:13], v[168:171], v[218:221], v[10:13]
	s_setprio 0
	s_setprio 1
	v_mfma_f32_16x16x32_bf16 v[62:65], v[150:153], v[196:199], v[62:65]
	v_mfma_f32_16x16x32_bf16 v[58:61], v[172:175], v[196:199], v[58:61]
	v_mfma_f32_16x16x32_bf16 v[50:53], v[150:153], v[204:207], v[50:53]
	v_mfma_f32_16x16x32_bf16 v[42:45], v[172:175], v[204:207], v[42:45]
	v_mfma_f32_16x16x32_bf16 v[34:37], v[150:153], v[212:215], v[34:37]
	v_mfma_f32_16x16x32_bf16 v[26:29], v[172:175], v[212:215], v[26:29]
	v_mfma_f32_16x16x32_bf16 v[18:21], v[150:153], v[222:225], v[18:21]
	v_mfma_f32_16x16x32_bf16 v[10:13], v[172:175], v[222:225], v[10:13]
	s_setprio 0
	s_setprio 1
	v_mfma_f32_16x16x32_bf16 v[54:57], v[176:179], v[192:195], v[54:57]
	v_mfma_f32_16x16x32_bf16 v[46:49], v[184:187], v[192:195], v[46:49]
	v_mfma_f32_16x16x32_bf16 v[38:41], v[176:179], v[200:203], v[38:41]
	v_mfma_f32_16x16x32_bf16 v[30:33], v[184:187], v[200:203], v[30:33]
	v_mfma_f32_16x16x32_bf16 v[22:25], v[176:179], v[208:211], v[22:25]
	v_mfma_f32_16x16x32_bf16 v[14:17], v[184:187], v[208:211], v[14:17]
	v_mfma_f32_16x16x32_bf16 v[6:9], v[176:179], v[218:221], v[6:9]
	v_mfma_f32_16x16x32_bf16 v[2:5], v[184:187], v[218:221], v[2:5]
	s_setprio 0
	s_setprio 1
	v_mfma_f32_16x16x32_bf16 v[54:57], v[180:183], v[196:199], v[54:57]
	v_mfma_f32_16x16x32_bf16 v[46:49], v[188:191], v[196:199], v[46:49]
	v_mfma_f32_16x16x32_bf16 v[38:41], v[180:183], v[204:207], v[38:41]
	v_mfma_f32_16x16x32_bf16 v[30:33], v[188:191], v[204:207], v[30:33]
	v_mfma_f32_16x16x32_bf16 v[22:25], v[180:183], v[212:215], v[22:25]
	v_mfma_f32_16x16x32_bf16 v[14:17], v[188:191], v[212:215], v[14:17]
	v_mfma_f32_16x16x32_bf16 v[6:9], v[180:183], v[222:225], v[6:9]
	v_mfma_f32_16x16x32_bf16 v[2:5], v[188:191], v[222:225], v[2:5]
	s_setprio 0
	s_barrier
	s_add_i32 s89, s89, 2
	s_add_u32 s84, s84, 0x100
	s_addc_u32 s85, s85, 0
	s_add_u32 s77, s77, 0x100
	s_addc_u32 s88, s88, 0
	s_cmp_gt_u32 s89, 5
	s_cbranch_scc0 .LBB0_685
	s_and_b64 vcc, exec, s[66:67]
	s_cbranch_vccz .LBB0_688
	s_barrier

.LBB0_715:
	ds_read_b128 v[146:149], v1
	ds_read_b128 v[160:163], v1 offset:1024
	ds_read_b128 v[164:167], v1 offset:2048
	ds_read_b128 v[168:171], v1 offset:3072
	ds_read_b128 v[172:175], v154
	ds_read_b128 v[176:179], v154 offset:1024
	ds_read_b128 v[180:183], v154 offset:2048
	ds_read_b128 v[184:187], v154 offset:3072
	s_add_u32 s34, s84, 0xfffe0080
	s_addc_u32 s35, s85, -1
	s_cmp_eq_u32 s88, 4
	s_cselect_b32 s87, s0, s35
	s_cselect_b32 s86, s1, s34
	s_cselect_b32 s35, s52, s83
	s_cselect_b32 s34, s71, s77
	v_lshl_add_u64 v[150:151], s[84:85], 0, v[138:139]
	s_add_i32 m0, s33, 0xc000
	ds_read_b128 v[188:191], v155
	ds_read_b128 v[192:195], v155 offset:1024
	ds_read_b128 v[196:199], v155 offset:2048
	ds_read_b128 v[200:203], v155 offset:3072
	ds_read_b128 v[204:207], v155 offset:4096
	ds_read_b128 v[208:211], v155 offset:5120
	ds_read_b128 v[212:215], v155 offset:6144
	ds_read_b128 v[218:221], v155 offset:7168
	global_load_lds_dwordx4 v[150:151], off
	v_lshl_add_u64 v[150:151], s[84:85], 0, v[140:141]
	s_add_i32 m0, s33, 0xe000
	s_nop 0
	global_load_lds_dwordx4 v[150:151], off
	s_waitcnt vmcnt(8)
	s_waitcnt lgkmcnt(0)
	s_barrier
	s_setprio 1
	s_waitcnt lgkmcnt(0)
	v_mfma_f32_16x16x32_bf16 v[126:129], v[146:149], v[188:191], v[126:129]
	v_mfma_f32_16x16x32_bf16 v[122:125], v[164:167], v[188:191], v[122:125]
	v_mfma_f32_16x16x32_bf16 v[110:113], v[146:149], v[196:199], v[110:113]
	v_mfma_f32_16x16x32_bf16 v[106:109], v[164:167], v[196:199], v[106:109]
	v_mfma_f32_16x16x32_bf16 v[94:97], v[146:149], v[204:207], v[94:97]
	v_mfma_f32_16x16x32_bf16 v[90:93], v[164:167], v[204:207], v[90:93]
	v_mfma_f32_16x16x32_bf16 v[78:81], v[146:149], v[212:215], v[78:81]
	v_mfma_f32_16x16x32_bf16 v[74:77], v[164:167], v[212:215], v[74:77]
	s_setprio 0
	s_setprio 1
	v_mfma_f32_16x16x32_bf16 v[126:129], v[160:163], v[192:195], v[126:129]
	v_mfma_f32_16x16x32_bf16 v[122:125], v[168:171], v[192:195], v[122:125]
	v_mfma_f32_16x16x32_bf16 v[110:113], v[160:163], v[200:203], v[110:113]
	v_mfma_f32_16x16x32_bf16 v[106:109], v[168:171], v[200:203], v[106:109]
	v_mfma_f32_16x16x32_bf16 v[94:97], v[160:163], v[208:211], v[94:97]
	v_mfma_f32_16x16x32_bf16 v[90:93], v[168:171], v[208:211], v[90:93]
	v_mfma_f32_16x16x32_bf16 v[78:81], v[160:163], v[218:221], v[78:81]
	v_mfma_f32_16x16x32_bf16 v[74:77], v[168:171], v[218:221], v[74:77]
	s_setprio 0
	s_setprio 1
	v_mfma_f32_16x16x32_bf16 v[118:121], v[172:175], v[188:191], v[118:121]
	v_mfma_f32_16x16x32_bf16 v[114:117], v[180:183], v[188:191], v[114:117]
	v_mfma_f32_16x16x32_bf16 v[102:105], v[172:175], v[196:199], v[102:105]
	v_mfma_f32_16x16x32_bf16 v[98:101], v[180:183], v[196:199], v[98:101]
	v_mfma_f32_16x16x32_bf16 v[86:89], v[172:175], v[204:207], v[86:89]
	v_mfma_f32_16x16x32_bf16 v[82:85], v[180:183], v[204:207], v[82:85]
	v_mfma_f32_16x16x32_bf16 v[70:73], v[172:175], v[212:215], v[70:73]
	v_mfma_f32_16x16x32_bf16 v[66:69], v[180:183], v[212:215], v[66:69]
	s_setprio 0
	s_setprio 1
	v_mfma_f32_16x16x32_bf16 v[118:121], v[176:179], v[192:195], v[118:121]
	v_mfma_f32_16x16x32_bf16 v[114:117], v[184:187], v[192:195], v[114:117]
	v_mfma_f32_16x16x32_bf16 v[102:105], v[176:179], v[200:203], v[102:105]
	v_mfma_f32_16x16x32_bf16 v[98:101], v[184:187], v[200:203], v[98:101]
	v_mfma_f32_16x16x32_bf16 v[86:89], v[176:179], v[208:211], v[86:89]
	v_mfma_f32_16x16x32_bf16 v[82:85], v[184:187], v[208:211], v[82:85]
	v_mfma_f32_16x16x32_bf16 v[70:73], v[176:179], v[218:221], v[70:73]
	v_mfma_f32_16x16x32_bf16 v[66:69], v[184:187], v[218:221], v[66:69]
	s_setprio 0
	s_barrier
	s_add_i32 s53, s73, s13
	v_lshl_add_u64 v[150:151], s[34:35], 0, v[132:133]
	s_mov_b32 m0, s53
	ds_read_b128 v[188:191], v155 offset:16384
	ds_read_b128 v[192:195], v155 offset:17408
	ds_read_b128 v[196:199], v155 offset:18432
	ds_read_b128 v[200:203], v155 offset:19456
	ds_read_b128 v[204:207], v155 offset:20480
	ds_read_b128 v[208:211], v155 offset:21504
	ds_read_b128 v[212:215], v155 offset:22528
	ds_read_b128 v[218:221], v155 offset:23552
	global_load_lds_dwordx4 v[150:151], off
	s_add_i32 m0, s53, 0x2000
	s_add_u32 s54, s34, 0x20000
	v_lshl_add_u64 v[222:223], s[34:35], 0, v[136:137]
	s_addc_u32 s55, s35, 0
	s_add_i32 s53, s74, s13
	global_load_lds_dwordx4 v[222:223], off
	v_lshl_add_u64 v[224:225], s[54:55], 0, v[132:133]
	s_mov_b32 m0, s53
	v_lshl_add_u64 v[226:227], s[86:87], 0, v[134:135]
	global_load_lds_dwordx4 v[224:225], off
	v_lshl_add_u64 v[224:225], s[54:55], 0, v[136:137]
	s_add_i32 m0, s53, 0x2000
	s_nop 0
	global_load_lds_dwordx4 v[224:225], off
	v_lshl_add_u64 v[224:225], s[86:87], 0, v[130:131]
	s_mov_b32 m0, s33
	s_nop 0
	global_load_lds_dwordx4 v[224:225], off
	s_mov_b32 m0, s56
	s_nop 0
	global_load_lds_dwordx4 v[226:227], off
	s_waitcnt vmcnt(8)
	s_waitcnt lgkmcnt(0)
	s_barrier
	s_setprio 1
	s_waitcnt lgkmcnt(0)
	v_mfma_f32_16x16x32_bf16 v[62:65], v[146:149], v[188:191], v[62:65]
	v_mfma_f32_16x16x32_bf16 v[58:61], v[164:167], v[188:191], v[58:61]
	v_mfma_f32_16x16x32_bf16 v[50:53], v[146:149], v[196:199], v[50:53]
	v_mfma_f32_16x16x32_bf16 v[42:45], v[164:167], v[196:199], v[42:45]
	v_mfma_f32_16x16x32_bf16 v[34:37], v[146:149], v[204:207], v[34:37]
	v_mfma_f32_16x16x32_bf16 v[26:29], v[164:167], v[204:207], v[26:29]
	v_mfma_f32_16x16x32_bf16 v[18:21], v[146:149], v[212:215], v[18:21]
	v_mfma_f32_16x16x32_bf16 v[10:13], v[164:167], v[212:215], v[10:13]
	s_setprio 0
	s_setprio 1
	v_mfma_f32_16x16x32_bf16 v[62:65], v[160:163], v[192:195], v[62:65]
	v_mfma_f32_16x16x32_bf16 v[58:61], v[168:171], v[192:195], v[58:61]
	v_mfma_f32_16x16x32_bf16 v[50:53], v[160:163], v[200:203], v[50:53]
	v_mfma_f32_16x16x32_bf16 v[42:45], v[168:171], v[200:203], v[42:45]
	v_mfma_f32_16x16x32_bf16 v[34:37], v[160:163], v[208:211], v[34:37]
	v_mfma_f32_16x16x32_bf16 v[26:29], v[168:171], v[208:211], v[26:29]
	v_mfma_f32_16x16x32_bf16 v[18:21], v[160:163], v[218:221], v[18:21]
	v_mfma_f32_16x16x32_bf16 v[10:13], v[168:171], v[218:221], v[10:13]
	s_setprio 0
	s_setprio 1
	v_mfma_f32_16x16x32_bf16 v[54:57], v[172:175], v[188:191], v[54:57]
	v_mfma_f32_16x16x32_bf16 v[46:49], v[180:183], v[188:191], v[46:49]
	v_mfma_f32_16x16x32_bf16 v[38:41], v[172:175], v[196:199], v[38:41]
	v_mfma_f32_16x16x32_bf16 v[30:33], v[180:183], v[196:199], v[30:33]
	v_mfma_f32_16x16x32_bf16 v[22:25], v[172:175], v[204:207], v[22:25]
	v_mfma_f32_16x16x32_bf16 v[14:17], v[180:183], v[204:207], v[14:17]
	v_mfma_f32_16x16x32_bf16 v[6:9], v[172:175], v[212:215], v[6:9]
	v_mfma_f32_16x16x32_bf16 v[2:5], v[180:183], v[212:215], v[2:5]
	s_setprio 0
	s_setprio 1
	v_mfma_f32_16x16x32_bf16 v[54:57], v[176:179], v[192:195], v[54:57]
	v_mfma_f32_16x16x32_bf16 v[46:49], v[184:187], v[192:195], v[46:49]
	v_mfma_f32_16x16x32_bf16 v[38:41], v[176:179], v[200:203], v[38:41]
	v_mfma_f32_16x16x32_bf16 v[30:33], v[184:187], v[200:203], v[30:33]
	v_mfma_f32_16x16x32_bf16 v[22:25], v[176:179], v[208:211], v[22:25]
	v_mfma_f32_16x16x32_bf16 v[14:17], v[184:187], v[208:211], v[14:17]
	v_mfma_f32_16x16x32_bf16 v[6:9], v[176:179], v[218:221], v[6:9]
	v_mfma_f32_16x16x32_bf16 v[2:5], v[184:187], v[218:221], v[2:5]
	s_setprio 0
	s_barrier
	s_add_i32 s53, 0, 0x18000
	v_add_u32_e32 v156, s53, v153
	s_add_i32 s62, 0, 0x1c000
	ds_read_b128 v[146:149], v156
	ds_read_b128 v[160:163], v156 offset:1024
	ds_read_b128 v[164:167], v156 offset:2048
	ds_read_b128 v[168:171], v156 offset:3072
	v_add_u32_e32 v156, s62, v153
	ds_read_b128 v[172:175], v156
	ds_read_b128 v[176:179], v156 offset:1024
	ds_read_b128 v[180:183], v156 offset:2048
	ds_read_b128 v[184:187], v156 offset:3072
	s_add_u32 s54, s86, 0x20000
	s_addc_u32 s55, s87, 0
	s_mov_b32 m0, s57
	v_lshl_add_u64 v[228:229], s[54:55], 0, v[130:131]
	ds_read_b128 v[188:191], v155 offset:32768
	ds_read_b128 v[192:195], v155 offset:33792
	ds_read_b128 v[196:199], v155 offset:34816
	ds_read_b128 v[200:203], v155 offset:35840
	ds_read_b128 v[204:207], v155 offset:36864
	ds_read_b128 v[208:211], v155 offset:37888
	ds_read_b128 v[212:215], v155 offset:38912
	ds_read_b128 v[218:221], v155 offset:39936
	global_load_lds_dwordx4 v[228:229], off
	v_lshl_add_u64 v[228:229], s[54:55], 0, v[134:135]
	s_mov_b32 m0, s58
	s_nop 0
	global_load_lds_dwordx4 v[228:229], off
	s_waitcnt vmcnt(8)
	s_waitcnt lgkmcnt(0)
	s_barrier
	s_setprio 1
	s_waitcnt lgkmcnt(0)
	v_mfma_f32_16x16x32_bf16 v[126:129], v[146:149], v[188:191], v[126:129]
	v_mfma_f32_16x16x32_bf16 v[122:125], v[164:167], v[188:191], v[122:125]
	v_mfma_f32_16x16x32_bf16 v[110:113], v[146:149], v[196:199], v[110:113]
	v_mfma_f32_16x16x32_bf16 v[106:109], v[164:167], v[196:199], v[106:109]
	v_mfma_f32_16x16x32_bf16 v[94:97], v[146:149], v[204:207], v[94:97]
	v_mfma_f32_16x16x32_bf16 v[90:93], v[164:167], v[204:207], v[90:93]
	v_mfma_f32_16x16x32_bf16 v[78:81], v[146:149], v[212:215], v[78:81]
	v_mfma_f32_16x16x32_bf16 v[74:77], v[164:167], v[212:215], v[74:77]
	s_setprio 0
	s_setprio 1
	v_mfma_f32_16x16x32_bf16 v[126:129], v[160:163], v[192:195], v[126:129]
	v_mfma_f32_16x16x32_bf16 v[122:125], v[168:171], v[192:195], v[122:125]
	v_mfma_f32_16x16x32_bf16 v[110:113], v[160:163], v[200:203], v[110:113]
	v_mfma_f32_16x16x32_bf16 v[106:109], v[168:171], v[200:203], v[106:109]
	v_mfma_f32_16x16x32_bf16 v[94:97], v[160:163], v[208:211], v[94:97]
	v_mfma_f32_16x16x32_bf16 v[90:93], v[168:171], v[208:211], v[90:93]
	v_mfma_f32_16x16x32_bf16 v[78:81], v[160:163], v[218:221], v[78:81]
	v_mfma_f32_16x16x32_bf16 v[74:77], v[168:171], v[218:221], v[74:77]
	s_setprio 0
	s_setprio 1
	v_mfma_f32_16x16x32_bf16 v[118:121], v[172:175], v[188:191], v[118:121]
	v_mfma_f32_16x16x32_bf16 v[114:117], v[180:183], v[188:191], v[114:117]
	v_mfma_f32_16x16x32_bf16 v[102:105], v[172:175], v[196:199], v[102:105]
	v_mfma_f32_16x16x32_bf16 v[98:101], v[180:183], v[196:199], v[98:101]
	v_mfma_f32_16x16x32_bf16 v[86:89], v[172:175], v[204:207], v[86:89]
	v_mfma_f32_16x16x32_bf16 v[82:85], v[180:183], v[204:207], v[82:85]
	v_mfma_f32_16x16x32_bf16 v[70:73], v[172:175], v[212:215], v[70:73]
	v_mfma_f32_16x16x32_bf16 v[66:69], v[180:183], v[212:215], v[66:69]
	s_setprio 0
	s_setprio 1
	v_mfma_f32_16x16x32_bf16 v[118:121], v[176:179], v[192:195], v[118:121]
	v_mfma_f32_16x16x32_bf16 v[114:117], v[184:187], v[192:195], v[114:117]
	v_mfma_f32_16x16x32_bf16 v[102:105], v[176:179], v[200:203], v[102:105]
	v_mfma_f32_16x16x32_bf16 v[98:101], v[184:187], v[200:203], v[98:101]
	v_mfma_f32_16x16x32_bf16 v[86:89], v[176:179], v[208:211], v[86:89]
	v_mfma_f32_16x16x32_bf16 v[82:85], v[184:187], v[208:211], v[82:85]
	v_mfma_f32_16x16x32_bf16 v[70:73], v[176:179], v[218:221], v[70:73]
	v_mfma_f32_16x16x32_bf16 v[66:69], v[184:187], v[218:221], v[66:69]
	s_setprio 0
	s_barrier
	s_add_i32 s53, s53, s13
	v_lshl_add_u64 v[150:151], v[150:151], 0, s[8:9]
	s_mov_b32 m0, s53
	ds_read_b128 v[188:191], v155 offset:49152
	ds_read_b128 v[192:195], v155 offset:50176
	ds_read_b128 v[196:199], v155 offset:51200
	ds_read_b128 v[200:203], v155 offset:52224
	ds_read_b128 v[204:207], v155 offset:53248
	ds_read_b128 v[208:211], v155 offset:54272
	ds_read_b128 v[212:215], v155 offset:55296
	ds_read_b128 v[218:221], v155 offset:56320
	global_load_lds_dwordx4 v[150:151], off
	s_add_i32 m0, s53, 0x2000
	s_add_u32 s34, s34, 0x20080
	v_lshl_add_u64 v[150:151], v[222:223], 0, s[8:9]
	s_addc_u32 s35, s35, 0
	s_add_i32 s53, s62, s13
	global_load_lds_dwordx4 v[150:151], off
	v_lshl_add_u64 v[150:151], s[34:35], 0, v[132:133]
	s_mov_b32 m0, s53
	s_nop 0
	global_load_lds_dwordx4 v[150:151], off
	v_lshl_add_u64 v[150:151], s[34:35], 0, v[136:137]
	s_add_i32 m0, s53, 0x2000
	s_nop 0
	global_load_lds_dwordx4 v[150:151], off
	v_lshl_add_u64 v[150:151], v[224:225], 0, s[8:9]
	s_mov_b32 m0, s60
	s_nop 0
	global_load_lds_dwordx4 v[150:151], off
	v_lshl_add_u64 v[150:151], v[226:227], 0, s[8:9]
	s_mov_b32 m0, s61
	s_nop 0
	global_load_lds_dwordx4 v[150:151], off
	s_waitcnt vmcnt(8)
	s_waitcnt lgkmcnt(0)
	s_barrier
	s_setprio 1
	s_waitcnt lgkmcnt(0)
	v_mfma_f32_16x16x32_bf16 v[62:65], v[146:149], v[188:191], v[62:65]
	v_mfma_f32_16x16x32_bf16 v[58:61], v[164:167], v[188:191], v[58:61]
	v_mfma_f32_16x16x32_bf16 v[50:53], v[146:149], v[196:199], v[50:53]
	v_mfma_f32_16x16x32_bf16 v[42:45], v[164:167], v[196:199], v[42:45]
	v_mfma_f32_16x16x32_bf16 v[34:37], v[146:149], v[204:207], v[34:37]
	v_mfma_f32_16x16x32_bf16 v[26:29], v[164:167], v[204:207], v[26:29]
	v_mfma_f32_16x16x32_bf16 v[18:21], v[146:149], v[212:215], v[18:21]
	v_mfma_f32_16x16x32_bf16 v[10:13], v[164:167], v[212:215], v[10:13]
	s_setprio 0
	s_setprio 1
	v_mfma_f32_16x16x32_bf16 v[62:65], v[160:163], v[192:195], v[62:65]
	v_mfma_f32_16x16x32_bf16 v[58:61], v[168:171], v[192:195], v[58:61]
	v_mfma_f32_16x16x32_bf16 v[50:53], v[160:163], v[200:203], v[50:53]
	v_mfma_f32_16x16x32_bf16 v[42:45], v[168:171], v[200:203], v[42:45]
	v_mfma_f32_16x16x32_bf16 v[34:37], v[160:163], v[208:211], v[34:37]
	v_mfma_f32_16x16x32_bf16 v[26:29], v[168:171], v[208:211], v[26:29]
	v_mfma_f32_16x16x32_bf16 v[18:21], v[160:163], v[218:221], v[18:21]
	v_mfma_f32_16x16x32_bf16 v[10:13], v[168:171], v[218:221], v[10:13]
	s_setprio 0
	s_setprio 1
	v_mfma_f32_16x16x32_bf16 v[54:57], v[172:175], v[188:191], v[54:57]
	v_mfma_f32_16x16x32_bf16 v[46:49], v[180:183], v[188:191], v[46:49]
	v_mfma_f32_16x16x32_bf16 v[38:41], v[172:175], v[196:199], v[38:41]
	v_mfma_f32_16x16x32_bf16 v[30:33], v[180:183], v[196:199], v[30:33]
	v_mfma_f32_16x16x32_bf16 v[22:25], v[172:175], v[204:207], v[22:25]
	v_mfma_f32_16x16x32_bf16 v[14:17], v[180:183], v[204:207], v[14:17]
	v_mfma_f32_16x16x32_bf16 v[6:9], v[172:175], v[212:215], v[6:9]
	v_mfma_f32_16x16x32_bf16 v[2:5], v[180:183], v[212:215], v[2:5]
	s_setprio 0
	s_setprio 1
	v_mfma_f32_16x16x32_bf16 v[54:57], v[176:179], v[192:195], v[54:57]
	v_mfma_f32_16x16x32_bf16 v[46:49], v[184:187], v[192:195], v[46:49]
	v_mfma_f32_16x16x32_bf16 v[38:41], v[176:179], v[200:203], v[38:41]
	v_mfma_f32_16x16x32_bf16 v[30:33], v[184:187], v[200:203], v[30:33]
	v_mfma_f32_16x16x32_bf16 v[22:25], v[176:179], v[208:211], v[22:25]
	v_mfma_f32_16x16x32_bf16 v[14:17], v[184:187], v[208:211], v[14:17]
	v_mfma_f32_16x16x32_bf16 v[6:9], v[176:179], v[218:221], v[6:9]
	v_mfma_f32_16x16x32_bf16 v[2:5], v[184:187], v[218:221], v[2:5]
	s_setprio 0
	s_barrier
	s_add_i32 s88, s88, 2
	s_add_u32 s84, s84, 0x100
	s_addc_u32 s85, s85, 0
	s_add_u32 s77, s77, 0x100
	s_addc_u32 s83, s83, 0
	s_cmp_gt_u32 s88, 5
	s_cbranch_scc0 .LBB0_715
	s_and_b64 vcc, exec, s[66:67]
	s_cbranch_vccz .LBB0_718
	s_barrier

.LBB0_995:
	ds_read_b128 v[146:149], v164
	ds_read_b128 v[150:153], v164 offset:1024
	ds_read_b128 v[154:157], v164 offset:2048
	ds_read_b128 v[158:161], v164 offset:3072
	ds_read_b128 v[168:171], v165
	ds_read_b128 v[172:175], v165 offset:1024
	ds_read_b128 v[176:179], v165 offset:2048
	ds_read_b128 v[180:183], v165 offset:3072
	s_add_u32 s34, s88, 0xfff80080
	s_addc_u32 s35, s89, -1
	s_cmp_eq_u32 s81, 28
	s_cselect_b32 s91, s0, s35
	s_cselect_b32 s90, s1, s34
	s_cselect_b32 s35, s52, s77
	s_cselect_b32 s34, s74, s75
	v_lshl_add_u64 v[218:219], s[88:89], 0, v[138:139]
	s_add_i32 m0, s33, 0xc000
	ds_read_b128 v[184:187], v166
	ds_read_b128 v[188:191], v166 offset:1024
	ds_read_b128 v[192:195], v166 offset:2048
	ds_read_b128 v[196:199], v166 offset:3072
	ds_read_b128 v[200:203], v166 offset:4096
	ds_read_b128 v[204:207], v166 offset:5120
	ds_read_b128 v[208:211], v166 offset:6144
	ds_read_b128 v[212:215], v166 offset:7168
	global_load_lds_dwordx4 v[218:219], off
	v_lshl_add_u64 v[218:219], s[88:89], 0, v[140:141]
	s_add_i32 m0, s33, 0xe000
	s_nop 0
	global_load_lds_dwordx4 v[218:219], off
	s_waitcnt vmcnt(8)
	s_waitcnt lgkmcnt(0)
	s_barrier
	s_setprio 1
	s_waitcnt lgkmcnt(0)
	v_mfma_f32_16x16x32_bf16 v[126:129], v[146:149], v[184:187], v[126:129]
	v_mfma_f32_16x16x32_bf16 v[122:125], v[154:157], v[184:187], v[122:125]
	v_mfma_f32_16x16x32_bf16 v[110:113], v[146:149], v[192:195], v[110:113]
	v_mfma_f32_16x16x32_bf16 v[106:109], v[154:157], v[192:195], v[106:109]
	v_mfma_f32_16x16x32_bf16 v[94:97], v[146:149], v[200:203], v[94:97]
	v_mfma_f32_16x16x32_bf16 v[90:93], v[154:157], v[200:203], v[90:93]
	v_mfma_f32_16x16x32_bf16 v[78:81], v[146:149], v[208:211], v[78:81]
	v_mfma_f32_16x16x32_bf16 v[74:77], v[154:157], v[208:211], v[74:77]
	s_setprio 0
	s_setprio 1
	v_mfma_f32_16x16x32_bf16 v[126:129], v[150:153], v[188:191], v[126:129]
	v_mfma_f32_16x16x32_bf16 v[122:125], v[158:161], v[188:191], v[122:125]
	v_mfma_f32_16x16x32_bf16 v[110:113], v[150:153], v[196:199], v[110:113]
	v_mfma_f32_16x16x32_bf16 v[106:109], v[158:161], v[196:199], v[106:109]
	v_mfma_f32_16x16x32_bf16 v[94:97], v[150:153], v[204:207], v[94:97]
	v_mfma_f32_16x16x32_bf16 v[90:93], v[158:161], v[204:207], v[90:93]
	v_mfma_f32_16x16x32_bf16 v[78:81], v[150:153], v[212:215], v[78:81]
	v_mfma_f32_16x16x32_bf16 v[74:77], v[158:161], v[212:215], v[74:77]
	s_setprio 0
	s_setprio 1
	v_mfma_f32_16x16x32_bf16 v[118:121], v[168:171], v[184:187], v[118:121]
	v_mfma_f32_16x16x32_bf16 v[114:117], v[176:179], v[184:187], v[114:117]
	v_mfma_f32_16x16x32_bf16 v[102:105], v[168:171], v[192:195], v[102:105]
	v_mfma_f32_16x16x32_bf16 v[98:101], v[176:179], v[192:195], v[98:101]
	v_mfma_f32_16x16x32_bf16 v[86:89], v[168:171], v[200:203], v[86:89]
	v_mfma_f32_16x16x32_bf16 v[82:85], v[176:179], v[200:203], v[82:85]
	v_mfma_f32_16x16x32_bf16 v[70:73], v[168:171], v[208:211], v[70:73]
	v_mfma_f32_16x16x32_bf16 v[66:69], v[176:179], v[208:211], v[66:69]
	s_setprio 0
	s_setprio 1
	v_mfma_f32_16x16x32_bf16 v[118:121], v[172:175], v[188:191], v[118:121]
	v_mfma_f32_16x16x32_bf16 v[114:117], v[180:183], v[188:191], v[114:117]
	v_mfma_f32_16x16x32_bf16 v[102:105], v[172:175], v[196:199], v[102:105]
	v_mfma_f32_16x16x32_bf16 v[98:101], v[180:183], v[196:199], v[98:101]
	v_mfma_f32_16x16x32_bf16 v[86:89], v[172:175], v[204:207], v[86:89]
	v_mfma_f32_16x16x32_bf16 v[82:85], v[180:183], v[204:207], v[82:85]
	v_mfma_f32_16x16x32_bf16 v[70:73], v[172:175], v[212:215], v[70:73]
	v_mfma_f32_16x16x32_bf16 v[66:69], v[180:183], v[212:215], v[66:69]
	s_setprio 0
	s_barrier
	s_add_i32 s53, s71, s31
	v_lshl_add_u64 v[218:219], s[34:35], 0, v[132:133]
	s_mov_b32 m0, s53
	ds_read_b128 v[184:187], v166 offset:16384
	ds_read_b128 v[188:191], v166 offset:17408
	ds_read_b128 v[192:195], v166 offset:18432
	ds_read_b128 v[196:199], v166 offset:19456
	ds_read_b128 v[200:203], v166 offset:20480
	ds_read_b128 v[204:207], v166 offset:21504
	ds_read_b128 v[208:211], v166 offset:22528
	ds_read_b128 v[212:215], v166 offset:23552
	global_load_lds_dwordx4 v[218:219], off
	s_add_i32 m0, s53, 0x2000
	s_add_u32 s54, s34, 0x80000
	v_lshl_add_u64 v[220:221], s[34:35], 0, v[136:137]
	s_addc_u32 s55, s35, 0
	s_add_i32 s53, s72, s31
	global_load_lds_dwordx4 v[220:221], off
	v_lshl_add_u64 v[222:223], s[54:55], 0, v[132:133]
	s_mov_b32 m0, s53
	v_lshl_add_u64 v[224:225], s[90:91], 0, v[134:135]
	global_load_lds_dwordx4 v[222:223], off
	v_lshl_add_u64 v[222:223], s[54:55], 0, v[136:137]
	s_add_i32 m0, s53, 0x2000
	s_nop 0
	global_load_lds_dwordx4 v[222:223], off
	v_lshl_add_u64 v[222:223], s[90:91], 0, v[130:131]
	s_mov_b32 m0, s33
	s_nop 0
	global_load_lds_dwordx4 v[222:223], off
	s_mov_b32 m0, s56
	s_nop 0
	global_load_lds_dwordx4 v[224:225], off
	s_waitcnt vmcnt(8)
	s_waitcnt lgkmcnt(0)
	s_barrier
	s_setprio 1
	s_waitcnt lgkmcnt(0)
	v_mfma_f32_16x16x32_bf16 v[62:65], v[146:149], v[184:187], v[62:65]
	v_mfma_f32_16x16x32_bf16 v[58:61], v[154:157], v[184:187], v[58:61]
	v_mfma_f32_16x16x32_bf16 v[46:49], v[146:149], v[192:195], v[46:49]
	v_mfma_f32_16x16x32_bf16 v[42:45], v[154:157], v[192:195], v[42:45]
	v_mfma_f32_16x16x32_bf16 v[30:33], v[146:149], v[200:203], v[30:33]
	v_mfma_f32_16x16x32_bf16 v[26:29], v[154:157], v[200:203], v[26:29]
	v_mfma_f32_16x16x32_bf16 v[14:17], v[146:149], v[208:211], v[14:17]
	v_mfma_f32_16x16x32_bf16 v[10:13], v[154:157], v[208:211], v[10:13]
	s_setprio 0
	s_setprio 1
	v_mfma_f32_16x16x32_bf16 v[62:65], v[150:153], v[188:191], v[62:65]
	v_mfma_f32_16x16x32_bf16 v[58:61], v[158:161], v[188:191], v[58:61]
	v_mfma_f32_16x16x32_bf16 v[46:49], v[150:153], v[196:199], v[46:49]
	v_mfma_f32_16x16x32_bf16 v[42:45], v[158:161], v[196:199], v[42:45]
	v_mfma_f32_16x16x32_bf16 v[30:33], v[150:153], v[204:207], v[30:33]
	v_mfma_f32_16x16x32_bf16 v[26:29], v[158:161], v[204:207], v[26:29]
	v_mfma_f32_16x16x32_bf16 v[14:17], v[150:153], v[212:215], v[14:17]
	v_mfma_f32_16x16x32_bf16 v[10:13], v[158:161], v[212:215], v[10:13]
	s_setprio 0
	s_setprio 1
	v_mfma_f32_16x16x32_bf16 v[54:57], v[168:171], v[184:187], v[54:57]
	v_mfma_f32_16x16x32_bf16 v[50:53], v[176:179], v[184:187], v[50:53]
	v_mfma_f32_16x16x32_bf16 v[38:41], v[168:171], v[192:195], v[38:41]
	v_mfma_f32_16x16x32_bf16 v[34:37], v[176:179], v[192:195], v[34:37]
	v_mfma_f32_16x16x32_bf16 v[22:25], v[168:171], v[200:203], v[22:25]
	v_mfma_f32_16x16x32_bf16 v[18:21], v[176:179], v[200:203], v[18:21]
	v_mfma_f32_16x16x32_bf16 v[6:9], v[168:171], v[208:211], v[6:9]
	v_mfma_f32_16x16x32_bf16 v[2:5], v[176:179], v[208:211], v[2:5]
	s_setprio 0
	s_setprio 1
	v_mfma_f32_16x16x32_bf16 v[54:57], v[172:175], v[188:191], v[54:57]
	v_mfma_f32_16x16x32_bf16 v[50:53], v[180:183], v[188:191], v[50:53]
	v_mfma_f32_16x16x32_bf16 v[38:41], v[172:175], v[196:199], v[38:41]
	v_mfma_f32_16x16x32_bf16 v[34:37], v[180:183], v[196:199], v[34:37]
	v_mfma_f32_16x16x32_bf16 v[22:25], v[172:175], v[204:207], v[22:25]
	v_mfma_f32_16x16x32_bf16 v[18:21], v[180:183], v[204:207], v[18:21]
	v_mfma_f32_16x16x32_bf16 v[6:9], v[172:175], v[212:215], v[6:9]
	v_mfma_f32_16x16x32_bf16 v[2:5], v[180:183], v[212:215], v[2:5]
	s_setprio 0
	s_barrier
	s_add_i32 s53, 0, 0x18000
	s_add_i32 s62, 0, 0x1c000
	v_add_u32_e32 v158, s53, v162
	v_add_u32_e32 v167, s62, v162
	ds_read_b128 v[146:149], v158
	ds_read_b128 v[150:153], v158 offset:1024
	ds_read_b128 v[154:157], v158 offset:2048
	ds_read_b128 v[158:161], v158 offset:3072
	ds_read_b128 v[168:171], v167
	ds_read_b128 v[172:175], v167 offset:1024
	ds_read_b128 v[176:179], v167 offset:2048
	ds_read_b128 v[180:183], v167 offset:3072
	s_add_u32 s54, s90, 0x80000
	s_addc_u32 s55, s91, 0
	s_mov_b32 m0, s57
	v_lshl_add_u64 v[226:227], s[54:55], 0, v[130:131]
	ds_read_b128 v[184:187], v166 offset:32768
	ds_read_b128 v[188:191], v166 offset:33792
	ds_read_b128 v[192:195], v166 offset:34816
	ds_read_b128 v[196:199], v166 offset:35840
	ds_read_b128 v[200:203], v166 offset:36864
	ds_read_b128 v[204:207], v166 offset:37888
	ds_read_b128 v[208:211], v166 offset:38912
	ds_read_b128 v[212:215], v166 offset:39936
	global_load_lds_dwordx4 v[226:227], off
	v_lshl_add_u64 v[226:227], s[54:55], 0, v[134:135]
	s_mov_b32 m0, s58
	s_nop 0
	global_load_lds_dwordx4 v[226:227], off
	s_waitcnt vmcnt(8)
	s_waitcnt lgkmcnt(0)
	s_barrier
	s_setprio 1
	s_waitcnt lgkmcnt(0)
	v_mfma_f32_16x16x32_bf16 v[126:129], v[146:149], v[184:187], v[126:129]
	v_mfma_f32_16x16x32_bf16 v[122:125], v[154:157], v[184:187], v[122:125]
	v_mfma_f32_16x16x32_bf16 v[110:113], v[146:149], v[192:195], v[110:113]
	v_mfma_f32_16x16x32_bf16 v[106:109], v[154:157], v[192:195], v[106:109]
	v_mfma_f32_16x16x32_bf16 v[94:97], v[146:149], v[200:203], v[94:97]
	v_mfma_f32_16x16x32_bf16 v[90:93], v[154:157], v[200:203], v[90:93]
	v_mfma_f32_16x16x32_bf16 v[78:81], v[146:149], v[208:211], v[78:81]
	v_mfma_f32_16x16x32_bf16 v[74:77], v[154:157], v[208:211], v[74:77]
	s_setprio 0
	s_setprio 1
	v_mfma_f32_16x16x32_bf16 v[126:129], v[150:153], v[188:191], v[126:129]
	v_mfma_f32_16x16x32_bf16 v[122:125], v[158:161], v[188:191], v[122:125]
	v_mfma_f32_16x16x32_bf16 v[110:113], v[150:153], v[196:199], v[110:113]
	v_mfma_f32_16x16x32_bf16 v[106:109], v[158:161], v[196:199], v[106:109]
	v_mfma_f32_16x16x32_bf16 v[94:97], v[150:153], v[204:207], v[94:97]
	v_mfma_f32_16x16x32_bf16 v[90:93], v[158:161], v[204:207], v[90:93]
	v_mfma_f32_16x16x32_bf16 v[78:81], v[150:153], v[212:215], v[78:81]
	v_mfma_f32_16x16x32_bf16 v[74:77], v[158:161], v[212:215], v[74:77]
	s_setprio 0
	s_setprio 1
	v_mfma_f32_16x16x32_bf16 v[118:121], v[168:171], v[184:187], v[118:121]
	v_mfma_f32_16x16x32_bf16 v[114:117], v[176:179], v[184:187], v[114:117]
	v_mfma_f32_16x16x32_bf16 v[102:105], v[168:171], v[192:195], v[102:105]
	v_mfma_f32_16x16x32_bf16 v[98:101], v[176:179], v[192:195], v[98:101]
	v_mfma_f32_16x16x32_bf16 v[86:89], v[168:171], v[200:203], v[86:89]
	v_mfma_f32_16x16x32_bf16 v[82:85], v[176:179], v[200:203], v[82:85]
	v_mfma_f32_16x16x32_bf16 v[70:73], v[168:171], v[208:211], v[70:73]
	v_mfma_f32_16x16x32_bf16 v[66:69], v[176:179], v[208:211], v[66:69]
	s_setprio 0
	s_setprio 1
	v_mfma_f32_16x16x32_bf16 v[118:121], v[172:175], v[188:191], v[118:121]
	v_mfma_f32_16x16x32_bf16 v[114:117], v[180:183], v[188:191], v[114:117]
	v_mfma_f32_16x16x32_bf16 v[102:105], v[172:175], v[196:199], v[102:105]
	v_mfma_f32_16x16x32_bf16 v[98:101], v[180:183], v[196:199], v[98:101]
	v_mfma_f32_16x16x32_bf16 v[86:89], v[172:175], v[204:207], v[86:89]
	v_mfma_f32_16x16x32_bf16 v[82:85], v[180:183], v[204:207], v[82:85]
	v_mfma_f32_16x16x32_bf16 v[70:73], v[172:175], v[212:215], v[70:73]
	v_mfma_f32_16x16x32_bf16 v[66:69], v[180:183], v[212:215], v[66:69]
	s_setprio 0
	s_barrier
	s_add_i32 s53, s53, s31
	v_lshl_add_u64 v[218:219], v[218:219], 0, s[8:9]
	s_mov_b32 m0, s53
	ds_read_b128 v[184:187], v166 offset:49152
	ds_read_b128 v[188:191], v166 offset:50176
	ds_read_b128 v[192:195], v166 offset:51200
	ds_read_b128 v[196:199], v166 offset:52224
	ds_read_b128 v[200:203], v166 offset:53248
	ds_read_b128 v[204:207], v166 offset:54272
	ds_read_b128 v[208:211], v166 offset:55296
	ds_read_b128 v[212:215], v166 offset:56320
	global_load_lds_dwordx4 v[218:219], off
	s_add_i32 m0, s53, 0x2000
	s_add_u32 s34, s34, 0x80080
	v_lshl_add_u64 v[218:219], v[220:221], 0, s[8:9]
	s_addc_u32 s35, s35, 0
	s_add_i32 s53, s62, s31
	global_load_lds_dwordx4 v[218:219], off
	v_lshl_add_u64 v[218:219], s[34:35], 0, v[132:133]
	s_mov_b32 m0, s53
	s_nop 0
	global_load_lds_dwordx4 v[218:219], off
	v_lshl_add_u64 v[218:219], s[34:35], 0, v[136:137]
	s_add_i32 m0, s53, 0x2000
	s_nop 0
	global_load_lds_dwordx4 v[218:219], off
	v_lshl_add_u64 v[218:219], v[222:223], 0, s[8:9]
	s_mov_b32 m0, s60
	s_nop 0
	global_load_lds_dwordx4 v[218:219], off
	v_lshl_add_u64 v[218:219], v[224:225], 0, s[8:9]
	s_mov_b32 m0, s61
	s_nop 0
	global_load_lds_dwordx4 v[218:219], off
	s_waitcnt vmcnt(8)
	s_waitcnt lgkmcnt(0)
	s_barrier
	s_setprio 1
	s_waitcnt lgkmcnt(0)
	v_mfma_f32_16x16x32_bf16 v[62:65], v[146:149], v[184:187], v[62:65]
	v_mfma_f32_16x16x32_bf16 v[58:61], v[154:157], v[184:187], v[58:61]
	v_mfma_f32_16x16x32_bf16 v[46:49], v[146:149], v[192:195], v[46:49]
	v_mfma_f32_16x16x32_bf16 v[42:45], v[154:157], v[192:195], v[42:45]
	v_mfma_f32_16x16x32_bf16 v[30:33], v[146:149], v[200:203], v[30:33]
	v_mfma_f32_16x16x32_bf16 v[26:29], v[154:157], v[200:203], v[26:29]
	v_mfma_f32_16x16x32_bf16 v[14:17], v[146:149], v[208:211], v[14:17]
	v_mfma_f32_16x16x32_bf16 v[10:13], v[154:157], v[208:211], v[10:13]
	s_setprio 0
	s_setprio 1
	v_mfma_f32_16x16x32_bf16 v[62:65], v[150:153], v[188:191], v[62:65]
	v_mfma_f32_16x16x32_bf16 v[58:61], v[158:161], v[188:191], v[58:61]
	v_mfma_f32_16x16x32_bf16 v[46:49], v[150:153], v[196:199], v[46:49]
	v_mfma_f32_16x16x32_bf16 v[42:45], v[158:161], v[196:199], v[42:45]
	v_mfma_f32_16x16x32_bf16 v[30:33], v[150:153], v[204:207], v[30:33]
	v_mfma_f32_16x16x32_bf16 v[26:29], v[158:161], v[204:207], v[26:29]
	v_mfma_f32_16x16x32_bf16 v[14:17], v[150:153], v[212:215], v[14:17]
	v_mfma_f32_16x16x32_bf16 v[10:13], v[158:161], v[212:215], v[10:13]
	s_setprio 0
	s_setprio 1
	v_mfma_f32_16x16x32_bf16 v[54:57], v[168:171], v[184:187], v[54:57]
	v_mfma_f32_16x16x32_bf16 v[50:53], v[176:179], v[184:187], v[50:53]
	v_mfma_f32_16x16x32_bf16 v[38:41], v[168:171], v[192:195], v[38:41]
	v_mfma_f32_16x16x32_bf16 v[34:37], v[176:179], v[192:195], v[34:37]
	v_mfma_f32_16x16x32_bf16 v[22:25], v[168:171], v[200:203], v[22:25]
	v_mfma_f32_16x16x32_bf16 v[18:21], v[176:179], v[200:203], v[18:21]
	v_mfma_f32_16x16x32_bf16 v[6:9], v[168:171], v[208:211], v[6:9]
	v_mfma_f32_16x16x32_bf16 v[2:5], v[176:179], v[208:211], v[2:5]
	s_setprio 0
	s_setprio 1
	v_mfma_f32_16x16x32_bf16 v[54:57], v[172:175], v[188:191], v[54:57]
	v_mfma_f32_16x16x32_bf16 v[50:53], v[180:183], v[188:191], v[50:53]
	v_mfma_f32_16x16x32_bf16 v[38:41], v[172:175], v[196:199], v[38:41]
	v_mfma_f32_16x16x32_bf16 v[34:37], v[180:183], v[196:199], v[34:37]
	v_mfma_f32_16x16x32_bf16 v[22:25], v[172:175], v[204:207], v[22:25]
	v_mfma_f32_16x16x32_bf16 v[18:21], v[180:183], v[204:207], v[18:21]
	v_mfma_f32_16x16x32_bf16 v[6:9], v[172:175], v[212:215], v[6:9]
	v_mfma_f32_16x16x32_bf16 v[2:5], v[180:183], v[212:215], v[2:5]
	s_setprio 0
	s_barrier
	s_add_i32 s81, s81, 2
	s_add_u32 s88, s88, 0x100
	s_addc_u32 s89, s89, 0
	s_add_u32 s75, s75, 0x100
	s_addc_u32 s77, s77, 0
	s_cmp_gt_u32 s81, 29
	s_cbranch_scc0 .LBB0_995
	s_and_b64 vcc, exec, s[78:79]
	s_cbranch_vccz .LBB0_998
	s_barrier

.LBB0_1124:
	ds_read_b128 v[146:149], v153
	ds_read_b128 v[156:159], v153 offset:1024
	ds_read_b128 v[160:163], v153 offset:2048
	ds_read_b128 v[164:167], v153 offset:3072
	ds_read_b128 v[168:171], v154
	ds_read_b128 v[172:175], v154 offset:1024
	ds_read_b128 v[176:179], v154 offset:2048
	ds_read_b128 v[180:183], v154 offset:3072
	s_add_u32 s34, s88, 0xfff80080
	s_addc_u32 s35, s89, -1
	s_cmp_eq_u32 s92, 28
	s_cselect_b32 s91, s0, s35
	s_cselect_b32 s90, s1, s34
	s_cselect_b32 s35, s52, s83
	s_cselect_b32 s34, s77, s81
	v_lshl_add_u64 v[218:219], s[88:89], 0, v[138:139]
	s_add_i32 m0, s56, 0xc000
	ds_read_b128 v[184:187], v155
	ds_read_b128 v[188:191], v155 offset:1024
	ds_read_b128 v[192:195], v155 offset:2048
	ds_read_b128 v[196:199], v155 offset:3072
	ds_read_b128 v[200:203], v155 offset:4096
	ds_read_b128 v[204:207], v155 offset:5120
	ds_read_b128 v[208:211], v155 offset:6144
	ds_read_b128 v[212:215], v155 offset:7168
	global_load_lds_dwordx4 v[218:219], off
	v_lshl_add_u64 v[218:219], s[88:89], 0, v[140:141]
	s_add_i32 m0, s56, 0xe000
	s_nop 0
	global_load_lds_dwordx4 v[218:219], off
	s_waitcnt vmcnt(8)
	s_waitcnt lgkmcnt(0)
	s_barrier
	s_setprio 1
	s_waitcnt lgkmcnt(0)
	v_mfma_f32_16x16x32_bf16 v[126:129], v[146:149], v[184:187], v[126:129]
	v_mfma_f32_16x16x32_bf16 v[118:121], v[160:163], v[184:187], v[118:121]
	v_mfma_f32_16x16x32_bf16 v[110:113], v[146:149], v[192:195], v[110:113]
	v_mfma_f32_16x16x32_bf16 v[102:105], v[160:163], v[192:195], v[102:105]
	v_mfma_f32_16x16x32_bf16 v[94:97], v[146:149], v[200:203], v[94:97]
	v_mfma_f32_16x16x32_bf16 v[86:89], v[160:163], v[200:203], v[86:89]
	v_mfma_f32_16x16x32_bf16 v[78:81], v[146:149], v[208:211], v[78:81]
	v_mfma_f32_16x16x32_bf16 v[70:73], v[160:163], v[208:211], v[70:73]
	s_setprio 0
	s_setprio 1
	v_mfma_f32_16x16x32_bf16 v[126:129], v[156:159], v[188:191], v[126:129]
	v_mfma_f32_16x16x32_bf16 v[118:121], v[164:167], v[188:191], v[118:121]
	v_mfma_f32_16x16x32_bf16 v[110:113], v[156:159], v[196:199], v[110:113]
	v_mfma_f32_16x16x32_bf16 v[102:105], v[164:167], v[196:199], v[102:105]
	v_mfma_f32_16x16x32_bf16 v[94:97], v[156:159], v[204:207], v[94:97]
	v_mfma_f32_16x16x32_bf16 v[86:89], v[164:167], v[204:207], v[86:89]
	v_mfma_f32_16x16x32_bf16 v[78:81], v[156:159], v[212:215], v[78:81]
	v_mfma_f32_16x16x32_bf16 v[70:73], v[164:167], v[212:215], v[70:73]
	s_setprio 0
	s_setprio 1
	v_mfma_f32_16x16x32_bf16 v[122:125], v[168:171], v[184:187], v[122:125]
	v_mfma_f32_16x16x32_bf16 v[114:117], v[176:179], v[184:187], v[114:117]
	v_mfma_f32_16x16x32_bf16 v[106:109], v[168:171], v[192:195], v[106:109]
	v_mfma_f32_16x16x32_bf16 v[98:101], v[176:179], v[192:195], v[98:101]
	v_mfma_f32_16x16x32_bf16 v[90:93], v[168:171], v[200:203], v[90:93]
	v_mfma_f32_16x16x32_bf16 v[82:85], v[176:179], v[200:203], v[82:85]
	v_mfma_f32_16x16x32_bf16 v[74:77], v[168:171], v[208:211], v[74:77]
	v_mfma_f32_16x16x32_bf16 v[66:69], v[176:179], v[208:211], v[66:69]
	s_setprio 0
	s_setprio 1
	v_mfma_f32_16x16x32_bf16 v[122:125], v[172:175], v[188:191], v[122:125]
	v_mfma_f32_16x16x32_bf16 v[114:117], v[180:183], v[188:191], v[114:117]
	v_mfma_f32_16x16x32_bf16 v[106:109], v[172:175], v[196:199], v[106:109]
	v_mfma_f32_16x16x32_bf16 v[98:101], v[180:183], v[196:199], v[98:101]
	v_mfma_f32_16x16x32_bf16 v[90:93], v[172:175], v[204:207], v[90:93]
	v_mfma_f32_16x16x32_bf16 v[82:85], v[180:183], v[204:207], v[82:85]
	v_mfma_f32_16x16x32_bf16 v[74:77], v[172:175], v[212:215], v[74:77]
	v_mfma_f32_16x16x32_bf16 v[66:69], v[180:183], v[212:215], v[66:69]
	s_setprio 0
	s_barrier
	s_add_i32 s53, s72, s30
	v_lshl_add_u64 v[218:219], s[34:35], 0, v[134:135]
	s_mov_b32 m0, s53
	ds_read_b128 v[184:187], v155 offset:16384
	ds_read_b128 v[188:191], v155 offset:17408
	ds_read_b128 v[192:195], v155 offset:18432
	ds_read_b128 v[196:199], v155 offset:19456
	ds_read_b128 v[200:203], v155 offset:20480
	ds_read_b128 v[204:207], v155 offset:21504
	ds_read_b128 v[208:211], v155 offset:22528
	ds_read_b128 v[212:215], v155 offset:23552
	global_load_lds_dwordx4 v[218:219], off
	s_add_i32 m0, s53, 0x2000
	s_add_u32 s54, s34, 0x80000
	v_lshl_add_u64 v[220:221], s[34:35], 0, v[130:131]
	s_addc_u32 s55, s35, 0
	s_add_i32 s53, s73, s30
	global_load_lds_dwordx4 v[220:221], off
	v_lshl_add_u64 v[222:223], s[54:55], 0, v[134:135]
	s_mov_b32 m0, s53
	v_lshl_add_u64 v[224:225], s[90:91], 0, v[132:133]
	global_load_lds_dwordx4 v[222:223], off
	v_lshl_add_u64 v[222:223], s[54:55], 0, v[130:131]
	s_add_i32 m0, s53, 0x2000
	s_nop 0
	global_load_lds_dwordx4 v[222:223], off
	v_lshl_add_u64 v[222:223], s[90:91], 0, v[136:137]
	s_mov_b32 m0, s56
	s_nop 0
	global_load_lds_dwordx4 v[222:223], off
	s_mov_b32 m0, s57
	s_nop 0
	global_load_lds_dwordx4 v[224:225], off
	s_waitcnt vmcnt(8)
	s_waitcnt lgkmcnt(0)
	s_barrier
	s_setprio 1
	s_waitcnt lgkmcnt(0)
	v_mfma_f32_16x16x32_bf16 v[62:65], v[146:149], v[184:187], v[62:65]
	v_mfma_f32_16x16x32_bf16 v[54:57], v[160:163], v[184:187], v[54:57]
	v_mfma_f32_16x16x32_bf16 v[46:49], v[146:149], v[192:195], v[46:49]
	v_mfma_f32_16x16x32_bf16 v[38:41], v[160:163], v[192:195], v[38:41]
	v_mfma_f32_16x16x32_bf16 v[30:33], v[146:149], v[200:203], v[30:33]
	v_mfma_f32_16x16x32_bf16 v[22:25], v[160:163], v[200:203], v[22:25]
	v_mfma_f32_16x16x32_bf16 v[14:17], v[146:149], v[208:211], v[14:17]
	v_mfma_f32_16x16x32_bf16 v[6:9], v[160:163], v[208:211], v[6:9]
	s_setprio 0
	s_setprio 1
	v_mfma_f32_16x16x32_bf16 v[62:65], v[156:159], v[188:191], v[62:65]
	v_mfma_f32_16x16x32_bf16 v[54:57], v[164:167], v[188:191], v[54:57]
	v_mfma_f32_16x16x32_bf16 v[46:49], v[156:159], v[196:199], v[46:49]
	v_mfma_f32_16x16x32_bf16 v[38:41], v[164:167], v[196:199], v[38:41]
	v_mfma_f32_16x16x32_bf16 v[30:33], v[156:159], v[204:207], v[30:33]
	v_mfma_f32_16x16x32_bf16 v[22:25], v[164:167], v[204:207], v[22:25]
	v_mfma_f32_16x16x32_bf16 v[14:17], v[156:159], v[212:215], v[14:17]
	v_mfma_f32_16x16x32_bf16 v[6:9], v[164:167], v[212:215], v[6:9]
	s_setprio 0
	s_setprio 1
	v_mfma_f32_16x16x32_bf16 v[58:61], v[168:171], v[184:187], v[58:61]
	v_mfma_f32_16x16x32_bf16 v[50:53], v[176:179], v[184:187], v[50:53]
	v_mfma_f32_16x16x32_bf16 v[42:45], v[168:171], v[192:195], v[42:45]
	v_mfma_f32_16x16x32_bf16 v[34:37], v[176:179], v[192:195], v[34:37]
	v_mfma_f32_16x16x32_bf16 v[26:29], v[168:171], v[200:203], v[26:29]
	v_mfma_f32_16x16x32_bf16 v[18:21], v[176:179], v[200:203], v[18:21]
	v_mfma_f32_16x16x32_bf16 v[10:13], v[168:171], v[208:211], v[10:13]
	v_mfma_f32_16x16x32_bf16 v[2:5], v[176:179], v[208:211], v[2:5]
	s_setprio 0
	s_setprio 1
	v_mfma_f32_16x16x32_bf16 v[58:61], v[172:175], v[188:191], v[58:61]
	v_mfma_f32_16x16x32_bf16 v[50:53], v[180:183], v[188:191], v[50:53]
	v_mfma_f32_16x16x32_bf16 v[42:45], v[172:175], v[196:199], v[42:45]
	v_mfma_f32_16x16x32_bf16 v[34:37], v[180:183], v[196:199], v[34:37]
	v_mfma_f32_16x16x32_bf16 v[26:29], v[172:175], v[204:207], v[26:29]
	v_mfma_f32_16x16x32_bf16 v[18:21], v[180:183], v[204:207], v[18:21]
	v_mfma_f32_16x16x32_bf16 v[10:13], v[172:175], v[212:215], v[10:13]
	v_mfma_f32_16x16x32_bf16 v[2:5], v[180:183], v[212:215], v[2:5]
	s_setprio 0
	s_barrier
	s_add_i32 s53, 0, 0x18000
	s_add_i32 s62, 0, 0x1c000
	v_add_u32_e32 v164, s53, v151
	v_add_u32_e32 v180, s62, v151
	ds_read_b128 v[146:149], v164
	ds_read_b128 v[156:159], v164 offset:1024
	ds_read_b128 v[160:163], v164 offset:2048
	ds_read_b128 v[164:167], v164 offset:3072
	ds_read_b128 v[168:171], v180
	ds_read_b128 v[172:175], v180 offset:1024
	ds_read_b128 v[176:179], v180 offset:2048
	ds_read_b128 v[180:183], v180 offset:3072
	s_add_u32 s54, s90, 0x80000
	s_addc_u32 s55, s91, 0
	s_mov_b32 m0, s58
	v_lshl_add_u64 v[226:227], s[54:55], 0, v[136:137]
	ds_read_b128 v[184:187], v155 offset:32768
	ds_read_b128 v[188:191], v155 offset:33792
	ds_read_b128 v[192:195], v155 offset:34816
	ds_read_b128 v[196:199], v155 offset:35840
	ds_read_b128 v[200:203], v155 offset:36864
	ds_read_b128 v[204:207], v155 offset:37888
	ds_read_b128 v[208:211], v155 offset:38912
	ds_read_b128 v[212:215], v155 offset:39936
	global_load_lds_dwordx4 v[226:227], off
	v_lshl_add_u64 v[226:227], s[54:55], 0, v[132:133]
	s_mov_b32 m0, s59
	s_nop 0
	global_load_lds_dwordx4 v[226:227], off
	s_waitcnt vmcnt(8)
	s_waitcnt lgkmcnt(0)
	s_barrier
	s_setprio 1
	s_waitcnt lgkmcnt(0)
	v_mfma_f32_16x16x32_bf16 v[126:129], v[146:149], v[184:187], v[126:129]
	v_mfma_f32_16x16x32_bf16 v[118:121], v[160:163], v[184:187], v[118:121]
	v_mfma_f32_16x16x32_bf16 v[110:113], v[146:149], v[192:195], v[110:113]
	v_mfma_f32_16x16x32_bf16 v[102:105], v[160:163], v[192:195], v[102:105]
	v_mfma_f32_16x16x32_bf16 v[94:97], v[146:149], v[200:203], v[94:97]
	v_mfma_f32_16x16x32_bf16 v[86:89], v[160:163], v[200:203], v[86:89]
	v_mfma_f32_16x16x32_bf16 v[78:81], v[146:149], v[208:211], v[78:81]
	v_mfma_f32_16x16x32_bf16 v[70:73], v[160:163], v[208:211], v[70:73]
	s_setprio 0
	s_setprio 1
	v_mfma_f32_16x16x32_bf16 v[126:129], v[156:159], v[188:191], v[126:129]
	v_mfma_f32_16x16x32_bf16 v[118:121], v[164:167], v[188:191], v[118:121]
	v_mfma_f32_16x16x32_bf16 v[110:113], v[156:159], v[196:199], v[110:113]
	v_mfma_f32_16x16x32_bf16 v[102:105], v[164:167], v[196:199], v[102:105]
	v_mfma_f32_16x16x32_bf16 v[94:97], v[156:159], v[204:207], v[94:97]
	v_mfma_f32_16x16x32_bf16 v[86:89], v[164:167], v[204:207], v[86:89]
	v_mfma_f32_16x16x32_bf16 v[78:81], v[156:159], v[212:215], v[78:81]
	v_mfma_f32_16x16x32_bf16 v[70:73], v[164:167], v[212:215], v[70:73]
	s_setprio 0
	s_setprio 1
	v_mfma_f32_16x16x32_bf16 v[122:125], v[168:171], v[184:187], v[122:125]
	v_mfma_f32_16x16x32_bf16 v[114:117], v[176:179], v[184:187], v[114:117]
	v_mfma_f32_16x16x32_bf16 v[106:109], v[168:171], v[192:195], v[106:109]
	v_mfma_f32_16x16x32_bf16 v[98:101], v[176:179], v[192:195], v[98:101]
	v_mfma_f32_16x16x32_bf16 v[90:93], v[168:171], v[200:203], v[90:93]
	v_mfma_f32_16x16x32_bf16 v[82:85], v[176:179], v[200:203], v[82:85]
	v_mfma_f32_16x16x32_bf16 v[74:77], v[168:171], v[208:211], v[74:77]
	v_mfma_f32_16x16x32_bf16 v[66:69], v[176:179], v[208:211], v[66:69]
	s_setprio 0
	s_setprio 1
	v_mfma_f32_16x16x32_bf16 v[122:125], v[172:175], v[188:191], v[122:125]
	v_mfma_f32_16x16x32_bf16 v[114:117], v[180:183], v[188:191], v[114:117]
	v_mfma_f32_16x16x32_bf16 v[106:109], v[172:175], v[196:199], v[106:109]
	v_mfma_f32_16x16x32_bf16 v[98:101], v[180:183], v[196:199], v[98:101]
	v_mfma_f32_16x16x32_bf16 v[90:93], v[172:175], v[204:207], v[90:93]
	v_mfma_f32_16x16x32_bf16 v[82:85], v[180:183], v[204:207], v[82:85]
	v_mfma_f32_16x16x32_bf16 v[74:77], v[172:175], v[212:215], v[74:77]
	v_mfma_f32_16x16x32_bf16 v[66:69], v[180:183], v[212:215], v[66:69]
	s_setprio 0
	s_barrier
	s_add_i32 s53, s53, s30
	v_lshl_add_u64 v[218:219], v[218:219], 0, s[8:9]
	s_mov_b32 m0, s53
	ds_read_b128 v[184:187], v155 offset:49152
	ds_read_b128 v[188:191], v155 offset:50176
	ds_read_b128 v[192:195], v155 offset:51200
	ds_read_b128 v[196:199], v155 offset:52224
	ds_read_b128 v[200:203], v155 offset:53248
	ds_read_b128 v[204:207], v155 offset:54272
	ds_read_b128 v[208:211], v155 offset:55296
	ds_read_b128 v[212:215], v155 offset:56320
	global_load_lds_dwordx4 v[218:219], off
	s_add_i32 m0, s53, 0x2000
	s_add_u32 s34, s34, 0x80080
	v_lshl_add_u64 v[218:219], v[220:221], 0, s[8:9]
	s_addc_u32 s35, s35, 0
	s_add_i32 s53, s62, s30
	global_load_lds_dwordx4 v[218:219], off
	v_lshl_add_u64 v[218:219], s[34:35], 0, v[134:135]
	s_mov_b32 m0, s53
	s_nop 0
	global_load_lds_dwordx4 v[218:219], off
	v_lshl_add_u64 v[218:219], s[34:35], 0, v[130:131]
	s_add_i32 m0, s53, 0x2000
	s_nop 0
	global_load_lds_dwordx4 v[218:219], off
	v_lshl_add_u64 v[218:219], v[222:223], 0, s[8:9]
	s_mov_b32 m0, s61
	s_nop 0
	global_load_lds_dwordx4 v[218:219], off
	v_lshl_add_u64 v[218:219], v[224:225], 0, s[8:9]
	s_mov_b32 m0, s70
	s_nop 0
	global_load_lds_dwordx4 v[218:219], off
	s_waitcnt vmcnt(8)
	s_waitcnt lgkmcnt(0)
	s_barrier
	s_setprio 1
	s_waitcnt lgkmcnt(0)
	v_mfma_f32_16x16x32_bf16 v[62:65], v[146:149], v[184:187], v[62:65]
	v_mfma_f32_16x16x32_bf16 v[54:57], v[160:163], v[184:187], v[54:57]
	v_mfma_f32_16x16x32_bf16 v[46:49], v[146:149], v[192:195], v[46:49]
	v_mfma_f32_16x16x32_bf16 v[38:41], v[160:163], v[192:195], v[38:41]
	v_mfma_f32_16x16x32_bf16 v[30:33], v[146:149], v[200:203], v[30:33]
	v_mfma_f32_16x16x32_bf16 v[22:25], v[160:163], v[200:203], v[22:25]
	v_mfma_f32_16x16x32_bf16 v[14:17], v[146:149], v[208:211], v[14:17]
	v_mfma_f32_16x16x32_bf16 v[6:9], v[160:163], v[208:211], v[6:9]
	s_setprio 0
	s_setprio 1
	v_mfma_f32_16x16x32_bf16 v[62:65], v[156:159], v[188:191], v[62:65]
	v_mfma_f32_16x16x32_bf16 v[54:57], v[164:167], v[188:191], v[54:57]
	v_mfma_f32_16x16x32_bf16 v[46:49], v[156:159], v[196:199], v[46:49]
	v_mfma_f32_16x16x32_bf16 v[38:41], v[164:167], v[196:199], v[38:41]
	v_mfma_f32_16x16x32_bf16 v[30:33], v[156:159], v[204:207], v[30:33]
	v_mfma_f32_16x16x32_bf16 v[22:25], v[164:167], v[204:207], v[22:25]
	v_mfma_f32_16x16x32_bf16 v[14:17], v[156:159], v[212:215], v[14:17]
	v_mfma_f32_16x16x32_bf16 v[6:9], v[164:167], v[212:215], v[6:9]
	s_setprio 0
	s_setprio 1
	v_mfma_f32_16x16x32_bf16 v[58:61], v[168:171], v[184:187], v[58:61]
	v_mfma_f32_16x16x32_bf16 v[50:53], v[176:179], v[184:187], v[50:53]
	v_mfma_f32_16x16x32_bf16 v[42:45], v[168:171], v[192:195], v[42:45]
	v_mfma_f32_16x16x32_bf16 v[34:37], v[176:179], v[192:195], v[34:37]
	v_mfma_f32_16x16x32_bf16 v[26:29], v[168:171], v[200:203], v[26:29]
	v_mfma_f32_16x16x32_bf16 v[18:21], v[176:179], v[200:203], v[18:21]
	v_mfma_f32_16x16x32_bf16 v[10:13], v[168:171], v[208:211], v[10:13]
	v_mfma_f32_16x16x32_bf16 v[2:5], v[176:179], v[208:211], v[2:5]
	s_setprio 0
	s_setprio 1
	v_mfma_f32_16x16x32_bf16 v[58:61], v[172:175], v[188:191], v[58:61]
	v_mfma_f32_16x16x32_bf16 v[50:53], v[180:183], v[188:191], v[50:53]
	v_mfma_f32_16x16x32_bf16 v[42:45], v[172:175], v[196:199], v[42:45]
	v_mfma_f32_16x16x32_bf16 v[34:37], v[180:183], v[196:199], v[34:37]
	v_mfma_f32_16x16x32_bf16 v[26:29], v[172:175], v[204:207], v[26:29]
	v_mfma_f32_16x16x32_bf16 v[18:21], v[180:183], v[204:207], v[18:21]
	v_mfma_f32_16x16x32_bf16 v[10:13], v[172:175], v[212:215], v[10:13]
	v_mfma_f32_16x16x32_bf16 v[2:5], v[180:183], v[212:215], v[2:5]
	s_setprio 0
	s_barrier
	s_add_i32 s92, s92, 2
	s_add_u32 s88, s88, 0x100
	s_addc_u32 s89, s89, 0
	s_add_u32 s81, s81, 0x100
	s_addc_u32 s83, s83, 0
	s_cmp_gt_u32 s92, 29
	s_cbranch_scc0 .LBB0_1124
	s_and_b64 vcc, exec, s[78:79]
	s_cbranch_vccz .LBB0_1127
	s_barrier

.LBB0_1237:
	ds_read_b128 v[146:149], v164
	ds_read_b128 v[150:153], v164 offset:1024
	ds_read_b128 v[154:157], v164 offset:2048
	ds_read_b128 v[158:161], v164 offset:3072
	ds_read_b128 v[168:171], v165
	ds_read_b128 v[172:175], v165 offset:1024
	ds_read_b128 v[176:179], v165 offset:2048
	ds_read_b128 v[180:183], v165 offset:3072
	s_add_u32 s34, s76, 0xffea0080
	s_addc_u32 s35, s77, -1
	s_cmpk_eq_i32 s52, 0x54
	s_cselect_b32 s85, s5, s35
	s_cselect_b32 s84, s4, s34
	s_cselect_b32 s35, s83, s1
	s_cselect_b32 s34, s82, s0
	v_lshl_add_u64 v[218:219], s[76:77], 0, v[138:139]
	s_add_i32 m0, s33, 0xc000
	ds_read_b128 v[184:187], v166
	ds_read_b128 v[188:191], v166 offset:1024
	ds_read_b128 v[192:195], v166 offset:2048
	ds_read_b128 v[196:199], v166 offset:3072
	ds_read_b128 v[200:203], v166 offset:4096
	ds_read_b128 v[204:207], v166 offset:5120
	ds_read_b128 v[208:211], v166 offset:6144
	ds_read_b128 v[212:215], v166 offset:7168
	global_load_lds_dwordx4 v[218:219], off
	v_lshl_add_u64 v[218:219], s[76:77], 0, v[140:141]
	s_add_i32 m0, s33, 0xe000
	s_nop 0
	global_load_lds_dwordx4 v[218:219], off
	s_waitcnt vmcnt(8)
	s_waitcnt lgkmcnt(0)
	s_barrier
	s_setprio 1
	s_waitcnt lgkmcnt(0)
	v_mfma_f32_16x16x32_bf16 v[126:129], v[146:149], v[184:187], v[126:129]
	v_mfma_f32_16x16x32_bf16 v[122:125], v[154:157], v[184:187], v[122:125]
	v_mfma_f32_16x16x32_bf16 v[110:113], v[146:149], v[192:195], v[110:113]
	v_mfma_f32_16x16x32_bf16 v[106:109], v[154:157], v[192:195], v[106:109]
	v_mfma_f32_16x16x32_bf16 v[94:97], v[146:149], v[200:203], v[94:97]
	v_mfma_f32_16x16x32_bf16 v[90:93], v[154:157], v[200:203], v[90:93]
	v_mfma_f32_16x16x32_bf16 v[78:81], v[146:149], v[208:211], v[78:81]
	v_mfma_f32_16x16x32_bf16 v[74:77], v[154:157], v[208:211], v[74:77]
	s_setprio 0
	s_setprio 1
	v_mfma_f32_16x16x32_bf16 v[126:129], v[150:153], v[188:191], v[126:129]
	v_mfma_f32_16x16x32_bf16 v[122:125], v[158:161], v[188:191], v[122:125]
	v_mfma_f32_16x16x32_bf16 v[110:113], v[150:153], v[196:199], v[110:113]
	v_mfma_f32_16x16x32_bf16 v[106:109], v[158:161], v[196:199], v[106:109]
	v_mfma_f32_16x16x32_bf16 v[94:97], v[150:153], v[204:207], v[94:97]
	v_mfma_f32_16x16x32_bf16 v[90:93], v[158:161], v[204:207], v[90:93]
	v_mfma_f32_16x16x32_bf16 v[78:81], v[150:153], v[212:215], v[78:81]
	v_mfma_f32_16x16x32_bf16 v[74:77], v[158:161], v[212:215], v[74:77]
	s_setprio 0
	s_setprio 1
	v_mfma_f32_16x16x32_bf16 v[118:121], v[168:171], v[184:187], v[118:121]
	v_mfma_f32_16x16x32_bf16 v[114:117], v[176:179], v[184:187], v[114:117]
	v_mfma_f32_16x16x32_bf16 v[102:105], v[168:171], v[192:195], v[102:105]
	v_mfma_f32_16x16x32_bf16 v[98:101], v[176:179], v[192:195], v[98:101]
	v_mfma_f32_16x16x32_bf16 v[86:89], v[168:171], v[200:203], v[86:89]
	v_mfma_f32_16x16x32_bf16 v[82:85], v[176:179], v[200:203], v[82:85]
	v_mfma_f32_16x16x32_bf16 v[70:73], v[168:171], v[208:211], v[70:73]
	v_mfma_f32_16x16x32_bf16 v[66:69], v[176:179], v[208:211], v[66:69]
	s_setprio 0
	s_setprio 1
	v_mfma_f32_16x16x32_bf16 v[118:121], v[172:175], v[188:191], v[118:121]
	v_mfma_f32_16x16x32_bf16 v[114:117], v[180:183], v[188:191], v[114:117]
	v_mfma_f32_16x16x32_bf16 v[102:105], v[172:175], v[196:199], v[102:105]
	v_mfma_f32_16x16x32_bf16 v[98:101], v[180:183], v[196:199], v[98:101]
	v_mfma_f32_16x16x32_bf16 v[86:89], v[172:175], v[204:207], v[86:89]
	v_mfma_f32_16x16x32_bf16 v[82:85], v[180:183], v[204:207], v[82:85]
	v_mfma_f32_16x16x32_bf16 v[70:73], v[172:175], v[212:215], v[70:73]
	v_mfma_f32_16x16x32_bf16 v[66:69], v[180:183], v[212:215], v[66:69]
	s_setprio 0
	s_barrier
	s_add_i32 s53, s71, s31
	v_lshl_add_u64 v[218:219], s[34:35], 0, v[132:133]
	s_mov_b32 m0, s53
	ds_read_b128 v[184:187], v166 offset:16384
	ds_read_b128 v[188:191], v166 offset:17408
	ds_read_b128 v[192:195], v166 offset:18432
	ds_read_b128 v[196:199], v166 offset:19456
	ds_read_b128 v[200:203], v166 offset:20480
	ds_read_b128 v[204:207], v166 offset:21504
	ds_read_b128 v[208:211], v166 offset:22528
	ds_read_b128 v[212:215], v166 offset:23552
	global_load_lds_dwordx4 v[218:219], off
	s_add_i32 m0, s53, 0x2000
	s_add_u32 s54, s34, 0x160000
	v_lshl_add_u64 v[220:221], s[34:35], 0, v[136:137]
	s_addc_u32 s55, s35, 0
	s_add_i32 s53, s72, s31
	global_load_lds_dwordx4 v[220:221], off
	v_lshl_add_u64 v[222:223], s[54:55], 0, v[132:133]
	s_mov_b32 m0, s53
	v_lshl_add_u64 v[224:225], s[84:85], 0, v[134:135]
	global_load_lds_dwordx4 v[222:223], off
	v_lshl_add_u64 v[222:223], s[54:55], 0, v[136:137]
	s_add_i32 m0, s53, 0x2000
	s_nop 0
	global_load_lds_dwordx4 v[222:223], off
	v_lshl_add_u64 v[222:223], s[84:85], 0, v[130:131]
	s_mov_b32 m0, s33
	s_nop 0
	global_load_lds_dwordx4 v[222:223], off
	s_mov_b32 m0, s56
	s_nop 0
	global_load_lds_dwordx4 v[224:225], off
	s_waitcnt vmcnt(8)
	s_waitcnt lgkmcnt(0)
	s_barrier
	s_setprio 1
	s_waitcnt lgkmcnt(0)
	v_mfma_f32_16x16x32_bf16 v[62:65], v[146:149], v[184:187], v[62:65]
	v_mfma_f32_16x16x32_bf16 v[58:61], v[154:157], v[184:187], v[58:61]
	v_mfma_f32_16x16x32_bf16 v[46:49], v[146:149], v[192:195], v[46:49]
	v_mfma_f32_16x16x32_bf16 v[42:45], v[154:157], v[192:195], v[42:45]
	v_mfma_f32_16x16x32_bf16 v[30:33], v[146:149], v[200:203], v[30:33]
	v_mfma_f32_16x16x32_bf16 v[26:29], v[154:157], v[200:203], v[26:29]
	v_mfma_f32_16x16x32_bf16 v[14:17], v[146:149], v[208:211], v[14:17]
	v_mfma_f32_16x16x32_bf16 v[10:13], v[154:157], v[208:211], v[10:13]
	s_setprio 0
	s_setprio 1
	v_mfma_f32_16x16x32_bf16 v[62:65], v[150:153], v[188:191], v[62:65]
	v_mfma_f32_16x16x32_bf16 v[58:61], v[158:161], v[188:191], v[58:61]
	v_mfma_f32_16x16x32_bf16 v[46:49], v[150:153], v[196:199], v[46:49]
	v_mfma_f32_16x16x32_bf16 v[42:45], v[158:161], v[196:199], v[42:45]
	v_mfma_f32_16x16x32_bf16 v[30:33], v[150:153], v[204:207], v[30:33]
	v_mfma_f32_16x16x32_bf16 v[26:29], v[158:161], v[204:207], v[26:29]
	v_mfma_f32_16x16x32_bf16 v[14:17], v[150:153], v[212:215], v[14:17]
	v_mfma_f32_16x16x32_bf16 v[10:13], v[158:161], v[212:215], v[10:13]
	s_setprio 0
	s_setprio 1
	v_mfma_f32_16x16x32_bf16 v[54:57], v[168:171], v[184:187], v[54:57]
	v_mfma_f32_16x16x32_bf16 v[50:53], v[176:179], v[184:187], v[50:53]
	v_mfma_f32_16x16x32_bf16 v[38:41], v[168:171], v[192:195], v[38:41]
	v_mfma_f32_16x16x32_bf16 v[34:37], v[176:179], v[192:195], v[34:37]
	v_mfma_f32_16x16x32_bf16 v[22:25], v[168:171], v[200:203], v[22:25]
	v_mfma_f32_16x16x32_bf16 v[18:21], v[176:179], v[200:203], v[18:21]
	v_mfma_f32_16x16x32_bf16 v[6:9], v[168:171], v[208:211], v[6:9]
	v_mfma_f32_16x16x32_bf16 v[2:5], v[176:179], v[208:211], v[2:5]
	s_setprio 0
	s_setprio 1
	v_mfma_f32_16x16x32_bf16 v[54:57], v[172:175], v[188:191], v[54:57]
	v_mfma_f32_16x16x32_bf16 v[50:53], v[180:183], v[188:191], v[50:53]
	v_mfma_f32_16x16x32_bf16 v[38:41], v[172:175], v[196:199], v[38:41]
	v_mfma_f32_16x16x32_bf16 v[34:37], v[180:183], v[196:199], v[34:37]
	v_mfma_f32_16x16x32_bf16 v[22:25], v[172:175], v[204:207], v[22:25]
	v_mfma_f32_16x16x32_bf16 v[18:21], v[180:183], v[204:207], v[18:21]
	v_mfma_f32_16x16x32_bf16 v[6:9], v[172:175], v[212:215], v[6:9]
	v_mfma_f32_16x16x32_bf16 v[2:5], v[180:183], v[212:215], v[2:5]
	s_setprio 0
	s_barrier
	s_add_i32 s53, 0, 0x18000
	s_add_i32 s62, 0, 0x1c000
	v_add_u32_e32 v158, s53, v162
	v_add_u32_e32 v167, s62, v162
	ds_read_b128 v[146:149], v158
	ds_read_b128 v[150:153], v158 offset:1024
	ds_read_b128 v[154:157], v158 offset:2048
	ds_read_b128 v[158:161], v158 offset:3072
	ds_read_b128 v[168:171], v167
	ds_read_b128 v[172:175], v167 offset:1024
	ds_read_b128 v[176:179], v167 offset:2048
	ds_read_b128 v[180:183], v167 offset:3072
	s_add_u32 s54, s84, 0x160000
	s_addc_u32 s55, s85, 0
	s_mov_b32 m0, s57
	v_lshl_add_u64 v[226:227], s[54:55], 0, v[130:131]
	ds_read_b128 v[184:187], v166 offset:32768
	ds_read_b128 v[188:191], v166 offset:33792
	ds_read_b128 v[192:195], v166 offset:34816
	ds_read_b128 v[196:199], v166 offset:35840
	ds_read_b128 v[200:203], v166 offset:36864
	ds_read_b128 v[204:207], v166 offset:37888
	ds_read_b128 v[208:211], v166 offset:38912
	ds_read_b128 v[212:215], v166 offset:39936
	global_load_lds_dwordx4 v[226:227], off
	v_lshl_add_u64 v[226:227], s[54:55], 0, v[134:135]
	s_mov_b32 m0, s58
	s_nop 0
	global_load_lds_dwordx4 v[226:227], off
	s_waitcnt vmcnt(8)
	s_waitcnt lgkmcnt(0)
	s_barrier
	s_setprio 1
	s_waitcnt lgkmcnt(0)
	v_mfma_f32_16x16x32_bf16 v[126:129], v[146:149], v[184:187], v[126:129]
	v_mfma_f32_16x16x32_bf16 v[122:125], v[154:157], v[184:187], v[122:125]
	v_mfma_f32_16x16x32_bf16 v[110:113], v[146:149], v[192:195], v[110:113]
	v_mfma_f32_16x16x32_bf16 v[106:109], v[154:157], v[192:195], v[106:109]
	v_mfma_f32_16x16x32_bf16 v[94:97], v[146:149], v[200:203], v[94:97]
	v_mfma_f32_16x16x32_bf16 v[90:93], v[154:157], v[200:203], v[90:93]
	v_mfma_f32_16x16x32_bf16 v[78:81], v[146:149], v[208:211], v[78:81]
	v_mfma_f32_16x16x32_bf16 v[74:77], v[154:157], v[208:211], v[74:77]
	s_setprio 0
	s_setprio 1
	v_mfma_f32_16x16x32_bf16 v[126:129], v[150:153], v[188:191], v[126:129]
	v_mfma_f32_16x16x32_bf16 v[122:125], v[158:161], v[188:191], v[122:125]
	v_mfma_f32_16x16x32_bf16 v[110:113], v[150:153], v[196:199], v[110:113]
	v_mfma_f32_16x16x32_bf16 v[106:109], v[158:161], v[196:199], v[106:109]
	v_mfma_f32_16x16x32_bf16 v[94:97], v[150:153], v[204:207], v[94:97]
	v_mfma_f32_16x16x32_bf16 v[90:93], v[158:161], v[204:207], v[90:93]
	v_mfma_f32_16x16x32_bf16 v[78:81], v[150:153], v[212:215], v[78:81]
	v_mfma_f32_16x16x32_bf16 v[74:77], v[158:161], v[212:215], v[74:77]
	s_setprio 0
	s_setprio 1
	v_mfma_f32_16x16x32_bf16 v[118:121], v[168:171], v[184:187], v[118:121]
	v_mfma_f32_16x16x32_bf16 v[114:117], v[176:179], v[184:187], v[114:117]
	v_mfma_f32_16x16x32_bf16 v[102:105], v[168:171], v[192:195], v[102:105]
	v_mfma_f32_16x16x32_bf16 v[98:101], v[176:179], v[192:195], v[98:101]
	v_mfma_f32_16x16x32_bf16 v[86:89], v[168:171], v[200:203], v[86:89]
	v_mfma_f32_16x16x32_bf16 v[82:85], v[176:179], v[200:203], v[82:85]
	v_mfma_f32_16x16x32_bf16 v[70:73], v[168:171], v[208:211], v[70:73]
	v_mfma_f32_16x16x32_bf16 v[66:69], v[176:179], v[208:211], v[66:69]
	s_setprio 0
	s_setprio 1
	v_mfma_f32_16x16x32_bf16 v[118:121], v[172:175], v[188:191], v[118:121]
	v_mfma_f32_16x16x32_bf16 v[114:117], v[180:183], v[188:191], v[114:117]
	v_mfma_f32_16x16x32_bf16 v[102:105], v[172:175], v[196:199], v[102:105]
	v_mfma_f32_16x16x32_bf16 v[98:101], v[180:183], v[196:199], v[98:101]
	v_mfma_f32_16x16x32_bf16 v[86:89], v[172:175], v[204:207], v[86:89]
	v_mfma_f32_16x16x32_bf16 v[82:85], v[180:183], v[204:207], v[82:85]
	v_mfma_f32_16x16x32_bf16 v[70:73], v[172:175], v[212:215], v[70:73]
	v_mfma_f32_16x16x32_bf16 v[66:69], v[180:183], v[212:215], v[66:69]
	s_setprio 0
	s_barrier
	s_add_i32 s53, s53, s31
	v_lshl_add_u64 v[218:219], v[218:219], 0, s[78:79]
	s_mov_b32 m0, s53
	ds_read_b128 v[184:187], v166 offset:49152
	ds_read_b128 v[188:191], v166 offset:50176
	ds_read_b128 v[192:195], v166 offset:51200
	ds_read_b128 v[196:199], v166 offset:52224
	ds_read_b128 v[200:203], v166 offset:53248
	ds_read_b128 v[204:207], v166 offset:54272
	ds_read_b128 v[208:211], v166 offset:55296
	ds_read_b128 v[212:215], v166 offset:56320
	global_load_lds_dwordx4 v[218:219], off
	s_add_i32 m0, s53, 0x2000
	s_add_u32 s34, s34, 0x160080
	v_lshl_add_u64 v[218:219], v[220:221], 0, s[78:79]
	s_addc_u32 s35, s35, 0
	s_add_i32 s53, s62, s31
	global_load_lds_dwordx4 v[218:219], off
	v_lshl_add_u64 v[218:219], s[34:35], 0, v[132:133]
	s_mov_b32 m0, s53
	s_nop 0
	global_load_lds_dwordx4 v[218:219], off
	v_lshl_add_u64 v[218:219], s[34:35], 0, v[136:137]
	s_add_i32 m0, s53, 0x2000
	s_nop 0
	global_load_lds_dwordx4 v[218:219], off
	v_lshl_add_u64 v[218:219], v[222:223], 0, s[78:79]
	s_mov_b32 m0, s60
	s_nop 0
	global_load_lds_dwordx4 v[218:219], off
	v_lshl_add_u64 v[218:219], v[224:225], 0, s[78:79]
	s_mov_b32 m0, s61
	s_nop 0
	global_load_lds_dwordx4 v[218:219], off
	s_waitcnt vmcnt(8)
	s_waitcnt lgkmcnt(0)
	s_barrier
	s_setprio 1
	s_waitcnt lgkmcnt(0)
	v_mfma_f32_16x16x32_bf16 v[62:65], v[146:149], v[184:187], v[62:65]
	v_mfma_f32_16x16x32_bf16 v[58:61], v[154:157], v[184:187], v[58:61]
	v_mfma_f32_16x16x32_bf16 v[46:49], v[146:149], v[192:195], v[46:49]
	v_mfma_f32_16x16x32_bf16 v[42:45], v[154:157], v[192:195], v[42:45]
	v_mfma_f32_16x16x32_bf16 v[30:33], v[146:149], v[200:203], v[30:33]
	v_mfma_f32_16x16x32_bf16 v[26:29], v[154:157], v[200:203], v[26:29]
	v_mfma_f32_16x16x32_bf16 v[14:17], v[146:149], v[208:211], v[14:17]
	v_mfma_f32_16x16x32_bf16 v[10:13], v[154:157], v[208:211], v[10:13]
	s_setprio 0
	s_setprio 1
	v_mfma_f32_16x16x32_bf16 v[62:65], v[150:153], v[188:191], v[62:65]
	v_mfma_f32_16x16x32_bf16 v[58:61], v[158:161], v[188:191], v[58:61]
	v_mfma_f32_16x16x32_bf16 v[46:49], v[150:153], v[196:199], v[46:49]
	v_mfma_f32_16x16x32_bf16 v[42:45], v[158:161], v[196:199], v[42:45]
	v_mfma_f32_16x16x32_bf16 v[30:33], v[150:153], v[204:207], v[30:33]
	v_mfma_f32_16x16x32_bf16 v[26:29], v[158:161], v[204:207], v[26:29]
	v_mfma_f32_16x16x32_bf16 v[14:17], v[150:153], v[212:215], v[14:17]
	v_mfma_f32_16x16x32_bf16 v[10:13], v[158:161], v[212:215], v[10:13]
	s_setprio 0
	s_setprio 1
	v_mfma_f32_16x16x32_bf16 v[54:57], v[168:171], v[184:187], v[54:57]
	v_mfma_f32_16x16x32_bf16 v[50:53], v[176:179], v[184:187], v[50:53]
	v_mfma_f32_16x16x32_bf16 v[38:41], v[168:171], v[192:195], v[38:41]
	v_mfma_f32_16x16x32_bf16 v[34:37], v[176:179], v[192:195], v[34:37]
	v_mfma_f32_16x16x32_bf16 v[22:25], v[168:171], v[200:203], v[22:25]
	v_mfma_f32_16x16x32_bf16 v[18:21], v[176:179], v[200:203], v[18:21]
	v_mfma_f32_16x16x32_bf16 v[6:9], v[168:171], v[208:211], v[6:9]
	v_mfma_f32_16x16x32_bf16 v[2:5], v[176:179], v[208:211], v[2:5]
	s_setprio 0
	s_setprio 1
	v_mfma_f32_16x16x32_bf16 v[54:57], v[172:175], v[188:191], v[54:57]
	v_mfma_f32_16x16x32_bf16 v[50:53], v[180:183], v[188:191], v[50:53]
	v_mfma_f32_16x16x32_bf16 v[38:41], v[172:175], v[196:199], v[38:41]
	v_mfma_f32_16x16x32_bf16 v[34:37], v[180:183], v[196:199], v[34:37]
	v_mfma_f32_16x16x32_bf16 v[22:25], v[172:175], v[204:207], v[22:25]
	v_mfma_f32_16x16x32_bf16 v[18:21], v[180:183], v[204:207], v[18:21]
	v_mfma_f32_16x16x32_bf16 v[6:9], v[172:175], v[212:215], v[6:9]
	v_mfma_f32_16x16x32_bf16 v[2:5], v[180:183], v[212:215], v[2:5]
	s_setprio 0
	s_barrier
	s_add_i32 s52, s52, 2
	s_add_u32 s76, s76, 0x100
	s_addc_u32 s77, s77, 0
	s_add_u32 s0, s0, 0x100
	s_addc_u32 s1, s1, 0
	s_cmpk_gt_u32 s52, 0x55
	s_cbranch_scc0 .LBB0_1237
	s_and_b64 vcc, exec, s[80:81]
	s_cbranch_vccz .LBB0_1240
	s_barrier

.LBB0_1624:
	ds_read_b128 v[154:157], v151
	ds_read_b128 v[158:161], v151 offset:1024
	ds_read_b128 v[162:165], v151 offset:2048
	ds_read_b128 v[166:169], v151 offset:3072
	ds_read_b128 v[170:173], v152
	ds_read_b128 v[174:177], v152 offset:1024
	ds_read_b128 v[178:181], v152 offset:2048
	ds_read_b128 v[182:185], v152 offset:3072
	s_add_u32 s34, s88, 0xfff80080
	s_addc_u32 s35, s89, -1
	s_cmp_eq_u32 s83, 28
	s_cselect_b32 s91, s0, s35
	s_cselect_b32 s90, s1, s34
	s_cselect_b32 s35, s52, s81
	s_cselect_b32 s34, s75, s77
	v_lshl_add_u64 v[146:147], s[88:89], 0, v[138:139]
	s_add_i32 m0, s33, 0xc000
	ds_read_b128 v[186:189], v153
	ds_read_b128 v[190:193], v153 offset:1024
	ds_read_b128 v[194:197], v153 offset:2048
	ds_read_b128 v[198:201], v153 offset:3072
	ds_read_b128 v[202:205], v153 offset:4096
	ds_read_b128 v[206:209], v153 offset:5120
	ds_read_b128 v[210:213], v153 offset:6144
	ds_read_b128 v[218:221], v153 offset:7168
	global_load_lds_dwordx4 v[146:147], off
	v_lshl_add_u64 v[146:147], s[88:89], 0, v[140:141]
	s_add_i32 m0, s33, 0xe000
	s_nop 0
	global_load_lds_dwordx4 v[146:147], off
	s_waitcnt vmcnt(8)
	s_waitcnt lgkmcnt(0)
	s_barrier
	s_setprio 1
	s_waitcnt lgkmcnt(0)
	v_mfma_f32_16x16x32_bf16 v[126:129], v[154:157], v[186:189], v[126:129]
	v_mfma_f32_16x16x32_bf16 v[122:125], v[162:165], v[186:189], v[122:125]
	v_mfma_f32_16x16x32_bf16 v[114:117], v[154:157], v[194:197], v[114:117]
	v_mfma_f32_16x16x32_bf16 v[106:109], v[162:165], v[194:197], v[106:109]
	v_mfma_f32_16x16x32_bf16 v[98:101], v[154:157], v[202:205], v[98:101]
	v_mfma_f32_16x16x32_bf16 v[90:93], v[162:165], v[202:205], v[90:93]
	v_mfma_f32_16x16x32_bf16 v[82:85], v[154:157], v[210:213], v[82:85]
	v_mfma_f32_16x16x32_bf16 v[74:77], v[162:165], v[210:213], v[74:77]
	s_setprio 0
	s_setprio 1
	v_mfma_f32_16x16x32_bf16 v[126:129], v[158:161], v[190:193], v[126:129]
	v_mfma_f32_16x16x32_bf16 v[122:125], v[166:169], v[190:193], v[122:125]
	v_mfma_f32_16x16x32_bf16 v[114:117], v[158:161], v[198:201], v[114:117]
	v_mfma_f32_16x16x32_bf16 v[106:109], v[166:169], v[198:201], v[106:109]
	v_mfma_f32_16x16x32_bf16 v[98:101], v[158:161], v[206:209], v[98:101]
	v_mfma_f32_16x16x32_bf16 v[90:93], v[166:169], v[206:209], v[90:93]
	v_mfma_f32_16x16x32_bf16 v[82:85], v[158:161], v[218:221], v[82:85]
	v_mfma_f32_16x16x32_bf16 v[74:77], v[166:169], v[218:221], v[74:77]
	s_setprio 0
	s_setprio 1
	v_mfma_f32_16x16x32_bf16 v[118:121], v[170:173], v[186:189], v[118:121]
	v_mfma_f32_16x16x32_bf16 v[110:113], v[178:181], v[186:189], v[110:113]
	v_mfma_f32_16x16x32_bf16 v[102:105], v[170:173], v[194:197], v[102:105]
	v_mfma_f32_16x16x32_bf16 v[94:97], v[178:181], v[194:197], v[94:97]
	v_mfma_f32_16x16x32_bf16 v[86:89], v[170:173], v[202:205], v[86:89]
	v_mfma_f32_16x16x32_bf16 v[78:81], v[178:181], v[202:205], v[78:81]
	v_mfma_f32_16x16x32_bf16 v[70:73], v[170:173], v[210:213], v[70:73]
	v_mfma_f32_16x16x32_bf16 v[66:69], v[178:181], v[210:213], v[66:69]
	s_setprio 0
	s_setprio 1
	v_mfma_f32_16x16x32_bf16 v[118:121], v[174:177], v[190:193], v[118:121]
	v_mfma_f32_16x16x32_bf16 v[110:113], v[182:185], v[190:193], v[110:113]
	v_mfma_f32_16x16x32_bf16 v[102:105], v[174:177], v[198:201], v[102:105]
	v_mfma_f32_16x16x32_bf16 v[94:97], v[182:185], v[198:201], v[94:97]
	v_mfma_f32_16x16x32_bf16 v[86:89], v[174:177], v[206:209], v[86:89]
	v_mfma_f32_16x16x32_bf16 v[78:81], v[182:185], v[206:209], v[78:81]
	v_mfma_f32_16x16x32_bf16 v[70:73], v[174:177], v[218:221], v[70:73]
	v_mfma_f32_16x16x32_bf16 v[66:69], v[182:185], v[218:221], v[66:69]
	s_setprio 0
	s_barrier
	s_add_i32 s53, s71, s12
	v_lshl_add_u64 v[146:147], s[34:35], 0, v[134:135]
	s_mov_b32 m0, s53
	ds_read_b128 v[186:189], v153 offset:16384
	ds_read_b128 v[190:193], v153 offset:17408
	ds_read_b128 v[194:197], v153 offset:18432
	ds_read_b128 v[198:201], v153 offset:19456
	ds_read_b128 v[202:205], v153 offset:20480
	ds_read_b128 v[206:209], v153 offset:21504
	ds_read_b128 v[210:213], v153 offset:22528
	ds_read_b128 v[218:221], v153 offset:23552
	global_load_lds_dwordx4 v[146:147], off
	s_add_i32 m0, s53, 0x2000
	s_add_u32 s54, s34, 0x80000
	v_lshl_add_u64 v[214:215], s[34:35], 0, v[130:131]
	s_addc_u32 s55, s35, 0
	s_add_i32 s53, s72, s12
	global_load_lds_dwordx4 v[214:215], off
	v_lshl_add_u64 v[222:223], s[54:55], 0, v[134:135]
	s_mov_b32 m0, s53
	v_lshl_add_u64 v[224:225], s[90:91], 0, v[132:133]
	global_load_lds_dwordx4 v[222:223], off
	v_lshl_add_u64 v[222:223], s[54:55], 0, v[130:131]
	s_add_i32 m0, s53, 0x2000
	s_nop 0
	global_load_lds_dwordx4 v[222:223], off
	v_lshl_add_u64 v[222:223], s[90:91], 0, v[136:137]
	s_mov_b32 m0, s33
	s_nop 0
	global_load_lds_dwordx4 v[222:223], off
	s_mov_b32 m0, s56
	s_nop 0
	global_load_lds_dwordx4 v[224:225], off
	s_waitcnt vmcnt(8)
	s_waitcnt lgkmcnt(0)
	s_barrier
	s_setprio 1
	s_waitcnt lgkmcnt(0)
	v_mfma_f32_16x16x32_bf16 v[62:65], v[154:157], v[186:189], v[62:65]
	v_mfma_f32_16x16x32_bf16 v[58:61], v[162:165], v[186:189], v[58:61]
	v_mfma_f32_16x16x32_bf16 v[50:53], v[154:157], v[194:197], v[50:53]
	v_mfma_f32_16x16x32_bf16 v[42:45], v[162:165], v[194:197], v[42:45]
	v_mfma_f32_16x16x32_bf16 v[34:37], v[154:157], v[202:205], v[34:37]
	v_mfma_f32_16x16x32_bf16 v[26:29], v[162:165], v[202:205], v[26:29]
	v_mfma_f32_16x16x32_bf16 v[18:21], v[154:157], v[210:213], v[18:21]
	v_mfma_f32_16x16x32_bf16 v[10:13], v[162:165], v[210:213], v[10:13]
	s_setprio 0
	s_setprio 1
	v_mfma_f32_16x16x32_bf16 v[62:65], v[158:161], v[190:193], v[62:65]
	v_mfma_f32_16x16x32_bf16 v[58:61], v[166:169], v[190:193], v[58:61]
	v_mfma_f32_16x16x32_bf16 v[50:53], v[158:161], v[198:201], v[50:53]
	v_mfma_f32_16x16x32_bf16 v[42:45], v[166:169], v[198:201], v[42:45]
	v_mfma_f32_16x16x32_bf16 v[34:37], v[158:161], v[206:209], v[34:37]
	v_mfma_f32_16x16x32_bf16 v[26:29], v[166:169], v[206:209], v[26:29]
	v_mfma_f32_16x16x32_bf16 v[18:21], v[158:161], v[218:221], v[18:21]
	v_mfma_f32_16x16x32_bf16 v[10:13], v[166:169], v[218:221], v[10:13]
	s_setprio 0
	s_setprio 1
	v_mfma_f32_16x16x32_bf16 v[54:57], v[170:173], v[186:189], v[54:57]
	v_mfma_f32_16x16x32_bf16 v[46:49], v[178:181], v[186:189], v[46:49]
	v_mfma_f32_16x16x32_bf16 v[38:41], v[170:173], v[194:197], v[38:41]
	v_mfma_f32_16x16x32_bf16 v[30:33], v[178:181], v[194:197], v[30:33]
	v_mfma_f32_16x16x32_bf16 v[22:25], v[170:173], v[202:205], v[22:25]
	v_mfma_f32_16x16x32_bf16 v[14:17], v[178:181], v[202:205], v[14:17]
	v_mfma_f32_16x16x32_bf16 v[6:9], v[170:173], v[210:213], v[6:9]
	v_mfma_f32_16x16x32_bf16 v[2:5], v[178:181], v[210:213], v[2:5]
	s_setprio 0
	s_setprio 1
	v_mfma_f32_16x16x32_bf16 v[54:57], v[174:177], v[190:193], v[54:57]
	v_mfma_f32_16x16x32_bf16 v[46:49], v[182:185], v[190:193], v[46:49]
	v_mfma_f32_16x16x32_bf16 v[38:41], v[174:177], v[198:201], v[38:41]
	v_mfma_f32_16x16x32_bf16 v[30:33], v[182:185], v[198:201], v[30:33]
	v_mfma_f32_16x16x32_bf16 v[22:25], v[174:177], v[206:209], v[22:25]
	v_mfma_f32_16x16x32_bf16 v[14:17], v[182:185], v[206:209], v[14:17]
	v_mfma_f32_16x16x32_bf16 v[6:9], v[174:177], v[218:221], v[6:9]
	v_mfma_f32_16x16x32_bf16 v[2:5], v[182:185], v[218:221], v[2:5]
	s_setprio 0
	s_barrier
	s_add_i32 s53, 0, 0x18000
	s_add_i32 s62, 0, 0x1c000
	v_add_u32_e32 v166, s53, v149
	v_add_u32_e32 v182, s62, v149
	ds_read_b128 v[154:157], v166
	ds_read_b128 v[158:161], v166 offset:1024
	ds_read_b128 v[162:165], v166 offset:2048
	ds_read_b128 v[166:169], v166 offset:3072
	ds_read_b128 v[170:173], v182
	ds_read_b128 v[174:177], v182 offset:1024
	ds_read_b128 v[178:181], v182 offset:2048
	ds_read_b128 v[182:185], v182 offset:3072
	s_add_u32 s54, s90, 0x80000
	s_addc_u32 s55, s91, 0
	s_mov_b32 m0, s57
	v_lshl_add_u64 v[226:227], s[54:55], 0, v[136:137]
	ds_read_b128 v[186:189], v153 offset:32768
	ds_read_b128 v[190:193], v153 offset:33792
	ds_read_b128 v[194:197], v153 offset:34816
	ds_read_b128 v[198:201], v153 offset:35840
	ds_read_b128 v[202:205], v153 offset:36864
	ds_read_b128 v[206:209], v153 offset:37888
	ds_read_b128 v[210:213], v153 offset:38912
	ds_read_b128 v[218:221], v153 offset:39936
	global_load_lds_dwordx4 v[226:227], off
	v_lshl_add_u64 v[226:227], s[54:55], 0, v[132:133]
	s_mov_b32 m0, s58
	s_nop 0
	global_load_lds_dwordx4 v[226:227], off
	s_waitcnt vmcnt(8)
	s_waitcnt lgkmcnt(0)
	s_barrier
	s_setprio 1
	s_waitcnt lgkmcnt(0)
	v_mfma_f32_16x16x32_bf16 v[126:129], v[154:157], v[186:189], v[126:129]
	v_mfma_f32_16x16x32_bf16 v[122:125], v[162:165], v[186:189], v[122:125]
	v_mfma_f32_16x16x32_bf16 v[114:117], v[154:157], v[194:197], v[114:117]
	v_mfma_f32_16x16x32_bf16 v[106:109], v[162:165], v[194:197], v[106:109]
	v_mfma_f32_16x16x32_bf16 v[98:101], v[154:157], v[202:205], v[98:101]
	v_mfma_f32_16x16x32_bf16 v[90:93], v[162:165], v[202:205], v[90:93]
	v_mfma_f32_16x16x32_bf16 v[82:85], v[154:157], v[210:213], v[82:85]
	v_mfma_f32_16x16x32_bf16 v[74:77], v[162:165], v[210:213], v[74:77]
	s_setprio 0
	s_setprio 1
	v_mfma_f32_16x16x32_bf16 v[126:129], v[158:161], v[190:193], v[126:129]
	v_mfma_f32_16x16x32_bf16 v[122:125], v[166:169], v[190:193], v[122:125]
	v_mfma_f32_16x16x32_bf16 v[114:117], v[158:161], v[198:201], v[114:117]
	v_mfma_f32_16x16x32_bf16 v[106:109], v[166:169], v[198:201], v[106:109]
	v_mfma_f32_16x16x32_bf16 v[98:101], v[158:161], v[206:209], v[98:101]
	v_mfma_f32_16x16x32_bf16 v[90:93], v[166:169], v[206:209], v[90:93]
	v_mfma_f32_16x16x32_bf16 v[82:85], v[158:161], v[218:221], v[82:85]
	v_mfma_f32_16x16x32_bf16 v[74:77], v[166:169], v[218:221], v[74:77]
	s_setprio 0
	s_setprio 1
	v_mfma_f32_16x16x32_bf16 v[118:121], v[170:173], v[186:189], v[118:121]
	v_mfma_f32_16x16x32_bf16 v[110:113], v[178:181], v[186:189], v[110:113]
	v_mfma_f32_16x16x32_bf16 v[102:105], v[170:173], v[194:197], v[102:105]
	v_mfma_f32_16x16x32_bf16 v[94:97], v[178:181], v[194:197], v[94:97]
	v_mfma_f32_16x16x32_bf16 v[86:89], v[170:173], v[202:205], v[86:89]
	v_mfma_f32_16x16x32_bf16 v[78:81], v[178:181], v[202:205], v[78:81]
	v_mfma_f32_16x16x32_bf16 v[70:73], v[170:173], v[210:213], v[70:73]
	v_mfma_f32_16x16x32_bf16 v[66:69], v[178:181], v[210:213], v[66:69]
	s_setprio 0
	s_setprio 1
	v_mfma_f32_16x16x32_bf16 v[118:121], v[174:177], v[190:193], v[118:121]
	v_mfma_f32_16x16x32_bf16 v[110:113], v[182:185], v[190:193], v[110:113]
	v_mfma_f32_16x16x32_bf16 v[102:105], v[174:177], v[198:201], v[102:105]
	v_mfma_f32_16x16x32_bf16 v[94:97], v[182:185], v[198:201], v[94:97]
	v_mfma_f32_16x16x32_bf16 v[86:89], v[174:177], v[206:209], v[86:89]
	v_mfma_f32_16x16x32_bf16 v[78:81], v[182:185], v[206:209], v[78:81]
	v_mfma_f32_16x16x32_bf16 v[70:73], v[174:177], v[218:221], v[70:73]
	v_mfma_f32_16x16x32_bf16 v[66:69], v[182:185], v[218:221], v[66:69]
	s_setprio 0
	s_barrier
	s_add_i32 s53, s53, s12
	v_lshl_add_u64 v[146:147], v[146:147], 0, s[8:9]
	s_mov_b32 m0, s53
	ds_read_b128 v[186:189], v153 offset:49152
	ds_read_b128 v[190:193], v153 offset:50176
	ds_read_b128 v[194:197], v153 offset:51200
	ds_read_b128 v[198:201], v153 offset:52224
	ds_read_b128 v[202:205], v153 offset:53248
	ds_read_b128 v[206:209], v153 offset:54272
	ds_read_b128 v[210:213], v153 offset:55296
	ds_read_b128 v[218:221], v153 offset:56320
	global_load_lds_dwordx4 v[146:147], off
	s_add_i32 m0, s53, 0x2000
	s_add_u32 s34, s34, 0x80080
	v_lshl_add_u64 v[146:147], v[214:215], 0, s[8:9]
	s_addc_u32 s35, s35, 0
	s_add_i32 s53, s62, s12
	global_load_lds_dwordx4 v[146:147], off
	v_lshl_add_u64 v[146:147], s[34:35], 0, v[134:135]
	s_mov_b32 m0, s53
	s_nop 0
	global_load_lds_dwordx4 v[146:147], off
	v_lshl_add_u64 v[146:147], s[34:35], 0, v[130:131]
	s_add_i32 m0, s53, 0x2000
	s_nop 0
	global_load_lds_dwordx4 v[146:147], off
	v_lshl_add_u64 v[146:147], v[222:223], 0, s[8:9]
	s_mov_b32 m0, s60
	s_nop 0
	global_load_lds_dwordx4 v[146:147], off
	v_lshl_add_u64 v[146:147], v[224:225], 0, s[8:9]
	s_mov_b32 m0, s61
	s_nop 0
	global_load_lds_dwordx4 v[146:147], off
	s_waitcnt vmcnt(8)
	s_waitcnt lgkmcnt(0)
	s_barrier
	s_setprio 1
	s_waitcnt lgkmcnt(0)
	v_mfma_f32_16x16x32_bf16 v[62:65], v[154:157], v[186:189], v[62:65]
	v_mfma_f32_16x16x32_bf16 v[58:61], v[162:165], v[186:189], v[58:61]
	v_mfma_f32_16x16x32_bf16 v[50:53], v[154:157], v[194:197], v[50:53]
	v_mfma_f32_16x16x32_bf16 v[42:45], v[162:165], v[194:197], v[42:45]
	v_mfma_f32_16x16x32_bf16 v[34:37], v[154:157], v[202:205], v[34:37]
	v_mfma_f32_16x16x32_bf16 v[26:29], v[162:165], v[202:205], v[26:29]
	v_mfma_f32_16x16x32_bf16 v[18:21], v[154:157], v[210:213], v[18:21]
	v_mfma_f32_16x16x32_bf16 v[10:13], v[162:165], v[210:213], v[10:13]
	s_setprio 0
	s_setprio 1
	v_mfma_f32_16x16x32_bf16 v[62:65], v[158:161], v[190:193], v[62:65]
	v_mfma_f32_16x16x32_bf16 v[58:61], v[166:169], v[190:193], v[58:61]
	v_mfma_f32_16x16x32_bf16 v[50:53], v[158:161], v[198:201], v[50:53]
	v_mfma_f32_16x16x32_bf16 v[42:45], v[166:169], v[198:201], v[42:45]
	v_mfma_f32_16x16x32_bf16 v[34:37], v[158:161], v[206:209], v[34:37]
	v_mfma_f32_16x16x32_bf16 v[26:29], v[166:169], v[206:209], v[26:29]
	v_mfma_f32_16x16x32_bf16 v[18:21], v[158:161], v[218:221], v[18:21]
	v_mfma_f32_16x16x32_bf16 v[10:13], v[166:169], v[218:221], v[10:13]
	s_setprio 0
	s_setprio 1
	v_mfma_f32_16x16x32_bf16 v[54:57], v[170:173], v[186:189], v[54:57]
	v_mfma_f32_16x16x32_bf16 v[46:49], v[178:181], v[186:189], v[46:49]
	v_mfma_f32_16x16x32_bf16 v[38:41], v[170:173], v[194:197], v[38:41]
	v_mfma_f32_16x16x32_bf16 v[30:33], v[178:181], v[194:197], v[30:33]
	v_mfma_f32_16x16x32_bf16 v[22:25], v[170:173], v[202:205], v[22:25]
	v_mfma_f32_16x16x32_bf16 v[14:17], v[178:181], v[202:205], v[14:17]
	v_mfma_f32_16x16x32_bf16 v[6:9], v[170:173], v[210:213], v[6:9]
	v_mfma_f32_16x16x32_bf16 v[2:5], v[178:181], v[210:213], v[2:5]
	s_setprio 0
	s_setprio 1
	v_mfma_f32_16x16x32_bf16 v[54:57], v[174:177], v[190:193], v[54:57]
	v_mfma_f32_16x16x32_bf16 v[46:49], v[182:185], v[190:193], v[46:49]
	v_mfma_f32_16x16x32_bf16 v[38:41], v[174:177], v[198:201], v[38:41]
	v_mfma_f32_16x16x32_bf16 v[30:33], v[182:185], v[198:201], v[30:33]
	v_mfma_f32_16x16x32_bf16 v[22:25], v[174:177], v[206:209], v[22:25]
	v_mfma_f32_16x16x32_bf16 v[14:17], v[182:185], v[206:209], v[14:17]
	v_mfma_f32_16x16x32_bf16 v[6:9], v[174:177], v[218:221], v[6:9]
	v_mfma_f32_16x16x32_bf16 v[2:5], v[182:185], v[218:221], v[2:5]
	s_setprio 0
	s_barrier
	s_add_i32 s83, s83, 2
	s_add_u32 s88, s88, 0x100
	s_addc_u32 s89, s89, 0
	s_add_u32 s77, s77, 0x100
	s_addc_u32 s81, s81, 0
	s_cmp_gt_u32 s83, 29
	s_cbranch_scc0 .LBB0_1624
	s_and_b64 vcc, exec, s[78:79]
	s_cbranch_vccz .LBB0_1627
	s_barrier

.LBB0_2089:
	ds_read_b128 v[130:133], v178
	ds_read_b128 v[134:137], v178 offset:1024
	ds_read_b128 v[138:141], v178 offset:2048
	ds_read_b128 v[142:145], v178 offset:3072
	ds_read_b128 v[162:165], v179
	ds_read_b128 v[166:169], v179 offset:1024
	ds_read_b128 v[170:173], v179 offset:2048
	ds_read_b128 v[182:185], v179 offset:3072
	s_add_u32 s34, s38, 0xffea0080
	s_addc_u32 s35, s39, -1
	s_cmpk_eq_i32 s52, 0x54
	s_cselect_b32 s41, s5, s35
	s_cselect_b32 s40, s4, s34
	s_cselect_b32 s35, s37, s1
	s_cselect_b32 s34, s36, s0
	v_lshl_add_u64 v[174:175], s[38:39], 0, v[154:155]
	s_add_i32 m0, s33, 0xc000
	ds_read_b128 v[186:189], v180
	ds_read_b128 v[190:193], v180 offset:1024
	ds_read_b128 v[194:197], v180 offset:2048
	ds_read_b128 v[198:201], v180 offset:3072
	ds_read_b128 v[202:205], v180 offset:4096
	ds_read_b128 v[206:209], v180 offset:5120
	ds_read_b128 v[210:213], v180 offset:6144
	ds_read_b128 v[218:221], v180 offset:7168
	global_load_lds_dwordx4 v[174:175], off
	v_lshl_add_u64 v[174:175], s[38:39], 0, v[156:157]
	s_add_i32 m0, s33, 0xe000
	s_nop 0
	global_load_lds_dwordx4 v[174:175], off
	s_waitcnt vmcnt(8)
	s_waitcnt lgkmcnt(0)
	s_barrier
	s_setprio 1
	s_waitcnt lgkmcnt(0)
	v_mfma_f32_16x16x32_bf16 v[126:129], v[130:133], v[186:189], v[126:129]
	v_mfma_f32_16x16x32_bf16 v[122:125], v[138:141], v[186:189], v[122:125]
	v_mfma_f32_16x16x32_bf16 v[110:113], v[130:133], v[194:197], v[110:113]
	v_mfma_f32_16x16x32_bf16 v[106:109], v[138:141], v[194:197], v[106:109]
	v_mfma_f32_16x16x32_bf16 v[94:97], v[130:133], v[202:205], v[94:97]
	v_mfma_f32_16x16x32_bf16 v[90:93], v[138:141], v[202:205], v[90:93]
	v_mfma_f32_16x16x32_bf16 v[78:81], v[130:133], v[210:213], v[78:81]
	v_mfma_f32_16x16x32_bf16 v[74:77], v[138:141], v[210:213], v[74:77]
	s_setprio 0
	s_setprio 1
	v_mfma_f32_16x16x32_bf16 v[126:129], v[134:137], v[190:193], v[126:129]
	v_mfma_f32_16x16x32_bf16 v[122:125], v[142:145], v[190:193], v[122:125]
	v_mfma_f32_16x16x32_bf16 v[110:113], v[134:137], v[198:201], v[110:113]
	v_mfma_f32_16x16x32_bf16 v[106:109], v[142:145], v[198:201], v[106:109]
	v_mfma_f32_16x16x32_bf16 v[94:97], v[134:137], v[206:209], v[94:97]
	v_mfma_f32_16x16x32_bf16 v[90:93], v[142:145], v[206:209], v[90:93]
	v_mfma_f32_16x16x32_bf16 v[78:81], v[134:137], v[218:221], v[78:81]
	v_mfma_f32_16x16x32_bf16 v[74:77], v[142:145], v[218:221], v[74:77]
	s_setprio 0
	s_setprio 1
	v_mfma_f32_16x16x32_bf16 v[118:121], v[162:165], v[186:189], v[118:121]
	v_mfma_f32_16x16x32_bf16 v[114:117], v[170:173], v[186:189], v[114:117]
	v_mfma_f32_16x16x32_bf16 v[102:105], v[162:165], v[194:197], v[102:105]
	v_mfma_f32_16x16x32_bf16 v[98:101], v[170:173], v[194:197], v[98:101]
	v_mfma_f32_16x16x32_bf16 v[86:89], v[162:165], v[202:205], v[86:89]
	v_mfma_f32_16x16x32_bf16 v[82:85], v[170:173], v[202:205], v[82:85]
	v_mfma_f32_16x16x32_bf16 v[70:73], v[162:165], v[210:213], v[70:73]
	v_mfma_f32_16x16x32_bf16 v[66:69], v[170:173], v[210:213], v[66:69]
	s_setprio 0
	s_setprio 1
	v_mfma_f32_16x16x32_bf16 v[118:121], v[166:169], v[190:193], v[118:121]
	v_mfma_f32_16x16x32_bf16 v[114:117], v[182:185], v[190:193], v[114:117]
	v_mfma_f32_16x16x32_bf16 v[102:105], v[166:169], v[198:201], v[102:105]
	v_mfma_f32_16x16x32_bf16 v[98:101], v[182:185], v[198:201], v[98:101]
	v_mfma_f32_16x16x32_bf16 v[86:89], v[166:169], v[206:209], v[86:89]
	v_mfma_f32_16x16x32_bf16 v[82:85], v[182:185], v[206:209], v[82:85]
	v_mfma_f32_16x16x32_bf16 v[70:73], v[166:169], v[218:221], v[70:73]
	v_mfma_f32_16x16x32_bf16 v[66:69], v[182:185], v[218:221], v[66:69]
	s_setprio 0
	s_barrier
	s_add_i32 s53, s61, s31
	v_lshl_add_u64 v[174:175], s[34:35], 0, v[148:149]
	s_mov_b32 m0, s53
	ds_read_b128 v[186:189], v180 offset:16384
	ds_read_b128 v[190:193], v180 offset:17408
	ds_read_b128 v[194:197], v180 offset:18432
	ds_read_b128 v[198:201], v180 offset:19456
	ds_read_b128 v[202:205], v180 offset:20480
	ds_read_b128 v[206:209], v180 offset:21504
	ds_read_b128 v[210:213], v180 offset:22528
	ds_read_b128 v[218:221], v180 offset:23552
	global_load_lds_dwordx4 v[174:175], off
	s_add_i32 m0, s53, 0x2000
	s_add_u32 s54, s34, 0x160000
	v_lshl_add_u64 v[214:215], s[34:35], 0, v[152:153]
	s_addc_u32 s55, s35, 0
	s_add_i32 s53, s70, s31
	global_load_lds_dwordx4 v[214:215], off
	v_lshl_add_u64 v[222:223], s[54:55], 0, v[148:149]
	s_mov_b32 m0, s53
	v_lshl_add_u64 v[224:225], s[40:41], 0, v[150:151]
	global_load_lds_dwordx4 v[222:223], off
	v_lshl_add_u64 v[222:223], s[54:55], 0, v[152:153]
	s_add_i32 m0, s53, 0x2000
	s_nop 0
	global_load_lds_dwordx4 v[222:223], off
	v_lshl_add_u64 v[222:223], s[40:41], 0, v[146:147]
	s_mov_b32 m0, s33
	s_nop 0
	global_load_lds_dwordx4 v[222:223], off
	s_mov_b32 m0, s46
	s_nop 0
	global_load_lds_dwordx4 v[224:225], off
	s_waitcnt vmcnt(8)
	s_waitcnt lgkmcnt(0)
	s_barrier
	s_setprio 1
	s_waitcnt lgkmcnt(0)
	v_mfma_f32_16x16x32_bf16 v[62:65], v[130:133], v[186:189], v[62:65]
	v_mfma_f32_16x16x32_bf16 v[58:61], v[138:141], v[186:189], v[58:61]
	v_mfma_f32_16x16x32_bf16 v[50:53], v[130:133], v[194:197], v[50:53]
	v_mfma_f32_16x16x32_bf16 v[42:45], v[138:141], v[194:197], v[42:45]
	v_mfma_f32_16x16x32_bf16 v[38:41], v[130:133], v[202:205], v[38:41]
	v_mfma_f32_16x16x32_bf16 v[34:37], v[138:141], v[202:205], v[34:37]
	v_mfma_f32_16x16x32_bf16 v[14:17], v[130:133], v[210:213], v[14:17]
	v_mfma_f32_16x16x32_bf16 v[10:13], v[138:141], v[210:213], v[10:13]
	s_setprio 0
	s_setprio 1
	v_mfma_f32_16x16x32_bf16 v[62:65], v[134:137], v[190:193], v[62:65]
	v_mfma_f32_16x16x32_bf16 v[58:61], v[142:145], v[190:193], v[58:61]
	v_mfma_f32_16x16x32_bf16 v[50:53], v[134:137], v[198:201], v[50:53]
	v_mfma_f32_16x16x32_bf16 v[42:45], v[142:145], v[198:201], v[42:45]
	v_mfma_f32_16x16x32_bf16 v[38:41], v[134:137], v[206:209], v[38:41]
	v_mfma_f32_16x16x32_bf16 v[34:37], v[142:145], v[206:209], v[34:37]
	v_mfma_f32_16x16x32_bf16 v[14:17], v[134:137], v[218:221], v[14:17]
	v_mfma_f32_16x16x32_bf16 v[10:13], v[142:145], v[218:221], v[10:13]
	s_setprio 0
	s_setprio 1
	v_mfma_f32_16x16x32_bf16 v[54:57], v[162:165], v[186:189], v[54:57]
	v_mfma_f32_16x16x32_bf16 v[46:49], v[170:173], v[186:189], v[46:49]
	v_mfma_f32_16x16x32_bf16 v[30:33], v[162:165], v[194:197], v[30:33]
	v_mfma_f32_16x16x32_bf16 v[26:29], v[170:173], v[194:197], v[26:29]
	v_mfma_f32_16x16x32_bf16 v[22:25], v[162:165], v[202:205], v[22:25]
	v_mfma_f32_16x16x32_bf16 v[18:21], v[170:173], v[202:205], v[18:21]
	v_mfma_f32_16x16x32_bf16 v[6:9], v[162:165], v[210:213], v[6:9]
	v_mfma_f32_16x16x32_bf16 v[2:5], v[170:173], v[210:213], v[2:5]
	s_setprio 0
	s_setprio 1
	v_mfma_f32_16x16x32_bf16 v[54:57], v[166:169], v[190:193], v[54:57]
	v_mfma_f32_16x16x32_bf16 v[46:49], v[182:185], v[190:193], v[46:49]
	v_mfma_f32_16x16x32_bf16 v[30:33], v[166:169], v[198:201], v[30:33]
	v_mfma_f32_16x16x32_bf16 v[26:29], v[182:185], v[198:201], v[26:29]
	v_mfma_f32_16x16x32_bf16 v[22:25], v[166:169], v[206:209], v[22:25]
	v_mfma_f32_16x16x32_bf16 v[18:21], v[182:185], v[206:209], v[18:21]
	v_mfma_f32_16x16x32_bf16 v[6:9], v[166:169], v[218:221], v[6:9]
	v_mfma_f32_16x16x32_bf16 v[2:5], v[182:185], v[218:221], v[2:5]
	s_setprio 0
	s_barrier
	s_add_i32 s53, 0, 0x18000
	s_add_i32 s54, 0, 0x1c000
	v_add_u32_e32 v142, s53, v176
	v_add_u32_e32 v181, s54, v176
	ds_read_b128 v[130:133], v142
	ds_read_b128 v[134:137], v142 offset:1024
	ds_read_b128 v[138:141], v142 offset:2048
	ds_read_b128 v[142:145], v142 offset:3072
	ds_read_b128 v[162:165], v181
	ds_read_b128 v[166:169], v181 offset:1024
	ds_read_b128 v[170:173], v181 offset:2048
	ds_read_b128 v[182:185], v181 offset:3072
	s_add_u32 s40, s40, 0x160000
	s_addc_u32 s41, s41, 0
	s_mov_b32 m0, s47
	v_lshl_add_u64 v[226:227], s[40:41], 0, v[146:147]
	ds_read_b128 v[186:189], v180 offset:32768
	ds_read_b128 v[190:193], v180 offset:33792
	ds_read_b128 v[194:197], v180 offset:34816
	ds_read_b128 v[198:201], v180 offset:35840
	ds_read_b128 v[202:205], v180 offset:36864
	ds_read_b128 v[206:209], v180 offset:37888
	ds_read_b128 v[210:213], v180 offset:38912
	ds_read_b128 v[218:221], v180 offset:39936
	global_load_lds_dwordx4 v[226:227], off
	v_lshl_add_u64 v[226:227], s[40:41], 0, v[150:151]
	s_mov_b32 m0, s56
	s_nop 0
	global_load_lds_dwordx4 v[226:227], off
	s_waitcnt vmcnt(8)
	s_waitcnt lgkmcnt(0)
	s_barrier
	s_setprio 1
	s_waitcnt lgkmcnt(0)
	v_mfma_f32_16x16x32_bf16 v[126:129], v[130:133], v[186:189], v[126:129]
	v_mfma_f32_16x16x32_bf16 v[122:125], v[138:141], v[186:189], v[122:125]
	v_mfma_f32_16x16x32_bf16 v[110:113], v[130:133], v[194:197], v[110:113]
	v_mfma_f32_16x16x32_bf16 v[106:109], v[138:141], v[194:197], v[106:109]
	v_mfma_f32_16x16x32_bf16 v[94:97], v[130:133], v[202:205], v[94:97]
	v_mfma_f32_16x16x32_bf16 v[90:93], v[138:141], v[202:205], v[90:93]
	v_mfma_f32_16x16x32_bf16 v[78:81], v[130:133], v[210:213], v[78:81]
	v_mfma_f32_16x16x32_bf16 v[74:77], v[138:141], v[210:213], v[74:77]
	s_setprio 0
	s_setprio 1
	v_mfma_f32_16x16x32_bf16 v[126:129], v[134:137], v[190:193], v[126:129]
	v_mfma_f32_16x16x32_bf16 v[122:125], v[142:145], v[190:193], v[122:125]
	v_mfma_f32_16x16x32_bf16 v[110:113], v[134:137], v[198:201], v[110:113]
	v_mfma_f32_16x16x32_bf16 v[106:109], v[142:145], v[198:201], v[106:109]
	v_mfma_f32_16x16x32_bf16 v[94:97], v[134:137], v[206:209], v[94:97]
	v_mfma_f32_16x16x32_bf16 v[90:93], v[142:145], v[206:209], v[90:93]
	v_mfma_f32_16x16x32_bf16 v[78:81], v[134:137], v[218:221], v[78:81]
	v_mfma_f32_16x16x32_bf16 v[74:77], v[142:145], v[218:221], v[74:77]
	s_setprio 0
	s_setprio 1
	v_mfma_f32_16x16x32_bf16 v[118:121], v[162:165], v[186:189], v[118:121]
	v_mfma_f32_16x16x32_bf16 v[114:117], v[170:173], v[186:189], v[114:117]
	v_mfma_f32_16x16x32_bf16 v[102:105], v[162:165], v[194:197], v[102:105]
	v_mfma_f32_16x16x32_bf16 v[98:101], v[170:173], v[194:197], v[98:101]
	v_mfma_f32_16x16x32_bf16 v[86:89], v[162:165], v[202:205], v[86:89]
	v_mfma_f32_16x16x32_bf16 v[82:85], v[170:173], v[202:205], v[82:85]
	v_mfma_f32_16x16x32_bf16 v[70:73], v[162:165], v[210:213], v[70:73]
	v_mfma_f32_16x16x32_bf16 v[66:69], v[170:173], v[210:213], v[66:69]
	s_setprio 0
	s_setprio 1
	v_mfma_f32_16x16x32_bf16 v[118:121], v[166:169], v[190:193], v[118:121]
	v_mfma_f32_16x16x32_bf16 v[114:117], v[182:185], v[190:193], v[114:117]
	v_mfma_f32_16x16x32_bf16 v[102:105], v[166:169], v[198:201], v[102:105]
	v_mfma_f32_16x16x32_bf16 v[98:101], v[182:185], v[198:201], v[98:101]
	v_mfma_f32_16x16x32_bf16 v[86:89], v[166:169], v[206:209], v[86:89]
	v_mfma_f32_16x16x32_bf16 v[82:85], v[182:185], v[206:209], v[82:85]
	v_mfma_f32_16x16x32_bf16 v[70:73], v[166:169], v[218:221], v[70:73]
	v_mfma_f32_16x16x32_bf16 v[66:69], v[182:185], v[218:221], v[66:69]
	s_setprio 0
	s_barrier
	s_add_i32 s40, s53, s31
	v_lshl_add_u64 v[174:175], v[174:175], 0, s[24:25]
	s_mov_b32 m0, s40
	ds_read_b128 v[186:189], v180 offset:49152
	ds_read_b128 v[190:193], v180 offset:50176
	ds_read_b128 v[194:197], v180 offset:51200
	ds_read_b128 v[198:201], v180 offset:52224
	ds_read_b128 v[202:205], v180 offset:53248
	ds_read_b128 v[206:209], v180 offset:54272
	ds_read_b128 v[210:213], v180 offset:55296
	ds_read_b128 v[218:221], v180 offset:56320
	global_load_lds_dwordx4 v[174:175], off
	s_add_i32 m0, s40, 0x2000
	s_add_u32 s34, s34, 0x160080
	v_lshl_add_u64 v[174:175], v[214:215], 0, s[24:25]
	s_addc_u32 s35, s35, 0
	s_add_i32 s40, s54, s31
	global_load_lds_dwordx4 v[174:175], off
	v_lshl_add_u64 v[174:175], s[34:35], 0, v[148:149]
	s_mov_b32 m0, s40
	s_nop 0
	global_load_lds_dwordx4 v[174:175], off
	v_lshl_add_u64 v[174:175], s[34:35], 0, v[152:153]
	s_add_i32 m0, s40, 0x2000
	s_nop 0
	global_load_lds_dwordx4 v[174:175], off
	v_lshl_add_u64 v[174:175], v[222:223], 0, s[24:25]
	s_mov_b32 m0, s58
	s_nop 0
	global_load_lds_dwordx4 v[174:175], off
	v_lshl_add_u64 v[174:175], v[224:225], 0, s[24:25]
	s_mov_b32 m0, s59
	s_nop 0
	global_load_lds_dwordx4 v[174:175], off
	s_waitcnt vmcnt(8)
	s_waitcnt lgkmcnt(0)
	s_barrier
	s_setprio 1
	s_waitcnt lgkmcnt(0)
	v_mfma_f32_16x16x32_bf16 v[62:65], v[130:133], v[186:189], v[62:65]
	v_mfma_f32_16x16x32_bf16 v[58:61], v[138:141], v[186:189], v[58:61]
	v_mfma_f32_16x16x32_bf16 v[50:53], v[130:133], v[194:197], v[50:53]
	v_mfma_f32_16x16x32_bf16 v[42:45], v[138:141], v[194:197], v[42:45]
	v_mfma_f32_16x16x32_bf16 v[38:41], v[130:133], v[202:205], v[38:41]
	v_mfma_f32_16x16x32_bf16 v[34:37], v[138:141], v[202:205], v[34:37]
	v_mfma_f32_16x16x32_bf16 v[14:17], v[130:133], v[210:213], v[14:17]
	v_mfma_f32_16x16x32_bf16 v[10:13], v[138:141], v[210:213], v[10:13]
	s_setprio 0
	s_setprio 1
	v_mfma_f32_16x16x32_bf16 v[62:65], v[134:137], v[190:193], v[62:65]
	v_mfma_f32_16x16x32_bf16 v[58:61], v[142:145], v[190:193], v[58:61]
	v_mfma_f32_16x16x32_bf16 v[50:53], v[134:137], v[198:201], v[50:53]
	v_mfma_f32_16x16x32_bf16 v[42:45], v[142:145], v[198:201], v[42:45]
	v_mfma_f32_16x16x32_bf16 v[38:41], v[134:137], v[206:209], v[38:41]
	v_mfma_f32_16x16x32_bf16 v[34:37], v[142:145], v[206:209], v[34:37]
	v_mfma_f32_16x16x32_bf16 v[14:17], v[134:137], v[218:221], v[14:17]
	v_mfma_f32_16x16x32_bf16 v[10:13], v[142:145], v[218:221], v[10:13]
	s_setprio 0
	s_setprio 1
	v_mfma_f32_16x16x32_bf16 v[54:57], v[162:165], v[186:189], v[54:57]
	v_mfma_f32_16x16x32_bf16 v[46:49], v[170:173], v[186:189], v[46:49]
	v_mfma_f32_16x16x32_bf16 v[30:33], v[162:165], v[194:197], v[30:33]
	v_mfma_f32_16x16x32_bf16 v[26:29], v[170:173], v[194:197], v[26:29]
	v_mfma_f32_16x16x32_bf16 v[22:25], v[162:165], v[202:205], v[22:25]
	v_mfma_f32_16x16x32_bf16 v[18:21], v[170:173], v[202:205], v[18:21]
	v_mfma_f32_16x16x32_bf16 v[6:9], v[162:165], v[210:213], v[6:9]
	v_mfma_f32_16x16x32_bf16 v[2:5], v[170:173], v[210:213], v[2:5]
	s_setprio 0
	s_setprio 1
	v_mfma_f32_16x16x32_bf16 v[54:57], v[166:169], v[190:193], v[54:57]
	v_mfma_f32_16x16x32_bf16 v[46:49], v[182:185], v[190:193], v[46:49]
	v_mfma_f32_16x16x32_bf16 v[30:33], v[166:169], v[198:201], v[30:33]
	v_mfma_f32_16x16x32_bf16 v[26:29], v[182:185], v[198:201], v[26:29]
	v_mfma_f32_16x16x32_bf16 v[22:25], v[166:169], v[206:209], v[22:25]
	v_mfma_f32_16x16x32_bf16 v[18:21], v[182:185], v[206:209], v[18:21]
	v_mfma_f32_16x16x32_bf16 v[6:9], v[166:169], v[218:221], v[6:9]
	v_mfma_f32_16x16x32_bf16 v[2:5], v[182:185], v[218:221], v[2:5]
	s_setprio 0
	s_barrier
	s_add_i32 s52, s52, 2
	s_add_u32 s38, s38, 0x100
	s_addc_u32 s39, s39, 0
	s_add_u32 s0, s0, 0x100
	s_addc_u32 s1, s1, 0
	s_cmpk_gt_u32 s52, 0x55
	s_cbranch_scc0 .LBB0_2089
	s_and_b64 vcc, exec, s[26:27]
	s_cbranch_vccz .LBB0_2092
	s_barrier

.LBB0_2218:
	ds_read_b128 v[146:149], v153
	ds_read_b128 v[156:159], v153 offset:1024
	ds_read_b128 v[160:163], v153 offset:2048
	ds_read_b128 v[164:167], v153 offset:3072
	ds_read_b128 v[168:171], v154
	ds_read_b128 v[172:175], v154 offset:1024
	ds_read_b128 v[176:179], v154 offset:2048
	ds_read_b128 v[180:183], v154 offset:3072
	s_add_u32 s34, s76, 0xfff80080
	s_addc_u32 s35, s77, -1
	s_cmp_eq_u32 s80, 28
	s_cselect_b32 s79, s0, s35
	s_cselect_b32 s78, s1, s34
	s_cselect_b32 s35, s27, s75
	s_cselect_b32 s34, s37, s52
	v_lshl_add_u64 v[218:219], s[76:77], 0, v[138:139]
	s_add_i32 m0, s47, 0xc000
	ds_read_b128 v[184:187], v155
	ds_read_b128 v[188:191], v155 offset:1024
	ds_read_b128 v[192:195], v155 offset:2048
	ds_read_b128 v[196:199], v155 offset:3072
	ds_read_b128 v[200:203], v155 offset:4096
	ds_read_b128 v[204:207], v155 offset:5120
	ds_read_b128 v[208:211], v155 offset:6144
	ds_read_b128 v[212:215], v155 offset:7168
	global_load_lds_dwordx4 v[218:219], off
	v_lshl_add_u64 v[218:219], s[76:77], 0, v[140:141]
	s_add_i32 m0, s47, 0xe000
	s_nop 0
	global_load_lds_dwordx4 v[218:219], off
	s_waitcnt vmcnt(8)
	s_waitcnt lgkmcnt(0)
	s_barrier
	s_setprio 1
	s_waitcnt lgkmcnt(0)
	v_mfma_f32_16x16x32_bf16 v[126:129], v[146:149], v[184:187], v[126:129]
	v_mfma_f32_16x16x32_bf16 v[118:121], v[160:163], v[184:187], v[118:121]
	v_mfma_f32_16x16x32_bf16 v[110:113], v[146:149], v[192:195], v[110:113]
	v_mfma_f32_16x16x32_bf16 v[102:105], v[160:163], v[192:195], v[102:105]
	v_mfma_f32_16x16x32_bf16 v[94:97], v[146:149], v[200:203], v[94:97]
	v_mfma_f32_16x16x32_bf16 v[86:89], v[160:163], v[200:203], v[86:89]
	v_mfma_f32_16x16x32_bf16 v[78:81], v[146:149], v[208:211], v[78:81]
	v_mfma_f32_16x16x32_bf16 v[70:73], v[160:163], v[208:211], v[70:73]
	s_setprio 0
	s_setprio 1
	v_mfma_f32_16x16x32_bf16 v[126:129], v[156:159], v[188:191], v[126:129]
	v_mfma_f32_16x16x32_bf16 v[118:121], v[164:167], v[188:191], v[118:121]
	v_mfma_f32_16x16x32_bf16 v[110:113], v[156:159], v[196:199], v[110:113]
	v_mfma_f32_16x16x32_bf16 v[102:105], v[164:167], v[196:199], v[102:105]
	v_mfma_f32_16x16x32_bf16 v[94:97], v[156:159], v[204:207], v[94:97]
	v_mfma_f32_16x16x32_bf16 v[86:89], v[164:167], v[204:207], v[86:89]
	v_mfma_f32_16x16x32_bf16 v[78:81], v[156:159], v[212:215], v[78:81]
	v_mfma_f32_16x16x32_bf16 v[70:73], v[164:167], v[212:215], v[70:73]
	s_setprio 0
	s_setprio 1
	v_mfma_f32_16x16x32_bf16 v[122:125], v[168:171], v[184:187], v[122:125]
	v_mfma_f32_16x16x32_bf16 v[114:117], v[176:179], v[184:187], v[114:117]
	v_mfma_f32_16x16x32_bf16 v[106:109], v[168:171], v[192:195], v[106:109]
	v_mfma_f32_16x16x32_bf16 v[98:101], v[176:179], v[192:195], v[98:101]
	v_mfma_f32_16x16x32_bf16 v[90:93], v[168:171], v[200:203], v[90:93]
	v_mfma_f32_16x16x32_bf16 v[82:85], v[176:179], v[200:203], v[82:85]
	v_mfma_f32_16x16x32_bf16 v[74:77], v[168:171], v[208:211], v[74:77]
	v_mfma_f32_16x16x32_bf16 v[66:69], v[176:179], v[208:211], v[66:69]
	s_setprio 0
	s_setprio 1
	v_mfma_f32_16x16x32_bf16 v[122:125], v[172:175], v[188:191], v[122:125]
	v_mfma_f32_16x16x32_bf16 v[114:117], v[180:183], v[188:191], v[114:117]
	v_mfma_f32_16x16x32_bf16 v[106:109], v[172:175], v[196:199], v[106:109]
	v_mfma_f32_16x16x32_bf16 v[98:101], v[180:183], v[196:199], v[98:101]
	v_mfma_f32_16x16x32_bf16 v[90:93], v[172:175], v[204:207], v[90:93]
	v_mfma_f32_16x16x32_bf16 v[82:85], v[180:183], v[204:207], v[82:85]
	v_mfma_f32_16x16x32_bf16 v[74:77], v[172:175], v[212:215], v[74:77]
	v_mfma_f32_16x16x32_bf16 v[66:69], v[180:183], v[212:215], v[66:69]
	s_setprio 0
	s_barrier
	s_add_i32 s53, s71, s30
	v_lshl_add_u64 v[218:219], s[34:35], 0, v[134:135]
	s_mov_b32 m0, s53
	ds_read_b128 v[184:187], v155 offset:16384
	ds_read_b128 v[188:191], v155 offset:17408
	ds_read_b128 v[192:195], v155 offset:18432
	ds_read_b128 v[196:199], v155 offset:19456
	ds_read_b128 v[200:203], v155 offset:20480
	ds_read_b128 v[204:207], v155 offset:21504
	ds_read_b128 v[208:211], v155 offset:22528
	ds_read_b128 v[212:215], v155 offset:23552
	global_load_lds_dwordx4 v[218:219], off
	s_add_i32 m0, s53, 0x2000
	s_add_u32 s54, s34, 0x80000
	v_lshl_add_u64 v[220:221], s[34:35], 0, v[130:131]
	s_addc_u32 s55, s35, 0
	s_add_i32 s53, s72, s30
	global_load_lds_dwordx4 v[220:221], off
	v_lshl_add_u64 v[222:223], s[54:55], 0, v[134:135]
	s_mov_b32 m0, s53
	v_lshl_add_u64 v[224:225], s[78:79], 0, v[132:133]
	global_load_lds_dwordx4 v[222:223], off
	v_lshl_add_u64 v[222:223], s[54:55], 0, v[130:131]
	s_add_i32 m0, s53, 0x2000
	s_nop 0
	global_load_lds_dwordx4 v[222:223], off
	v_lshl_add_u64 v[222:223], s[78:79], 0, v[136:137]
	s_mov_b32 m0, s47
	s_nop 0
	global_load_lds_dwordx4 v[222:223], off
	s_mov_b32 m0, s56
	s_nop 0
	global_load_lds_dwordx4 v[224:225], off
	s_waitcnt vmcnt(8)
	s_waitcnt lgkmcnt(0)
	s_barrier
	s_setprio 1
	s_waitcnt lgkmcnt(0)
	v_mfma_f32_16x16x32_bf16 v[62:65], v[146:149], v[184:187], v[62:65]
	v_mfma_f32_16x16x32_bf16 v[54:57], v[160:163], v[184:187], v[54:57]
	v_mfma_f32_16x16x32_bf16 v[46:49], v[146:149], v[192:195], v[46:49]
	v_mfma_f32_16x16x32_bf16 v[38:41], v[160:163], v[192:195], v[38:41]
	v_mfma_f32_16x16x32_bf16 v[30:33], v[146:149], v[200:203], v[30:33]
	v_mfma_f32_16x16x32_bf16 v[22:25], v[160:163], v[200:203], v[22:25]
	v_mfma_f32_16x16x32_bf16 v[14:17], v[146:149], v[208:211], v[14:17]
	v_mfma_f32_16x16x32_bf16 v[6:9], v[160:163], v[208:211], v[6:9]
	s_setprio 0
	s_setprio 1
	v_mfma_f32_16x16x32_bf16 v[62:65], v[156:159], v[188:191], v[62:65]
	v_mfma_f32_16x16x32_bf16 v[54:57], v[164:167], v[188:191], v[54:57]
	v_mfma_f32_16x16x32_bf16 v[46:49], v[156:159], v[196:199], v[46:49]
	v_mfma_f32_16x16x32_bf16 v[38:41], v[164:167], v[196:199], v[38:41]
	v_mfma_f32_16x16x32_bf16 v[30:33], v[156:159], v[204:207], v[30:33]
	v_mfma_f32_16x16x32_bf16 v[22:25], v[164:167], v[204:207], v[22:25]
	v_mfma_f32_16x16x32_bf16 v[14:17], v[156:159], v[212:215], v[14:17]
	v_mfma_f32_16x16x32_bf16 v[6:9], v[164:167], v[212:215], v[6:9]
	s_setprio 0
	s_setprio 1
	v_mfma_f32_16x16x32_bf16 v[58:61], v[168:171], v[184:187], v[58:61]
	v_mfma_f32_16x16x32_bf16 v[50:53], v[176:179], v[184:187], v[50:53]
	v_mfma_f32_16x16x32_bf16 v[42:45], v[168:171], v[192:195], v[42:45]
	v_mfma_f32_16x16x32_bf16 v[34:37], v[176:179], v[192:195], v[34:37]
	v_mfma_f32_16x16x32_bf16 v[26:29], v[168:171], v[200:203], v[26:29]
	v_mfma_f32_16x16x32_bf16 v[18:21], v[176:179], v[200:203], v[18:21]
	v_mfma_f32_16x16x32_bf16 v[10:13], v[168:171], v[208:211], v[10:13]
	v_mfma_f32_16x16x32_bf16 v[2:5], v[176:179], v[208:211], v[2:5]
	s_setprio 0
	s_setprio 1
	v_mfma_f32_16x16x32_bf16 v[58:61], v[172:175], v[188:191], v[58:61]
	v_mfma_f32_16x16x32_bf16 v[50:53], v[180:183], v[188:191], v[50:53]
	v_mfma_f32_16x16x32_bf16 v[42:45], v[172:175], v[196:199], v[42:45]
	v_mfma_f32_16x16x32_bf16 v[34:37], v[180:183], v[196:199], v[34:37]
	v_mfma_f32_16x16x32_bf16 v[26:29], v[172:175], v[204:207], v[26:29]
	v_mfma_f32_16x16x32_bf16 v[18:21], v[180:183], v[204:207], v[18:21]
	v_mfma_f32_16x16x32_bf16 v[10:13], v[172:175], v[212:215], v[10:13]
	v_mfma_f32_16x16x32_bf16 v[2:5], v[180:183], v[212:215], v[2:5]
	s_setprio 0
	s_barrier
	s_add_i32 s53, 0, 0x18000
	s_add_i32 s62, 0, 0x1c000
	v_add_u32_e32 v164, s53, v151
	v_add_u32_e32 v180, s62, v151
	ds_read_b128 v[146:149], v164
	ds_read_b128 v[156:159], v164 offset:1024
	ds_read_b128 v[160:163], v164 offset:2048
	ds_read_b128 v[164:167], v164 offset:3072
	ds_read_b128 v[168:171], v180
	ds_read_b128 v[172:175], v180 offset:1024
	ds_read_b128 v[176:179], v180 offset:2048
	ds_read_b128 v[180:183], v180 offset:3072
	s_add_u32 s54, s78, 0x80000
	s_addc_u32 s55, s79, 0
	s_mov_b32 m0, s57
	v_lshl_add_u64 v[226:227], s[54:55], 0, v[136:137]
	ds_read_b128 v[184:187], v155 offset:32768
	ds_read_b128 v[188:191], v155 offset:33792
	ds_read_b128 v[192:195], v155 offset:34816
	ds_read_b128 v[196:199], v155 offset:35840
	ds_read_b128 v[200:203], v155 offset:36864
	ds_read_b128 v[204:207], v155 offset:37888
	ds_read_b128 v[208:211], v155 offset:38912
	ds_read_b128 v[212:215], v155 offset:39936
	global_load_lds_dwordx4 v[226:227], off
	v_lshl_add_u64 v[226:227], s[54:55], 0, v[132:133]
	s_mov_b32 m0, s58
	s_nop 0
	global_load_lds_dwordx4 v[226:227], off
	s_waitcnt vmcnt(8)
	s_waitcnt lgkmcnt(0)
	s_barrier
	s_setprio 1
	s_waitcnt lgkmcnt(0)
	v_mfma_f32_16x16x32_bf16 v[126:129], v[146:149], v[184:187], v[126:129]
	v_mfma_f32_16x16x32_bf16 v[118:121], v[160:163], v[184:187], v[118:121]
	v_mfma_f32_16x16x32_bf16 v[110:113], v[146:149], v[192:195], v[110:113]
	v_mfma_f32_16x16x32_bf16 v[102:105], v[160:163], v[192:195], v[102:105]
	v_mfma_f32_16x16x32_bf16 v[94:97], v[146:149], v[200:203], v[94:97]
	v_mfma_f32_16x16x32_bf16 v[86:89], v[160:163], v[200:203], v[86:89]
	v_mfma_f32_16x16x32_bf16 v[78:81], v[146:149], v[208:211], v[78:81]
	v_mfma_f32_16x16x32_bf16 v[70:73], v[160:163], v[208:211], v[70:73]
	s_setprio 0
	s_setprio 1
	v_mfma_f32_16x16x32_bf16 v[126:129], v[156:159], v[188:191], v[126:129]
	v_mfma_f32_16x16x32_bf16 v[118:121], v[164:167], v[188:191], v[118:121]
	v_mfma_f32_16x16x32_bf16 v[110:113], v[156:159], v[196:199], v[110:113]
	v_mfma_f32_16x16x32_bf16 v[102:105], v[164:167], v[196:199], v[102:105]
	v_mfma_f32_16x16x32_bf16 v[94:97], v[156:159], v[204:207], v[94:97]
	v_mfma_f32_16x16x32_bf16 v[86:89], v[164:167], v[204:207], v[86:89]
	v_mfma_f32_16x16x32_bf16 v[78:81], v[156:159], v[212:215], v[78:81]
	v_mfma_f32_16x16x32_bf16 v[70:73], v[164:167], v[212:215], v[70:73]
	s_setprio 0
	s_setprio 1
	v_mfma_f32_16x16x32_bf16 v[122:125], v[168:171], v[184:187], v[122:125]
	v_mfma_f32_16x16x32_bf16 v[114:117], v[176:179], v[184:187], v[114:117]
	v_mfma_f32_16x16x32_bf16 v[106:109], v[168:171], v[192:195], v[106:109]
	v_mfma_f32_16x16x32_bf16 v[98:101], v[176:179], v[192:195], v[98:101]
	v_mfma_f32_16x16x32_bf16 v[90:93], v[168:171], v[200:203], v[90:93]
	v_mfma_f32_16x16x32_bf16 v[82:85], v[176:179], v[200:203], v[82:85]
	v_mfma_f32_16x16x32_bf16 v[74:77], v[168:171], v[208:211], v[74:77]
	v_mfma_f32_16x16x32_bf16 v[66:69], v[176:179], v[208:211], v[66:69]
	s_setprio 0
	s_setprio 1
	v_mfma_f32_16x16x32_bf16 v[122:125], v[172:175], v[188:191], v[122:125]
	v_mfma_f32_16x16x32_bf16 v[114:117], v[180:183], v[188:191], v[114:117]
	v_mfma_f32_16x16x32_bf16 v[106:109], v[172:175], v[196:199], v[106:109]
	v_mfma_f32_16x16x32_bf16 v[98:101], v[180:183], v[196:199], v[98:101]
	v_mfma_f32_16x16x32_bf16 v[90:93], v[172:175], v[204:207], v[90:93]
	v_mfma_f32_16x16x32_bf16 v[82:85], v[180:183], v[204:207], v[82:85]
	v_mfma_f32_16x16x32_bf16 v[74:77], v[172:175], v[212:215], v[74:77]
	v_mfma_f32_16x16x32_bf16 v[66:69], v[180:183], v[212:215], v[66:69]
	s_setprio 0
	s_barrier
	s_add_i32 s53, s53, s30
	v_lshl_add_u64 v[218:219], v[218:219], 0, s[8:9]
	s_mov_b32 m0, s53
	ds_read_b128 v[184:187], v155 offset:49152
	ds_read_b128 v[188:191], v155 offset:50176
	ds_read_b128 v[192:195], v155 offset:51200
	ds_read_b128 v[196:199], v155 offset:52224
	ds_read_b128 v[200:203], v155 offset:53248
	ds_read_b128 v[204:207], v155 offset:54272
	ds_read_b128 v[208:211], v155 offset:55296
	ds_read_b128 v[212:215], v155 offset:56320
	global_load_lds_dwordx4 v[218:219], off
	s_add_i32 m0, s53, 0x2000
	s_add_u32 s34, s34, 0x80080
	v_lshl_add_u64 v[218:219], v[220:221], 0, s[8:9]
	s_addc_u32 s35, s35, 0
	s_add_i32 s53, s62, s30
	global_load_lds_dwordx4 v[218:219], off
	v_lshl_add_u64 v[218:219], s[34:35], 0, v[134:135]
	s_mov_b32 m0, s53
	s_nop 0
	global_load_lds_dwordx4 v[218:219], off
	v_lshl_add_u64 v[218:219], s[34:35], 0, v[130:131]
	s_add_i32 m0, s53, 0x2000
	s_nop 0
	global_load_lds_dwordx4 v[218:219], off
	v_lshl_add_u64 v[218:219], v[222:223], 0, s[8:9]
	s_mov_b32 m0, s60
	s_nop 0
	global_load_lds_dwordx4 v[218:219], off
	v_lshl_add_u64 v[218:219], v[224:225], 0, s[8:9]
	s_mov_b32 m0, s61
	s_nop 0
	global_load_lds_dwordx4 v[218:219], off
	s_waitcnt vmcnt(8)
	s_waitcnt lgkmcnt(0)
	s_barrier
	s_setprio 1
	s_waitcnt lgkmcnt(0)
	v_mfma_f32_16x16x32_bf16 v[62:65], v[146:149], v[184:187], v[62:65]
	v_mfma_f32_16x16x32_bf16 v[54:57], v[160:163], v[184:187], v[54:57]
	v_mfma_f32_16x16x32_bf16 v[46:49], v[146:149], v[192:195], v[46:49]
	v_mfma_f32_16x16x32_bf16 v[38:41], v[160:163], v[192:195], v[38:41]
	v_mfma_f32_16x16x32_bf16 v[30:33], v[146:149], v[200:203], v[30:33]
	v_mfma_f32_16x16x32_bf16 v[22:25], v[160:163], v[200:203], v[22:25]
	v_mfma_f32_16x16x32_bf16 v[14:17], v[146:149], v[208:211], v[14:17]
	v_mfma_f32_16x16x32_bf16 v[6:9], v[160:163], v[208:211], v[6:9]
	s_setprio 0
	s_setprio 1
	v_mfma_f32_16x16x32_bf16 v[62:65], v[156:159], v[188:191], v[62:65]
	v_mfma_f32_16x16x32_bf16 v[54:57], v[164:167], v[188:191], v[54:57]
	v_mfma_f32_16x16x32_bf16 v[46:49], v[156:159], v[196:199], v[46:49]
	v_mfma_f32_16x16x32_bf16 v[38:41], v[164:167], v[196:199], v[38:41]
	v_mfma_f32_16x16x32_bf16 v[30:33], v[156:159], v[204:207], v[30:33]
	v_mfma_f32_16x16x32_bf16 v[22:25], v[164:167], v[204:207], v[22:25]
	v_mfma_f32_16x16x32_bf16 v[14:17], v[156:159], v[212:215], v[14:17]
	v_mfma_f32_16x16x32_bf16 v[6:9], v[164:167], v[212:215], v[6:9]
	s_setprio 0
	s_setprio 1
	v_mfma_f32_16x16x32_bf16 v[58:61], v[168:171], v[184:187], v[58:61]
	v_mfma_f32_16x16x32_bf16 v[50:53], v[176:179], v[184:187], v[50:53]
	v_mfma_f32_16x16x32_bf16 v[42:45], v[168:171], v[192:195], v[42:45]
	v_mfma_f32_16x16x32_bf16 v[34:37], v[176:179], v[192:195], v[34:37]
	v_mfma_f32_16x16x32_bf16 v[26:29], v[168:171], v[200:203], v[26:29]
	v_mfma_f32_16x16x32_bf16 v[18:21], v[176:179], v[200:203], v[18:21]
	v_mfma_f32_16x16x32_bf16 v[10:13], v[168:171], v[208:211], v[10:13]
	v_mfma_f32_16x16x32_bf16 v[2:5], v[176:179], v[208:211], v[2:5]
	s_setprio 0
	s_setprio 1
	v_mfma_f32_16x16x32_bf16 v[58:61], v[172:175], v[188:191], v[58:61]
	v_mfma_f32_16x16x32_bf16 v[50:53], v[180:183], v[188:191], v[50:53]
	v_mfma_f32_16x16x32_bf16 v[42:45], v[172:175], v[196:199], v[42:45]
	v_mfma_f32_16x16x32_bf16 v[34:37], v[180:183], v[196:199], v[34:37]
	v_mfma_f32_16x16x32_bf16 v[26:29], v[172:175], v[204:207], v[26:29]
	v_mfma_f32_16x16x32_bf16 v[18:21], v[180:183], v[204:207], v[18:21]
	v_mfma_f32_16x16x32_bf16 v[10:13], v[172:175], v[212:215], v[10:13]
	v_mfma_f32_16x16x32_bf16 v[2:5], v[180:183], v[212:215], v[2:5]
	s_setprio 0
	s_barrier
	s_add_i32 s80, s80, 2
	s_add_u32 s76, s76, 0x100
	s_addc_u32 s77, s77, 0
	s_add_u32 s52, s52, 0x100
	s_addc_u32 s75, s75, 0
	s_cmp_gt_u32 s80, 29
	s_cbranch_scc0 .LBB0_2218
	s_and_b64 vcc, exec, s[24:25]
	s_cbranch_vccz .LBB0_2221
	s_barrier

.LBB0_2462:
	ds_read_b128 v[160:163], v155
	ds_read_b128 v[164:167], v155 offset:1024
	ds_read_b128 v[168:171], v155 offset:2048
	ds_read_b128 v[172:175], v155 offset:3072
	ds_read_b128 v[176:179], v156
	ds_read_b128 v[180:183], v156 offset:1024
	ds_read_b128 v[184:187], v156 offset:2048
	ds_read_b128 v[188:191], v156 offset:3072
	s_add_u32 s34, s76, 0xfff80080
	s_addc_u32 s35, s77, -1
	s_cmp_eq_u32 s74, 28
	s_cselect_b32 s89, s0, s35
	s_cselect_b32 s88, s1, s34
	s_cselect_b32 s35, s7, s52
	s_cselect_b32 s34, s9, s36
	v_lshl_add_u64 v[152:153], s[76:77], 0, v[144:145]
	s_add_i32 m0, s31, 0xc000
	ds_read_b128 v[192:195], v157
	ds_read_b128 v[196:199], v157 offset:1024
	ds_read_b128 v[200:203], v157 offset:2048
	ds_read_b128 v[204:207], v157 offset:3072
	ds_read_b128 v[208:211], v157 offset:4096
	ds_read_b128 v[212:215], v157 offset:5120
	ds_read_b128 v[218:221], v157 offset:6144
	ds_read_b128 v[222:225], v157 offset:7168
	global_load_lds_dwordx4 v[152:153], off
	v_lshl_add_u64 v[152:153], s[76:77], 0, v[146:147]
	s_add_i32 m0, s31, 0xe000
	s_nop 0
	global_load_lds_dwordx4 v[152:153], off
	s_waitcnt vmcnt(8)
	s_waitcnt lgkmcnt(0)
	s_barrier
	s_setprio 1
	s_waitcnt lgkmcnt(0)
	v_mfma_f32_16x16x32_bf16 v[126:129], v[160:163], v[192:195], v[126:129]
	v_mfma_f32_16x16x32_bf16 v[122:125], v[168:171], v[192:195], v[122:125]
	v_mfma_f32_16x16x32_bf16 v[110:113], v[160:163], v[200:203], v[110:113]
	v_mfma_f32_16x16x32_bf16 v[106:109], v[168:171], v[200:203], v[106:109]
	v_mfma_f32_16x16x32_bf16 v[94:97], v[160:163], v[208:211], v[94:97]
	v_mfma_f32_16x16x32_bf16 v[90:93], v[168:171], v[208:211], v[90:93]
	v_mfma_f32_16x16x32_bf16 v[78:81], v[160:163], v[218:221], v[78:81]
	v_mfma_f32_16x16x32_bf16 v[74:77], v[168:171], v[218:221], v[74:77]
	s_setprio 0
	s_setprio 1
	v_mfma_f32_16x16x32_bf16 v[126:129], v[164:167], v[196:199], v[126:129]
	v_mfma_f32_16x16x32_bf16 v[122:125], v[172:175], v[196:199], v[122:125]
	v_mfma_f32_16x16x32_bf16 v[110:113], v[164:167], v[204:207], v[110:113]
	v_mfma_f32_16x16x32_bf16 v[106:109], v[172:175], v[204:207], v[106:109]
	v_mfma_f32_16x16x32_bf16 v[94:97], v[164:167], v[212:215], v[94:97]
	v_mfma_f32_16x16x32_bf16 v[90:93], v[172:175], v[212:215], v[90:93]
	v_mfma_f32_16x16x32_bf16 v[78:81], v[164:167], v[222:225], v[78:81]
	v_mfma_f32_16x16x32_bf16 v[74:77], v[172:175], v[222:225], v[74:77]
	s_setprio 0
	s_setprio 1
	v_mfma_f32_16x16x32_bf16 v[118:121], v[176:179], v[192:195], v[118:121]
	v_mfma_f32_16x16x32_bf16 v[114:117], v[184:187], v[192:195], v[114:117]
	v_mfma_f32_16x16x32_bf16 v[102:105], v[176:179], v[200:203], v[102:105]
	v_mfma_f32_16x16x32_bf16 v[98:101], v[184:187], v[200:203], v[98:101]
	v_mfma_f32_16x16x32_bf16 v[86:89], v[176:179], v[208:211], v[86:89]
	v_mfma_f32_16x16x32_bf16 v[82:85], v[184:187], v[208:211], v[82:85]
	v_mfma_f32_16x16x32_bf16 v[70:73], v[176:179], v[218:221], v[70:73]
	v_mfma_f32_16x16x32_bf16 v[66:69], v[184:187], v[218:221], v[66:69]
	s_setprio 0
	s_setprio 1
	v_mfma_f32_16x16x32_bf16 v[118:121], v[180:183], v[196:199], v[118:121]
	v_mfma_f32_16x16x32_bf16 v[114:117], v[188:191], v[196:199], v[114:117]
	v_mfma_f32_16x16x32_bf16 v[102:105], v[180:183], v[204:207], v[102:105]
	v_mfma_f32_16x16x32_bf16 v[98:101], v[188:191], v[204:207], v[98:101]
	v_mfma_f32_16x16x32_bf16 v[86:89], v[180:183], v[212:215], v[86:89]
	v_mfma_f32_16x16x32_bf16 v[82:85], v[188:191], v[212:215], v[82:85]
	v_mfma_f32_16x16x32_bf16 v[70:73], v[180:183], v[222:225], v[70:73]
	v_mfma_f32_16x16x32_bf16 v[66:69], v[188:191], v[222:225], v[66:69]
	s_setprio 0
	s_barrier
	s_add_i32 s53, s71, s12
	v_lshl_add_u64 v[152:153], s[34:35], 0, v[132:133]
	s_mov_b32 m0, s53
	ds_read_b128 v[192:195], v157 offset:16384
	ds_read_b128 v[196:199], v157 offset:17408
	ds_read_b128 v[200:203], v157 offset:18432
	ds_read_b128 v[204:207], v157 offset:19456
	ds_read_b128 v[208:211], v157 offset:20480
	ds_read_b128 v[212:215], v157 offset:21504
	ds_read_b128 v[218:221], v157 offset:22528
	ds_read_b128 v[222:225], v157 offset:23552
	global_load_lds_dwordx4 v[152:153], off
	s_add_i32 m0, s53, 0x2000
	s_add_u32 s54, s34, 0x80000
	v_lshl_add_u64 v[226:227], s[34:35], 0, v[136:137]
	s_addc_u32 s55, s35, 0
	s_add_i32 s53, s72, s12
	global_load_lds_dwordx4 v[226:227], off
	v_lshl_add_u64 v[228:229], s[54:55], 0, v[132:133]
	s_mov_b32 m0, s53
	v_lshl_add_u64 v[230:231], s[88:89], 0, v[134:135]
	global_load_lds_dwordx4 v[228:229], off
	v_lshl_add_u64 v[228:229], s[54:55], 0, v[136:137]
	s_add_i32 m0, s53, 0x2000
	s_nop 0
	global_load_lds_dwordx4 v[228:229], off
	v_lshl_add_u64 v[228:229], s[88:89], 0, v[130:131]
	s_mov_b32 m0, s31
	s_nop 0
	global_load_lds_dwordx4 v[228:229], off
	s_mov_b32 m0, s33
	s_nop 0
	global_load_lds_dwordx4 v[230:231], off
	s_waitcnt vmcnt(8)
	s_waitcnt lgkmcnt(0)
	s_barrier
	s_setprio 1
	s_waitcnt lgkmcnt(0)
	v_mfma_f32_16x16x32_bf16 v[62:65], v[160:163], v[192:195], v[62:65]
	v_mfma_f32_16x16x32_bf16 v[58:61], v[168:171], v[192:195], v[58:61]
	v_mfma_f32_16x16x32_bf16 v[46:49], v[160:163], v[200:203], v[46:49]
	v_mfma_f32_16x16x32_bf16 v[42:45], v[168:171], v[200:203], v[42:45]
	v_mfma_f32_16x16x32_bf16 v[30:33], v[160:163], v[208:211], v[30:33]
	v_mfma_f32_16x16x32_bf16 v[26:29], v[168:171], v[208:211], v[26:29]
	v_mfma_f32_16x16x32_bf16 v[14:17], v[160:163], v[218:221], v[14:17]
	v_mfma_f32_16x16x32_bf16 v[10:13], v[168:171], v[218:221], v[10:13]
	s_setprio 0
	s_setprio 1
	v_mfma_f32_16x16x32_bf16 v[62:65], v[164:167], v[196:199], v[62:65]
	v_mfma_f32_16x16x32_bf16 v[58:61], v[172:175], v[196:199], v[58:61]
	v_mfma_f32_16x16x32_bf16 v[46:49], v[164:167], v[204:207], v[46:49]
	v_mfma_f32_16x16x32_bf16 v[42:45], v[172:175], v[204:207], v[42:45]
	v_mfma_f32_16x16x32_bf16 v[30:33], v[164:167], v[212:215], v[30:33]
	v_mfma_f32_16x16x32_bf16 v[26:29], v[172:175], v[212:215], v[26:29]
	v_mfma_f32_16x16x32_bf16 v[14:17], v[164:167], v[222:225], v[14:17]
	v_mfma_f32_16x16x32_bf16 v[10:13], v[172:175], v[222:225], v[10:13]
	s_setprio 0
	s_setprio 1
	v_mfma_f32_16x16x32_bf16 v[54:57], v[176:179], v[192:195], v[54:57]
	v_mfma_f32_16x16x32_bf16 v[50:53], v[184:187], v[192:195], v[50:53]
	v_mfma_f32_16x16x32_bf16 v[38:41], v[176:179], v[200:203], v[38:41]
	v_mfma_f32_16x16x32_bf16 v[34:37], v[184:187], v[200:203], v[34:37]
	v_mfma_f32_16x16x32_bf16 v[22:25], v[176:179], v[208:211], v[22:25]
	v_mfma_f32_16x16x32_bf16 v[18:21], v[184:187], v[208:211], v[18:21]
	v_mfma_f32_16x16x32_bf16 v[6:9], v[176:179], v[218:221], v[6:9]
	v_mfma_f32_16x16x32_bf16 v[2:5], v[184:187], v[218:221], v[2:5]
	s_setprio 0
	s_setprio 1
	v_mfma_f32_16x16x32_bf16 v[54:57], v[180:183], v[196:199], v[54:57]
	v_mfma_f32_16x16x32_bf16 v[50:53], v[188:191], v[196:199], v[50:53]
	v_mfma_f32_16x16x32_bf16 v[38:41], v[180:183], v[204:207], v[38:41]
	v_mfma_f32_16x16x32_bf16 v[34:37], v[188:191], v[204:207], v[34:37]
	v_mfma_f32_16x16x32_bf16 v[22:25], v[180:183], v[212:215], v[22:25]
	v_mfma_f32_16x16x32_bf16 v[18:21], v[188:191], v[212:215], v[18:21]
	v_mfma_f32_16x16x32_bf16 v[6:9], v[180:183], v[222:225], v[6:9]
	v_mfma_f32_16x16x32_bf16 v[2:5], v[188:191], v[222:225], v[2:5]
	s_setprio 0
	s_barrier
	s_add_i32 s53, 0, 0x18000
	v_add_u32_e32 v138, s53, v154
	s_add_i32 s62, 0, 0x1c000
	ds_read_b128 v[160:163], v138
	ds_read_b128 v[164:167], v138 offset:1024
	ds_read_b128 v[168:171], v138 offset:2048
	ds_read_b128 v[172:175], v138 offset:3072
	v_add_u32_e32 v138, s62, v154
	ds_read_b128 v[176:179], v138
	ds_read_b128 v[180:183], v138 offset:1024
	ds_read_b128 v[184:187], v138 offset:2048
	ds_read_b128 v[188:191], v138 offset:3072
	s_add_u32 s54, s88, 0x80000
	s_addc_u32 s55, s89, 0
	s_mov_b32 m0, s56
	v_lshl_add_u64 v[232:233], s[54:55], 0, v[130:131]
	ds_read_b128 v[192:195], v157 offset:32768
	ds_read_b128 v[196:199], v157 offset:33792
	ds_read_b128 v[200:203], v157 offset:34816
	ds_read_b128 v[204:207], v157 offset:35840
	ds_read_b128 v[208:211], v157 offset:36864
	ds_read_b128 v[212:215], v157 offset:37888
	ds_read_b128 v[218:221], v157 offset:38912
	ds_read_b128 v[222:225], v157 offset:39936
	global_load_lds_dwordx4 v[232:233], off
	v_lshl_add_u64 v[232:233], s[54:55], 0, v[134:135]
	s_mov_b32 m0, s57
	s_nop 0
	global_load_lds_dwordx4 v[232:233], off
	s_waitcnt vmcnt(8)
	s_waitcnt lgkmcnt(0)
	s_barrier
	s_setprio 1
	s_waitcnt lgkmcnt(0)
	v_mfma_f32_16x16x32_bf16 v[126:129], v[160:163], v[192:195], v[126:129]
	v_mfma_f32_16x16x32_bf16 v[122:125], v[168:171], v[192:195], v[122:125]
	v_mfma_f32_16x16x32_bf16 v[110:113], v[160:163], v[200:203], v[110:113]
	v_mfma_f32_16x16x32_bf16 v[106:109], v[168:171], v[200:203], v[106:109]
	v_mfma_f32_16x16x32_bf16 v[94:97], v[160:163], v[208:211], v[94:97]
	v_mfma_f32_16x16x32_bf16 v[90:93], v[168:171], v[208:211], v[90:93]
	v_mfma_f32_16x16x32_bf16 v[78:81], v[160:163], v[218:221], v[78:81]
	v_mfma_f32_16x16x32_bf16 v[74:77], v[168:171], v[218:221], v[74:77]
	s_setprio 0
	s_setprio 1
	v_mfma_f32_16x16x32_bf16 v[126:129], v[164:167], v[196:199], v[126:129]
	v_mfma_f32_16x16x32_bf16 v[122:125], v[172:175], v[196:199], v[122:125]
	v_mfma_f32_16x16x32_bf16 v[110:113], v[164:167], v[204:207], v[110:113]
	v_mfma_f32_16x16x32_bf16 v[106:109], v[172:175], v[204:207], v[106:109]
	v_mfma_f32_16x16x32_bf16 v[94:97], v[164:167], v[212:215], v[94:97]
	v_mfma_f32_16x16x32_bf16 v[90:93], v[172:175], v[212:215], v[90:93]
	v_mfma_f32_16x16x32_bf16 v[78:81], v[164:167], v[222:225], v[78:81]
	v_mfma_f32_16x16x32_bf16 v[74:77], v[172:175], v[222:225], v[74:77]
	s_setprio 0
	s_setprio 1
	v_mfma_f32_16x16x32_bf16 v[118:121], v[176:179], v[192:195], v[118:121]
	v_mfma_f32_16x16x32_bf16 v[114:117], v[184:187], v[192:195], v[114:117]
	v_mfma_f32_16x16x32_bf16 v[102:105], v[176:179], v[200:203], v[102:105]
	v_mfma_f32_16x16x32_bf16 v[98:101], v[184:187], v[200:203], v[98:101]
	v_mfma_f32_16x16x32_bf16 v[86:89], v[176:179], v[208:211], v[86:89]
	v_mfma_f32_16x16x32_bf16 v[82:85], v[184:187], v[208:211], v[82:85]
	v_mfma_f32_16x16x32_bf16 v[70:73], v[176:179], v[218:221], v[70:73]
	v_mfma_f32_16x16x32_bf16 v[66:69], v[184:187], v[218:221], v[66:69]
	s_setprio 0
	s_setprio 1
	v_mfma_f32_16x16x32_bf16 v[118:121], v[180:183], v[196:199], v[118:121]
	v_mfma_f32_16x16x32_bf16 v[114:117], v[188:191], v[196:199], v[114:117]
	v_mfma_f32_16x16x32_bf16 v[102:105], v[180:183], v[204:207], v[102:105]
	v_mfma_f32_16x16x32_bf16 v[98:101], v[188:191], v[204:207], v[98:101]
	v_mfma_f32_16x16x32_bf16 v[86:89], v[180:183], v[212:215], v[86:89]
	v_mfma_f32_16x16x32_bf16 v[82:85], v[188:191], v[212:215], v[82:85]
	v_mfma_f32_16x16x32_bf16 v[70:73], v[180:183], v[222:225], v[70:73]
	v_mfma_f32_16x16x32_bf16 v[66:69], v[188:191], v[222:225], v[66:69]
	s_setprio 0
	s_barrier
	s_add_i32 s53, s53, s12
	v_lshl_add_u64 v[152:153], v[152:153], 0, s[40:41]
	s_mov_b32 m0, s53
	ds_read_b128 v[192:195], v157 offset:49152
	ds_read_b128 v[196:199], v157 offset:50176
	ds_read_b128 v[200:203], v157 offset:51200
	ds_read_b128 v[204:207], v157 offset:52224
	ds_read_b128 v[208:211], v157 offset:53248
	ds_read_b128 v[212:215], v157 offset:54272
	ds_read_b128 v[218:221], v157 offset:55296
	ds_read_b128 v[222:225], v157 offset:56320
	global_load_lds_dwordx4 v[152:153], off
	s_add_i32 m0, s53, 0x2000
	s_add_u32 s34, s34, 0x80080
	v_lshl_add_u64 v[152:153], v[226:227], 0, s[40:41]
	s_addc_u32 s35, s35, 0
	s_add_i32 s53, s62, s12
	global_load_lds_dwordx4 v[152:153], off
	v_lshl_add_u64 v[152:153], s[34:35], 0, v[132:133]
	s_mov_b32 m0, s53
	s_nop 0
	global_load_lds_dwordx4 v[152:153], off
	v_lshl_add_u64 v[152:153], s[34:35], 0, v[136:137]
	s_add_i32 m0, s53, 0x2000
	s_nop 0
	global_load_lds_dwordx4 v[152:153], off
	v_lshl_add_u64 v[152:153], v[228:229], 0, s[40:41]
	s_mov_b32 m0, s59
	s_nop 0
	global_load_lds_dwordx4 v[152:153], off
	v_lshl_add_u64 v[152:153], v[230:231], 0, s[40:41]
	s_mov_b32 m0, s60
	s_nop 0
	global_load_lds_dwordx4 v[152:153], off
	s_waitcnt vmcnt(8)
	s_waitcnt lgkmcnt(0)
	s_barrier
	s_setprio 1
	s_waitcnt lgkmcnt(0)
	v_mfma_f32_16x16x32_bf16 v[62:65], v[160:163], v[192:195], v[62:65]
	v_mfma_f32_16x16x32_bf16 v[58:61], v[168:171], v[192:195], v[58:61]
	v_mfma_f32_16x16x32_bf16 v[46:49], v[160:163], v[200:203], v[46:49]
	v_mfma_f32_16x16x32_bf16 v[42:45], v[168:171], v[200:203], v[42:45]
	v_mfma_f32_16x16x32_bf16 v[30:33], v[160:163], v[208:211], v[30:33]
	v_mfma_f32_16x16x32_bf16 v[26:29], v[168:171], v[208:211], v[26:29]
	v_mfma_f32_16x16x32_bf16 v[14:17], v[160:163], v[218:221], v[14:17]
	v_mfma_f32_16x16x32_bf16 v[10:13], v[168:171], v[218:221], v[10:13]
	s_setprio 0
	s_setprio 1
	v_mfma_f32_16x16x32_bf16 v[62:65], v[164:167], v[196:199], v[62:65]
	v_mfma_f32_16x16x32_bf16 v[58:61], v[172:175], v[196:199], v[58:61]
	v_mfma_f32_16x16x32_bf16 v[46:49], v[164:167], v[204:207], v[46:49]
	v_mfma_f32_16x16x32_bf16 v[42:45], v[172:175], v[204:207], v[42:45]
	v_mfma_f32_16x16x32_bf16 v[30:33], v[164:167], v[212:215], v[30:33]
	v_mfma_f32_16x16x32_bf16 v[26:29], v[172:175], v[212:215], v[26:29]
	v_mfma_f32_16x16x32_bf16 v[14:17], v[164:167], v[222:225], v[14:17]
	v_mfma_f32_16x16x32_bf16 v[10:13], v[172:175], v[222:225], v[10:13]
	s_setprio 0
	s_setprio 1
	v_mfma_f32_16x16x32_bf16 v[54:57], v[176:179], v[192:195], v[54:57]
	v_mfma_f32_16x16x32_bf16 v[50:53], v[184:187], v[192:195], v[50:53]
	v_mfma_f32_16x16x32_bf16 v[38:41], v[176:179], v[200:203], v[38:41]
	v_mfma_f32_16x16x32_bf16 v[34:37], v[184:187], v[200:203], v[34:37]
	v_mfma_f32_16x16x32_bf16 v[22:25], v[176:179], v[208:211], v[22:25]
	v_mfma_f32_16x16x32_bf16 v[18:21], v[184:187], v[208:211], v[18:21]
	v_mfma_f32_16x16x32_bf16 v[6:9], v[176:179], v[218:221], v[6:9]
	v_mfma_f32_16x16x32_bf16 v[2:5], v[184:187], v[218:221], v[2:5]
	s_setprio 0
	s_setprio 1
	v_mfma_f32_16x16x32_bf16 v[54:57], v[180:183], v[196:199], v[54:57]
	v_mfma_f32_16x16x32_bf16 v[50:53], v[188:191], v[196:199], v[50:53]
	v_mfma_f32_16x16x32_bf16 v[38:41], v[180:183], v[204:207], v[38:41]
	v_mfma_f32_16x16x32_bf16 v[34:37], v[188:191], v[204:207], v[34:37]
	v_mfma_f32_16x16x32_bf16 v[22:25], v[180:183], v[212:215], v[22:25]
	v_mfma_f32_16x16x32_bf16 v[18:21], v[188:191], v[212:215], v[18:21]
	v_mfma_f32_16x16x32_bf16 v[6:9], v[180:183], v[222:225], v[6:9]
	v_mfma_f32_16x16x32_bf16 v[2:5], v[188:191], v[222:225], v[2:5]
	s_setprio 0
	s_barrier
	s_add_i32 s74, s74, 2
	s_add_u32 s76, s76, 0x100
	s_addc_u32 s77, s77, 0
	s_add_u32 s36, s36, 0x100
	s_addc_u32 s52, s52, 0
	s_cmp_gt_u32 s74, 29
	s_cbranch_scc0 .LBB0_2462
	s_and_b64 vcc, exec, s[46:47]
	s_cbranch_vccz .LBB0_2465
	s_barrier

.LBB0_2629:
	ds_read_b128 v[146:149], v165
	ds_read_b128 v[150:153], v165 offset:1024
	ds_read_b128 v[168:171], v165 offset:2048
	ds_read_b128 v[172:175], v165 offset:3072
	ds_read_b128 v[176:179], v166
	ds_read_b128 v[180:183], v166 offset:1024
	ds_read_b128 v[184:187], v166 offset:2048
	ds_read_b128 v[188:191], v166 offset:3072
	s_add_u32 s34, s74, 0xfffe0080
	s_addc_u32 s35, s75, -1
	s_cmp_eq_u32 s79, 4
	s_cselect_b32 s77, s0, s35
	s_cselect_b32 s76, s1, s34
	s_cselect_b32 s35, s27, s78
	s_cselect_b32 s34, s37, s52
	v_lshl_add_u64 v[226:227], s[74:75], 0, v[138:139]
	s_add_i32 m0, s33, 0xc000
	ds_read_b128 v[192:195], v167
	ds_read_b128 v[196:199], v167 offset:1024
	ds_read_b128 v[200:203], v167 offset:2048
	ds_read_b128 v[204:207], v167 offset:3072
	ds_read_b128 v[208:211], v167 offset:4096
	ds_read_b128 v[212:215], v167 offset:5120
	ds_read_b128 v[218:221], v167 offset:6144
	ds_read_b128 v[222:225], v167 offset:7168
	global_load_lds_dwordx4 v[226:227], off
	v_lshl_add_u64 v[226:227], s[74:75], 0, v[140:141]
	s_add_i32 m0, s33, 0xe000
	s_nop 0
	global_load_lds_dwordx4 v[226:227], off
	s_waitcnt vmcnt(8)
	s_waitcnt lgkmcnt(0)
	s_barrier
	s_setprio 1
	s_waitcnt lgkmcnt(0)
	v_mfma_f32_16x16x32_bf16 v[126:129], v[146:149], v[192:195], v[126:129]
	v_mfma_f32_16x16x32_bf16 v[122:125], v[168:171], v[192:195], v[122:125]
	v_mfma_f32_16x16x32_bf16 v[114:117], v[146:149], v[200:203], v[114:117]
	v_mfma_f32_16x16x32_bf16 v[106:109], v[168:171], v[200:203], v[106:109]
	v_mfma_f32_16x16x32_bf16 v[98:101], v[146:149], v[208:211], v[98:101]
	v_mfma_f32_16x16x32_bf16 v[90:93], v[168:171], v[208:211], v[90:93]
	v_mfma_f32_16x16x32_bf16 v[82:85], v[146:149], v[218:221], v[82:85]
	v_mfma_f32_16x16x32_bf16 v[74:77], v[168:171], v[218:221], v[74:77]
	s_setprio 0
	s_setprio 1
	v_mfma_f32_16x16x32_bf16 v[126:129], v[150:153], v[196:199], v[126:129]
	v_mfma_f32_16x16x32_bf16 v[122:125], v[172:175], v[196:199], v[122:125]
	v_mfma_f32_16x16x32_bf16 v[114:117], v[150:153], v[204:207], v[114:117]
	v_mfma_f32_16x16x32_bf16 v[106:109], v[172:175], v[204:207], v[106:109]
	v_mfma_f32_16x16x32_bf16 v[98:101], v[150:153], v[212:215], v[98:101]
	v_mfma_f32_16x16x32_bf16 v[90:93], v[172:175], v[212:215], v[90:93]
	v_mfma_f32_16x16x32_bf16 v[82:85], v[150:153], v[222:225], v[82:85]
	v_mfma_f32_16x16x32_bf16 v[74:77], v[172:175], v[222:225], v[74:77]
	s_setprio 0
	s_setprio 1
	v_mfma_f32_16x16x32_bf16 v[118:121], v[176:179], v[192:195], v[118:121]
	v_mfma_f32_16x16x32_bf16 v[110:113], v[184:187], v[192:195], v[110:113]
	v_mfma_f32_16x16x32_bf16 v[102:105], v[176:179], v[200:203], v[102:105]
	v_mfma_f32_16x16x32_bf16 v[94:97], v[184:187], v[200:203], v[94:97]
	v_mfma_f32_16x16x32_bf16 v[86:89], v[176:179], v[208:211], v[86:89]
	v_mfma_f32_16x16x32_bf16 v[78:81], v[184:187], v[208:211], v[78:81]
	v_mfma_f32_16x16x32_bf16 v[70:73], v[176:179], v[218:221], v[70:73]
	v_mfma_f32_16x16x32_bf16 v[66:69], v[184:187], v[218:221], v[66:69]
	s_setprio 0
	s_setprio 1
	v_mfma_f32_16x16x32_bf16 v[118:121], v[180:183], v[196:199], v[118:121]
	v_mfma_f32_16x16x32_bf16 v[110:113], v[188:191], v[196:199], v[110:113]
	v_mfma_f32_16x16x32_bf16 v[102:105], v[180:183], v[204:207], v[102:105]
	v_mfma_f32_16x16x32_bf16 v[94:97], v[188:191], v[204:207], v[94:97]
	v_mfma_f32_16x16x32_bf16 v[86:89], v[180:183], v[212:215], v[86:89]
	v_mfma_f32_16x16x32_bf16 v[78:81], v[188:191], v[212:215], v[78:81]
	v_mfma_f32_16x16x32_bf16 v[70:73], v[180:183], v[222:225], v[70:73]
	v_mfma_f32_16x16x32_bf16 v[66:69], v[188:191], v[222:225], v[66:69]
	s_setprio 0
	s_barrier
	s_add_i32 s53, s70, s12
	v_lshl_add_u64 v[226:227], s[34:35], 0, v[132:133]
	s_mov_b32 m0, s53
	ds_read_b128 v[192:195], v167 offset:16384
	ds_read_b128 v[196:199], v167 offset:17408
	ds_read_b128 v[200:203], v167 offset:18432
	ds_read_b128 v[204:207], v167 offset:19456
	ds_read_b128 v[208:211], v167 offset:20480
	ds_read_b128 v[212:215], v167 offset:21504
	ds_read_b128 v[218:221], v167 offset:22528
	ds_read_b128 v[222:225], v167 offset:23552
	global_load_lds_dwordx4 v[226:227], off
	s_add_i32 m0, s53, 0x2000
	s_add_u32 s54, s34, 0x20000
	v_lshl_add_u64 v[228:229], s[34:35], 0, v[136:137]
	s_addc_u32 s55, s35, 0
	s_add_i32 s53, s71, s12
	global_load_lds_dwordx4 v[228:229], off
	v_lshl_add_u64 v[230:231], s[54:55], 0, v[132:133]
	s_mov_b32 m0, s53
	v_lshl_add_u64 v[232:233], s[76:77], 0, v[134:135]
	global_load_lds_dwordx4 v[230:231], off
	v_lshl_add_u64 v[230:231], s[54:55], 0, v[136:137]
	s_add_i32 m0, s53, 0x2000
	s_nop 0
	global_load_lds_dwordx4 v[230:231], off
	v_lshl_add_u64 v[230:231], s[76:77], 0, v[130:131]
	s_mov_b32 m0, s33
	s_nop 0
	global_load_lds_dwordx4 v[230:231], off
	s_mov_b32 m0, s47
	s_nop 0
	global_load_lds_dwordx4 v[232:233], off
	s_waitcnt vmcnt(8)
	s_waitcnt lgkmcnt(0)
	s_barrier
	s_setprio 1
	s_waitcnt lgkmcnt(0)
	v_mfma_f32_16x16x32_bf16 v[62:65], v[146:149], v[192:195], v[62:65]
	v_mfma_f32_16x16x32_bf16 v[58:61], v[168:171], v[192:195], v[58:61]
	v_mfma_f32_16x16x32_bf16 v[50:53], v[146:149], v[200:203], v[50:53]
	v_mfma_f32_16x16x32_bf16 v[42:45], v[168:171], v[200:203], v[42:45]
	v_mfma_f32_16x16x32_bf16 v[34:37], v[146:149], v[208:211], v[34:37]
	v_mfma_f32_16x16x32_bf16 v[26:29], v[168:171], v[208:211], v[26:29]
	v_mfma_f32_16x16x32_bf16 v[18:21], v[146:149], v[218:221], v[18:21]
	v_mfma_f32_16x16x32_bf16 v[10:13], v[168:171], v[218:221], v[10:13]
	s_setprio 0
	s_setprio 1
	v_mfma_f32_16x16x32_bf16 v[62:65], v[150:153], v[196:199], v[62:65]
	v_mfma_f32_16x16x32_bf16 v[58:61], v[172:175], v[196:199], v[58:61]
	v_mfma_f32_16x16x32_bf16 v[50:53], v[150:153], v[204:207], v[50:53]
	v_mfma_f32_16x16x32_bf16 v[42:45], v[172:175], v[204:207], v[42:45]
	v_mfma_f32_16x16x32_bf16 v[34:37], v[150:153], v[212:215], v[34:37]
	v_mfma_f32_16x16x32_bf16 v[26:29], v[172:175], v[212:215], v[26:29]
	v_mfma_f32_16x16x32_bf16 v[18:21], v[150:153], v[222:225], v[18:21]
	v_mfma_f32_16x16x32_bf16 v[10:13], v[172:175], v[222:225], v[10:13]
	s_setprio 0
	s_setprio 1
	v_mfma_f32_16x16x32_bf16 v[54:57], v[176:179], v[192:195], v[54:57]
	v_mfma_f32_16x16x32_bf16 v[46:49], v[184:187], v[192:195], v[46:49]
	v_mfma_f32_16x16x32_bf16 v[38:41], v[176:179], v[200:203], v[38:41]
	v_mfma_f32_16x16x32_bf16 v[30:33], v[184:187], v[200:203], v[30:33]
	v_mfma_f32_16x16x32_bf16 v[22:25], v[176:179], v[208:211], v[22:25]
	v_mfma_f32_16x16x32_bf16 v[14:17], v[184:187], v[208:211], v[14:17]
	v_mfma_f32_16x16x32_bf16 v[6:9], v[176:179], v[218:221], v[6:9]
	v_mfma_f32_16x16x32_bf16 v[2:5], v[184:187], v[218:221], v[2:5]
	s_setprio 0
	s_setprio 1
	v_mfma_f32_16x16x32_bf16 v[54:57], v[180:183], v[196:199], v[54:57]
	v_mfma_f32_16x16x32_bf16 v[46:49], v[188:191], v[196:199], v[46:49]
	v_mfma_f32_16x16x32_bf16 v[38:41], v[180:183], v[204:207], v[38:41]
	v_mfma_f32_16x16x32_bf16 v[30:33], v[188:191], v[204:207], v[30:33]
	v_mfma_f32_16x16x32_bf16 v[22:25], v[180:183], v[212:215], v[22:25]
	v_mfma_f32_16x16x32_bf16 v[14:17], v[188:191], v[212:215], v[14:17]
	v_mfma_f32_16x16x32_bf16 v[6:9], v[180:183], v[222:225], v[6:9]
	v_mfma_f32_16x16x32_bf16 v[2:5], v[188:191], v[222:225], v[2:5]
	s_setprio 0
	s_barrier
	s_add_i32 s53, 0, 0x18000
	s_add_i32 s62, 0, 0x1c000
	v_add_u32_e32 v172, s53, v162
	v_add_u32_e32 v188, s62, v162
	ds_read_b128 v[146:149], v172
	ds_read_b128 v[150:153], v172 offset:1024
	ds_read_b128 v[168:171], v172 offset:2048
	ds_read_b128 v[172:175], v172 offset:3072
	ds_read_b128 v[176:179], v188
	ds_read_b128 v[180:183], v188 offset:1024
	ds_read_b128 v[184:187], v188 offset:2048
	ds_read_b128 v[188:191], v188 offset:3072
	s_add_u32 s54, s76, 0x20000
	s_addc_u32 s55, s77, 0
	s_mov_b32 m0, s56
	v_lshl_add_u64 v[234:235], s[54:55], 0, v[130:131]
	ds_read_b128 v[192:195], v167 offset:32768
	ds_read_b128 v[196:199], v167 offset:33792
	ds_read_b128 v[200:203], v167 offset:34816
	ds_read_b128 v[204:207], v167 offset:35840
	ds_read_b128 v[208:211], v167 offset:36864
	ds_read_b128 v[212:215], v167 offset:37888
	ds_read_b128 v[218:221], v167 offset:38912
	ds_read_b128 v[222:225], v167 offset:39936
	global_load_lds_dwordx4 v[234:235], off
	v_lshl_add_u64 v[234:235], s[54:55], 0, v[134:135]
	s_mov_b32 m0, s57
	s_nop 0
	global_load_lds_dwordx4 v[234:235], off
	s_waitcnt vmcnt(8)
	s_waitcnt lgkmcnt(0)
	s_barrier
	s_setprio 1
	s_waitcnt lgkmcnt(0)
	v_mfma_f32_16x16x32_bf16 v[126:129], v[146:149], v[192:195], v[126:129]
	v_mfma_f32_16x16x32_bf16 v[122:125], v[168:171], v[192:195], v[122:125]
	v_mfma_f32_16x16x32_bf16 v[114:117], v[146:149], v[200:203], v[114:117]
	v_mfma_f32_16x16x32_bf16 v[106:109], v[168:171], v[200:203], v[106:109]
	v_mfma_f32_16x16x32_bf16 v[98:101], v[146:149], v[208:211], v[98:101]
	v_mfma_f32_16x16x32_bf16 v[90:93], v[168:171], v[208:211], v[90:93]
	v_mfma_f32_16x16x32_bf16 v[82:85], v[146:149], v[218:221], v[82:85]
	v_mfma_f32_16x16x32_bf16 v[74:77], v[168:171], v[218:221], v[74:77]
	s_setprio 0
	s_setprio 1
	v_mfma_f32_16x16x32_bf16 v[126:129], v[150:153], v[196:199], v[126:129]
	v_mfma_f32_16x16x32_bf16 v[122:125], v[172:175], v[196:199], v[122:125]
	v_mfma_f32_16x16x32_bf16 v[114:117], v[150:153], v[204:207], v[114:117]
	v_mfma_f32_16x16x32_bf16 v[106:109], v[172:175], v[204:207], v[106:109]
	v_mfma_f32_16x16x32_bf16 v[98:101], v[150:153], v[212:215], v[98:101]
	v_mfma_f32_16x16x32_bf16 v[90:93], v[172:175], v[212:215], v[90:93]
	v_mfma_f32_16x16x32_bf16 v[82:85], v[150:153], v[222:225], v[82:85]
	v_mfma_f32_16x16x32_bf16 v[74:77], v[172:175], v[222:225], v[74:77]
	s_setprio 0
	s_setprio 1
	v_mfma_f32_16x16x32_bf16 v[118:121], v[176:179], v[192:195], v[118:121]
	v_mfma_f32_16x16x32_bf16 v[110:113], v[184:187], v[192:195], v[110:113]
	v_mfma_f32_16x16x32_bf16 v[102:105], v[176:179], v[200:203], v[102:105]
	v_mfma_f32_16x16x32_bf16 v[94:97], v[184:187], v[200:203], v[94:97]
	v_mfma_f32_16x16x32_bf16 v[86:89], v[176:179], v[208:211], v[86:89]
	v_mfma_f32_16x16x32_bf16 v[78:81], v[184:187], v[208:211], v[78:81]
	v_mfma_f32_16x16x32_bf16 v[70:73], v[176:179], v[218:221], v[70:73]
	v_mfma_f32_16x16x32_bf16 v[66:69], v[184:187], v[218:221], v[66:69]
	s_setprio 0
	s_setprio 1
	v_mfma_f32_16x16x32_bf16 v[118:121], v[180:183], v[196:199], v[118:121]
	v_mfma_f32_16x16x32_bf16 v[110:113], v[188:191], v[196:199], v[110:113]
	v_mfma_f32_16x16x32_bf16 v[102:105], v[180:183], v[204:207], v[102:105]
	v_mfma_f32_16x16x32_bf16 v[94:97], v[188:191], v[204:207], v[94:97]
	v_mfma_f32_16x16x32_bf16 v[86:89], v[180:183], v[212:215], v[86:89]
	v_mfma_f32_16x16x32_bf16 v[78:81], v[188:191], v[212:215], v[78:81]
	v_mfma_f32_16x16x32_bf16 v[70:73], v[180:183], v[222:225], v[70:73]
	v_mfma_f32_16x16x32_bf16 v[66:69], v[188:191], v[222:225], v[66:69]
	s_setprio 0
	s_barrier
	s_add_i32 s53, s53, s12
	v_lshl_add_u64 v[226:227], v[226:227], 0, s[8:9]
	s_mov_b32 m0, s53
	ds_read_b128 v[192:195], v167 offset:49152
	ds_read_b128 v[196:199], v167 offset:50176
	ds_read_b128 v[200:203], v167 offset:51200
	ds_read_b128 v[204:207], v167 offset:52224
	ds_read_b128 v[208:211], v167 offset:53248
	ds_read_b128 v[212:215], v167 offset:54272
	ds_read_b128 v[218:221], v167 offset:55296
	ds_read_b128 v[222:225], v167 offset:56320
	global_load_lds_dwordx4 v[226:227], off
	s_add_i32 m0, s53, 0x2000
	s_add_u32 s34, s34, 0x20080
	v_lshl_add_u64 v[226:227], v[228:229], 0, s[8:9]
	s_addc_u32 s35, s35, 0
	s_add_i32 s53, s62, s12
	global_load_lds_dwordx4 v[226:227], off
	v_lshl_add_u64 v[226:227], s[34:35], 0, v[132:133]
	s_mov_b32 m0, s53
	s_nop 0
	global_load_lds_dwordx4 v[226:227], off
	v_lshl_add_u64 v[226:227], s[34:35], 0, v[136:137]
	s_add_i32 m0, s53, 0x2000
	s_nop 0
	global_load_lds_dwordx4 v[226:227], off
	v_lshl_add_u64 v[226:227], v[230:231], 0, s[8:9]
	s_mov_b32 m0, s59
	s_nop 0
	global_load_lds_dwordx4 v[226:227], off
	v_lshl_add_u64 v[226:227], v[232:233], 0, s[8:9]
	s_mov_b32 m0, s60
	s_nop 0
	global_load_lds_dwordx4 v[226:227], off
	s_waitcnt vmcnt(8)
	s_waitcnt lgkmcnt(0)
	s_barrier
	s_setprio 1
	s_waitcnt lgkmcnt(0)
	v_mfma_f32_16x16x32_bf16 v[62:65], v[146:149], v[192:195], v[62:65]
	v_mfma_f32_16x16x32_bf16 v[58:61], v[168:171], v[192:195], v[58:61]
	v_mfma_f32_16x16x32_bf16 v[50:53], v[146:149], v[200:203], v[50:53]
	v_mfma_f32_16x16x32_bf16 v[42:45], v[168:171], v[200:203], v[42:45]
	v_mfma_f32_16x16x32_bf16 v[34:37], v[146:149], v[208:211], v[34:37]
	v_mfma_f32_16x16x32_bf16 v[26:29], v[168:171], v[208:211], v[26:29]
	v_mfma_f32_16x16x32_bf16 v[18:21], v[146:149], v[218:221], v[18:21]
	v_mfma_f32_16x16x32_bf16 v[10:13], v[168:171], v[218:221], v[10:13]
	s_setprio 0
	s_setprio 1
	v_mfma_f32_16x16x32_bf16 v[62:65], v[150:153], v[196:199], v[62:65]
	v_mfma_f32_16x16x32_bf16 v[58:61], v[172:175], v[196:199], v[58:61]
	v_mfma_f32_16x16x32_bf16 v[50:53], v[150:153], v[204:207], v[50:53]
	v_mfma_f32_16x16x32_bf16 v[42:45], v[172:175], v[204:207], v[42:45]
	v_mfma_f32_16x16x32_bf16 v[34:37], v[150:153], v[212:215], v[34:37]
	v_mfma_f32_16x16x32_bf16 v[26:29], v[172:175], v[212:215], v[26:29]
	v_mfma_f32_16x16x32_bf16 v[18:21], v[150:153], v[222:225], v[18:21]
	v_mfma_f32_16x16x32_bf16 v[10:13], v[172:175], v[222:225], v[10:13]
	s_setprio 0
	s_setprio 1
	v_mfma_f32_16x16x32_bf16 v[54:57], v[176:179], v[192:195], v[54:57]
	v_mfma_f32_16x16x32_bf16 v[46:49], v[184:187], v[192:195], v[46:49]
	v_mfma_f32_16x16x32_bf16 v[38:41], v[176:179], v[200:203], v[38:41]
	v_mfma_f32_16x16x32_bf16 v[30:33], v[184:187], v[200:203], v[30:33]
	v_mfma_f32_16x16x32_bf16 v[22:25], v[176:179], v[208:211], v[22:25]
	v_mfma_f32_16x16x32_bf16 v[14:17], v[184:187], v[208:211], v[14:17]
	v_mfma_f32_16x16x32_bf16 v[6:9], v[176:179], v[218:221], v[6:9]
	v_mfma_f32_16x16x32_bf16 v[2:5], v[184:187], v[218:221], v[2:5]
	s_setprio 0
	s_setprio 1
	v_mfma_f32_16x16x32_bf16 v[54:57], v[180:183], v[196:199], v[54:57]
	v_mfma_f32_16x16x32_bf16 v[46:49], v[188:191], v[196:199], v[46:49]
	v_mfma_f32_16x16x32_bf16 v[38:41], v[180:183], v[204:207], v[38:41]
	v_mfma_f32_16x16x32_bf16 v[30:33], v[188:191], v[204:207], v[30:33]
	v_mfma_f32_16x16x32_bf16 v[22:25], v[180:183], v[212:215], v[22:25]
	v_mfma_f32_16x16x32_bf16 v[14:17], v[188:191], v[212:215], v[14:17]
	v_mfma_f32_16x16x32_bf16 v[6:9], v[180:183], v[222:225], v[6:9]
	v_mfma_f32_16x16x32_bf16 v[2:5], v[188:191], v[222:225], v[2:5]
	s_setprio 0
	s_barrier
	s_add_i32 s79, s79, 2
	s_add_u32 s74, s74, 0x100
	s_addc_u32 s75, s75, 0
	s_add_u32 s52, s52, 0x100
	s_addc_u32 s78, s78, 0
	s_cmp_gt_u32 s79, 5
	s_cbranch_scc0 .LBB0_2629
	s_and_b64 vcc, exec, s[24:25]
	s_cbranch_vccz .LBB0_2632
	s_barrier

.LBB0_2659:
	ds_read_b128 v[146:149], v1
	ds_read_b128 v[160:163], v1 offset:1024
	ds_read_b128 v[164:167], v1 offset:2048
	ds_read_b128 v[168:171], v1 offset:3072
	ds_read_b128 v[172:175], v154
	ds_read_b128 v[176:179], v154 offset:1024
	ds_read_b128 v[180:183], v154 offset:2048
	ds_read_b128 v[184:187], v154 offset:3072
	s_add_u32 s34, s74, 0xfffe0080
	s_addc_u32 s35, s75, -1
	s_cmp_eq_u32 s72, 4
	s_cselect_b32 s77, s0, s35
	s_cselect_b32 s76, s1, s34
	s_cselect_b32 s35, s27, s71
	s_cselect_b32 s34, s37, s52
	v_lshl_add_u64 v[150:151], s[74:75], 0, v[138:139]
	s_add_i32 m0, s33, 0xc000
	ds_read_b128 v[188:191], v155
	ds_read_b128 v[192:195], v155 offset:1024
	ds_read_b128 v[196:199], v155 offset:2048
	ds_read_b128 v[200:203], v155 offset:3072
	ds_read_b128 v[204:207], v155 offset:4096
	ds_read_b128 v[208:211], v155 offset:5120
	ds_read_b128 v[212:215], v155 offset:6144
	ds_read_b128 v[218:221], v155 offset:7168
	global_load_lds_dwordx4 v[150:151], off
	v_lshl_add_u64 v[150:151], s[74:75], 0, v[140:141]
	s_add_i32 m0, s33, 0xe000
	s_nop 0
	global_load_lds_dwordx4 v[150:151], off
	s_waitcnt vmcnt(8)
	s_waitcnt lgkmcnt(0)
	s_barrier
	s_setprio 1
	s_waitcnt lgkmcnt(0)
	v_mfma_f32_16x16x32_bf16 v[126:129], v[146:149], v[188:191], v[126:129]
	v_mfma_f32_16x16x32_bf16 v[122:125], v[164:167], v[188:191], v[122:125]
	v_mfma_f32_16x16x32_bf16 v[110:113], v[146:149], v[196:199], v[110:113]
	v_mfma_f32_16x16x32_bf16 v[106:109], v[164:167], v[196:199], v[106:109]
	v_mfma_f32_16x16x32_bf16 v[94:97], v[146:149], v[204:207], v[94:97]
	v_mfma_f32_16x16x32_bf16 v[90:93], v[164:167], v[204:207], v[90:93]
	v_mfma_f32_16x16x32_bf16 v[78:81], v[146:149], v[212:215], v[78:81]
	v_mfma_f32_16x16x32_bf16 v[74:77], v[164:167], v[212:215], v[74:77]
	s_setprio 0
	s_setprio 1
	v_mfma_f32_16x16x32_bf16 v[126:129], v[160:163], v[192:195], v[126:129]
	v_mfma_f32_16x16x32_bf16 v[122:125], v[168:171], v[192:195], v[122:125]
	v_mfma_f32_16x16x32_bf16 v[110:113], v[160:163], v[200:203], v[110:113]
	v_mfma_f32_16x16x32_bf16 v[106:109], v[168:171], v[200:203], v[106:109]
	v_mfma_f32_16x16x32_bf16 v[94:97], v[160:163], v[208:211], v[94:97]
	v_mfma_f32_16x16x32_bf16 v[90:93], v[168:171], v[208:211], v[90:93]
	v_mfma_f32_16x16x32_bf16 v[78:81], v[160:163], v[218:221], v[78:81]
	v_mfma_f32_16x16x32_bf16 v[74:77], v[168:171], v[218:221], v[74:77]
	s_setprio 0
	s_setprio 1
	v_mfma_f32_16x16x32_bf16 v[118:121], v[172:175], v[188:191], v[118:121]
	v_mfma_f32_16x16x32_bf16 v[114:117], v[180:183], v[188:191], v[114:117]
	v_mfma_f32_16x16x32_bf16 v[102:105], v[172:175], v[196:199], v[102:105]
	v_mfma_f32_16x16x32_bf16 v[98:101], v[180:183], v[196:199], v[98:101]
	v_mfma_f32_16x16x32_bf16 v[86:89], v[172:175], v[204:207], v[86:89]
	v_mfma_f32_16x16x32_bf16 v[82:85], v[180:183], v[204:207], v[82:85]
	v_mfma_f32_16x16x32_bf16 v[70:73], v[172:175], v[212:215], v[70:73]
	v_mfma_f32_16x16x32_bf16 v[66:69], v[180:183], v[212:215], v[66:69]
	s_setprio 0
	s_setprio 1
	v_mfma_f32_16x16x32_bf16 v[118:121], v[176:179], v[192:195], v[118:121]
	v_mfma_f32_16x16x32_bf16 v[114:117], v[184:187], v[192:195], v[114:117]
	v_mfma_f32_16x16x32_bf16 v[102:105], v[176:179], v[200:203], v[102:105]
	v_mfma_f32_16x16x32_bf16 v[98:101], v[184:187], v[200:203], v[98:101]
	v_mfma_f32_16x16x32_bf16 v[86:89], v[176:179], v[208:211], v[86:89]
	v_mfma_f32_16x16x32_bf16 v[82:85], v[184:187], v[208:211], v[82:85]
	v_mfma_f32_16x16x32_bf16 v[70:73], v[176:179], v[218:221], v[70:73]
	v_mfma_f32_16x16x32_bf16 v[66:69], v[184:187], v[218:221], v[66:69]
	s_setprio 0
	s_barrier
	s_add_i32 s53, s60, s13
	v_lshl_add_u64 v[150:151], s[34:35], 0, v[132:133]
	s_mov_b32 m0, s53
	ds_read_b128 v[188:191], v155 offset:16384
	ds_read_b128 v[192:195], v155 offset:17408
	ds_read_b128 v[196:199], v155 offset:18432
	ds_read_b128 v[200:203], v155 offset:19456
	ds_read_b128 v[204:207], v155 offset:20480
	ds_read_b128 v[208:211], v155 offset:21504
	ds_read_b128 v[212:215], v155 offset:22528
	ds_read_b128 v[218:221], v155 offset:23552
	global_load_lds_dwordx4 v[150:151], off
	s_add_i32 m0, s53, 0x2000
	s_add_u32 s62, s34, 0x20000
	v_lshl_add_u64 v[222:223], s[34:35], 0, v[136:137]
	s_addc_u32 s63, s35, 0
	s_add_i32 s53, s61, s13
	global_load_lds_dwordx4 v[222:223], off
	v_lshl_add_u64 v[224:225], s[62:63], 0, v[132:133]
	s_mov_b32 m0, s53
	v_lshl_add_u64 v[226:227], s[76:77], 0, v[134:135]
	global_load_lds_dwordx4 v[224:225], off
	v_lshl_add_u64 v[224:225], s[62:63], 0, v[136:137]
	s_add_i32 m0, s53, 0x2000
	s_nop 0
	global_load_lds_dwordx4 v[224:225], off
	v_lshl_add_u64 v[224:225], s[76:77], 0, v[130:131]
	s_mov_b32 m0, s33
	s_nop 0
	global_load_lds_dwordx4 v[224:225], off
	s_mov_b32 m0, s47
	s_nop 0
	global_load_lds_dwordx4 v[226:227], off
	s_waitcnt vmcnt(8)
	s_waitcnt lgkmcnt(0)
	s_barrier
	s_setprio 1
	s_waitcnt lgkmcnt(0)
	v_mfma_f32_16x16x32_bf16 v[62:65], v[146:149], v[188:191], v[62:65]
	v_mfma_f32_16x16x32_bf16 v[58:61], v[164:167], v[188:191], v[58:61]
	v_mfma_f32_16x16x32_bf16 v[50:53], v[146:149], v[196:199], v[50:53]
	v_mfma_f32_16x16x32_bf16 v[42:45], v[164:167], v[196:199], v[42:45]
	v_mfma_f32_16x16x32_bf16 v[34:37], v[146:149], v[204:207], v[34:37]
	v_mfma_f32_16x16x32_bf16 v[26:29], v[164:167], v[204:207], v[26:29]
	v_mfma_f32_16x16x32_bf16 v[18:21], v[146:149], v[212:215], v[18:21]
	v_mfma_f32_16x16x32_bf16 v[10:13], v[164:167], v[212:215], v[10:13]
	s_setprio 0
	s_setprio 1
	v_mfma_f32_16x16x32_bf16 v[62:65], v[160:163], v[192:195], v[62:65]
	v_mfma_f32_16x16x32_bf16 v[58:61], v[168:171], v[192:195], v[58:61]
	v_mfma_f32_16x16x32_bf16 v[50:53], v[160:163], v[200:203], v[50:53]
	v_mfma_f32_16x16x32_bf16 v[42:45], v[168:171], v[200:203], v[42:45]
	v_mfma_f32_16x16x32_bf16 v[34:37], v[160:163], v[208:211], v[34:37]
	v_mfma_f32_16x16x32_bf16 v[26:29], v[168:171], v[208:211], v[26:29]
	v_mfma_f32_16x16x32_bf16 v[18:21], v[160:163], v[218:221], v[18:21]
	v_mfma_f32_16x16x32_bf16 v[10:13], v[168:171], v[218:221], v[10:13]
	s_setprio 0
	s_setprio 1
	v_mfma_f32_16x16x32_bf16 v[54:57], v[172:175], v[188:191], v[54:57]
	v_mfma_f32_16x16x32_bf16 v[46:49], v[180:183], v[188:191], v[46:49]
	v_mfma_f32_16x16x32_bf16 v[38:41], v[172:175], v[196:199], v[38:41]
	v_mfma_f32_16x16x32_bf16 v[30:33], v[180:183], v[196:199], v[30:33]
	v_mfma_f32_16x16x32_bf16 v[22:25], v[172:175], v[204:207], v[22:25]
	v_mfma_f32_16x16x32_bf16 v[14:17], v[180:183], v[204:207], v[14:17]
	v_mfma_f32_16x16x32_bf16 v[6:9], v[172:175], v[212:215], v[6:9]
	v_mfma_f32_16x16x32_bf16 v[2:5], v[180:183], v[212:215], v[2:5]
	s_setprio 0
	s_setprio 1
	v_mfma_f32_16x16x32_bf16 v[54:57], v[176:179], v[192:195], v[54:57]
	v_mfma_f32_16x16x32_bf16 v[46:49], v[184:187], v[192:195], v[46:49]
	v_mfma_f32_16x16x32_bf16 v[38:41], v[176:179], v[200:203], v[38:41]
	v_mfma_f32_16x16x32_bf16 v[30:33], v[184:187], v[200:203], v[30:33]
	v_mfma_f32_16x16x32_bf16 v[22:25], v[176:179], v[208:211], v[22:25]
	v_mfma_f32_16x16x32_bf16 v[14:17], v[184:187], v[208:211], v[14:17]
	v_mfma_f32_16x16x32_bf16 v[6:9], v[176:179], v[218:221], v[6:9]
	v_mfma_f32_16x16x32_bf16 v[2:5], v[184:187], v[218:221], v[2:5]
	s_setprio 0
	s_barrier
	s_add_i32 s53, 0, 0x18000
	v_add_u32_e32 v156, s53, v153
	s_add_i32 s66, 0, 0x1c000
	ds_read_b128 v[146:149], v156
	ds_read_b128 v[160:163], v156 offset:1024
	ds_read_b128 v[164:167], v156 offset:2048
	ds_read_b128 v[168:171], v156 offset:3072
	v_add_u32_e32 v156, s66, v153
	ds_read_b128 v[172:175], v156
	ds_read_b128 v[176:179], v156 offset:1024
	ds_read_b128 v[180:183], v156 offset:2048
	ds_read_b128 v[184:187], v156 offset:3072
	s_add_u32 s62, s76, 0x20000
	s_addc_u32 s63, s77, 0
	s_mov_b32 m0, s54
	v_lshl_add_u64 v[228:229], s[62:63], 0, v[130:131]
	ds_read_b128 v[188:191], v155 offset:32768
	ds_read_b128 v[192:195], v155 offset:33792
	ds_read_b128 v[196:199], v155 offset:34816
	ds_read_b128 v[200:203], v155 offset:35840
	ds_read_b128 v[204:207], v155 offset:36864
	ds_read_b128 v[208:211], v155 offset:37888
	ds_read_b128 v[212:215], v155 offset:38912
	ds_read_b128 v[218:221], v155 offset:39936
	global_load_lds_dwordx4 v[228:229], off
	v_lshl_add_u64 v[228:229], s[62:63], 0, v[134:135]
	s_mov_b32 m0, s55
	s_nop 0
	global_load_lds_dwordx4 v[228:229], off
	s_waitcnt vmcnt(8)
	s_waitcnt lgkmcnt(0)
	s_barrier
	s_setprio 1
	s_waitcnt lgkmcnt(0)
	v_mfma_f32_16x16x32_bf16 v[126:129], v[146:149], v[188:191], v[126:129]
	v_mfma_f32_16x16x32_bf16 v[122:125], v[164:167], v[188:191], v[122:125]
	v_mfma_f32_16x16x32_bf16 v[110:113], v[146:149], v[196:199], v[110:113]
	v_mfma_f32_16x16x32_bf16 v[106:109], v[164:167], v[196:199], v[106:109]
	v_mfma_f32_16x16x32_bf16 v[94:97], v[146:149], v[204:207], v[94:97]
	v_mfma_f32_16x16x32_bf16 v[90:93], v[164:167], v[204:207], v[90:93]
	v_mfma_f32_16x16x32_bf16 v[78:81], v[146:149], v[212:215], v[78:81]
	v_mfma_f32_16x16x32_bf16 v[74:77], v[164:167], v[212:215], v[74:77]
	s_setprio 0
	s_setprio 1
	v_mfma_f32_16x16x32_bf16 v[126:129], v[160:163], v[192:195], v[126:129]
	v_mfma_f32_16x16x32_bf16 v[122:125], v[168:171], v[192:195], v[122:125]
	v_mfma_f32_16x16x32_bf16 v[110:113], v[160:163], v[200:203], v[110:113]
	v_mfma_f32_16x16x32_bf16 v[106:109], v[168:171], v[200:203], v[106:109]
	v_mfma_f32_16x16x32_bf16 v[94:97], v[160:163], v[208:211], v[94:97]
	v_mfma_f32_16x16x32_bf16 v[90:93], v[168:171], v[208:211], v[90:93]
	v_mfma_f32_16x16x32_bf16 v[78:81], v[160:163], v[218:221], v[78:81]
	v_mfma_f32_16x16x32_bf16 v[74:77], v[168:171], v[218:221], v[74:77]
	s_setprio 0
	s_setprio 1
	v_mfma_f32_16x16x32_bf16 v[118:121], v[172:175], v[188:191], v[118:121]
	v_mfma_f32_16x16x32_bf16 v[114:117], v[180:183], v[188:191], v[114:117]
	v_mfma_f32_16x16x32_bf16 v[102:105], v[172:175], v[196:199], v[102:105]
	v_mfma_f32_16x16x32_bf16 v[98:101], v[180:183], v[196:199], v[98:101]
	v_mfma_f32_16x16x32_bf16 v[86:89], v[172:175], v[204:207], v[86:89]
	v_mfma_f32_16x16x32_bf16 v[82:85], v[180:183], v[204:207], v[82:85]
	v_mfma_f32_16x16x32_bf16 v[70:73], v[172:175], v[212:215], v[70:73]
	v_mfma_f32_16x16x32_bf16 v[66:69], v[180:183], v[212:215], v[66:69]
	s_setprio 0
	s_setprio 1
	v_mfma_f32_16x16x32_bf16 v[118:121], v[176:179], v[192:195], v[118:121]
	v_mfma_f32_16x16x32_bf16 v[114:117], v[184:187], v[192:195], v[114:117]
	v_mfma_f32_16x16x32_bf16 v[102:105], v[176:179], v[200:203], v[102:105]
	v_mfma_f32_16x16x32_bf16 v[98:101], v[184:187], v[200:203], v[98:101]
	v_mfma_f32_16x16x32_bf16 v[86:89], v[176:179], v[208:211], v[86:89]
	v_mfma_f32_16x16x32_bf16 v[82:85], v[184:187], v[208:211], v[82:85]
	v_mfma_f32_16x16x32_bf16 v[70:73], v[176:179], v[218:221], v[70:73]
	v_mfma_f32_16x16x32_bf16 v[66:69], v[184:187], v[218:221], v[66:69]
	s_setprio 0
	s_barrier
	s_add_i32 s53, s53, s13
	v_lshl_add_u64 v[150:151], v[150:151], 0, s[8:9]
	s_mov_b32 m0, s53
	ds_read_b128 v[188:191], v155 offset:49152
	ds_read_b128 v[192:195], v155 offset:50176
	ds_read_b128 v[196:199], v155 offset:51200
	ds_read_b128 v[200:203], v155 offset:52224
	ds_read_b128 v[204:207], v155 offset:53248
	ds_read_b128 v[208:211], v155 offset:54272
	ds_read_b128 v[212:215], v155 offset:55296
	ds_read_b128 v[218:221], v155 offset:56320
	global_load_lds_dwordx4 v[150:151], off
	s_add_i32 m0, s53, 0x2000
	s_add_u32 s34, s34, 0x20080
	v_lshl_add_u64 v[150:151], v[222:223], 0, s[8:9]
	s_addc_u32 s35, s35, 0
	s_add_i32 s53, s66, s13
	global_load_lds_dwordx4 v[150:151], off
	v_lshl_add_u64 v[150:151], s[34:35], 0, v[132:133]
	s_mov_b32 m0, s53
	s_nop 0
	global_load_lds_dwordx4 v[150:151], off
	v_lshl_add_u64 v[150:151], s[34:35], 0, v[136:137]
	s_add_i32 m0, s53, 0x2000
	s_nop 0
	global_load_lds_dwordx4 v[150:151], off
	v_lshl_add_u64 v[150:151], v[224:225], 0, s[8:9]
	s_mov_b32 m0, s57
	s_nop 0
	global_load_lds_dwordx4 v[150:151], off
	v_lshl_add_u64 v[150:151], v[226:227], 0, s[8:9]
	s_mov_b32 m0, s58
	s_nop 0
	global_load_lds_dwordx4 v[150:151], off
	s_waitcnt vmcnt(8)
	s_waitcnt lgkmcnt(0)
	s_barrier
	s_setprio 1
	s_waitcnt lgkmcnt(0)
	v_mfma_f32_16x16x32_bf16 v[62:65], v[146:149], v[188:191], v[62:65]
	v_mfma_f32_16x16x32_bf16 v[58:61], v[164:167], v[188:191], v[58:61]
	v_mfma_f32_16x16x32_bf16 v[50:53], v[146:149], v[196:199], v[50:53]
	v_mfma_f32_16x16x32_bf16 v[42:45], v[164:167], v[196:199], v[42:45]
	v_mfma_f32_16x16x32_bf16 v[34:37], v[146:149], v[204:207], v[34:37]
	v_mfma_f32_16x16x32_bf16 v[26:29], v[164:167], v[204:207], v[26:29]
	v_mfma_f32_16x16x32_bf16 v[18:21], v[146:149], v[212:215], v[18:21]
	v_mfma_f32_16x16x32_bf16 v[10:13], v[164:167], v[212:215], v[10:13]
	s_setprio 0
	s_setprio 1
	v_mfma_f32_16x16x32_bf16 v[62:65], v[160:163], v[192:195], v[62:65]
	v_mfma_f32_16x16x32_bf16 v[58:61], v[168:171], v[192:195], v[58:61]
	v_mfma_f32_16x16x32_bf16 v[50:53], v[160:163], v[200:203], v[50:53]
	v_mfma_f32_16x16x32_bf16 v[42:45], v[168:171], v[200:203], v[42:45]
	v_mfma_f32_16x16x32_bf16 v[34:37], v[160:163], v[208:211], v[34:37]
	v_mfma_f32_16x16x32_bf16 v[26:29], v[168:171], v[208:211], v[26:29]
	v_mfma_f32_16x16x32_bf16 v[18:21], v[160:163], v[218:221], v[18:21]
	v_mfma_f32_16x16x32_bf16 v[10:13], v[168:171], v[218:221], v[10:13]
	s_setprio 0
	s_setprio 1
	v_mfma_f32_16x16x32_bf16 v[54:57], v[172:175], v[188:191], v[54:57]
	v_mfma_f32_16x16x32_bf16 v[46:49], v[180:183], v[188:191], v[46:49]
	v_mfma_f32_16x16x32_bf16 v[38:41], v[172:175], v[196:199], v[38:41]
	v_mfma_f32_16x16x32_bf16 v[30:33], v[180:183], v[196:199], v[30:33]
	v_mfma_f32_16x16x32_bf16 v[22:25], v[172:175], v[204:207], v[22:25]
	v_mfma_f32_16x16x32_bf16 v[14:17], v[180:183], v[204:207], v[14:17]
	v_mfma_f32_16x16x32_bf16 v[6:9], v[172:175], v[212:215], v[6:9]
	v_mfma_f32_16x16x32_bf16 v[2:5], v[180:183], v[212:215], v[2:5]
	s_setprio 0
	s_setprio 1
	v_mfma_f32_16x16x32_bf16 v[54:57], v[176:179], v[192:195], v[54:57]
	v_mfma_f32_16x16x32_bf16 v[46:49], v[184:187], v[192:195], v[46:49]
	v_mfma_f32_16x16x32_bf16 v[38:41], v[176:179], v[200:203], v[38:41]
	v_mfma_f32_16x16x32_bf16 v[30:33], v[184:187], v[200:203], v[30:33]
	v_mfma_f32_16x16x32_bf16 v[22:25], v[176:179], v[208:211], v[22:25]
	v_mfma_f32_16x16x32_bf16 v[14:17], v[184:187], v[208:211], v[14:17]
	v_mfma_f32_16x16x32_bf16 v[6:9], v[176:179], v[218:221], v[6:9]
	v_mfma_f32_16x16x32_bf16 v[2:5], v[184:187], v[218:221], v[2:5]
	s_setprio 0
	s_barrier
	s_add_i32 s72, s72, 2
	s_add_u32 s74, s74, 0x100
	s_addc_u32 s75, s75, 0
	s_add_u32 s52, s52, 0x100
	s_addc_u32 s71, s71, 0
	s_cmp_gt_u32 s72, 5
	s_cbranch_scc0 .LBB0_2659
	s_and_b64 vcc, exec, s[24:25]
	s_cbranch_vccz .LBB0_2662
	s_barrier

.LBB0_2938:
	ds_read_b128 v[130:133], v174
	ds_read_b128 v[134:137], v174 offset:1024
	ds_read_b128 v[138:141], v174 offset:2048
	ds_read_b128 v[158:161], v174 offset:3072
	ds_read_b128 v[162:165], v175
	ds_read_b128 v[166:169], v175 offset:1024
	ds_read_b128 v[178:181], v175 offset:2048
	ds_read_b128 v[182:185], v175 offset:3072
	s_add_u32 s34, s46, 0xfff80080
	s_addc_u32 s35, s47, -1
	s_cmp_eq_u32 s72, 28
	s_cselect_b32 s69, s0, s35
	s_cselect_b32 s68, s1, s34
	s_cselect_b32 s35, s37, s71
	s_cselect_b32 s34, s39, s70
	v_lshl_add_u64 v[170:171], s[46:47], 0, v[150:151]
	s_add_i32 m0, s33, 0xc000
	ds_read_b128 v[186:189], v176
	ds_read_b128 v[190:193], v176 offset:1024
	ds_read_b128 v[194:197], v176 offset:2048
	ds_read_b128 v[198:201], v176 offset:3072
	ds_read_b128 v[202:205], v176 offset:4096
	ds_read_b128 v[206:209], v176 offset:5120
	ds_read_b128 v[210:213], v176 offset:6144
	ds_read_b128 v[218:221], v176 offset:7168
	global_load_lds_dwordx4 v[170:171], off
	v_lshl_add_u64 v[170:171], s[46:47], 0, v[152:153]
	s_add_i32 m0, s33, 0xe000
	s_nop 0
	global_load_lds_dwordx4 v[170:171], off
	s_waitcnt vmcnt(8)
	s_waitcnt lgkmcnt(0)
	s_barrier
	s_setprio 1
	s_waitcnt lgkmcnt(0)
	v_mfma_f32_16x16x32_bf16 v[126:129], v[130:133], v[186:189], v[126:129]
	v_mfma_f32_16x16x32_bf16 v[122:125], v[138:141], v[186:189], v[122:125]
	v_mfma_f32_16x16x32_bf16 v[110:113], v[130:133], v[194:197], v[110:113]
	v_mfma_f32_16x16x32_bf16 v[106:109], v[138:141], v[194:197], v[106:109]
	v_mfma_f32_16x16x32_bf16 v[94:97], v[130:133], v[202:205], v[94:97]
	v_mfma_f32_16x16x32_bf16 v[90:93], v[138:141], v[202:205], v[90:93]
	v_mfma_f32_16x16x32_bf16 v[78:81], v[130:133], v[210:213], v[78:81]
	v_mfma_f32_16x16x32_bf16 v[74:77], v[138:141], v[210:213], v[74:77]
	s_setprio 0
	s_setprio 1
	v_mfma_f32_16x16x32_bf16 v[126:129], v[134:137], v[190:193], v[126:129]
	v_mfma_f32_16x16x32_bf16 v[122:125], v[158:161], v[190:193], v[122:125]
	v_mfma_f32_16x16x32_bf16 v[110:113], v[134:137], v[198:201], v[110:113]
	v_mfma_f32_16x16x32_bf16 v[106:109], v[158:161], v[198:201], v[106:109]
	v_mfma_f32_16x16x32_bf16 v[94:97], v[134:137], v[206:209], v[94:97]
	v_mfma_f32_16x16x32_bf16 v[90:93], v[158:161], v[206:209], v[90:93]
	v_mfma_f32_16x16x32_bf16 v[78:81], v[134:137], v[218:221], v[78:81]
	v_mfma_f32_16x16x32_bf16 v[74:77], v[158:161], v[218:221], v[74:77]
	s_setprio 0
	s_setprio 1
	v_mfma_f32_16x16x32_bf16 v[118:121], v[162:165], v[186:189], v[118:121]
	v_mfma_f32_16x16x32_bf16 v[114:117], v[178:181], v[186:189], v[114:117]
	v_mfma_f32_16x16x32_bf16 v[102:105], v[162:165], v[194:197], v[102:105]
	v_mfma_f32_16x16x32_bf16 v[98:101], v[178:181], v[194:197], v[98:101]
	v_mfma_f32_16x16x32_bf16 v[86:89], v[162:165], v[202:205], v[86:89]
	v_mfma_f32_16x16x32_bf16 v[82:85], v[178:181], v[202:205], v[82:85]
	v_mfma_f32_16x16x32_bf16 v[70:73], v[162:165], v[210:213], v[70:73]
	v_mfma_f32_16x16x32_bf16 v[66:69], v[178:181], v[210:213], v[66:69]
	s_setprio 0
	s_setprio 1
	v_mfma_f32_16x16x32_bf16 v[118:121], v[166:169], v[190:193], v[118:121]
	v_mfma_f32_16x16x32_bf16 v[114:117], v[182:185], v[190:193], v[114:117]
	v_mfma_f32_16x16x32_bf16 v[102:105], v[166:169], v[198:201], v[102:105]
	v_mfma_f32_16x16x32_bf16 v[98:101], v[182:185], v[198:201], v[98:101]
	v_mfma_f32_16x16x32_bf16 v[86:89], v[166:169], v[206:209], v[86:89]
	v_mfma_f32_16x16x32_bf16 v[82:85], v[182:185], v[206:209], v[82:85]
	v_mfma_f32_16x16x32_bf16 v[70:73], v[166:169], v[218:221], v[70:73]
	v_mfma_f32_16x16x32_bf16 v[66:69], v[182:185], v[218:221], v[66:69]
	s_setprio 0
	s_barrier
	s_add_i32 s62, s58, s31
	v_lshl_add_u64 v[170:171], s[34:35], 0, v[144:145]
	s_mov_b32 m0, s62
	ds_read_b128 v[186:189], v176 offset:16384
	ds_read_b128 v[190:193], v176 offset:17408
	ds_read_b128 v[194:197], v176 offset:18432
	ds_read_b128 v[198:201], v176 offset:19456
	ds_read_b128 v[202:205], v176 offset:20480
	ds_read_b128 v[206:209], v176 offset:21504
	ds_read_b128 v[210:213], v176 offset:22528
	ds_read_b128 v[218:221], v176 offset:23552
	global_load_lds_dwordx4 v[170:171], off
	s_add_i32 m0, s62, 0x2000
	s_add_u32 s62, s34, 0x80000
	v_lshl_add_u64 v[214:215], s[34:35], 0, v[148:149]
	s_addc_u32 s63, s35, 0
	s_add_i32 s66, s59, s31
	global_load_lds_dwordx4 v[214:215], off
	v_lshl_add_u64 v[222:223], s[62:63], 0, v[144:145]
	s_mov_b32 m0, s66
	v_lshl_add_u64 v[224:225], s[68:69], 0, v[146:147]
	global_load_lds_dwordx4 v[222:223], off
	v_lshl_add_u64 v[222:223], s[62:63], 0, v[148:149]
	s_add_i32 m0, s66, 0x2000
	s_nop 0
	global_load_lds_dwordx4 v[222:223], off
	v_lshl_add_u64 v[222:223], s[68:69], 0, v[142:143]
	s_mov_b32 m0, s33
	s_nop 0
	global_load_lds_dwordx4 v[222:223], off
	s_mov_b32 m0, s45
	s_nop 0
	global_load_lds_dwordx4 v[224:225], off
	s_waitcnt vmcnt(8)
	s_waitcnt lgkmcnt(0)
	s_barrier
	s_setprio 1
	s_waitcnt lgkmcnt(0)
	v_mfma_f32_16x16x32_bf16 v[62:65], v[130:133], v[186:189], v[62:65]
	v_mfma_f32_16x16x32_bf16 v[58:61], v[138:141], v[186:189], v[58:61]
	v_mfma_f32_16x16x32_bf16 v[50:53], v[130:133], v[194:197], v[50:53]
	v_mfma_f32_16x16x32_bf16 v[42:45], v[138:141], v[194:197], v[42:45]
	v_mfma_f32_16x16x32_bf16 v[38:41], v[130:133], v[202:205], v[38:41]
	v_mfma_f32_16x16x32_bf16 v[34:37], v[138:141], v[202:205], v[34:37]
	v_mfma_f32_16x16x32_bf16 v[14:17], v[130:133], v[210:213], v[14:17]
	v_mfma_f32_16x16x32_bf16 v[10:13], v[138:141], v[210:213], v[10:13]
	s_setprio 0
	s_setprio 1
	v_mfma_f32_16x16x32_bf16 v[62:65], v[134:137], v[190:193], v[62:65]
	v_mfma_f32_16x16x32_bf16 v[58:61], v[158:161], v[190:193], v[58:61]
	v_mfma_f32_16x16x32_bf16 v[50:53], v[134:137], v[198:201], v[50:53]
	v_mfma_f32_16x16x32_bf16 v[42:45], v[158:161], v[198:201], v[42:45]
	v_mfma_f32_16x16x32_bf16 v[38:41], v[134:137], v[206:209], v[38:41]
	v_mfma_f32_16x16x32_bf16 v[34:37], v[158:161], v[206:209], v[34:37]
	v_mfma_f32_16x16x32_bf16 v[14:17], v[134:137], v[218:221], v[14:17]
	v_mfma_f32_16x16x32_bf16 v[10:13], v[158:161], v[218:221], v[10:13]
	s_setprio 0
	s_setprio 1
	v_mfma_f32_16x16x32_bf16 v[54:57], v[162:165], v[186:189], v[54:57]
	v_mfma_f32_16x16x32_bf16 v[46:49], v[178:181], v[186:189], v[46:49]
	v_mfma_f32_16x16x32_bf16 v[30:33], v[162:165], v[194:197], v[30:33]
	v_mfma_f32_16x16x32_bf16 v[26:29], v[178:181], v[194:197], v[26:29]
	v_mfma_f32_16x16x32_bf16 v[22:25], v[162:165], v[202:205], v[22:25]
	v_mfma_f32_16x16x32_bf16 v[18:21], v[178:181], v[202:205], v[18:21]
	v_mfma_f32_16x16x32_bf16 v[6:9], v[162:165], v[210:213], v[6:9]
	v_mfma_f32_16x16x32_bf16 v[2:5], v[178:181], v[210:213], v[2:5]
	s_setprio 0
	s_setprio 1
	v_mfma_f32_16x16x32_bf16 v[54:57], v[166:169], v[190:193], v[54:57]
	v_mfma_f32_16x16x32_bf16 v[46:49], v[182:185], v[190:193], v[46:49]
	v_mfma_f32_16x16x32_bf16 v[30:33], v[166:169], v[198:201], v[30:33]
	v_mfma_f32_16x16x32_bf16 v[26:29], v[182:185], v[198:201], v[26:29]
	v_mfma_f32_16x16x32_bf16 v[22:25], v[166:169], v[206:209], v[22:25]
	v_mfma_f32_16x16x32_bf16 v[18:21], v[182:185], v[206:209], v[18:21]
	v_mfma_f32_16x16x32_bf16 v[6:9], v[166:169], v[218:221], v[6:9]
	v_mfma_f32_16x16x32_bf16 v[2:5], v[182:185], v[218:221], v[2:5]
	s_setprio 0
	s_barrier
	s_add_i32 s66, 0, 0x18000
	s_add_i32 s67, 0, 0x1c000
	v_add_u32_e32 v158, s66, v172
	v_add_u32_e32 v177, s67, v172
	ds_read_b128 v[130:133], v158
	ds_read_b128 v[134:137], v158 offset:1024
	ds_read_b128 v[138:141], v158 offset:2048
	ds_read_b128 v[158:161], v158 offset:3072
	ds_read_b128 v[162:165], v177
	ds_read_b128 v[166:169], v177 offset:1024
	ds_read_b128 v[178:181], v177 offset:2048
	ds_read_b128 v[182:185], v177 offset:3072
	s_add_u32 s62, s68, 0x80000
	s_addc_u32 s63, s69, 0
	s_mov_b32 m0, s52
	v_lshl_add_u64 v[226:227], s[62:63], 0, v[142:143]
	ds_read_b128 v[186:189], v176 offset:32768
	ds_read_b128 v[190:193], v176 offset:33792
	ds_read_b128 v[194:197], v176 offset:34816
	ds_read_b128 v[198:201], v176 offset:35840
	ds_read_b128 v[202:205], v176 offset:36864
	ds_read_b128 v[206:209], v176 offset:37888
	ds_read_b128 v[210:213], v176 offset:38912
	ds_read_b128 v[218:221], v176 offset:39936
	global_load_lds_dwordx4 v[226:227], off
	v_lshl_add_u64 v[226:227], s[62:63], 0, v[146:147]
	s_mov_b32 m0, s53
	s_nop 0
	global_load_lds_dwordx4 v[226:227], off
	s_waitcnt vmcnt(8)
	s_waitcnt lgkmcnt(0)
	s_barrier
	s_setprio 1
	s_waitcnt lgkmcnt(0)
	v_mfma_f32_16x16x32_bf16 v[126:129], v[130:133], v[186:189], v[126:129]
	v_mfma_f32_16x16x32_bf16 v[122:125], v[138:141], v[186:189], v[122:125]
	v_mfma_f32_16x16x32_bf16 v[110:113], v[130:133], v[194:197], v[110:113]
	v_mfma_f32_16x16x32_bf16 v[106:109], v[138:141], v[194:197], v[106:109]
	v_mfma_f32_16x16x32_bf16 v[94:97], v[130:133], v[202:205], v[94:97]
	v_mfma_f32_16x16x32_bf16 v[90:93], v[138:141], v[202:205], v[90:93]
	v_mfma_f32_16x16x32_bf16 v[78:81], v[130:133], v[210:213], v[78:81]
	v_mfma_f32_16x16x32_bf16 v[74:77], v[138:141], v[210:213], v[74:77]
	s_setprio 0
	s_setprio 1
	v_mfma_f32_16x16x32_bf16 v[126:129], v[134:137], v[190:193], v[126:129]
	v_mfma_f32_16x16x32_bf16 v[122:125], v[158:161], v[190:193], v[122:125]
	v_mfma_f32_16x16x32_bf16 v[110:113], v[134:137], v[198:201], v[110:113]
	v_mfma_f32_16x16x32_bf16 v[106:109], v[158:161], v[198:201], v[106:109]
	v_mfma_f32_16x16x32_bf16 v[94:97], v[134:137], v[206:209], v[94:97]
	v_mfma_f32_16x16x32_bf16 v[90:93], v[158:161], v[206:209], v[90:93]
	v_mfma_f32_16x16x32_bf16 v[78:81], v[134:137], v[218:221], v[78:81]
	v_mfma_f32_16x16x32_bf16 v[74:77], v[158:161], v[218:221], v[74:77]
	s_setprio 0
	s_setprio 1
	v_mfma_f32_16x16x32_bf16 v[118:121], v[162:165], v[186:189], v[118:121]
	v_mfma_f32_16x16x32_bf16 v[114:117], v[178:181], v[186:189], v[114:117]
	v_mfma_f32_16x16x32_bf16 v[102:105], v[162:165], v[194:197], v[102:105]
	v_mfma_f32_16x16x32_bf16 v[98:101], v[178:181], v[194:197], v[98:101]
	v_mfma_f32_16x16x32_bf16 v[86:89], v[162:165], v[202:205], v[86:89]
	v_mfma_f32_16x16x32_bf16 v[82:85], v[178:181], v[202:205], v[82:85]
	v_mfma_f32_16x16x32_bf16 v[70:73], v[162:165], v[210:213], v[70:73]
	v_mfma_f32_16x16x32_bf16 v[66:69], v[178:181], v[210:213], v[66:69]
	s_setprio 0
	s_setprio 1
	v_mfma_f32_16x16x32_bf16 v[118:121], v[166:169], v[190:193], v[118:121]
	v_mfma_f32_16x16x32_bf16 v[114:117], v[182:185], v[190:193], v[114:117]
	v_mfma_f32_16x16x32_bf16 v[102:105], v[166:169], v[198:201], v[102:105]
	v_mfma_f32_16x16x32_bf16 v[98:101], v[182:185], v[198:201], v[98:101]
	v_mfma_f32_16x16x32_bf16 v[86:89], v[166:169], v[206:209], v[86:89]
	v_mfma_f32_16x16x32_bf16 v[82:85], v[182:185], v[206:209], v[82:85]
	v_mfma_f32_16x16x32_bf16 v[70:73], v[166:169], v[218:221], v[70:73]
	v_mfma_f32_16x16x32_bf16 v[66:69], v[182:185], v[218:221], v[66:69]
	s_setprio 0
	s_barrier
	s_add_i32 s62, s66, s31
	v_lshl_add_u64 v[170:171], v[170:171], 0, s[24:25]
	s_mov_b32 m0, s62
	ds_read_b128 v[186:189], v176 offset:49152
	ds_read_b128 v[190:193], v176 offset:50176
	ds_read_b128 v[194:197], v176 offset:51200
	ds_read_b128 v[198:201], v176 offset:52224
	ds_read_b128 v[202:205], v176 offset:53248
	ds_read_b128 v[206:209], v176 offset:54272
	ds_read_b128 v[210:213], v176 offset:55296
	ds_read_b128 v[218:221], v176 offset:56320
	global_load_lds_dwordx4 v[170:171], off
	s_add_i32 m0, s62, 0x2000
	s_add_u32 s34, s34, 0x80080
	v_lshl_add_u64 v[170:171], v[214:215], 0, s[24:25]
	s_addc_u32 s35, s35, 0
	s_add_i32 s62, s67, s31
	global_load_lds_dwordx4 v[170:171], off
	v_lshl_add_u64 v[170:171], s[34:35], 0, v[144:145]
	s_mov_b32 m0, s62
	s_nop 0
	global_load_lds_dwordx4 v[170:171], off
	v_lshl_add_u64 v[170:171], s[34:35], 0, v[148:149]
	s_add_i32 m0, s62, 0x2000
	s_nop 0
	global_load_lds_dwordx4 v[170:171], off
	v_lshl_add_u64 v[170:171], v[222:223], 0, s[24:25]
	s_mov_b32 m0, s55
	s_nop 0
	global_load_lds_dwordx4 v[170:171], off
	v_lshl_add_u64 v[170:171], v[224:225], 0, s[24:25]
	s_mov_b32 m0, s56
	s_nop 0
	global_load_lds_dwordx4 v[170:171], off
	s_waitcnt vmcnt(8)
	s_waitcnt lgkmcnt(0)
	s_barrier
	s_setprio 1
	s_waitcnt lgkmcnt(0)
	v_mfma_f32_16x16x32_bf16 v[62:65], v[130:133], v[186:189], v[62:65]
	v_mfma_f32_16x16x32_bf16 v[58:61], v[138:141], v[186:189], v[58:61]
	v_mfma_f32_16x16x32_bf16 v[50:53], v[130:133], v[194:197], v[50:53]
	v_mfma_f32_16x16x32_bf16 v[42:45], v[138:141], v[194:197], v[42:45]
	v_mfma_f32_16x16x32_bf16 v[38:41], v[130:133], v[202:205], v[38:41]
	v_mfma_f32_16x16x32_bf16 v[34:37], v[138:141], v[202:205], v[34:37]
	v_mfma_f32_16x16x32_bf16 v[14:17], v[130:133], v[210:213], v[14:17]
	v_mfma_f32_16x16x32_bf16 v[10:13], v[138:141], v[210:213], v[10:13]
	s_setprio 0
	s_setprio 1
	v_mfma_f32_16x16x32_bf16 v[62:65], v[134:137], v[190:193], v[62:65]
	v_mfma_f32_16x16x32_bf16 v[58:61], v[158:161], v[190:193], v[58:61]
	v_mfma_f32_16x16x32_bf16 v[50:53], v[134:137], v[198:201], v[50:53]
	v_mfma_f32_16x16x32_bf16 v[42:45], v[158:161], v[198:201], v[42:45]
	v_mfma_f32_16x16x32_bf16 v[38:41], v[134:137], v[206:209], v[38:41]
	v_mfma_f32_16x16x32_bf16 v[34:37], v[158:161], v[206:209], v[34:37]
	v_mfma_f32_16x16x32_bf16 v[14:17], v[134:137], v[218:221], v[14:17]
	v_mfma_f32_16x16x32_bf16 v[10:13], v[158:161], v[218:221], v[10:13]
	s_setprio 0
	s_setprio 1
	v_mfma_f32_16x16x32_bf16 v[54:57], v[162:165], v[186:189], v[54:57]
	v_mfma_f32_16x16x32_bf16 v[46:49], v[178:181], v[186:189], v[46:49]
	v_mfma_f32_16x16x32_bf16 v[30:33], v[162:165], v[194:197], v[30:33]
	v_mfma_f32_16x16x32_bf16 v[26:29], v[178:181], v[194:197], v[26:29]
	v_mfma_f32_16x16x32_bf16 v[22:25], v[162:165], v[202:205], v[22:25]
	v_mfma_f32_16x16x32_bf16 v[18:21], v[178:181], v[202:205], v[18:21]
	v_mfma_f32_16x16x32_bf16 v[6:9], v[162:165], v[210:213], v[6:9]
	v_mfma_f32_16x16x32_bf16 v[2:5], v[178:181], v[210:213], v[2:5]
	s_setprio 0
	s_setprio 1
	v_mfma_f32_16x16x32_bf16 v[54:57], v[166:169], v[190:193], v[54:57]
	v_mfma_f32_16x16x32_bf16 v[46:49], v[182:185], v[190:193], v[46:49]
	v_mfma_f32_16x16x32_bf16 v[30:33], v[166:169], v[198:201], v[30:33]
	v_mfma_f32_16x16x32_bf16 v[26:29], v[182:185], v[198:201], v[26:29]
	v_mfma_f32_16x16x32_bf16 v[22:25], v[166:169], v[206:209], v[22:25]
	v_mfma_f32_16x16x32_bf16 v[18:21], v[182:185], v[206:209], v[18:21]
	v_mfma_f32_16x16x32_bf16 v[6:9], v[166:169], v[218:221], v[6:9]
	v_mfma_f32_16x16x32_bf16 v[2:5], v[182:185], v[218:221], v[2:5]
	s_setprio 0
	s_barrier
	s_add_i32 s72, s72, 2
	s_add_u32 s46, s46, 0x100
	s_addc_u32 s47, s47, 0
	s_add_u32 s70, s70, 0x100
	s_addc_u32 s71, s71, 0
	s_cmp_gt_u32 s72, 29
	s_cbranch_scc0 .LBB0_2938
	s_and_b64 vcc, exec, s[26:27]
	s_cbranch_vccz .LBB0_2941
	s_barrier

.LBB0_3067:
	ds_read_b128 v[146:149], v153
	ds_read_b128 v[156:159], v153 offset:1024
	ds_read_b128 v[160:163], v153 offset:2048
	ds_read_b128 v[164:167], v153 offset:3072
	ds_read_b128 v[168:171], v154
	ds_read_b128 v[172:175], v154 offset:1024
	ds_read_b128 v[176:179], v154 offset:2048
	ds_read_b128 v[180:183], v154 offset:3072
	s_add_u32 s34, s44, 0xfff80080
	s_addc_u32 s35, s45, -1
	s_cmp_eq_u32 s71, 28
	s_cselect_b32 s47, s0, s35
	s_cselect_b32 s46, s1, s34
	s_cselect_b32 s35, s27, s70
	s_cselect_b32 s34, s37, s69
	v_lshl_add_u64 v[218:219], s[44:45], 0, v[138:139]
	s_add_i32 m0, s43, 0xc000
	ds_read_b128 v[184:187], v155
	ds_read_b128 v[188:191], v155 offset:1024
	ds_read_b128 v[192:195], v155 offset:2048
	ds_read_b128 v[196:199], v155 offset:3072
	ds_read_b128 v[200:203], v155 offset:4096
	ds_read_b128 v[204:207], v155 offset:5120
	ds_read_b128 v[208:211], v155 offset:6144
	ds_read_b128 v[212:215], v155 offset:7168
	global_load_lds_dwordx4 v[218:219], off
	v_lshl_add_u64 v[218:219], s[44:45], 0, v[140:141]
	s_add_i32 m0, s43, 0xe000
	s_nop 0
	global_load_lds_dwordx4 v[218:219], off
	s_waitcnt vmcnt(8)
	s_waitcnt lgkmcnt(0)
	s_barrier
	s_setprio 1
	s_waitcnt lgkmcnt(0)
	v_mfma_f32_16x16x32_bf16 v[126:129], v[146:149], v[184:187], v[126:129]
	v_mfma_f32_16x16x32_bf16 v[118:121], v[160:163], v[184:187], v[118:121]
	v_mfma_f32_16x16x32_bf16 v[110:113], v[146:149], v[192:195], v[110:113]
	v_mfma_f32_16x16x32_bf16 v[102:105], v[160:163], v[192:195], v[102:105]
	v_mfma_f32_16x16x32_bf16 v[94:97], v[146:149], v[200:203], v[94:97]
	v_mfma_f32_16x16x32_bf16 v[86:89], v[160:163], v[200:203], v[86:89]
	v_mfma_f32_16x16x32_bf16 v[78:81], v[146:149], v[208:211], v[78:81]
	v_mfma_f32_16x16x32_bf16 v[70:73], v[160:163], v[208:211], v[70:73]
	s_setprio 0
	s_setprio 1
	v_mfma_f32_16x16x32_bf16 v[126:129], v[156:159], v[188:191], v[126:129]
	v_mfma_f32_16x16x32_bf16 v[118:121], v[164:167], v[188:191], v[118:121]
	v_mfma_f32_16x16x32_bf16 v[110:113], v[156:159], v[196:199], v[110:113]
	v_mfma_f32_16x16x32_bf16 v[102:105], v[164:167], v[196:199], v[102:105]
	v_mfma_f32_16x16x32_bf16 v[94:97], v[156:159], v[204:207], v[94:97]
	v_mfma_f32_16x16x32_bf16 v[86:89], v[164:167], v[204:207], v[86:89]
	v_mfma_f32_16x16x32_bf16 v[78:81], v[156:159], v[212:215], v[78:81]
	v_mfma_f32_16x16x32_bf16 v[70:73], v[164:167], v[212:215], v[70:73]
	s_setprio 0
	s_setprio 1
	v_mfma_f32_16x16x32_bf16 v[122:125], v[168:171], v[184:187], v[122:125]
	v_mfma_f32_16x16x32_bf16 v[114:117], v[176:179], v[184:187], v[114:117]
	v_mfma_f32_16x16x32_bf16 v[106:109], v[168:171], v[192:195], v[106:109]
	v_mfma_f32_16x16x32_bf16 v[98:101], v[176:179], v[192:195], v[98:101]
	v_mfma_f32_16x16x32_bf16 v[90:93], v[168:171], v[200:203], v[90:93]
	v_mfma_f32_16x16x32_bf16 v[82:85], v[176:179], v[200:203], v[82:85]
	v_mfma_f32_16x16x32_bf16 v[74:77], v[168:171], v[208:211], v[74:77]
	v_mfma_f32_16x16x32_bf16 v[66:69], v[176:179], v[208:211], v[66:69]
	s_setprio 0
	s_setprio 1
	v_mfma_f32_16x16x32_bf16 v[122:125], v[172:175], v[188:191], v[122:125]
	v_mfma_f32_16x16x32_bf16 v[114:117], v[180:183], v[188:191], v[114:117]
	v_mfma_f32_16x16x32_bf16 v[106:109], v[172:175], v[196:199], v[106:109]
	v_mfma_f32_16x16x32_bf16 v[98:101], v[180:183], v[196:199], v[98:101]
	v_mfma_f32_16x16x32_bf16 v[90:93], v[172:175], v[204:207], v[90:93]
	v_mfma_f32_16x16x32_bf16 v[82:85], v[180:183], v[204:207], v[82:85]
	v_mfma_f32_16x16x32_bf16 v[74:77], v[172:175], v[212:215], v[74:77]
	v_mfma_f32_16x16x32_bf16 v[66:69], v[180:183], v[212:215], v[66:69]
	s_setprio 0
	s_barrier
	s_add_i32 s62, s59, s30
	v_lshl_add_u64 v[218:219], s[34:35], 0, v[134:135]
	s_mov_b32 m0, s62
	ds_read_b128 v[184:187], v155 offset:16384
	ds_read_b128 v[188:191], v155 offset:17408
	ds_read_b128 v[192:195], v155 offset:18432
	ds_read_b128 v[196:199], v155 offset:19456
	ds_read_b128 v[200:203], v155 offset:20480
	ds_read_b128 v[204:207], v155 offset:21504
	ds_read_b128 v[208:211], v155 offset:22528
	ds_read_b128 v[212:215], v155 offset:23552
	global_load_lds_dwordx4 v[218:219], off
	s_add_i32 m0, s62, 0x2000
	s_add_u32 s62, s34, 0x80000
	v_lshl_add_u64 v[220:221], s[34:35], 0, v[130:131]
	s_addc_u32 s63, s35, 0
	s_add_i32 s66, s60, s30
	global_load_lds_dwordx4 v[220:221], off
	v_lshl_add_u64 v[222:223], s[62:63], 0, v[134:135]
	s_mov_b32 m0, s66
	v_lshl_add_u64 v[224:225], s[46:47], 0, v[132:133]
	global_load_lds_dwordx4 v[222:223], off
	v_lshl_add_u64 v[222:223], s[62:63], 0, v[130:131]
	s_add_i32 m0, s66, 0x2000
	s_nop 0
	global_load_lds_dwordx4 v[222:223], off
	v_lshl_add_u64 v[222:223], s[46:47], 0, v[136:137]
	s_mov_b32 m0, s43
	s_nop 0
	global_load_lds_dwordx4 v[222:223], off
	s_mov_b32 m0, s52
	s_nop 0
	global_load_lds_dwordx4 v[224:225], off
	s_waitcnt vmcnt(8)
	s_waitcnt lgkmcnt(0)
	s_barrier
	s_setprio 1
	s_waitcnt lgkmcnt(0)
	v_mfma_f32_16x16x32_bf16 v[62:65], v[146:149], v[184:187], v[62:65]
	v_mfma_f32_16x16x32_bf16 v[54:57], v[160:163], v[184:187], v[54:57]
	v_mfma_f32_16x16x32_bf16 v[46:49], v[146:149], v[192:195], v[46:49]
	v_mfma_f32_16x16x32_bf16 v[38:41], v[160:163], v[192:195], v[38:41]
	v_mfma_f32_16x16x32_bf16 v[30:33], v[146:149], v[200:203], v[30:33]
	v_mfma_f32_16x16x32_bf16 v[22:25], v[160:163], v[200:203], v[22:25]
	v_mfma_f32_16x16x32_bf16 v[14:17], v[146:149], v[208:211], v[14:17]
	v_mfma_f32_16x16x32_bf16 v[6:9], v[160:163], v[208:211], v[6:9]
	s_setprio 0
	s_setprio 1
	v_mfma_f32_16x16x32_bf16 v[62:65], v[156:159], v[188:191], v[62:65]
	v_mfma_f32_16x16x32_bf16 v[54:57], v[164:167], v[188:191], v[54:57]
	v_mfma_f32_16x16x32_bf16 v[46:49], v[156:159], v[196:199], v[46:49]
	v_mfma_f32_16x16x32_bf16 v[38:41], v[164:167], v[196:199], v[38:41]
	v_mfma_f32_16x16x32_bf16 v[30:33], v[156:159], v[204:207], v[30:33]
	v_mfma_f32_16x16x32_bf16 v[22:25], v[164:167], v[204:207], v[22:25]
	v_mfma_f32_16x16x32_bf16 v[14:17], v[156:159], v[212:215], v[14:17]
	v_mfma_f32_16x16x32_bf16 v[6:9], v[164:167], v[212:215], v[6:9]
	s_setprio 0
	s_setprio 1
	v_mfma_f32_16x16x32_bf16 v[58:61], v[168:171], v[184:187], v[58:61]
	v_mfma_f32_16x16x32_bf16 v[50:53], v[176:179], v[184:187], v[50:53]
	v_mfma_f32_16x16x32_bf16 v[42:45], v[168:171], v[192:195], v[42:45]
	v_mfma_f32_16x16x32_bf16 v[34:37], v[176:179], v[192:195], v[34:37]
	v_mfma_f32_16x16x32_bf16 v[26:29], v[168:171], v[200:203], v[26:29]
	v_mfma_f32_16x16x32_bf16 v[18:21], v[176:179], v[200:203], v[18:21]
	v_mfma_f32_16x16x32_bf16 v[10:13], v[168:171], v[208:211], v[10:13]
	v_mfma_f32_16x16x32_bf16 v[2:5], v[176:179], v[208:211], v[2:5]
	s_setprio 0
	s_setprio 1
	v_mfma_f32_16x16x32_bf16 v[58:61], v[172:175], v[188:191], v[58:61]
	v_mfma_f32_16x16x32_bf16 v[50:53], v[180:183], v[188:191], v[50:53]
	v_mfma_f32_16x16x32_bf16 v[42:45], v[172:175], v[196:199], v[42:45]
	v_mfma_f32_16x16x32_bf16 v[34:37], v[180:183], v[196:199], v[34:37]
	v_mfma_f32_16x16x32_bf16 v[26:29], v[172:175], v[204:207], v[26:29]
	v_mfma_f32_16x16x32_bf16 v[18:21], v[180:183], v[204:207], v[18:21]
	v_mfma_f32_16x16x32_bf16 v[10:13], v[172:175], v[212:215], v[10:13]
	v_mfma_f32_16x16x32_bf16 v[2:5], v[180:183], v[212:215], v[2:5]
	s_setprio 0
	s_barrier
	s_add_i32 s62, 0, 0x18000
	s_add_i32 s63, 0, 0x1c000
	v_add_u32_e32 v164, s62, v151
	v_add_u32_e32 v180, s63, v151
	ds_read_b128 v[146:149], v164
	ds_read_b128 v[156:159], v164 offset:1024
	ds_read_b128 v[160:163], v164 offset:2048
	ds_read_b128 v[164:167], v164 offset:3072
	ds_read_b128 v[168:171], v180
	ds_read_b128 v[172:175], v180 offset:1024
	ds_read_b128 v[176:179], v180 offset:2048
	ds_read_b128 v[180:183], v180 offset:3072
	s_add_u32 s46, s46, 0x80000
	s_addc_u32 s47, s47, 0
	s_mov_b32 m0, s53
	v_lshl_add_u64 v[226:227], s[46:47], 0, v[136:137]
	ds_read_b128 v[184:187], v155 offset:32768
	ds_read_b128 v[188:191], v155 offset:33792
	ds_read_b128 v[192:195], v155 offset:34816
	ds_read_b128 v[196:199], v155 offset:35840
	ds_read_b128 v[200:203], v155 offset:36864
	ds_read_b128 v[204:207], v155 offset:37888
	ds_read_b128 v[208:211], v155 offset:38912
	ds_read_b128 v[212:215], v155 offset:39936
	global_load_lds_dwordx4 v[226:227], off
	v_lshl_add_u64 v[226:227], s[46:47], 0, v[132:133]
	s_mov_b32 m0, s54
	s_nop 0
	global_load_lds_dwordx4 v[226:227], off
	s_waitcnt vmcnt(8)
	s_waitcnt lgkmcnt(0)
	s_barrier
	s_setprio 1
	s_waitcnt lgkmcnt(0)
	v_mfma_f32_16x16x32_bf16 v[126:129], v[146:149], v[184:187], v[126:129]
	v_mfma_f32_16x16x32_bf16 v[118:121], v[160:163], v[184:187], v[118:121]
	v_mfma_f32_16x16x32_bf16 v[110:113], v[146:149], v[192:195], v[110:113]
	v_mfma_f32_16x16x32_bf16 v[102:105], v[160:163], v[192:195], v[102:105]
	v_mfma_f32_16x16x32_bf16 v[94:97], v[146:149], v[200:203], v[94:97]
	v_mfma_f32_16x16x32_bf16 v[86:89], v[160:163], v[200:203], v[86:89]
	v_mfma_f32_16x16x32_bf16 v[78:81], v[146:149], v[208:211], v[78:81]
	v_mfma_f32_16x16x32_bf16 v[70:73], v[160:163], v[208:211], v[70:73]
	s_setprio 0
	s_setprio 1
	v_mfma_f32_16x16x32_bf16 v[126:129], v[156:159], v[188:191], v[126:129]
	v_mfma_f32_16x16x32_bf16 v[118:121], v[164:167], v[188:191], v[118:121]
	v_mfma_f32_16x16x32_bf16 v[110:113], v[156:159], v[196:199], v[110:113]
	v_mfma_f32_16x16x32_bf16 v[102:105], v[164:167], v[196:199], v[102:105]
	v_mfma_f32_16x16x32_bf16 v[94:97], v[156:159], v[204:207], v[94:97]
	v_mfma_f32_16x16x32_bf16 v[86:89], v[164:167], v[204:207], v[86:89]
	v_mfma_f32_16x16x32_bf16 v[78:81], v[156:159], v[212:215], v[78:81]
	v_mfma_f32_16x16x32_bf16 v[70:73], v[164:167], v[212:215], v[70:73]
	s_setprio 0
	s_setprio 1
	v_mfma_f32_16x16x32_bf16 v[122:125], v[168:171], v[184:187], v[122:125]
	v_mfma_f32_16x16x32_bf16 v[114:117], v[176:179], v[184:187], v[114:117]
	v_mfma_f32_16x16x32_bf16 v[106:109], v[168:171], v[192:195], v[106:109]
	v_mfma_f32_16x16x32_bf16 v[98:101], v[176:179], v[192:195], v[98:101]
	v_mfma_f32_16x16x32_bf16 v[90:93], v[168:171], v[200:203], v[90:93]
	v_mfma_f32_16x16x32_bf16 v[82:85], v[176:179], v[200:203], v[82:85]
	v_mfma_f32_16x16x32_bf16 v[74:77], v[168:171], v[208:211], v[74:77]
	v_mfma_f32_16x16x32_bf16 v[66:69], v[176:179], v[208:211], v[66:69]
	s_setprio 0
	s_setprio 1
	v_mfma_f32_16x16x32_bf16 v[122:125], v[172:175], v[188:191], v[122:125]
	v_mfma_f32_16x16x32_bf16 v[114:117], v[180:183], v[188:191], v[114:117]
	v_mfma_f32_16x16x32_bf16 v[106:109], v[172:175], v[196:199], v[106:109]
	v_mfma_f32_16x16x32_bf16 v[98:101], v[180:183], v[196:199], v[98:101]
	v_mfma_f32_16x16x32_bf16 v[90:93], v[172:175], v[204:207], v[90:93]
	v_mfma_f32_16x16x32_bf16 v[82:85], v[180:183], v[204:207], v[82:85]
	v_mfma_f32_16x16x32_bf16 v[74:77], v[172:175], v[212:215], v[74:77]
	v_mfma_f32_16x16x32_bf16 v[66:69], v[180:183], v[212:215], v[66:69]
	s_setprio 0
	s_barrier
	s_add_i32 s46, s62, s30
	v_lshl_add_u64 v[218:219], v[218:219], 0, s[8:9]
	s_mov_b32 m0, s46
	ds_read_b128 v[184:187], v155 offset:49152
	ds_read_b128 v[188:191], v155 offset:50176
	ds_read_b128 v[192:195], v155 offset:51200
	ds_read_b128 v[196:199], v155 offset:52224
	ds_read_b128 v[200:203], v155 offset:53248
	ds_read_b128 v[204:207], v155 offset:54272
	ds_read_b128 v[208:211], v155 offset:55296
	ds_read_b128 v[212:215], v155 offset:56320
	global_load_lds_dwordx4 v[218:219], off
	s_add_i32 m0, s46, 0x2000
	s_add_u32 s34, s34, 0x80080
	v_lshl_add_u64 v[218:219], v[220:221], 0, s[8:9]
	s_addc_u32 s35, s35, 0
	s_add_i32 s46, s63, s30
	global_load_lds_dwordx4 v[218:219], off
	v_lshl_add_u64 v[218:219], s[34:35], 0, v[134:135]
	s_mov_b32 m0, s46
	s_nop 0
	global_load_lds_dwordx4 v[218:219], off
	v_lshl_add_u64 v[218:219], s[34:35], 0, v[130:131]
	s_add_i32 m0, s46, 0x2000
	s_nop 0
	global_load_lds_dwordx4 v[218:219], off
	v_lshl_add_u64 v[218:219], v[222:223], 0, s[8:9]
	s_mov_b32 m0, s56
	s_nop 0
	global_load_lds_dwordx4 v[218:219], off
	v_lshl_add_u64 v[218:219], v[224:225], 0, s[8:9]
	s_mov_b32 m0, s57
	s_nop 0
	global_load_lds_dwordx4 v[218:219], off
	s_waitcnt vmcnt(8)
	s_waitcnt lgkmcnt(0)
	s_barrier
	s_setprio 1
	s_waitcnt lgkmcnt(0)
	v_mfma_f32_16x16x32_bf16 v[62:65], v[146:149], v[184:187], v[62:65]
	v_mfma_f32_16x16x32_bf16 v[54:57], v[160:163], v[184:187], v[54:57]
	v_mfma_f32_16x16x32_bf16 v[46:49], v[146:149], v[192:195], v[46:49]
	v_mfma_f32_16x16x32_bf16 v[38:41], v[160:163], v[192:195], v[38:41]
	v_mfma_f32_16x16x32_bf16 v[30:33], v[146:149], v[200:203], v[30:33]
	v_mfma_f32_16x16x32_bf16 v[22:25], v[160:163], v[200:203], v[22:25]
	v_mfma_f32_16x16x32_bf16 v[14:17], v[146:149], v[208:211], v[14:17]
	v_mfma_f32_16x16x32_bf16 v[6:9], v[160:163], v[208:211], v[6:9]
	s_setprio 0
	s_setprio 1
	v_mfma_f32_16x16x32_bf16 v[62:65], v[156:159], v[188:191], v[62:65]
	v_mfma_f32_16x16x32_bf16 v[54:57], v[164:167], v[188:191], v[54:57]
	v_mfma_f32_16x16x32_bf16 v[46:49], v[156:159], v[196:199], v[46:49]
	v_mfma_f32_16x16x32_bf16 v[38:41], v[164:167], v[196:199], v[38:41]
	v_mfma_f32_16x16x32_bf16 v[30:33], v[156:159], v[204:207], v[30:33]
	v_mfma_f32_16x16x32_bf16 v[22:25], v[164:167], v[204:207], v[22:25]
	v_mfma_f32_16x16x32_bf16 v[14:17], v[156:159], v[212:215], v[14:17]
	v_mfma_f32_16x16x32_bf16 v[6:9], v[164:167], v[212:215], v[6:9]
	s_setprio 0
	s_setprio 1
	v_mfma_f32_16x16x32_bf16 v[58:61], v[168:171], v[184:187], v[58:61]
	v_mfma_f32_16x16x32_bf16 v[50:53], v[176:179], v[184:187], v[50:53]
	v_mfma_f32_16x16x32_bf16 v[42:45], v[168:171], v[192:195], v[42:45]
	v_mfma_f32_16x16x32_bf16 v[34:37], v[176:179], v[192:195], v[34:37]
	v_mfma_f32_16x16x32_bf16 v[26:29], v[168:171], v[200:203], v[26:29]
	v_mfma_f32_16x16x32_bf16 v[18:21], v[176:179], v[200:203], v[18:21]
	v_mfma_f32_16x16x32_bf16 v[10:13], v[168:171], v[208:211], v[10:13]
	v_mfma_f32_16x16x32_bf16 v[2:5], v[176:179], v[208:211], v[2:5]
	s_setprio 0
	s_setprio 1
	v_mfma_f32_16x16x32_bf16 v[58:61], v[172:175], v[188:191], v[58:61]
	v_mfma_f32_16x16x32_bf16 v[50:53], v[180:183], v[188:191], v[50:53]
	v_mfma_f32_16x16x32_bf16 v[42:45], v[172:175], v[196:199], v[42:45]
	v_mfma_f32_16x16x32_bf16 v[34:37], v[180:183], v[196:199], v[34:37]
	v_mfma_f32_16x16x32_bf16 v[26:29], v[172:175], v[204:207], v[26:29]
	v_mfma_f32_16x16x32_bf16 v[18:21], v[180:183], v[204:207], v[18:21]
	v_mfma_f32_16x16x32_bf16 v[10:13], v[172:175], v[212:215], v[10:13]
	v_mfma_f32_16x16x32_bf16 v[2:5], v[180:183], v[212:215], v[2:5]
	s_setprio 0
	s_barrier
	s_add_i32 s71, s71, 2
	s_add_u32 s44, s44, 0x100
	s_addc_u32 s45, s45, 0
	s_add_u32 s69, s69, 0x100
	s_addc_u32 s70, s70, 0
	s_cmp_gt_u32 s71, 29
	s_cbranch_scc0 .LBB0_3067
	s_and_b64 vcc, exec, s[24:25]
	s_cbranch_vccz .LBB0_3070
	s_barrier

.LBB0_3180:
	ds_read_b128 v[130:133], v174
	ds_read_b128 v[134:137], v174 offset:1024
	ds_read_b128 v[138:141], v174 offset:2048
	ds_read_b128 v[158:161], v174 offset:3072
	ds_read_b128 v[162:165], v175
	ds_read_b128 v[166:169], v175 offset:1024
	ds_read_b128 v[178:181], v175 offset:2048
	ds_read_b128 v[182:185], v175 offset:3072
	s_add_u32 s34, s40, 0xffea0080
	s_addc_u32 s35, s41, -1
	s_cmpk_eq_i32 s60, 0x54
	s_cselect_b32 s43, s5, s35
	s_cselect_b32 s42, s4, s34
	s_cselect_b32 s35, s39, s1
	s_cselect_b32 s34, s38, s0
	v_lshl_add_u64 v[170:171], s[40:41], 0, v[150:151]
	s_add_i32 m0, s33, 0xc000
	ds_read_b128 v[186:189], v176
	ds_read_b128 v[190:193], v176 offset:1024
	ds_read_b128 v[194:197], v176 offset:2048
	ds_read_b128 v[198:201], v176 offset:3072
	ds_read_b128 v[202:205], v176 offset:4096
	ds_read_b128 v[206:209], v176 offset:5120
	ds_read_b128 v[210:213], v176 offset:6144
	ds_read_b128 v[218:221], v176 offset:7168
	global_load_lds_dwordx4 v[170:171], off
	v_lshl_add_u64 v[170:171], s[40:41], 0, v[152:153]
	s_add_i32 m0, s33, 0xe000
	s_nop 0
	global_load_lds_dwordx4 v[170:171], off
	s_waitcnt vmcnt(8)
	s_waitcnt lgkmcnt(0)
	s_barrier
	s_setprio 1
	s_waitcnt lgkmcnt(0)
	v_mfma_f32_16x16x32_bf16 v[126:129], v[130:133], v[186:189], v[126:129]
	v_mfma_f32_16x16x32_bf16 v[122:125], v[138:141], v[186:189], v[122:125]
	v_mfma_f32_16x16x32_bf16 v[110:113], v[130:133], v[194:197], v[110:113]
	v_mfma_f32_16x16x32_bf16 v[106:109], v[138:141], v[194:197], v[106:109]
	v_mfma_f32_16x16x32_bf16 v[94:97], v[130:133], v[202:205], v[94:97]
	v_mfma_f32_16x16x32_bf16 v[90:93], v[138:141], v[202:205], v[90:93]
	v_mfma_f32_16x16x32_bf16 v[78:81], v[130:133], v[210:213], v[78:81]
	v_mfma_f32_16x16x32_bf16 v[74:77], v[138:141], v[210:213], v[74:77]
	s_setprio 0
	s_setprio 1
	v_mfma_f32_16x16x32_bf16 v[126:129], v[134:137], v[190:193], v[126:129]
	v_mfma_f32_16x16x32_bf16 v[122:125], v[158:161], v[190:193], v[122:125]
	v_mfma_f32_16x16x32_bf16 v[110:113], v[134:137], v[198:201], v[110:113]
	v_mfma_f32_16x16x32_bf16 v[106:109], v[158:161], v[198:201], v[106:109]
	v_mfma_f32_16x16x32_bf16 v[94:97], v[134:137], v[206:209], v[94:97]
	v_mfma_f32_16x16x32_bf16 v[90:93], v[158:161], v[206:209], v[90:93]
	v_mfma_f32_16x16x32_bf16 v[78:81], v[134:137], v[218:221], v[78:81]
	v_mfma_f32_16x16x32_bf16 v[74:77], v[158:161], v[218:221], v[74:77]
	s_setprio 0
	s_setprio 1
	v_mfma_f32_16x16x32_bf16 v[118:121], v[162:165], v[186:189], v[118:121]
	v_mfma_f32_16x16x32_bf16 v[114:117], v[178:181], v[186:189], v[114:117]
	v_mfma_f32_16x16x32_bf16 v[102:105], v[162:165], v[194:197], v[102:105]
	v_mfma_f32_16x16x32_bf16 v[98:101], v[178:181], v[194:197], v[98:101]
	v_mfma_f32_16x16x32_bf16 v[86:89], v[162:165], v[202:205], v[86:89]
	v_mfma_f32_16x16x32_bf16 v[82:85], v[178:181], v[202:205], v[82:85]
	v_mfma_f32_16x16x32_bf16 v[70:73], v[162:165], v[210:213], v[70:73]
	v_mfma_f32_16x16x32_bf16 v[66:69], v[178:181], v[210:213], v[66:69]
	s_setprio 0
	s_setprio 1
	v_mfma_f32_16x16x32_bf16 v[118:121], v[166:169], v[190:193], v[118:121]
	v_mfma_f32_16x16x32_bf16 v[114:117], v[182:185], v[190:193], v[114:117]
	v_mfma_f32_16x16x32_bf16 v[102:105], v[166:169], v[198:201], v[102:105]
	v_mfma_f32_16x16x32_bf16 v[98:101], v[182:185], v[198:201], v[98:101]
	v_mfma_f32_16x16x32_bf16 v[86:89], v[166:169], v[206:209], v[86:89]
	v_mfma_f32_16x16x32_bf16 v[82:85], v[182:185], v[206:209], v[82:85]
	v_mfma_f32_16x16x32_bf16 v[70:73], v[166:169], v[218:221], v[70:73]
	v_mfma_f32_16x16x32_bf16 v[66:69], v[182:185], v[218:221], v[66:69]
	s_setprio 0
	s_barrier
	s_add_i32 s61, s53, s31
	v_lshl_add_u64 v[170:171], s[34:35], 0, v[144:145]
	s_mov_b32 m0, s61
	ds_read_b128 v[186:189], v176 offset:16384
	ds_read_b128 v[190:193], v176 offset:17408
	ds_read_b128 v[194:197], v176 offset:18432
	ds_read_b128 v[198:201], v176 offset:19456
	ds_read_b128 v[202:205], v176 offset:20480
	ds_read_b128 v[206:209], v176 offset:21504
	ds_read_b128 v[210:213], v176 offset:22528
	ds_read_b128 v[218:221], v176 offset:23552
	global_load_lds_dwordx4 v[170:171], off
	s_add_i32 m0, s61, 0x2000
	s_add_u32 s62, s34, 0x160000
	v_lshl_add_u64 v[214:215], s[34:35], 0, v[148:149]
	s_addc_u32 s63, s35, 0
	s_add_i32 s61, s54, s31
	global_load_lds_dwordx4 v[214:215], off
	v_lshl_add_u64 v[222:223], s[62:63], 0, v[144:145]
	s_mov_b32 m0, s61
	v_lshl_add_u64 v[224:225], s[42:43], 0, v[146:147]
	global_load_lds_dwordx4 v[222:223], off
	v_lshl_add_u64 v[222:223], s[62:63], 0, v[148:149]
	s_add_i32 m0, s61, 0x2000
	s_nop 0
	global_load_lds_dwordx4 v[222:223], off
	v_lshl_add_u64 v[222:223], s[42:43], 0, v[142:143]
	s_mov_b32 m0, s33
	s_nop 0
	global_load_lds_dwordx4 v[222:223], off
	s_mov_b32 m0, s44
	s_nop 0
	global_load_lds_dwordx4 v[224:225], off
	s_waitcnt vmcnt(8)
	s_waitcnt lgkmcnt(0)
	s_barrier
	s_setprio 1
	s_waitcnt lgkmcnt(0)
	v_mfma_f32_16x16x32_bf16 v[62:65], v[130:133], v[186:189], v[62:65]
	v_mfma_f32_16x16x32_bf16 v[58:61], v[138:141], v[186:189], v[58:61]
	v_mfma_f32_16x16x32_bf16 v[50:53], v[130:133], v[194:197], v[50:53]
	v_mfma_f32_16x16x32_bf16 v[42:45], v[138:141], v[194:197], v[42:45]
	v_mfma_f32_16x16x32_bf16 v[38:41], v[130:133], v[202:205], v[38:41]
	v_mfma_f32_16x16x32_bf16 v[34:37], v[138:141], v[202:205], v[34:37]
	v_mfma_f32_16x16x32_bf16 v[14:17], v[130:133], v[210:213], v[14:17]
	v_mfma_f32_16x16x32_bf16 v[10:13], v[138:141], v[210:213], v[10:13]
	s_setprio 0
	s_setprio 1
	v_mfma_f32_16x16x32_bf16 v[62:65], v[134:137], v[190:193], v[62:65]
	v_mfma_f32_16x16x32_bf16 v[58:61], v[158:161], v[190:193], v[58:61]
	v_mfma_f32_16x16x32_bf16 v[50:53], v[134:137], v[198:201], v[50:53]
	v_mfma_f32_16x16x32_bf16 v[42:45], v[158:161], v[198:201], v[42:45]
	v_mfma_f32_16x16x32_bf16 v[38:41], v[134:137], v[206:209], v[38:41]
	v_mfma_f32_16x16x32_bf16 v[34:37], v[158:161], v[206:209], v[34:37]
	v_mfma_f32_16x16x32_bf16 v[14:17], v[134:137], v[218:221], v[14:17]
	v_mfma_f32_16x16x32_bf16 v[10:13], v[158:161], v[218:221], v[10:13]
	s_setprio 0
	s_setprio 1
	v_mfma_f32_16x16x32_bf16 v[54:57], v[162:165], v[186:189], v[54:57]
	v_mfma_f32_16x16x32_bf16 v[46:49], v[178:181], v[186:189], v[46:49]
	v_mfma_f32_16x16x32_bf16 v[30:33], v[162:165], v[194:197], v[30:33]
	v_mfma_f32_16x16x32_bf16 v[26:29], v[178:181], v[194:197], v[26:29]
	v_mfma_f32_16x16x32_bf16 v[22:25], v[162:165], v[202:205], v[22:25]
	v_mfma_f32_16x16x32_bf16 v[18:21], v[178:181], v[202:205], v[18:21]
	v_mfma_f32_16x16x32_bf16 v[6:9], v[162:165], v[210:213], v[6:9]
	v_mfma_f32_16x16x32_bf16 v[2:5], v[178:181], v[210:213], v[2:5]
	s_setprio 0
	s_setprio 1
	v_mfma_f32_16x16x32_bf16 v[54:57], v[166:169], v[190:193], v[54:57]
	v_mfma_f32_16x16x32_bf16 v[46:49], v[182:185], v[190:193], v[46:49]
	v_mfma_f32_16x16x32_bf16 v[30:33], v[166:169], v[198:201], v[30:33]
	v_mfma_f32_16x16x32_bf16 v[26:29], v[182:185], v[198:201], v[26:29]
	v_mfma_f32_16x16x32_bf16 v[22:25], v[166:169], v[206:209], v[22:25]
	v_mfma_f32_16x16x32_bf16 v[18:21], v[182:185], v[206:209], v[18:21]
	v_mfma_f32_16x16x32_bf16 v[6:9], v[166:169], v[218:221], v[6:9]
	v_mfma_f32_16x16x32_bf16 v[2:5], v[182:185], v[218:221], v[2:5]
	s_setprio 0
	s_barrier
	s_add_i32 s61, 0, 0x18000
	s_add_i32 s62, 0, 0x1c000
	v_add_u32_e32 v158, s61, v172
	v_add_u32_e32 v177, s62, v172
	ds_read_b128 v[130:133], v158
	ds_read_b128 v[134:137], v158 offset:1024
	ds_read_b128 v[138:141], v158 offset:2048
	ds_read_b128 v[158:161], v158 offset:3072
	ds_read_b128 v[162:165], v177
	ds_read_b128 v[166:169], v177 offset:1024
	ds_read_b128 v[178:181], v177 offset:2048
	ds_read_b128 v[182:185], v177 offset:3072
	s_add_u32 s42, s42, 0x160000
	s_addc_u32 s43, s43, 0
	s_mov_b32 m0, s45
	v_lshl_add_u64 v[226:227], s[42:43], 0, v[142:143]
	ds_read_b128 v[186:189], v176 offset:32768
	ds_read_b128 v[190:193], v176 offset:33792
	ds_read_b128 v[194:197], v176 offset:34816
	ds_read_b128 v[198:201], v176 offset:35840
	ds_read_b128 v[202:205], v176 offset:36864
	ds_read_b128 v[206:209], v176 offset:37888
	ds_read_b128 v[210:213], v176 offset:38912
	ds_read_b128 v[218:221], v176 offset:39936
	global_load_lds_dwordx4 v[226:227], off
	v_lshl_add_u64 v[226:227], s[42:43], 0, v[146:147]
	s_mov_b32 m0, s46
	s_nop 0
	global_load_lds_dwordx4 v[226:227], off
	s_waitcnt vmcnt(8)
	s_waitcnt lgkmcnt(0)
	s_barrier
	s_setprio 1
	s_waitcnt lgkmcnt(0)
	v_mfma_f32_16x16x32_bf16 v[126:129], v[130:133], v[186:189], v[126:129]
	v_mfma_f32_16x16x32_bf16 v[122:125], v[138:141], v[186:189], v[122:125]
	v_mfma_f32_16x16x32_bf16 v[110:113], v[130:133], v[194:197], v[110:113]
	v_mfma_f32_16x16x32_bf16 v[106:109], v[138:141], v[194:197], v[106:109]
	v_mfma_f32_16x16x32_bf16 v[94:97], v[130:133], v[202:205], v[94:97]
	v_mfma_f32_16x16x32_bf16 v[90:93], v[138:141], v[202:205], v[90:93]
	v_mfma_f32_16x16x32_bf16 v[78:81], v[130:133], v[210:213], v[78:81]
	v_mfma_f32_16x16x32_bf16 v[74:77], v[138:141], v[210:213], v[74:77]
	s_setprio 0
	s_setprio 1
	v_mfma_f32_16x16x32_bf16 v[126:129], v[134:137], v[190:193], v[126:129]
	v_mfma_f32_16x16x32_bf16 v[122:125], v[158:161], v[190:193], v[122:125]
	v_mfma_f32_16x16x32_bf16 v[110:113], v[134:137], v[198:201], v[110:113]
	v_mfma_f32_16x16x32_bf16 v[106:109], v[158:161], v[198:201], v[106:109]
	v_mfma_f32_16x16x32_bf16 v[94:97], v[134:137], v[206:209], v[94:97]
	v_mfma_f32_16x16x32_bf16 v[90:93], v[158:161], v[206:209], v[90:93]
	v_mfma_f32_16x16x32_bf16 v[78:81], v[134:137], v[218:221], v[78:81]
	v_mfma_f32_16x16x32_bf16 v[74:77], v[158:161], v[218:221], v[74:77]
	s_setprio 0
	s_setprio 1
	v_mfma_f32_16x16x32_bf16 v[118:121], v[162:165], v[186:189], v[118:121]
	v_mfma_f32_16x16x32_bf16 v[114:117], v[178:181], v[186:189], v[114:117]
	v_mfma_f32_16x16x32_bf16 v[102:105], v[162:165], v[194:197], v[102:105]
	v_mfma_f32_16x16x32_bf16 v[98:101], v[178:181], v[194:197], v[98:101]
	v_mfma_f32_16x16x32_bf16 v[86:89], v[162:165], v[202:205], v[86:89]
	v_mfma_f32_16x16x32_bf16 v[82:85], v[178:181], v[202:205], v[82:85]
	v_mfma_f32_16x16x32_bf16 v[70:73], v[162:165], v[210:213], v[70:73]
	v_mfma_f32_16x16x32_bf16 v[66:69], v[178:181], v[210:213], v[66:69]
	s_setprio 0
	s_setprio 1
	v_mfma_f32_16x16x32_bf16 v[118:121], v[166:169], v[190:193], v[118:121]
	v_mfma_f32_16x16x32_bf16 v[114:117], v[182:185], v[190:193], v[114:117]
	v_mfma_f32_16x16x32_bf16 v[102:105], v[166:169], v[198:201], v[102:105]
	v_mfma_f32_16x16x32_bf16 v[98:101], v[182:185], v[198:201], v[98:101]
	v_mfma_f32_16x16x32_bf16 v[86:89], v[166:169], v[206:209], v[86:89]
	v_mfma_f32_16x16x32_bf16 v[82:85], v[182:185], v[206:209], v[82:85]
	v_mfma_f32_16x16x32_bf16 v[70:73], v[166:169], v[218:221], v[70:73]
	v_mfma_f32_16x16x32_bf16 v[66:69], v[182:185], v[218:221], v[66:69]
	s_setprio 0
	s_barrier
	s_add_i32 s42, s61, s31
	v_lshl_add_u64 v[170:171], v[170:171], 0, s[24:25]
	s_mov_b32 m0, s42
	ds_read_b128 v[186:189], v176 offset:49152
	ds_read_b128 v[190:193], v176 offset:50176
	ds_read_b128 v[194:197], v176 offset:51200
	ds_read_b128 v[198:201], v176 offset:52224
	ds_read_b128 v[202:205], v176 offset:53248
	ds_read_b128 v[206:209], v176 offset:54272
	ds_read_b128 v[210:213], v176 offset:55296
	ds_read_b128 v[218:221], v176 offset:56320
	global_load_lds_dwordx4 v[170:171], off
	s_add_i32 m0, s42, 0x2000
	s_add_u32 s34, s34, 0x160080
	v_lshl_add_u64 v[170:171], v[214:215], 0, s[24:25]
	s_addc_u32 s35, s35, 0
	s_add_i32 s42, s62, s31
	global_load_lds_dwordx4 v[170:171], off
	v_lshl_add_u64 v[170:171], s[34:35], 0, v[144:145]
	s_mov_b32 m0, s42
	s_nop 0
	global_load_lds_dwordx4 v[170:171], off
	v_lshl_add_u64 v[170:171], s[34:35], 0, v[148:149]
	s_add_i32 m0, s42, 0x2000
	s_nop 0
	global_load_lds_dwordx4 v[170:171], off
	v_lshl_add_u64 v[170:171], v[222:223], 0, s[24:25]
	s_mov_b32 m0, s48
	s_nop 0
	global_load_lds_dwordx4 v[170:171], off
	v_lshl_add_u64 v[170:171], v[224:225], 0, s[24:25]
	s_mov_b32 m0, s49
	s_nop 0
	global_load_lds_dwordx4 v[170:171], off
	s_waitcnt vmcnt(8)
	s_waitcnt lgkmcnt(0)
	s_barrier
	s_setprio 1
	s_waitcnt lgkmcnt(0)
	v_mfma_f32_16x16x32_bf16 v[62:65], v[130:133], v[186:189], v[62:65]
	v_mfma_f32_16x16x32_bf16 v[58:61], v[138:141], v[186:189], v[58:61]
	v_mfma_f32_16x16x32_bf16 v[50:53], v[130:133], v[194:197], v[50:53]
	v_mfma_f32_16x16x32_bf16 v[42:45], v[138:141], v[194:197], v[42:45]
	v_mfma_f32_16x16x32_bf16 v[38:41], v[130:133], v[202:205], v[38:41]
	v_mfma_f32_16x16x32_bf16 v[34:37], v[138:141], v[202:205], v[34:37]
	v_mfma_f32_16x16x32_bf16 v[14:17], v[130:133], v[210:213], v[14:17]
	v_mfma_f32_16x16x32_bf16 v[10:13], v[138:141], v[210:213], v[10:13]
	s_setprio 0
	s_setprio 1
	v_mfma_f32_16x16x32_bf16 v[62:65], v[134:137], v[190:193], v[62:65]
	v_mfma_f32_16x16x32_bf16 v[58:61], v[158:161], v[190:193], v[58:61]
	v_mfma_f32_16x16x32_bf16 v[50:53], v[134:137], v[198:201], v[50:53]
	v_mfma_f32_16x16x32_bf16 v[42:45], v[158:161], v[198:201], v[42:45]
	v_mfma_f32_16x16x32_bf16 v[38:41], v[134:137], v[206:209], v[38:41]
	v_mfma_f32_16x16x32_bf16 v[34:37], v[158:161], v[206:209], v[34:37]
	v_mfma_f32_16x16x32_bf16 v[14:17], v[134:137], v[218:221], v[14:17]
	v_mfma_f32_16x16x32_bf16 v[10:13], v[158:161], v[218:221], v[10:13]
	s_setprio 0
	s_setprio 1
	v_mfma_f32_16x16x32_bf16 v[54:57], v[162:165], v[186:189], v[54:57]
	v_mfma_f32_16x16x32_bf16 v[46:49], v[178:181], v[186:189], v[46:49]
	v_mfma_f32_16x16x32_bf16 v[30:33], v[162:165], v[194:197], v[30:33]
	v_mfma_f32_16x16x32_bf16 v[26:29], v[178:181], v[194:197], v[26:29]
	v_mfma_f32_16x16x32_bf16 v[22:25], v[162:165], v[202:205], v[22:25]
	v_mfma_f32_16x16x32_bf16 v[18:21], v[178:181], v[202:205], v[18:21]
	v_mfma_f32_16x16x32_bf16 v[6:9], v[162:165], v[210:213], v[6:9]
	v_mfma_f32_16x16x32_bf16 v[2:5], v[178:181], v[210:213], v[2:5]
	s_setprio 0
	s_setprio 1
	v_mfma_f32_16x16x32_bf16 v[54:57], v[166:169], v[190:193], v[54:57]
	v_mfma_f32_16x16x32_bf16 v[46:49], v[182:185], v[190:193], v[46:49]
	v_mfma_f32_16x16x32_bf16 v[30:33], v[166:169], v[198:201], v[30:33]
	v_mfma_f32_16x16x32_bf16 v[26:29], v[182:185], v[198:201], v[26:29]
	v_mfma_f32_16x16x32_bf16 v[22:25], v[166:169], v[206:209], v[22:25]
	v_mfma_f32_16x16x32_bf16 v[18:21], v[182:185], v[206:209], v[18:21]
	v_mfma_f32_16x16x32_bf16 v[6:9], v[166:169], v[218:221], v[6:9]
	v_mfma_f32_16x16x32_bf16 v[2:5], v[182:185], v[218:221], v[2:5]
	s_setprio 0
	s_barrier
	s_add_i32 s60, s60, 2
	s_add_u32 s40, s40, 0x100
	s_addc_u32 s41, s41, 0
	s_add_u32 s0, s0, 0x100
	s_addc_u32 s1, s1, 0
	s_cmpk_gt_u32 s60, 0x55
	s_cbranch_scc0 .LBB0_3180
	s_and_b64 vcc, exec, s[26:27]
	s_cbranch_vccz .LBB0_3183
	s_barrier

.LBB0_3309:
	ds_read_b128 v[146:149], v153
	ds_read_b128 v[156:159], v153 offset:1024
	ds_read_b128 v[160:163], v153 offset:2048
	ds_read_b128 v[164:167], v153 offset:3072
	ds_read_b128 v[168:171], v154
	ds_read_b128 v[172:175], v154 offset:1024
	ds_read_b128 v[176:179], v154 offset:2048
	ds_read_b128 v[180:183], v154 offset:3072
	s_add_u32 s34, s44, 0xfff80080
	s_addc_u32 s35, s45, -1
	s_cmp_eq_u32 s69, 28
	s_cselect_b32 s47, s0, s35
	s_cselect_b32 s46, s1, s34
	s_cselect_b32 s35, s27, s68
	s_cselect_b32 s34, s37, s61
	v_lshl_add_u64 v[218:219], s[44:45], 0, v[138:139]
	s_add_i32 m0, s43, 0xc000
	ds_read_b128 v[184:187], v155
	ds_read_b128 v[188:191], v155 offset:1024
	ds_read_b128 v[192:195], v155 offset:2048
	ds_read_b128 v[196:199], v155 offset:3072
	ds_read_b128 v[200:203], v155 offset:4096
	ds_read_b128 v[204:207], v155 offset:5120
	ds_read_b128 v[208:211], v155 offset:6144
	ds_read_b128 v[212:215], v155 offset:7168
	global_load_lds_dwordx4 v[218:219], off
	v_lshl_add_u64 v[218:219], s[44:45], 0, v[140:141]
	s_add_i32 m0, s43, 0xe000
	s_nop 0
	global_load_lds_dwordx4 v[218:219], off
	s_waitcnt vmcnt(8)
	s_waitcnt lgkmcnt(0)
	s_barrier
	s_setprio 1
	s_waitcnt lgkmcnt(0)
	v_mfma_f32_16x16x32_bf16 v[126:129], v[146:149], v[184:187], v[126:129]
	v_mfma_f32_16x16x32_bf16 v[118:121], v[160:163], v[184:187], v[118:121]
	v_mfma_f32_16x16x32_bf16 v[110:113], v[146:149], v[192:195], v[110:113]
	v_mfma_f32_16x16x32_bf16 v[102:105], v[160:163], v[192:195], v[102:105]
	v_mfma_f32_16x16x32_bf16 v[94:97], v[146:149], v[200:203], v[94:97]
	v_mfma_f32_16x16x32_bf16 v[86:89], v[160:163], v[200:203], v[86:89]
	v_mfma_f32_16x16x32_bf16 v[78:81], v[146:149], v[208:211], v[78:81]
	v_mfma_f32_16x16x32_bf16 v[70:73], v[160:163], v[208:211], v[70:73]
	s_setprio 0
	s_setprio 1
	v_mfma_f32_16x16x32_bf16 v[126:129], v[156:159], v[188:191], v[126:129]
	v_mfma_f32_16x16x32_bf16 v[118:121], v[164:167], v[188:191], v[118:121]
	v_mfma_f32_16x16x32_bf16 v[110:113], v[156:159], v[196:199], v[110:113]
	v_mfma_f32_16x16x32_bf16 v[102:105], v[164:167], v[196:199], v[102:105]
	v_mfma_f32_16x16x32_bf16 v[94:97], v[156:159], v[204:207], v[94:97]
	v_mfma_f32_16x16x32_bf16 v[86:89], v[164:167], v[204:207], v[86:89]
	v_mfma_f32_16x16x32_bf16 v[78:81], v[156:159], v[212:215], v[78:81]
	v_mfma_f32_16x16x32_bf16 v[70:73], v[164:167], v[212:215], v[70:73]
	s_setprio 0
	s_setprio 1
	v_mfma_f32_16x16x32_bf16 v[122:125], v[168:171], v[184:187], v[122:125]
	v_mfma_f32_16x16x32_bf16 v[114:117], v[176:179], v[184:187], v[114:117]
	v_mfma_f32_16x16x32_bf16 v[106:109], v[168:171], v[192:195], v[106:109]
	v_mfma_f32_16x16x32_bf16 v[98:101], v[176:179], v[192:195], v[98:101]
	v_mfma_f32_16x16x32_bf16 v[90:93], v[168:171], v[200:203], v[90:93]
	v_mfma_f32_16x16x32_bf16 v[82:85], v[176:179], v[200:203], v[82:85]
	v_mfma_f32_16x16x32_bf16 v[74:77], v[168:171], v[208:211], v[74:77]
	v_mfma_f32_16x16x32_bf16 v[66:69], v[176:179], v[208:211], v[66:69]
	s_setprio 0
	s_setprio 1
	v_mfma_f32_16x16x32_bf16 v[122:125], v[172:175], v[188:191], v[122:125]
	v_mfma_f32_16x16x32_bf16 v[114:117], v[180:183], v[188:191], v[114:117]
	v_mfma_f32_16x16x32_bf16 v[106:109], v[172:175], v[196:199], v[106:109]
	v_mfma_f32_16x16x32_bf16 v[98:101], v[180:183], v[196:199], v[98:101]
	v_mfma_f32_16x16x32_bf16 v[90:93], v[172:175], v[204:207], v[90:93]
	v_mfma_f32_16x16x32_bf16 v[82:85], v[180:183], v[204:207], v[82:85]
	v_mfma_f32_16x16x32_bf16 v[74:77], v[172:175], v[212:215], v[74:77]
	v_mfma_f32_16x16x32_bf16 v[66:69], v[180:183], v[212:215], v[66:69]
	s_setprio 0
	s_barrier
	s_add_i32 s62, s57, s30
	v_lshl_add_u64 v[218:219], s[34:35], 0, v[134:135]
	s_mov_b32 m0, s62
	ds_read_b128 v[184:187], v155 offset:16384
	ds_read_b128 v[188:191], v155 offset:17408
	ds_read_b128 v[192:195], v155 offset:18432
	ds_read_b128 v[196:199], v155 offset:19456
	ds_read_b128 v[200:203], v155 offset:20480
	ds_read_b128 v[204:207], v155 offset:21504
	ds_read_b128 v[208:211], v155 offset:22528
	ds_read_b128 v[212:215], v155 offset:23552
	global_load_lds_dwordx4 v[218:219], off
	s_add_i32 m0, s62, 0x2000
	s_add_u32 s62, s34, 0x80000
	v_lshl_add_u64 v[220:221], s[34:35], 0, v[130:131]
	s_addc_u32 s63, s35, 0
	s_add_i32 s66, s58, s30
	global_load_lds_dwordx4 v[220:221], off
	v_lshl_add_u64 v[222:223], s[62:63], 0, v[134:135]
	s_mov_b32 m0, s66
	v_lshl_add_u64 v[224:225], s[46:47], 0, v[132:133]
	global_load_lds_dwordx4 v[222:223], off
	v_lshl_add_u64 v[222:223], s[62:63], 0, v[130:131]
	s_add_i32 m0, s66, 0x2000
	s_nop 0
	global_load_lds_dwordx4 v[222:223], off
	v_lshl_add_u64 v[222:223], s[46:47], 0, v[136:137]
	s_mov_b32 m0, s43
	s_nop 0
	global_load_lds_dwordx4 v[222:223], off
	s_mov_b32 m0, s48
	s_nop 0
	global_load_lds_dwordx4 v[224:225], off
	s_waitcnt vmcnt(8)
	s_waitcnt lgkmcnt(0)
	s_barrier
	s_setprio 1
	s_waitcnt lgkmcnt(0)
	v_mfma_f32_16x16x32_bf16 v[62:65], v[146:149], v[184:187], v[62:65]
	v_mfma_f32_16x16x32_bf16 v[54:57], v[160:163], v[184:187], v[54:57]
	v_mfma_f32_16x16x32_bf16 v[46:49], v[146:149], v[192:195], v[46:49]
	v_mfma_f32_16x16x32_bf16 v[38:41], v[160:163], v[192:195], v[38:41]
	v_mfma_f32_16x16x32_bf16 v[30:33], v[146:149], v[200:203], v[30:33]
	v_mfma_f32_16x16x32_bf16 v[22:25], v[160:163], v[200:203], v[22:25]
	v_mfma_f32_16x16x32_bf16 v[14:17], v[146:149], v[208:211], v[14:17]
	v_mfma_f32_16x16x32_bf16 v[6:9], v[160:163], v[208:211], v[6:9]
	s_setprio 0
	s_setprio 1
	v_mfma_f32_16x16x32_bf16 v[62:65], v[156:159], v[188:191], v[62:65]
	v_mfma_f32_16x16x32_bf16 v[54:57], v[164:167], v[188:191], v[54:57]
	v_mfma_f32_16x16x32_bf16 v[46:49], v[156:159], v[196:199], v[46:49]
	v_mfma_f32_16x16x32_bf16 v[38:41], v[164:167], v[196:199], v[38:41]
	v_mfma_f32_16x16x32_bf16 v[30:33], v[156:159], v[204:207], v[30:33]
	v_mfma_f32_16x16x32_bf16 v[22:25], v[164:167], v[204:207], v[22:25]
	v_mfma_f32_16x16x32_bf16 v[14:17], v[156:159], v[212:215], v[14:17]
	v_mfma_f32_16x16x32_bf16 v[6:9], v[164:167], v[212:215], v[6:9]
	s_setprio 0
	s_setprio 1
	v_mfma_f32_16x16x32_bf16 v[58:61], v[168:171], v[184:187], v[58:61]
	v_mfma_f32_16x16x32_bf16 v[50:53], v[176:179], v[184:187], v[50:53]
	v_mfma_f32_16x16x32_bf16 v[42:45], v[168:171], v[192:195], v[42:45]
	v_mfma_f32_16x16x32_bf16 v[34:37], v[176:179], v[192:195], v[34:37]
	v_mfma_f32_16x16x32_bf16 v[26:29], v[168:171], v[200:203], v[26:29]
	v_mfma_f32_16x16x32_bf16 v[18:21], v[176:179], v[200:203], v[18:21]
	v_mfma_f32_16x16x32_bf16 v[10:13], v[168:171], v[208:211], v[10:13]
	v_mfma_f32_16x16x32_bf16 v[2:5], v[176:179], v[208:211], v[2:5]
	s_setprio 0
	s_setprio 1
	v_mfma_f32_16x16x32_bf16 v[58:61], v[172:175], v[188:191], v[58:61]
	v_mfma_f32_16x16x32_bf16 v[50:53], v[180:183], v[188:191], v[50:53]
	v_mfma_f32_16x16x32_bf16 v[42:45], v[172:175], v[196:199], v[42:45]
	v_mfma_f32_16x16x32_bf16 v[34:37], v[180:183], v[196:199], v[34:37]
	v_mfma_f32_16x16x32_bf16 v[26:29], v[172:175], v[204:207], v[26:29]
	v_mfma_f32_16x16x32_bf16 v[18:21], v[180:183], v[204:207], v[18:21]
	v_mfma_f32_16x16x32_bf16 v[10:13], v[172:175], v[212:215], v[10:13]
	v_mfma_f32_16x16x32_bf16 v[2:5], v[180:183], v[212:215], v[2:5]
	s_setprio 0
	s_barrier
	s_add_i32 s62, 0, 0x18000
	s_add_i32 s63, 0, 0x1c000
	v_add_u32_e32 v164, s62, v151
	v_add_u32_e32 v180, s63, v151
	ds_read_b128 v[146:149], v164
	ds_read_b128 v[156:159], v164 offset:1024
	ds_read_b128 v[160:163], v164 offset:2048
	ds_read_b128 v[164:167], v164 offset:3072
	ds_read_b128 v[168:171], v180
	ds_read_b128 v[172:175], v180 offset:1024
	ds_read_b128 v[176:179], v180 offset:2048
	ds_read_b128 v[180:183], v180 offset:3072
	s_add_u32 s46, s46, 0x80000
	s_addc_u32 s47, s47, 0
	s_mov_b32 m0, s49
	v_lshl_add_u64 v[226:227], s[46:47], 0, v[136:137]
	ds_read_b128 v[184:187], v155 offset:32768
	ds_read_b128 v[188:191], v155 offset:33792
	ds_read_b128 v[192:195], v155 offset:34816
	ds_read_b128 v[196:199], v155 offset:35840
	ds_read_b128 v[200:203], v155 offset:36864
	ds_read_b128 v[204:207], v155 offset:37888
	ds_read_b128 v[208:211], v155 offset:38912
	ds_read_b128 v[212:215], v155 offset:39936
	global_load_lds_dwordx4 v[226:227], off
	v_lshl_add_u64 v[226:227], s[46:47], 0, v[132:133]
	s_mov_b32 m0, s52
	s_nop 0
	global_load_lds_dwordx4 v[226:227], off
	s_waitcnt vmcnt(8)
	s_waitcnt lgkmcnt(0)
	s_barrier
	s_setprio 1
	s_waitcnt lgkmcnt(0)
	v_mfma_f32_16x16x32_bf16 v[126:129], v[146:149], v[184:187], v[126:129]
	v_mfma_f32_16x16x32_bf16 v[118:121], v[160:163], v[184:187], v[118:121]
	v_mfma_f32_16x16x32_bf16 v[110:113], v[146:149], v[192:195], v[110:113]
	v_mfma_f32_16x16x32_bf16 v[102:105], v[160:163], v[192:195], v[102:105]
	v_mfma_f32_16x16x32_bf16 v[94:97], v[146:149], v[200:203], v[94:97]
	v_mfma_f32_16x16x32_bf16 v[86:89], v[160:163], v[200:203], v[86:89]
	v_mfma_f32_16x16x32_bf16 v[78:81], v[146:149], v[208:211], v[78:81]
	v_mfma_f32_16x16x32_bf16 v[70:73], v[160:163], v[208:211], v[70:73]
	s_setprio 0
	s_setprio 1
	v_mfma_f32_16x16x32_bf16 v[126:129], v[156:159], v[188:191], v[126:129]
	v_mfma_f32_16x16x32_bf16 v[118:121], v[164:167], v[188:191], v[118:121]
	v_mfma_f32_16x16x32_bf16 v[110:113], v[156:159], v[196:199], v[110:113]
	v_mfma_f32_16x16x32_bf16 v[102:105], v[164:167], v[196:199], v[102:105]
	v_mfma_f32_16x16x32_bf16 v[94:97], v[156:159], v[204:207], v[94:97]
	v_mfma_f32_16x16x32_bf16 v[86:89], v[164:167], v[204:207], v[86:89]
	v_mfma_f32_16x16x32_bf16 v[78:81], v[156:159], v[212:215], v[78:81]
	v_mfma_f32_16x16x32_bf16 v[70:73], v[164:167], v[212:215], v[70:73]
	s_setprio 0
	s_setprio 1
	v_mfma_f32_16x16x32_bf16 v[122:125], v[168:171], v[184:187], v[122:125]
	v_mfma_f32_16x16x32_bf16 v[114:117], v[176:179], v[184:187], v[114:117]
	v_mfma_f32_16x16x32_bf16 v[106:109], v[168:171], v[192:195], v[106:109]
	v_mfma_f32_16x16x32_bf16 v[98:101], v[176:179], v[192:195], v[98:101]
	v_mfma_f32_16x16x32_bf16 v[90:93], v[168:171], v[200:203], v[90:93]
	v_mfma_f32_16x16x32_bf16 v[82:85], v[176:179], v[200:203], v[82:85]
	v_mfma_f32_16x16x32_bf16 v[74:77], v[168:171], v[208:211], v[74:77]
	v_mfma_f32_16x16x32_bf16 v[66:69], v[176:179], v[208:211], v[66:69]
	s_setprio 0
	s_setprio 1
	v_mfma_f32_16x16x32_bf16 v[122:125], v[172:175], v[188:191], v[122:125]
	v_mfma_f32_16x16x32_bf16 v[114:117], v[180:183], v[188:191], v[114:117]
	v_mfma_f32_16x16x32_bf16 v[106:109], v[172:175], v[196:199], v[106:109]
	v_mfma_f32_16x16x32_bf16 v[98:101], v[180:183], v[196:199], v[98:101]
	v_mfma_f32_16x16x32_bf16 v[90:93], v[172:175], v[204:207], v[90:93]
	v_mfma_f32_16x16x32_bf16 v[82:85], v[180:183], v[204:207], v[82:85]
	v_mfma_f32_16x16x32_bf16 v[74:77], v[172:175], v[212:215], v[74:77]
	v_mfma_f32_16x16x32_bf16 v[66:69], v[180:183], v[212:215], v[66:69]
	s_setprio 0
	s_barrier
	s_add_i32 s46, s62, s30
	v_lshl_add_u64 v[218:219], v[218:219], 0, s[8:9]
	s_mov_b32 m0, s46
	ds_read_b128 v[184:187], v155 offset:49152
	ds_read_b128 v[188:191], v155 offset:50176
	ds_read_b128 v[192:195], v155 offset:51200
	ds_read_b128 v[196:199], v155 offset:52224
	ds_read_b128 v[200:203], v155 offset:53248
	ds_read_b128 v[204:207], v155 offset:54272
	ds_read_b128 v[208:211], v155 offset:55296
	ds_read_b128 v[212:215], v155 offset:56320
	global_load_lds_dwordx4 v[218:219], off
	s_add_i32 m0, s46, 0x2000
	s_add_u32 s34, s34, 0x80080
	v_lshl_add_u64 v[218:219], v[220:221], 0, s[8:9]
	s_addc_u32 s35, s35, 0
	s_add_i32 s46, s63, s30
	global_load_lds_dwordx4 v[218:219], off
	v_lshl_add_u64 v[218:219], s[34:35], 0, v[134:135]
	s_mov_b32 m0, s46
	s_nop 0
	global_load_lds_dwordx4 v[218:219], off
	v_lshl_add_u64 v[218:219], s[34:35], 0, v[130:131]
	s_add_i32 m0, s46, 0x2000
	s_nop 0
	global_load_lds_dwordx4 v[218:219], off
	v_lshl_add_u64 v[218:219], v[222:223], 0, s[8:9]
	s_mov_b32 m0, s54
	s_nop 0
	global_load_lds_dwordx4 v[218:219], off
	v_lshl_add_u64 v[218:219], v[224:225], 0, s[8:9]
	s_mov_b32 m0, s55
	s_nop 0
	global_load_lds_dwordx4 v[218:219], off
	s_waitcnt vmcnt(8)
	s_waitcnt lgkmcnt(0)
	s_barrier
	s_setprio 1
	s_waitcnt lgkmcnt(0)
	v_mfma_f32_16x16x32_bf16 v[62:65], v[146:149], v[184:187], v[62:65]
	v_mfma_f32_16x16x32_bf16 v[54:57], v[160:163], v[184:187], v[54:57]
	v_mfma_f32_16x16x32_bf16 v[46:49], v[146:149], v[192:195], v[46:49]
	v_mfma_f32_16x16x32_bf16 v[38:41], v[160:163], v[192:195], v[38:41]
	v_mfma_f32_16x16x32_bf16 v[30:33], v[146:149], v[200:203], v[30:33]
	v_mfma_f32_16x16x32_bf16 v[22:25], v[160:163], v[200:203], v[22:25]
	v_mfma_f32_16x16x32_bf16 v[14:17], v[146:149], v[208:211], v[14:17]
	v_mfma_f32_16x16x32_bf16 v[6:9], v[160:163], v[208:211], v[6:9]
	s_setprio 0
	s_setprio 1
	v_mfma_f32_16x16x32_bf16 v[62:65], v[156:159], v[188:191], v[62:65]
	v_mfma_f32_16x16x32_bf16 v[54:57], v[164:167], v[188:191], v[54:57]
	v_mfma_f32_16x16x32_bf16 v[46:49], v[156:159], v[196:199], v[46:49]
	v_mfma_f32_16x16x32_bf16 v[38:41], v[164:167], v[196:199], v[38:41]
	v_mfma_f32_16x16x32_bf16 v[30:33], v[156:159], v[204:207], v[30:33]
	v_mfma_f32_16x16x32_bf16 v[22:25], v[164:167], v[204:207], v[22:25]
	v_mfma_f32_16x16x32_bf16 v[14:17], v[156:159], v[212:215], v[14:17]
	v_mfma_f32_16x16x32_bf16 v[6:9], v[164:167], v[212:215], v[6:9]
	s_setprio 0
	s_setprio 1
	v_mfma_f32_16x16x32_bf16 v[58:61], v[168:171], v[184:187], v[58:61]
	v_mfma_f32_16x16x32_bf16 v[50:53], v[176:179], v[184:187], v[50:53]
	v_mfma_f32_16x16x32_bf16 v[42:45], v[168:171], v[192:195], v[42:45]
	v_mfma_f32_16x16x32_bf16 v[34:37], v[176:179], v[192:195], v[34:37]
	v_mfma_f32_16x16x32_bf16 v[26:29], v[168:171], v[200:203], v[26:29]
	v_mfma_f32_16x16x32_bf16 v[18:21], v[176:179], v[200:203], v[18:21]
	v_mfma_f32_16x16x32_bf16 v[10:13], v[168:171], v[208:211], v[10:13]
	v_mfma_f32_16x16x32_bf16 v[2:5], v[176:179], v[208:211], v[2:5]
	s_setprio 0
	s_setprio 1
	v_mfma_f32_16x16x32_bf16 v[58:61], v[172:175], v[188:191], v[58:61]
	v_mfma_f32_16x16x32_bf16 v[50:53], v[180:183], v[188:191], v[50:53]
	v_mfma_f32_16x16x32_bf16 v[42:45], v[172:175], v[196:199], v[42:45]
	v_mfma_f32_16x16x32_bf16 v[34:37], v[180:183], v[196:199], v[34:37]
	v_mfma_f32_16x16x32_bf16 v[26:29], v[172:175], v[204:207], v[26:29]
	v_mfma_f32_16x16x32_bf16 v[18:21], v[180:183], v[204:207], v[18:21]
	v_mfma_f32_16x16x32_bf16 v[10:13], v[172:175], v[212:215], v[10:13]
	v_mfma_f32_16x16x32_bf16 v[2:5], v[180:183], v[212:215], v[2:5]
	s_setprio 0
	s_barrier
	s_add_i32 s69, s69, 2
	s_add_u32 s44, s44, 0x100
	s_addc_u32 s45, s45, 0
	s_add_u32 s61, s61, 0x100
	s_addc_u32 s68, s68, 0
	s_cmp_gt_u32 s69, 29
	s_cbranch_scc0 .LBB0_3309
	s_and_b64 vcc, exec, s[24:25]
	s_cbranch_vccz .LBB0_3312
	s_barrier

.LBB0_3533:
	ds_read_b128 v[154:157], v151
	ds_read_b128 v[158:161], v151 offset:1024
	ds_read_b128 v[162:165], v151 offset:2048
	ds_read_b128 v[166:169], v151 offset:3072
	ds_read_b128 v[170:173], v152
	ds_read_b128 v[174:177], v152 offset:1024
	ds_read_b128 v[178:181], v152 offset:2048
	ds_read_b128 v[182:185], v152 offset:3072
	s_add_u32 s34, s44, 0xfff80080
	s_addc_u32 s35, s45, -1
	s_cmp_eq_u32 s68, 28
	s_cselect_b32 s47, s0, s35
	s_cselect_b32 s46, s1, s34
	s_cselect_b32 s35, s27, s61
	s_cselect_b32 s34, s37, s60
	v_lshl_add_u64 v[146:147], s[44:45], 0, v[138:139]
	s_add_i32 m0, s33, 0xc000
	ds_read_b128 v[186:189], v153
	ds_read_b128 v[190:193], v153 offset:1024
	ds_read_b128 v[194:197], v153 offset:2048
	ds_read_b128 v[198:201], v153 offset:3072
	ds_read_b128 v[202:205], v153 offset:4096
	ds_read_b128 v[206:209], v153 offset:5120
	ds_read_b128 v[210:213], v153 offset:6144
	ds_read_b128 v[218:221], v153 offset:7168
	global_load_lds_dwordx4 v[146:147], off
	v_lshl_add_u64 v[146:147], s[44:45], 0, v[140:141]
	s_add_i32 m0, s33, 0xe000
	s_nop 0
	global_load_lds_dwordx4 v[146:147], off
	s_waitcnt vmcnt(8)
	s_waitcnt lgkmcnt(0)
	s_barrier
	s_setprio 1
	s_waitcnt lgkmcnt(0)
	v_mfma_f32_16x16x32_bf16 v[126:129], v[154:157], v[186:189], v[126:129]
	v_mfma_f32_16x16x32_bf16 v[122:125], v[162:165], v[186:189], v[122:125]
	v_mfma_f32_16x16x32_bf16 v[114:117], v[154:157], v[194:197], v[114:117]
	v_mfma_f32_16x16x32_bf16 v[106:109], v[162:165], v[194:197], v[106:109]
	v_mfma_f32_16x16x32_bf16 v[98:101], v[154:157], v[202:205], v[98:101]
	v_mfma_f32_16x16x32_bf16 v[90:93], v[162:165], v[202:205], v[90:93]
	v_mfma_f32_16x16x32_bf16 v[82:85], v[154:157], v[210:213], v[82:85]
	v_mfma_f32_16x16x32_bf16 v[74:77], v[162:165], v[210:213], v[74:77]
	s_setprio 0
	s_setprio 1
	v_mfma_f32_16x16x32_bf16 v[126:129], v[158:161], v[190:193], v[126:129]
	v_mfma_f32_16x16x32_bf16 v[122:125], v[166:169], v[190:193], v[122:125]
	v_mfma_f32_16x16x32_bf16 v[114:117], v[158:161], v[198:201], v[114:117]
	v_mfma_f32_16x16x32_bf16 v[106:109], v[166:169], v[198:201], v[106:109]
	v_mfma_f32_16x16x32_bf16 v[98:101], v[158:161], v[206:209], v[98:101]
	v_mfma_f32_16x16x32_bf16 v[90:93], v[166:169], v[206:209], v[90:93]
	v_mfma_f32_16x16x32_bf16 v[82:85], v[158:161], v[218:221], v[82:85]
	v_mfma_f32_16x16x32_bf16 v[74:77], v[166:169], v[218:221], v[74:77]
	s_setprio 0
	s_setprio 1
	v_mfma_f32_16x16x32_bf16 v[118:121], v[170:173], v[186:189], v[118:121]
	v_mfma_f32_16x16x32_bf16 v[110:113], v[178:181], v[186:189], v[110:113]
	v_mfma_f32_16x16x32_bf16 v[102:105], v[170:173], v[194:197], v[102:105]
	v_mfma_f32_16x16x32_bf16 v[94:97], v[178:181], v[194:197], v[94:97]
	v_mfma_f32_16x16x32_bf16 v[86:89], v[170:173], v[202:205], v[86:89]
	v_mfma_f32_16x16x32_bf16 v[78:81], v[178:181], v[202:205], v[78:81]
	v_mfma_f32_16x16x32_bf16 v[70:73], v[170:173], v[210:213], v[70:73]
	v_mfma_f32_16x16x32_bf16 v[66:69], v[178:181], v[210:213], v[66:69]
	s_setprio 0
	s_setprio 1
	v_mfma_f32_16x16x32_bf16 v[118:121], v[174:177], v[190:193], v[118:121]
	v_mfma_f32_16x16x32_bf16 v[110:113], v[182:185], v[190:193], v[110:113]
	v_mfma_f32_16x16x32_bf16 v[102:105], v[174:177], v[198:201], v[102:105]
	v_mfma_f32_16x16x32_bf16 v[94:97], v[182:185], v[198:201], v[94:97]
	v_mfma_f32_16x16x32_bf16 v[86:89], v[174:177], v[206:209], v[86:89]
	v_mfma_f32_16x16x32_bf16 v[78:81], v[182:185], v[206:209], v[78:81]
	v_mfma_f32_16x16x32_bf16 v[70:73], v[174:177], v[218:221], v[70:73]
	v_mfma_f32_16x16x32_bf16 v[66:69], v[182:185], v[218:221], v[66:69]
	s_setprio 0
	s_barrier
	s_add_i32 s62, s56, s12
	v_lshl_add_u64 v[146:147], s[34:35], 0, v[134:135]
	s_mov_b32 m0, s62
	ds_read_b128 v[186:189], v153 offset:16384
	ds_read_b128 v[190:193], v153 offset:17408
	ds_read_b128 v[194:197], v153 offset:18432
	ds_read_b128 v[198:201], v153 offset:19456
	ds_read_b128 v[202:205], v153 offset:20480
	ds_read_b128 v[206:209], v153 offset:21504
	ds_read_b128 v[210:213], v153 offset:22528
	ds_read_b128 v[218:221], v153 offset:23552
	global_load_lds_dwordx4 v[146:147], off
	s_add_i32 m0, s62, 0x2000
	s_add_u32 s62, s34, 0x80000
	v_lshl_add_u64 v[214:215], s[34:35], 0, v[130:131]
	s_addc_u32 s63, s35, 0
	s_add_i32 s66, s57, s12
	global_load_lds_dwordx4 v[214:215], off
	v_lshl_add_u64 v[222:223], s[62:63], 0, v[134:135]
	s_mov_b32 m0, s66
	v_lshl_add_u64 v[224:225], s[46:47], 0, v[132:133]
	global_load_lds_dwordx4 v[222:223], off
	v_lshl_add_u64 v[222:223], s[62:63], 0, v[130:131]
	s_add_i32 m0, s66, 0x2000
	s_nop 0
	global_load_lds_dwordx4 v[222:223], off
	v_lshl_add_u64 v[222:223], s[46:47], 0, v[136:137]
	s_mov_b32 m0, s33
	s_nop 0
	global_load_lds_dwordx4 v[222:223], off
	s_mov_b32 m0, s43
	s_nop 0
	global_load_lds_dwordx4 v[224:225], off
	s_waitcnt vmcnt(8)
	s_waitcnt lgkmcnt(0)
	s_barrier
	s_setprio 1
	s_waitcnt lgkmcnt(0)
	v_mfma_f32_16x16x32_bf16 v[62:65], v[154:157], v[186:189], v[62:65]
	v_mfma_f32_16x16x32_bf16 v[58:61], v[162:165], v[186:189], v[58:61]
	v_mfma_f32_16x16x32_bf16 v[50:53], v[154:157], v[194:197], v[50:53]
	v_mfma_f32_16x16x32_bf16 v[42:45], v[162:165], v[194:197], v[42:45]
	v_mfma_f32_16x16x32_bf16 v[34:37], v[154:157], v[202:205], v[34:37]
	v_mfma_f32_16x16x32_bf16 v[26:29], v[162:165], v[202:205], v[26:29]
	v_mfma_f32_16x16x32_bf16 v[18:21], v[154:157], v[210:213], v[18:21]
	v_mfma_f32_16x16x32_bf16 v[10:13], v[162:165], v[210:213], v[10:13]
	s_setprio 0
	s_setprio 1
	v_mfma_f32_16x16x32_bf16 v[62:65], v[158:161], v[190:193], v[62:65]
	v_mfma_f32_16x16x32_bf16 v[58:61], v[166:169], v[190:193], v[58:61]
	v_mfma_f32_16x16x32_bf16 v[50:53], v[158:161], v[198:201], v[50:53]
	v_mfma_f32_16x16x32_bf16 v[42:45], v[166:169], v[198:201], v[42:45]
	v_mfma_f32_16x16x32_bf16 v[34:37], v[158:161], v[206:209], v[34:37]
	v_mfma_f32_16x16x32_bf16 v[26:29], v[166:169], v[206:209], v[26:29]
	v_mfma_f32_16x16x32_bf16 v[18:21], v[158:161], v[218:221], v[18:21]
	v_mfma_f32_16x16x32_bf16 v[10:13], v[166:169], v[218:221], v[10:13]
	s_setprio 0
	s_setprio 1
	v_mfma_f32_16x16x32_bf16 v[54:57], v[170:173], v[186:189], v[54:57]
	v_mfma_f32_16x16x32_bf16 v[46:49], v[178:181], v[186:189], v[46:49]
	v_mfma_f32_16x16x32_bf16 v[38:41], v[170:173], v[194:197], v[38:41]
	v_mfma_f32_16x16x32_bf16 v[30:33], v[178:181], v[194:197], v[30:33]
	v_mfma_f32_16x16x32_bf16 v[22:25], v[170:173], v[202:205], v[22:25]
	v_mfma_f32_16x16x32_bf16 v[14:17], v[178:181], v[202:205], v[14:17]
	v_mfma_f32_16x16x32_bf16 v[6:9], v[170:173], v[210:213], v[6:9]
	v_mfma_f32_16x16x32_bf16 v[2:5], v[178:181], v[210:213], v[2:5]
	s_setprio 0
	s_setprio 1
	v_mfma_f32_16x16x32_bf16 v[54:57], v[174:177], v[190:193], v[54:57]
	v_mfma_f32_16x16x32_bf16 v[46:49], v[182:185], v[190:193], v[46:49]
	v_mfma_f32_16x16x32_bf16 v[38:41], v[174:177], v[198:201], v[38:41]
	v_mfma_f32_16x16x32_bf16 v[30:33], v[182:185], v[198:201], v[30:33]
	v_mfma_f32_16x16x32_bf16 v[22:25], v[174:177], v[206:209], v[22:25]
	v_mfma_f32_16x16x32_bf16 v[14:17], v[182:185], v[206:209], v[14:17]
	v_mfma_f32_16x16x32_bf16 v[6:9], v[174:177], v[218:221], v[6:9]
	v_mfma_f32_16x16x32_bf16 v[2:5], v[182:185], v[218:221], v[2:5]
	s_setprio 0
	s_barrier
	s_add_i32 s62, 0, 0x18000
	s_add_i32 s63, 0, 0x1c000
	v_add_u32_e32 v166, s62, v149
	v_add_u32_e32 v182, s63, v149
	ds_read_b128 v[154:157], v166
	ds_read_b128 v[158:161], v166 offset:1024
	ds_read_b128 v[162:165], v166 offset:2048
	ds_read_b128 v[166:169], v166 offset:3072
	ds_read_b128 v[170:173], v182
	ds_read_b128 v[174:177], v182 offset:1024
	ds_read_b128 v[178:181], v182 offset:2048
	ds_read_b128 v[182:185], v182 offset:3072
	s_add_u32 s46, s46, 0x80000
	s_addc_u32 s47, s47, 0
	s_mov_b32 m0, s48
	v_lshl_add_u64 v[226:227], s[46:47], 0, v[136:137]
	ds_read_b128 v[186:189], v153 offset:32768
	ds_read_b128 v[190:193], v153 offset:33792
	ds_read_b128 v[194:197], v153 offset:34816
	ds_read_b128 v[198:201], v153 offset:35840
	ds_read_b128 v[202:205], v153 offset:36864
	ds_read_b128 v[206:209], v153 offset:37888
	ds_read_b128 v[210:213], v153 offset:38912
	ds_read_b128 v[218:221], v153 offset:39936
	global_load_lds_dwordx4 v[226:227], off
	v_lshl_add_u64 v[226:227], s[46:47], 0, v[132:133]
	s_mov_b32 m0, s49
	s_nop 0
	global_load_lds_dwordx4 v[226:227], off
	s_waitcnt vmcnt(8)
	s_waitcnt lgkmcnt(0)
	s_barrier
	s_setprio 1
	s_waitcnt lgkmcnt(0)
	v_mfma_f32_16x16x32_bf16 v[126:129], v[154:157], v[186:189], v[126:129]
	v_mfma_f32_16x16x32_bf16 v[122:125], v[162:165], v[186:189], v[122:125]
	v_mfma_f32_16x16x32_bf16 v[114:117], v[154:157], v[194:197], v[114:117]
	v_mfma_f32_16x16x32_bf16 v[106:109], v[162:165], v[194:197], v[106:109]
	v_mfma_f32_16x16x32_bf16 v[98:101], v[154:157], v[202:205], v[98:101]
	v_mfma_f32_16x16x32_bf16 v[90:93], v[162:165], v[202:205], v[90:93]
	v_mfma_f32_16x16x32_bf16 v[82:85], v[154:157], v[210:213], v[82:85]
	v_mfma_f32_16x16x32_bf16 v[74:77], v[162:165], v[210:213], v[74:77]
	s_setprio 0
	s_setprio 1
	v_mfma_f32_16x16x32_bf16 v[126:129], v[158:161], v[190:193], v[126:129]
	v_mfma_f32_16x16x32_bf16 v[122:125], v[166:169], v[190:193], v[122:125]
	v_mfma_f32_16x16x32_bf16 v[114:117], v[158:161], v[198:201], v[114:117]
	v_mfma_f32_16x16x32_bf16 v[106:109], v[166:169], v[198:201], v[106:109]
	v_mfma_f32_16x16x32_bf16 v[98:101], v[158:161], v[206:209], v[98:101]
	v_mfma_f32_16x16x32_bf16 v[90:93], v[166:169], v[206:209], v[90:93]
	v_mfma_f32_16x16x32_bf16 v[82:85], v[158:161], v[218:221], v[82:85]
	v_mfma_f32_16x16x32_bf16 v[74:77], v[166:169], v[218:221], v[74:77]
	s_setprio 0
	s_setprio 1
	v_mfma_f32_16x16x32_bf16 v[118:121], v[170:173], v[186:189], v[118:121]
	v_mfma_f32_16x16x32_bf16 v[110:113], v[178:181], v[186:189], v[110:113]
	v_mfma_f32_16x16x32_bf16 v[102:105], v[170:173], v[194:197], v[102:105]
	v_mfma_f32_16x16x32_bf16 v[94:97], v[178:181], v[194:197], v[94:97]
	v_mfma_f32_16x16x32_bf16 v[86:89], v[170:173], v[202:205], v[86:89]
	v_mfma_f32_16x16x32_bf16 v[78:81], v[178:181], v[202:205], v[78:81]
	v_mfma_f32_16x16x32_bf16 v[70:73], v[170:173], v[210:213], v[70:73]
	v_mfma_f32_16x16x32_bf16 v[66:69], v[178:181], v[210:213], v[66:69]
	s_setprio 0
	s_setprio 1
	v_mfma_f32_16x16x32_bf16 v[118:121], v[174:177], v[190:193], v[118:121]
	v_mfma_f32_16x16x32_bf16 v[110:113], v[182:185], v[190:193], v[110:113]
	v_mfma_f32_16x16x32_bf16 v[102:105], v[174:177], v[198:201], v[102:105]
	v_mfma_f32_16x16x32_bf16 v[94:97], v[182:185], v[198:201], v[94:97]
	v_mfma_f32_16x16x32_bf16 v[86:89], v[174:177], v[206:209], v[86:89]
	v_mfma_f32_16x16x32_bf16 v[78:81], v[182:185], v[206:209], v[78:81]
	v_mfma_f32_16x16x32_bf16 v[70:73], v[174:177], v[218:221], v[70:73]
	v_mfma_f32_16x16x32_bf16 v[66:69], v[182:185], v[218:221], v[66:69]
	s_setprio 0
	s_barrier
	s_add_i32 s46, s62, s12
	v_lshl_add_u64 v[146:147], v[146:147], 0, s[8:9]
	s_mov_b32 m0, s46
	ds_read_b128 v[186:189], v153 offset:49152
	ds_read_b128 v[190:193], v153 offset:50176
	ds_read_b128 v[194:197], v153 offset:51200
	ds_read_b128 v[198:201], v153 offset:52224
	ds_read_b128 v[202:205], v153 offset:53248
	ds_read_b128 v[206:209], v153 offset:54272
	ds_read_b128 v[210:213], v153 offset:55296
	ds_read_b128 v[218:221], v153 offset:56320
	global_load_lds_dwordx4 v[146:147], off
	s_add_i32 m0, s46, 0x2000
	s_add_u32 s34, s34, 0x80080
	v_lshl_add_u64 v[146:147], v[214:215], 0, s[8:9]
	s_addc_u32 s35, s35, 0
	s_add_i32 s46, s63, s12
	global_load_lds_dwordx4 v[146:147], off
	v_lshl_add_u64 v[146:147], s[34:35], 0, v[134:135]
	s_mov_b32 m0, s46
	s_nop 0
	global_load_lds_dwordx4 v[146:147], off
	v_lshl_add_u64 v[146:147], s[34:35], 0, v[130:131]
	s_add_i32 m0, s46, 0x2000
	s_nop 0
	global_load_lds_dwordx4 v[146:147], off
	v_lshl_add_u64 v[146:147], v[222:223], 0, s[8:9]
	s_mov_b32 m0, s53
	s_nop 0
	global_load_lds_dwordx4 v[146:147], off
	v_lshl_add_u64 v[146:147], v[224:225], 0, s[8:9]
	s_mov_b32 m0, s54
	s_nop 0
	global_load_lds_dwordx4 v[146:147], off
	s_waitcnt vmcnt(8)
	s_waitcnt lgkmcnt(0)
	s_barrier
	s_setprio 1
	s_waitcnt lgkmcnt(0)
	v_mfma_f32_16x16x32_bf16 v[62:65], v[154:157], v[186:189], v[62:65]
	v_mfma_f32_16x16x32_bf16 v[58:61], v[162:165], v[186:189], v[58:61]
	v_mfma_f32_16x16x32_bf16 v[50:53], v[154:157], v[194:197], v[50:53]
	v_mfma_f32_16x16x32_bf16 v[42:45], v[162:165], v[194:197], v[42:45]
	v_mfma_f32_16x16x32_bf16 v[34:37], v[154:157], v[202:205], v[34:37]
	v_mfma_f32_16x16x32_bf16 v[26:29], v[162:165], v[202:205], v[26:29]
	v_mfma_f32_16x16x32_bf16 v[18:21], v[154:157], v[210:213], v[18:21]
	v_mfma_f32_16x16x32_bf16 v[10:13], v[162:165], v[210:213], v[10:13]
	s_setprio 0
	s_setprio 1
	v_mfma_f32_16x16x32_bf16 v[62:65], v[158:161], v[190:193], v[62:65]
	v_mfma_f32_16x16x32_bf16 v[58:61], v[166:169], v[190:193], v[58:61]
	v_mfma_f32_16x16x32_bf16 v[50:53], v[158:161], v[198:201], v[50:53]
	v_mfma_f32_16x16x32_bf16 v[42:45], v[166:169], v[198:201], v[42:45]
	v_mfma_f32_16x16x32_bf16 v[34:37], v[158:161], v[206:209], v[34:37]
	v_mfma_f32_16x16x32_bf16 v[26:29], v[166:169], v[206:209], v[26:29]
	v_mfma_f32_16x16x32_bf16 v[18:21], v[158:161], v[218:221], v[18:21]
	v_mfma_f32_16x16x32_bf16 v[10:13], v[166:169], v[218:221], v[10:13]
	s_setprio 0
	s_setprio 1
	v_mfma_f32_16x16x32_bf16 v[54:57], v[170:173], v[186:189], v[54:57]
	v_mfma_f32_16x16x32_bf16 v[46:49], v[178:181], v[186:189], v[46:49]
	v_mfma_f32_16x16x32_bf16 v[38:41], v[170:173], v[194:197], v[38:41]
	v_mfma_f32_16x16x32_bf16 v[30:33], v[178:181], v[194:197], v[30:33]
	v_mfma_f32_16x16x32_bf16 v[22:25], v[170:173], v[202:205], v[22:25]
	v_mfma_f32_16x16x32_bf16 v[14:17], v[178:181], v[202:205], v[14:17]
	v_mfma_f32_16x16x32_bf16 v[6:9], v[170:173], v[210:213], v[6:9]
	v_mfma_f32_16x16x32_bf16 v[2:5], v[178:181], v[210:213], v[2:5]
	s_setprio 0
	s_setprio 1
	v_mfma_f32_16x16x32_bf16 v[54:57], v[174:177], v[190:193], v[54:57]
	v_mfma_f32_16x16x32_bf16 v[46:49], v[182:185], v[190:193], v[46:49]
	v_mfma_f32_16x16x32_bf16 v[38:41], v[174:177], v[198:201], v[38:41]
	v_mfma_f32_16x16x32_bf16 v[30:33], v[182:185], v[198:201], v[30:33]
	v_mfma_f32_16x16x32_bf16 v[22:25], v[174:177], v[206:209], v[22:25]
	v_mfma_f32_16x16x32_bf16 v[14:17], v[182:185], v[206:209], v[14:17]
	v_mfma_f32_16x16x32_bf16 v[6:9], v[174:177], v[218:221], v[6:9]
	v_mfma_f32_16x16x32_bf16 v[2:5], v[182:185], v[218:221], v[2:5]
	s_setprio 0
	s_barrier
	s_add_i32 s68, s68, 2
	s_add_u32 s44, s44, 0x100
	s_addc_u32 s45, s45, 0
	s_add_u32 s60, s60, 0x100
	s_addc_u32 s61, s61, 0
	s_cmp_gt_u32 s68, 29
	s_cbranch_scc0 .LBB0_3533
	s_and_b64 vcc, exec, s[24:25]
	s_cbranch_vccz .LBB0_3536
	s_barrier

.LBB0_3706:
	ds_read_b128 v[130:133], v174
	ds_read_b128 v[134:137], v174 offset:1024
	ds_read_b128 v[138:141], v174 offset:2048
	ds_read_b128 v[158:161], v174 offset:3072
	ds_read_b128 v[162:165], v175
	ds_read_b128 v[166:169], v175 offset:1024
	ds_read_b128 v[178:181], v175 offset:2048
	ds_read_b128 v[182:185], v175 offset:3072
	s_add_u32 s34, s42, 0xfff80080
	s_addc_u32 s35, s43, -1
	s_cmp_eq_u32 s60, 28
	s_cselect_b32 s45, s0, s35
	s_cselect_b32 s44, s1, s34
	s_cselect_b32 s35, s25, s59
	s_cselect_b32 s34, s27, s58
	v_lshl_add_u64 v[170:171], s[42:43], 0, v[150:151]
	s_add_i32 m0, s41, 0xc000
	ds_read_b128 v[186:189], v176
	ds_read_b128 v[190:193], v176 offset:1024
	ds_read_b128 v[194:197], v176 offset:2048
	ds_read_b128 v[198:201], v176 offset:3072
	ds_read_b128 v[202:205], v176 offset:4096
	ds_read_b128 v[206:209], v176 offset:5120
	ds_read_b128 v[210:213], v176 offset:6144
	ds_read_b128 v[218:221], v176 offset:7168
	global_load_lds_dwordx4 v[170:171], off
	v_lshl_add_u64 v[170:171], s[42:43], 0, v[152:153]
	s_add_i32 m0, s41, 0xe000
	s_nop 0
	global_load_lds_dwordx4 v[170:171], off
	s_waitcnt vmcnt(8)
	s_waitcnt lgkmcnt(0)
	s_barrier
	s_setprio 1
	s_waitcnt lgkmcnt(0)
	v_mfma_f32_16x16x32_bf16 v[126:129], v[130:133], v[186:189], v[126:129]
	v_mfma_f32_16x16x32_bf16 v[122:125], v[138:141], v[186:189], v[122:125]
	v_mfma_f32_16x16x32_bf16 v[110:113], v[130:133], v[194:197], v[110:113]
	v_mfma_f32_16x16x32_bf16 v[106:109], v[138:141], v[194:197], v[106:109]
	v_mfma_f32_16x16x32_bf16 v[94:97], v[130:133], v[202:205], v[94:97]
	v_mfma_f32_16x16x32_bf16 v[90:93], v[138:141], v[202:205], v[90:93]
	v_mfma_f32_16x16x32_bf16 v[78:81], v[130:133], v[210:213], v[78:81]
	v_mfma_f32_16x16x32_bf16 v[74:77], v[138:141], v[210:213], v[74:77]
	s_setprio 0
	s_setprio 1
	v_mfma_f32_16x16x32_bf16 v[126:129], v[134:137], v[190:193], v[126:129]
	v_mfma_f32_16x16x32_bf16 v[122:125], v[158:161], v[190:193], v[122:125]
	v_mfma_f32_16x16x32_bf16 v[110:113], v[134:137], v[198:201], v[110:113]
	v_mfma_f32_16x16x32_bf16 v[106:109], v[158:161], v[198:201], v[106:109]
	v_mfma_f32_16x16x32_bf16 v[94:97], v[134:137], v[206:209], v[94:97]
	v_mfma_f32_16x16x32_bf16 v[90:93], v[158:161], v[206:209], v[90:93]
	v_mfma_f32_16x16x32_bf16 v[78:81], v[134:137], v[218:221], v[78:81]
	v_mfma_f32_16x16x32_bf16 v[74:77], v[158:161], v[218:221], v[74:77]
	s_setprio 0
	s_setprio 1
	v_mfma_f32_16x16x32_bf16 v[118:121], v[162:165], v[186:189], v[118:121]
	v_mfma_f32_16x16x32_bf16 v[114:117], v[178:181], v[186:189], v[114:117]
	v_mfma_f32_16x16x32_bf16 v[102:105], v[162:165], v[194:197], v[102:105]
	v_mfma_f32_16x16x32_bf16 v[98:101], v[178:181], v[194:197], v[98:101]
	v_mfma_f32_16x16x32_bf16 v[86:89], v[162:165], v[202:205], v[86:89]
	v_mfma_f32_16x16x32_bf16 v[82:85], v[178:181], v[202:205], v[82:85]
	v_mfma_f32_16x16x32_bf16 v[70:73], v[162:165], v[210:213], v[70:73]
	v_mfma_f32_16x16x32_bf16 v[66:69], v[178:181], v[210:213], v[66:69]
	s_setprio 0
	s_setprio 1
	v_mfma_f32_16x16x32_bf16 v[118:121], v[166:169], v[190:193], v[118:121]
	v_mfma_f32_16x16x32_bf16 v[114:117], v[182:185], v[190:193], v[114:117]
	v_mfma_f32_16x16x32_bf16 v[102:105], v[166:169], v[198:201], v[102:105]
	v_mfma_f32_16x16x32_bf16 v[98:101], v[182:185], v[198:201], v[98:101]
	v_mfma_f32_16x16x32_bf16 v[86:89], v[166:169], v[206:209], v[86:89]
	v_mfma_f32_16x16x32_bf16 v[82:85], v[182:185], v[206:209], v[82:85]
	v_mfma_f32_16x16x32_bf16 v[70:73], v[166:169], v[218:221], v[70:73]
	v_mfma_f32_16x16x32_bf16 v[66:69], v[182:185], v[218:221], v[66:69]
	s_setprio 0
	s_barrier
	s_add_i32 s61, s54, s46
	v_lshl_add_u64 v[170:171], s[34:35], 0, v[144:145]
	s_mov_b32 m0, s61
	ds_read_b128 v[186:189], v176 offset:16384
	ds_read_b128 v[190:193], v176 offset:17408
	ds_read_b128 v[194:197], v176 offset:18432
	ds_read_b128 v[198:201], v176 offset:19456
	ds_read_b128 v[202:205], v176 offset:20480
	ds_read_b128 v[206:209], v176 offset:21504
	ds_read_b128 v[210:213], v176 offset:22528
	ds_read_b128 v[218:221], v176 offset:23552
	global_load_lds_dwordx4 v[170:171], off
	s_add_i32 m0, s61, 0x2000
	s_add_u32 s62, s34, 0x80000
	v_lshl_add_u64 v[214:215], s[34:35], 0, v[148:149]
	s_addc_u32 s63, s35, 0
	s_add_i32 s61, s55, s46
	global_load_lds_dwordx4 v[214:215], off
	v_lshl_add_u64 v[222:223], s[62:63], 0, v[144:145]
	s_mov_b32 m0, s61
	v_lshl_add_u64 v[224:225], s[44:45], 0, v[146:147]
	global_load_lds_dwordx4 v[222:223], off
	v_lshl_add_u64 v[222:223], s[62:63], 0, v[148:149]
	s_add_i32 m0, s61, 0x2000
	s_nop 0
	global_load_lds_dwordx4 v[222:223], off
	v_lshl_add_u64 v[222:223], s[44:45], 0, v[142:143]
	s_mov_b32 m0, s41
	s_nop 0
	global_load_lds_dwordx4 v[222:223], off
	s_mov_b32 m0, s47
	s_nop 0
	global_load_lds_dwordx4 v[224:225], off
	s_waitcnt vmcnt(8)
	s_waitcnt lgkmcnt(0)
	s_barrier
	s_setprio 1
	s_waitcnt lgkmcnt(0)
	v_mfma_f32_16x16x32_bf16 v[62:65], v[130:133], v[186:189], v[62:65]
	v_mfma_f32_16x16x32_bf16 v[58:61], v[138:141], v[186:189], v[58:61]
	v_mfma_f32_16x16x32_bf16 v[50:53], v[130:133], v[194:197], v[50:53]
	v_mfma_f32_16x16x32_bf16 v[42:45], v[138:141], v[194:197], v[42:45]
	v_mfma_f32_16x16x32_bf16 v[38:41], v[130:133], v[202:205], v[38:41]
	v_mfma_f32_16x16x32_bf16 v[34:37], v[138:141], v[202:205], v[34:37]
	v_mfma_f32_16x16x32_bf16 v[14:17], v[130:133], v[210:213], v[14:17]
	v_mfma_f32_16x16x32_bf16 v[10:13], v[138:141], v[210:213], v[10:13]
	s_setprio 0
	s_setprio 1
	v_mfma_f32_16x16x32_bf16 v[62:65], v[134:137], v[190:193], v[62:65]
	v_mfma_f32_16x16x32_bf16 v[58:61], v[158:161], v[190:193], v[58:61]
	v_mfma_f32_16x16x32_bf16 v[50:53], v[134:137], v[198:201], v[50:53]
	v_mfma_f32_16x16x32_bf16 v[42:45], v[158:161], v[198:201], v[42:45]
	v_mfma_f32_16x16x32_bf16 v[38:41], v[134:137], v[206:209], v[38:41]
	v_mfma_f32_16x16x32_bf16 v[34:37], v[158:161], v[206:209], v[34:37]
	v_mfma_f32_16x16x32_bf16 v[14:17], v[134:137], v[218:221], v[14:17]
	v_mfma_f32_16x16x32_bf16 v[10:13], v[158:161], v[218:221], v[10:13]
	s_setprio 0
	s_setprio 1
	v_mfma_f32_16x16x32_bf16 v[54:57], v[162:165], v[186:189], v[54:57]
	v_mfma_f32_16x16x32_bf16 v[46:49], v[178:181], v[186:189], v[46:49]
	v_mfma_f32_16x16x32_bf16 v[30:33], v[162:165], v[194:197], v[30:33]
	v_mfma_f32_16x16x32_bf16 v[26:29], v[178:181], v[194:197], v[26:29]
	v_mfma_f32_16x16x32_bf16 v[22:25], v[162:165], v[202:205], v[22:25]
	v_mfma_f32_16x16x32_bf16 v[18:21], v[178:181], v[202:205], v[18:21]
	v_mfma_f32_16x16x32_bf16 v[6:9], v[162:165], v[210:213], v[6:9]
	v_mfma_f32_16x16x32_bf16 v[2:5], v[178:181], v[210:213], v[2:5]
	s_setprio 0
	s_setprio 1
	v_mfma_f32_16x16x32_bf16 v[54:57], v[166:169], v[190:193], v[54:57]
	v_mfma_f32_16x16x32_bf16 v[46:49], v[182:185], v[190:193], v[46:49]
	v_mfma_f32_16x16x32_bf16 v[30:33], v[166:169], v[198:201], v[30:33]
	v_mfma_f32_16x16x32_bf16 v[26:29], v[182:185], v[198:201], v[26:29]
	v_mfma_f32_16x16x32_bf16 v[22:25], v[166:169], v[206:209], v[22:25]
	v_mfma_f32_16x16x32_bf16 v[18:21], v[182:185], v[206:209], v[18:21]
	v_mfma_f32_16x16x32_bf16 v[6:9], v[166:169], v[218:221], v[6:9]
	v_mfma_f32_16x16x32_bf16 v[2:5], v[182:185], v[218:221], v[2:5]
	s_setprio 0
	s_barrier
	s_add_i32 s61, 0, 0x18000
	s_add_i32 s62, 0, 0x1c000
	v_add_u32_e32 v158, s61, v172
	v_add_u32_e32 v177, s62, v172
	ds_read_b128 v[130:133], v158
	ds_read_b128 v[134:137], v158 offset:1024
	ds_read_b128 v[138:141], v158 offset:2048
	ds_read_b128 v[158:161], v158 offset:3072
	ds_read_b128 v[162:165], v177
	ds_read_b128 v[166:169], v177 offset:1024
	ds_read_b128 v[178:181], v177 offset:2048
	ds_read_b128 v[182:185], v177 offset:3072
	s_add_u32 s44, s44, 0x80000
	s_addc_u32 s45, s45, 0
	s_mov_b32 m0, s48
	v_lshl_add_u64 v[226:227], s[44:45], 0, v[142:143]
	ds_read_b128 v[186:189], v176 offset:32768
	ds_read_b128 v[190:193], v176 offset:33792
	ds_read_b128 v[194:197], v176 offset:34816
	ds_read_b128 v[198:201], v176 offset:35840
	ds_read_b128 v[202:205], v176 offset:36864
	ds_read_b128 v[206:209], v176 offset:37888
	ds_read_b128 v[210:213], v176 offset:38912
	ds_read_b128 v[218:221], v176 offset:39936
	global_load_lds_dwordx4 v[226:227], off
	v_lshl_add_u64 v[226:227], s[44:45], 0, v[146:147]
	s_mov_b32 m0, s49
	s_nop 0
	global_load_lds_dwordx4 v[226:227], off
	s_waitcnt vmcnt(8)
	s_waitcnt lgkmcnt(0)
	s_barrier
	s_setprio 1
	s_waitcnt lgkmcnt(0)
	v_mfma_f32_16x16x32_bf16 v[126:129], v[130:133], v[186:189], v[126:129]
	v_mfma_f32_16x16x32_bf16 v[122:125], v[138:141], v[186:189], v[122:125]
	v_mfma_f32_16x16x32_bf16 v[110:113], v[130:133], v[194:197], v[110:113]
	v_mfma_f32_16x16x32_bf16 v[106:109], v[138:141], v[194:197], v[106:109]
	v_mfma_f32_16x16x32_bf16 v[94:97], v[130:133], v[202:205], v[94:97]
	v_mfma_f32_16x16x32_bf16 v[90:93], v[138:141], v[202:205], v[90:93]
	v_mfma_f32_16x16x32_bf16 v[78:81], v[130:133], v[210:213], v[78:81]
	v_mfma_f32_16x16x32_bf16 v[74:77], v[138:141], v[210:213], v[74:77]
	s_setprio 0
	s_setprio 1
	v_mfma_f32_16x16x32_bf16 v[126:129], v[134:137], v[190:193], v[126:129]
	v_mfma_f32_16x16x32_bf16 v[122:125], v[158:161], v[190:193], v[122:125]
	v_mfma_f32_16x16x32_bf16 v[110:113], v[134:137], v[198:201], v[110:113]
	v_mfma_f32_16x16x32_bf16 v[106:109], v[158:161], v[198:201], v[106:109]
	v_mfma_f32_16x16x32_bf16 v[94:97], v[134:137], v[206:209], v[94:97]
	v_mfma_f32_16x16x32_bf16 v[90:93], v[158:161], v[206:209], v[90:93]
	v_mfma_f32_16x16x32_bf16 v[78:81], v[134:137], v[218:221], v[78:81]
	v_mfma_f32_16x16x32_bf16 v[74:77], v[158:161], v[218:221], v[74:77]
	s_setprio 0
	s_setprio 1
	v_mfma_f32_16x16x32_bf16 v[118:121], v[162:165], v[186:189], v[118:121]
	v_mfma_f32_16x16x32_bf16 v[114:117], v[178:181], v[186:189], v[114:117]
	v_mfma_f32_16x16x32_bf16 v[102:105], v[162:165], v[194:197], v[102:105]
	v_mfma_f32_16x16x32_bf16 v[98:101], v[178:181], v[194:197], v[98:101]
	v_mfma_f32_16x16x32_bf16 v[86:89], v[162:165], v[202:205], v[86:89]
	v_mfma_f32_16x16x32_bf16 v[82:85], v[178:181], v[202:205], v[82:85]
	v_mfma_f32_16x16x32_bf16 v[70:73], v[162:165], v[210:213], v[70:73]
	v_mfma_f32_16x16x32_bf16 v[66:69], v[178:181], v[210:213], v[66:69]
	s_setprio 0
	s_setprio 1
	v_mfma_f32_16x16x32_bf16 v[118:121], v[166:169], v[190:193], v[118:121]
	v_mfma_f32_16x16x32_bf16 v[114:117], v[182:185], v[190:193], v[114:117]
	v_mfma_f32_16x16x32_bf16 v[102:105], v[166:169], v[198:201], v[102:105]
	v_mfma_f32_16x16x32_bf16 v[98:101], v[182:185], v[198:201], v[98:101]
	v_mfma_f32_16x16x32_bf16 v[86:89], v[166:169], v[206:209], v[86:89]
	v_mfma_f32_16x16x32_bf16 v[82:85], v[182:185], v[206:209], v[82:85]
	v_mfma_f32_16x16x32_bf16 v[70:73], v[166:169], v[218:221], v[70:73]
	v_mfma_f32_16x16x32_bf16 v[66:69], v[182:185], v[218:221], v[66:69]
	s_setprio 0
	s_barrier
	s_add_i32 s44, s61, s46
	v_lshl_add_u64 v[170:171], v[170:171], 0, s[12:13]
	s_mov_b32 m0, s44
	ds_read_b128 v[186:189], v176 offset:49152
	ds_read_b128 v[190:193], v176 offset:50176
	ds_read_b128 v[194:197], v176 offset:51200
	ds_read_b128 v[198:201], v176 offset:52224
	ds_read_b128 v[202:205], v176 offset:53248
	ds_read_b128 v[206:209], v176 offset:54272
	ds_read_b128 v[210:213], v176 offset:55296
	ds_read_b128 v[218:221], v176 offset:56320
	global_load_lds_dwordx4 v[170:171], off
	s_add_i32 m0, s44, 0x2000
	s_add_u32 s34, s34, 0x80080
	v_lshl_add_u64 v[170:171], v[214:215], 0, s[12:13]
	s_addc_u32 s35, s35, 0
	s_add_i32 s44, s62, s46
	global_load_lds_dwordx4 v[170:171], off
	v_lshl_add_u64 v[170:171], s[34:35], 0, v[144:145]
	s_mov_b32 m0, s44
	s_nop 0
	global_load_lds_dwordx4 v[170:171], off
	v_lshl_add_u64 v[170:171], s[34:35], 0, v[148:149]
	s_add_i32 m0, s44, 0x2000
	s_nop 0
	global_load_lds_dwordx4 v[170:171], off
	v_lshl_add_u64 v[170:171], v[222:223], 0, s[12:13]
	s_mov_b32 m0, s51
	s_nop 0
	global_load_lds_dwordx4 v[170:171], off
	v_lshl_add_u64 v[170:171], v[224:225], 0, s[12:13]
	s_mov_b32 m0, s52
	s_nop 0
	global_load_lds_dwordx4 v[170:171], off
	s_waitcnt vmcnt(8)
	s_waitcnt lgkmcnt(0)
	s_barrier
	s_setprio 1
	s_waitcnt lgkmcnt(0)
	v_mfma_f32_16x16x32_bf16 v[62:65], v[130:133], v[186:189], v[62:65]
	v_mfma_f32_16x16x32_bf16 v[58:61], v[138:141], v[186:189], v[58:61]
	v_mfma_f32_16x16x32_bf16 v[50:53], v[130:133], v[194:197], v[50:53]
	v_mfma_f32_16x16x32_bf16 v[42:45], v[138:141], v[194:197], v[42:45]
	v_mfma_f32_16x16x32_bf16 v[38:41], v[130:133], v[202:205], v[38:41]
	v_mfma_f32_16x16x32_bf16 v[34:37], v[138:141], v[202:205], v[34:37]
	v_mfma_f32_16x16x32_bf16 v[14:17], v[130:133], v[210:213], v[14:17]
	v_mfma_f32_16x16x32_bf16 v[10:13], v[138:141], v[210:213], v[10:13]
	s_setprio 0
	s_setprio 1
	v_mfma_f32_16x16x32_bf16 v[62:65], v[134:137], v[190:193], v[62:65]
	v_mfma_f32_16x16x32_bf16 v[58:61], v[158:161], v[190:193], v[58:61]
	v_mfma_f32_16x16x32_bf16 v[50:53], v[134:137], v[198:201], v[50:53]
	v_mfma_f32_16x16x32_bf16 v[42:45], v[158:161], v[198:201], v[42:45]
	v_mfma_f32_16x16x32_bf16 v[38:41], v[134:137], v[206:209], v[38:41]
	v_mfma_f32_16x16x32_bf16 v[34:37], v[158:161], v[206:209], v[34:37]
	v_mfma_f32_16x16x32_bf16 v[14:17], v[134:137], v[218:221], v[14:17]
	v_mfma_f32_16x16x32_bf16 v[10:13], v[158:161], v[218:221], v[10:13]
	s_setprio 0
	s_setprio 1
	v_mfma_f32_16x16x32_bf16 v[54:57], v[162:165], v[186:189], v[54:57]
	v_mfma_f32_16x16x32_bf16 v[46:49], v[178:181], v[186:189], v[46:49]
	v_mfma_f32_16x16x32_bf16 v[30:33], v[162:165], v[194:197], v[30:33]
	v_mfma_f32_16x16x32_bf16 v[26:29], v[178:181], v[194:197], v[26:29]
	v_mfma_f32_16x16x32_bf16 v[22:25], v[162:165], v[202:205], v[22:25]
	v_mfma_f32_16x16x32_bf16 v[18:21], v[178:181], v[202:205], v[18:21]
	v_mfma_f32_16x16x32_bf16 v[6:9], v[162:165], v[210:213], v[6:9]
	v_mfma_f32_16x16x32_bf16 v[2:5], v[178:181], v[210:213], v[2:5]
	s_setprio 0
	s_setprio 1
	v_mfma_f32_16x16x32_bf16 v[54:57], v[166:169], v[190:193], v[54:57]
	v_mfma_f32_16x16x32_bf16 v[46:49], v[182:185], v[190:193], v[46:49]
	v_mfma_f32_16x16x32_bf16 v[30:33], v[166:169], v[198:201], v[30:33]
	v_mfma_f32_16x16x32_bf16 v[26:29], v[182:185], v[198:201], v[26:29]
	v_mfma_f32_16x16x32_bf16 v[22:25], v[166:169], v[206:209], v[22:25]
	v_mfma_f32_16x16x32_bf16 v[18:21], v[182:185], v[206:209], v[18:21]
	v_mfma_f32_16x16x32_bf16 v[6:9], v[166:169], v[218:221], v[6:9]
	v_mfma_f32_16x16x32_bf16 v[2:5], v[182:185], v[218:221], v[2:5]
	s_setprio 0
	s_barrier
	s_add_i32 s60, s60, 2
	s_add_u32 s42, s42, 0x100
	s_addc_u32 s43, s43, 0
	s_add_u32 s58, s58, 0x100
	s_addc_u32 s59, s59, 0
	s_cmp_gt_u32 s60, 29
	s_cbranch_scc0 .LBB0_3706
	s_and_b64 vcc, exec, s[14:15]
	s_cbranch_vccz .LBB0_3709
	s_barrier

.LBB0_3835:
	ds_read_b128 v[146:149], v153
	ds_read_b128 v[156:159], v153 offset:1024
	ds_read_b128 v[160:163], v153 offset:2048
	ds_read_b128 v[164:167], v153 offset:3072
	ds_read_b128 v[168:171], v154
	ds_read_b128 v[172:175], v154 offset:1024
	ds_read_b128 v[176:179], v154 offset:2048
	ds_read_b128 v[180:183], v154 offset:3072
	s_add_u32 s34, s38, 0xfff80080
	s_addc_u32 s35, s39, -1
	s_cmp_eq_u32 s57, 28
	s_cselect_b32 s41, s0, s35
	s_cselect_b32 s40, s1, s34
	s_cselect_b32 s35, s15, s56
	s_cselect_b32 s34, s17, s55
	v_lshl_add_u64 v[218:219], s[38:39], 0, v[138:139]
	s_add_i32 m0, s37, 0xc000
	ds_read_b128 v[184:187], v155
	ds_read_b128 v[188:191], v155 offset:1024
	ds_read_b128 v[192:195], v155 offset:2048
	ds_read_b128 v[196:199], v155 offset:3072
	ds_read_b128 v[200:203], v155 offset:4096
	ds_read_b128 v[204:207], v155 offset:5120
	ds_read_b128 v[208:211], v155 offset:6144
	ds_read_b128 v[212:215], v155 offset:7168
	global_load_lds_dwordx4 v[218:219], off
	v_lshl_add_u64 v[218:219], s[38:39], 0, v[140:141]
	s_add_i32 m0, s37, 0xe000
	s_nop 0
	global_load_lds_dwordx4 v[218:219], off
	s_waitcnt vmcnt(8)
	s_waitcnt lgkmcnt(0)
	s_barrier
	s_setprio 1
	s_waitcnt lgkmcnt(0)
	v_mfma_f32_16x16x32_bf16 v[126:129], v[146:149], v[184:187], v[126:129]
	v_mfma_f32_16x16x32_bf16 v[118:121], v[160:163], v[184:187], v[118:121]
	v_mfma_f32_16x16x32_bf16 v[110:113], v[146:149], v[192:195], v[110:113]
	v_mfma_f32_16x16x32_bf16 v[102:105], v[160:163], v[192:195], v[102:105]
	v_mfma_f32_16x16x32_bf16 v[94:97], v[146:149], v[200:203], v[94:97]
	v_mfma_f32_16x16x32_bf16 v[86:89], v[160:163], v[200:203], v[86:89]
	v_mfma_f32_16x16x32_bf16 v[78:81], v[146:149], v[208:211], v[78:81]
	v_mfma_f32_16x16x32_bf16 v[70:73], v[160:163], v[208:211], v[70:73]
	s_setprio 0
	s_setprio 1
	v_mfma_f32_16x16x32_bf16 v[126:129], v[156:159], v[188:191], v[126:129]
	v_mfma_f32_16x16x32_bf16 v[118:121], v[164:167], v[188:191], v[118:121]
	v_mfma_f32_16x16x32_bf16 v[110:113], v[156:159], v[196:199], v[110:113]
	v_mfma_f32_16x16x32_bf16 v[102:105], v[164:167], v[196:199], v[102:105]
	v_mfma_f32_16x16x32_bf16 v[94:97], v[156:159], v[204:207], v[94:97]
	v_mfma_f32_16x16x32_bf16 v[86:89], v[164:167], v[204:207], v[86:89]
	v_mfma_f32_16x16x32_bf16 v[78:81], v[156:159], v[212:215], v[78:81]
	v_mfma_f32_16x16x32_bf16 v[70:73], v[164:167], v[212:215], v[70:73]
	s_setprio 0
	s_setprio 1
	v_mfma_f32_16x16x32_bf16 v[122:125], v[168:171], v[184:187], v[122:125]
	v_mfma_f32_16x16x32_bf16 v[114:117], v[176:179], v[184:187], v[114:117]
	v_mfma_f32_16x16x32_bf16 v[106:109], v[168:171], v[192:195], v[106:109]
	v_mfma_f32_16x16x32_bf16 v[98:101], v[176:179], v[192:195], v[98:101]
	v_mfma_f32_16x16x32_bf16 v[90:93], v[168:171], v[200:203], v[90:93]
	v_mfma_f32_16x16x32_bf16 v[82:85], v[176:179], v[200:203], v[82:85]
	v_mfma_f32_16x16x32_bf16 v[74:77], v[168:171], v[208:211], v[74:77]
	v_mfma_f32_16x16x32_bf16 v[66:69], v[176:179], v[208:211], v[66:69]
	s_setprio 0
	s_setprio 1
	v_mfma_f32_16x16x32_bf16 v[122:125], v[172:175], v[188:191], v[122:125]
	v_mfma_f32_16x16x32_bf16 v[114:117], v[180:183], v[188:191], v[114:117]
	v_mfma_f32_16x16x32_bf16 v[106:109], v[172:175], v[196:199], v[106:109]
	v_mfma_f32_16x16x32_bf16 v[98:101], v[180:183], v[196:199], v[98:101]
	v_mfma_f32_16x16x32_bf16 v[90:93], v[172:175], v[204:207], v[90:93]
	v_mfma_f32_16x16x32_bf16 v[82:85], v[180:183], v[204:207], v[82:85]
	v_mfma_f32_16x16x32_bf16 v[74:77], v[172:175], v[212:215], v[74:77]
	v_mfma_f32_16x16x32_bf16 v[66:69], v[180:183], v[212:215], v[66:69]
	s_setprio 0
	s_barrier
	s_add_i32 s58, s51, s33
	v_lshl_add_u64 v[218:219], s[34:35], 0, v[134:135]
	s_mov_b32 m0, s58
	ds_read_b128 v[184:187], v155 offset:16384
	ds_read_b128 v[188:191], v155 offset:17408
	ds_read_b128 v[192:195], v155 offset:18432
	ds_read_b128 v[196:199], v155 offset:19456
	ds_read_b128 v[200:203], v155 offset:20480
	ds_read_b128 v[204:207], v155 offset:21504
	ds_read_b128 v[208:211], v155 offset:22528
	ds_read_b128 v[212:215], v155 offset:23552
	global_load_lds_dwordx4 v[218:219], off
	s_add_i32 m0, s58, 0x2000
	s_add_u32 s58, s34, 0x80000
	v_lshl_add_u64 v[220:221], s[34:35], 0, v[130:131]
	s_addc_u32 s59, s35, 0
	s_add_i32 s60, s52, s33
	global_load_lds_dwordx4 v[220:221], off
	v_lshl_add_u64 v[222:223], s[58:59], 0, v[134:135]
	s_mov_b32 m0, s60
	v_lshl_add_u64 v[224:225], s[40:41], 0, v[132:133]
	global_load_lds_dwordx4 v[222:223], off
	v_lshl_add_u64 v[222:223], s[58:59], 0, v[130:131]
	s_add_i32 m0, s60, 0x2000
	s_nop 0
	global_load_lds_dwordx4 v[222:223], off
	v_lshl_add_u64 v[222:223], s[40:41], 0, v[136:137]
	s_mov_b32 m0, s37
	s_nop 0
	global_load_lds_dwordx4 v[222:223], off
	s_mov_b32 m0, s44
	s_nop 0
	global_load_lds_dwordx4 v[224:225], off
	s_waitcnt vmcnt(8)
	s_waitcnt lgkmcnt(0)
	s_barrier
	s_setprio 1
	s_waitcnt lgkmcnt(0)
	v_mfma_f32_16x16x32_bf16 v[62:65], v[146:149], v[184:187], v[62:65]
	v_mfma_f32_16x16x32_bf16 v[54:57], v[160:163], v[184:187], v[54:57]
	v_mfma_f32_16x16x32_bf16 v[46:49], v[146:149], v[192:195], v[46:49]
	v_mfma_f32_16x16x32_bf16 v[38:41], v[160:163], v[192:195], v[38:41]
	v_mfma_f32_16x16x32_bf16 v[30:33], v[146:149], v[200:203], v[30:33]
	v_mfma_f32_16x16x32_bf16 v[22:25], v[160:163], v[200:203], v[22:25]
	v_mfma_f32_16x16x32_bf16 v[14:17], v[146:149], v[208:211], v[14:17]
	v_mfma_f32_16x16x32_bf16 v[6:9], v[160:163], v[208:211], v[6:9]
	s_setprio 0
	s_setprio 1
	v_mfma_f32_16x16x32_bf16 v[62:65], v[156:159], v[188:191], v[62:65]
	v_mfma_f32_16x16x32_bf16 v[54:57], v[164:167], v[188:191], v[54:57]
	v_mfma_f32_16x16x32_bf16 v[46:49], v[156:159], v[196:199], v[46:49]
	v_mfma_f32_16x16x32_bf16 v[38:41], v[164:167], v[196:199], v[38:41]
	v_mfma_f32_16x16x32_bf16 v[30:33], v[156:159], v[204:207], v[30:33]
	v_mfma_f32_16x16x32_bf16 v[22:25], v[164:167], v[204:207], v[22:25]
	v_mfma_f32_16x16x32_bf16 v[14:17], v[156:159], v[212:215], v[14:17]
	v_mfma_f32_16x16x32_bf16 v[6:9], v[164:167], v[212:215], v[6:9]
	s_setprio 0
	s_setprio 1
	v_mfma_f32_16x16x32_bf16 v[58:61], v[168:171], v[184:187], v[58:61]
	v_mfma_f32_16x16x32_bf16 v[50:53], v[176:179], v[184:187], v[50:53]
	v_mfma_f32_16x16x32_bf16 v[42:45], v[168:171], v[192:195], v[42:45]
	v_mfma_f32_16x16x32_bf16 v[34:37], v[176:179], v[192:195], v[34:37]
	v_mfma_f32_16x16x32_bf16 v[26:29], v[168:171], v[200:203], v[26:29]
	v_mfma_f32_16x16x32_bf16 v[18:21], v[176:179], v[200:203], v[18:21]
	v_mfma_f32_16x16x32_bf16 v[10:13], v[168:171], v[208:211], v[10:13]
	v_mfma_f32_16x16x32_bf16 v[2:5], v[176:179], v[208:211], v[2:5]
	s_setprio 0
	s_setprio 1
	v_mfma_f32_16x16x32_bf16 v[58:61], v[172:175], v[188:191], v[58:61]
	v_mfma_f32_16x16x32_bf16 v[50:53], v[180:183], v[188:191], v[50:53]
	v_mfma_f32_16x16x32_bf16 v[42:45], v[172:175], v[196:199], v[42:45]
	v_mfma_f32_16x16x32_bf16 v[34:37], v[180:183], v[196:199], v[34:37]
	v_mfma_f32_16x16x32_bf16 v[26:29], v[172:175], v[204:207], v[26:29]
	v_mfma_f32_16x16x32_bf16 v[18:21], v[180:183], v[204:207], v[18:21]
	v_mfma_f32_16x16x32_bf16 v[10:13], v[172:175], v[212:215], v[10:13]
	v_mfma_f32_16x16x32_bf16 v[2:5], v[180:183], v[212:215], v[2:5]
	s_setprio 0
	s_barrier
	s_add_i32 s58, 0, 0x18000
	s_add_i32 s59, 0, 0x1c000
	v_add_u32_e32 v164, s58, v151
	v_add_u32_e32 v180, s59, v151
	ds_read_b128 v[146:149], v164
	ds_read_b128 v[156:159], v164 offset:1024
	ds_read_b128 v[160:163], v164 offset:2048
	ds_read_b128 v[164:167], v164 offset:3072
	ds_read_b128 v[168:171], v180
	ds_read_b128 v[172:175], v180 offset:1024
	ds_read_b128 v[176:179], v180 offset:2048
	ds_read_b128 v[180:183], v180 offset:3072
	s_add_u32 s40, s40, 0x80000
	s_addc_u32 s41, s41, 0
	s_mov_b32 m0, s45
	v_lshl_add_u64 v[226:227], s[40:41], 0, v[136:137]
	ds_read_b128 v[184:187], v155 offset:32768
	ds_read_b128 v[188:191], v155 offset:33792
	ds_read_b128 v[192:195], v155 offset:34816
	ds_read_b128 v[196:199], v155 offset:35840
	ds_read_b128 v[200:203], v155 offset:36864
	ds_read_b128 v[204:207], v155 offset:37888
	ds_read_b128 v[208:211], v155 offset:38912
	ds_read_b128 v[212:215], v155 offset:39936
	global_load_lds_dwordx4 v[226:227], off
	v_lshl_add_u64 v[226:227], s[40:41], 0, v[132:133]
	s_mov_b32 m0, s46
	s_nop 0
	global_load_lds_dwordx4 v[226:227], off
	s_waitcnt vmcnt(8)
	s_waitcnt lgkmcnt(0)
	s_barrier
	s_setprio 1
	s_waitcnt lgkmcnt(0)
	v_mfma_f32_16x16x32_bf16 v[126:129], v[146:149], v[184:187], v[126:129]
	v_mfma_f32_16x16x32_bf16 v[118:121], v[160:163], v[184:187], v[118:121]
	v_mfma_f32_16x16x32_bf16 v[110:113], v[146:149], v[192:195], v[110:113]
	v_mfma_f32_16x16x32_bf16 v[102:105], v[160:163], v[192:195], v[102:105]
	v_mfma_f32_16x16x32_bf16 v[94:97], v[146:149], v[200:203], v[94:97]
	v_mfma_f32_16x16x32_bf16 v[86:89], v[160:163], v[200:203], v[86:89]
	v_mfma_f32_16x16x32_bf16 v[78:81], v[146:149], v[208:211], v[78:81]
	v_mfma_f32_16x16x32_bf16 v[70:73], v[160:163], v[208:211], v[70:73]
	s_setprio 0
	s_setprio 1
	v_mfma_f32_16x16x32_bf16 v[126:129], v[156:159], v[188:191], v[126:129]
	v_mfma_f32_16x16x32_bf16 v[118:121], v[164:167], v[188:191], v[118:121]
	v_mfma_f32_16x16x32_bf16 v[110:113], v[156:159], v[196:199], v[110:113]
	v_mfma_f32_16x16x32_bf16 v[102:105], v[164:167], v[196:199], v[102:105]
	v_mfma_f32_16x16x32_bf16 v[94:97], v[156:159], v[204:207], v[94:97]
	v_mfma_f32_16x16x32_bf16 v[86:89], v[164:167], v[204:207], v[86:89]
	v_mfma_f32_16x16x32_bf16 v[78:81], v[156:159], v[212:215], v[78:81]
	v_mfma_f32_16x16x32_bf16 v[70:73], v[164:167], v[212:215], v[70:73]
	s_setprio 0
	s_setprio 1
	v_mfma_f32_16x16x32_bf16 v[122:125], v[168:171], v[184:187], v[122:125]
	v_mfma_f32_16x16x32_bf16 v[114:117], v[176:179], v[184:187], v[114:117]
	v_mfma_f32_16x16x32_bf16 v[106:109], v[168:171], v[192:195], v[106:109]
	v_mfma_f32_16x16x32_bf16 v[98:101], v[176:179], v[192:195], v[98:101]
	v_mfma_f32_16x16x32_bf16 v[90:93], v[168:171], v[200:203], v[90:93]
	v_mfma_f32_16x16x32_bf16 v[82:85], v[176:179], v[200:203], v[82:85]
	v_mfma_f32_16x16x32_bf16 v[74:77], v[168:171], v[208:211], v[74:77]
	v_mfma_f32_16x16x32_bf16 v[66:69], v[176:179], v[208:211], v[66:69]
	s_setprio 0
	s_setprio 1
	v_mfma_f32_16x16x32_bf16 v[122:125], v[172:175], v[188:191], v[122:125]
	v_mfma_f32_16x16x32_bf16 v[114:117], v[180:183], v[188:191], v[114:117]
	v_mfma_f32_16x16x32_bf16 v[106:109], v[172:175], v[196:199], v[106:109]
	v_mfma_f32_16x16x32_bf16 v[98:101], v[180:183], v[196:199], v[98:101]
	v_mfma_f32_16x16x32_bf16 v[90:93], v[172:175], v[204:207], v[90:93]
	v_mfma_f32_16x16x32_bf16 v[82:85], v[180:183], v[204:207], v[82:85]
	v_mfma_f32_16x16x32_bf16 v[74:77], v[172:175], v[212:215], v[74:77]
	v_mfma_f32_16x16x32_bf16 v[66:69], v[180:183], v[212:215], v[66:69]
	s_setprio 0
	s_barrier
	s_add_i32 s40, s58, s33
	v_lshl_add_u64 v[218:219], v[218:219], 0, s[8:9]
	s_mov_b32 m0, s40
	ds_read_b128 v[184:187], v155 offset:49152
	ds_read_b128 v[188:191], v155 offset:50176
	ds_read_b128 v[192:195], v155 offset:51200
	ds_read_b128 v[196:199], v155 offset:52224
	ds_read_b128 v[200:203], v155 offset:53248
	ds_read_b128 v[204:207], v155 offset:54272
	ds_read_b128 v[208:211], v155 offset:55296
	ds_read_b128 v[212:215], v155 offset:56320
	global_load_lds_dwordx4 v[218:219], off
	s_add_i32 m0, s40, 0x2000
	s_add_u32 s34, s34, 0x80080
	v_lshl_add_u64 v[218:219], v[220:221], 0, s[8:9]
	s_addc_u32 s35, s35, 0
	s_add_i32 s40, s59, s33
	global_load_lds_dwordx4 v[218:219], off
	v_lshl_add_u64 v[218:219], s[34:35], 0, v[134:135]
	s_mov_b32 m0, s40
	s_nop 0
	global_load_lds_dwordx4 v[218:219], off
	v_lshl_add_u64 v[218:219], s[34:35], 0, v[130:131]
	s_add_i32 m0, s40, 0x2000
	s_nop 0
	global_load_lds_dwordx4 v[218:219], off
	v_lshl_add_u64 v[218:219], v[222:223], 0, s[8:9]
	s_mov_b32 m0, s48
	s_nop 0
	global_load_lds_dwordx4 v[218:219], off
	v_lshl_add_u64 v[218:219], v[224:225], 0, s[8:9]
	s_mov_b32 m0, s49
	s_nop 0
	global_load_lds_dwordx4 v[218:219], off
	s_waitcnt vmcnt(8)
	s_waitcnt lgkmcnt(0)
	s_barrier
	s_setprio 1
	s_waitcnt lgkmcnt(0)
	v_mfma_f32_16x16x32_bf16 v[62:65], v[146:149], v[184:187], v[62:65]
	v_mfma_f32_16x16x32_bf16 v[54:57], v[160:163], v[184:187], v[54:57]
	v_mfma_f32_16x16x32_bf16 v[46:49], v[146:149], v[192:195], v[46:49]
	v_mfma_f32_16x16x32_bf16 v[38:41], v[160:163], v[192:195], v[38:41]
	v_mfma_f32_16x16x32_bf16 v[30:33], v[146:149], v[200:203], v[30:33]
	v_mfma_f32_16x16x32_bf16 v[22:25], v[160:163], v[200:203], v[22:25]
	v_mfma_f32_16x16x32_bf16 v[14:17], v[146:149], v[208:211], v[14:17]
	v_mfma_f32_16x16x32_bf16 v[6:9], v[160:163], v[208:211], v[6:9]
	s_setprio 0
	s_setprio 1
	v_mfma_f32_16x16x32_bf16 v[62:65], v[156:159], v[188:191], v[62:65]
	v_mfma_f32_16x16x32_bf16 v[54:57], v[164:167], v[188:191], v[54:57]
	v_mfma_f32_16x16x32_bf16 v[46:49], v[156:159], v[196:199], v[46:49]
	v_mfma_f32_16x16x32_bf16 v[38:41], v[164:167], v[196:199], v[38:41]
	v_mfma_f32_16x16x32_bf16 v[30:33], v[156:159], v[204:207], v[30:33]
	v_mfma_f32_16x16x32_bf16 v[22:25], v[164:167], v[204:207], v[22:25]
	v_mfma_f32_16x16x32_bf16 v[14:17], v[156:159], v[212:215], v[14:17]
	v_mfma_f32_16x16x32_bf16 v[6:9], v[164:167], v[212:215], v[6:9]
	s_setprio 0
	s_setprio 1
	v_mfma_f32_16x16x32_bf16 v[58:61], v[168:171], v[184:187], v[58:61]
	v_mfma_f32_16x16x32_bf16 v[50:53], v[176:179], v[184:187], v[50:53]
	v_mfma_f32_16x16x32_bf16 v[42:45], v[168:171], v[192:195], v[42:45]
	v_mfma_f32_16x16x32_bf16 v[34:37], v[176:179], v[192:195], v[34:37]
	v_mfma_f32_16x16x32_bf16 v[26:29], v[168:171], v[200:203], v[26:29]
	v_mfma_f32_16x16x32_bf16 v[18:21], v[176:179], v[200:203], v[18:21]
	v_mfma_f32_16x16x32_bf16 v[10:13], v[168:171], v[208:211], v[10:13]
	v_mfma_f32_16x16x32_bf16 v[2:5], v[176:179], v[208:211], v[2:5]
	s_setprio 0
	s_setprio 1
	v_mfma_f32_16x16x32_bf16 v[58:61], v[172:175], v[188:191], v[58:61]
	v_mfma_f32_16x16x32_bf16 v[50:53], v[180:183], v[188:191], v[50:53]
	v_mfma_f32_16x16x32_bf16 v[42:45], v[172:175], v[196:199], v[42:45]
	v_mfma_f32_16x16x32_bf16 v[34:37], v[180:183], v[196:199], v[34:37]
	v_mfma_f32_16x16x32_bf16 v[26:29], v[172:175], v[204:207], v[26:29]
	v_mfma_f32_16x16x32_bf16 v[18:21], v[180:183], v[204:207], v[18:21]
	v_mfma_f32_16x16x32_bf16 v[10:13], v[172:175], v[212:215], v[10:13]
	v_mfma_f32_16x16x32_bf16 v[2:5], v[180:183], v[212:215], v[2:5]
	s_setprio 0
	s_barrier
	s_add_i32 s57, s57, 2
	s_add_u32 s38, s38, 0x100
	s_addc_u32 s39, s39, 0
	s_add_u32 s55, s55, 0x100
	s_addc_u32 s56, s56, 0
	s_cmp_gt_u32 s57, 29
	s_cbranch_scc0 .LBB0_3835
	s_and_b64 vcc, exec, s[12:13]
	s_cbranch_vccz .LBB0_3838
	s_barrier

.LBB0_3930:
	ds_read_b128 v[144:147], v155
	ds_read_b128 v[148:151], v155 offset:1024
	ds_read_b128 v[158:161], v155 offset:2048
	ds_read_b128 v[162:165], v155 offset:3072
	ds_read_b128 v[166:169], v156
	ds_read_b128 v[170:173], v156 offset:1024
	ds_read_b128 v[174:177], v156 offset:2048
	ds_read_b128 v[178:181], v156 offset:3072
	s_add_u32 s20, s18, 0xffea0080
	s_addc_u32 s21, s19, -1
	s_cmpk_eq_i32 s45, 0x54
	s_cselect_b32 s23, s5, s21
	s_cselect_b32 s22, s4, s20
	s_cselect_b32 s21, s17, s1
	s_cselect_b32 s20, s16, s0
	v_lshl_add_u64 v[214:215], s[18:19], 0, v[136:137]
	s_add_i32 m0, s30, 0xc000
	ds_read_b128 v[182:185], v157
	ds_read_b128 v[186:189], v157 offset:1024
	ds_read_b128 v[190:193], v157 offset:2048
	ds_read_b128 v[194:197], v157 offset:3072
	ds_read_b128 v[198:201], v157 offset:4096
	ds_read_b128 v[202:205], v157 offset:5120
	ds_read_b128 v[206:209], v157 offset:6144
	ds_read_b128 v[210:213], v157 offset:7168
	global_load_lds_dwordx4 v[214:215], off
	v_lshl_add_u64 v[214:215], s[18:19], 0, v[138:139]
	s_add_i32 m0, s30, 0xe000
	s_nop 0
	global_load_lds_dwordx4 v[214:215], off
	s_waitcnt vmcnt(8)
	s_waitcnt lgkmcnt(0)
	s_barrier
	s_setprio 1
	s_waitcnt lgkmcnt(0)
	v_mfma_f32_16x16x32_bf16 v[124:127], v[144:147], v[182:185], v[124:127]
	v_mfma_f32_16x16x32_bf16 v[120:123], v[158:161], v[182:185], v[120:123]
	v_mfma_f32_16x16x32_bf16 v[116:119], v[144:147], v[190:193], v[116:119]
	v_mfma_f32_16x16x32_bf16 v[112:115], v[158:161], v[190:193], v[112:115]
	v_mfma_f32_16x16x32_bf16 v[92:95], v[144:147], v[198:201], v[92:95]
	v_mfma_f32_16x16x32_bf16 v[88:91], v[158:161], v[198:201], v[88:91]
	v_mfma_f32_16x16x32_bf16 v[84:87], v[144:147], v[206:209], v[84:87]
	v_mfma_f32_16x16x32_bf16 v[80:83], v[158:161], v[206:209], v[80:83]
	s_setprio 0
	s_setprio 1
	v_mfma_f32_16x16x32_bf16 v[124:127], v[148:151], v[186:189], v[124:127]
	v_mfma_f32_16x16x32_bf16 v[120:123], v[162:165], v[186:189], v[120:123]
	v_mfma_f32_16x16x32_bf16 v[116:119], v[148:151], v[194:197], v[116:119]
	v_mfma_f32_16x16x32_bf16 v[112:115], v[162:165], v[194:197], v[112:115]
	v_mfma_f32_16x16x32_bf16 v[92:95], v[148:151], v[202:205], v[92:95]
	v_mfma_f32_16x16x32_bf16 v[88:91], v[162:165], v[202:205], v[88:91]
	v_mfma_f32_16x16x32_bf16 v[84:87], v[148:151], v[210:213], v[84:87]
	v_mfma_f32_16x16x32_bf16 v[80:83], v[162:165], v[210:213], v[80:83]
	s_setprio 0
	s_setprio 1
	v_mfma_f32_16x16x32_bf16 v[108:111], v[166:169], v[182:185], v[108:111]
	v_mfma_f32_16x16x32_bf16 v[104:107], v[174:177], v[182:185], v[104:107]
	v_mfma_f32_16x16x32_bf16 v[100:103], v[166:169], v[190:193], v[100:103]
	v_mfma_f32_16x16x32_bf16 v[96:99], v[174:177], v[190:193], v[96:99]
	v_mfma_f32_16x16x32_bf16 v[76:79], v[166:169], v[198:201], v[76:79]
	v_mfma_f32_16x16x32_bf16 v[72:75], v[174:177], v[198:201], v[72:75]
	v_mfma_f32_16x16x32_bf16 v[68:71], v[166:169], v[206:209], v[68:71]
	v_mfma_f32_16x16x32_bf16 v[64:67], v[174:177], v[206:209], v[64:67]
	s_setprio 0
	s_setprio 1
	v_mfma_f32_16x16x32_bf16 v[108:111], v[170:173], v[186:189], v[108:111]
	v_mfma_f32_16x16x32_bf16 v[104:107], v[178:181], v[186:189], v[104:107]
	v_mfma_f32_16x16x32_bf16 v[100:103], v[170:173], v[194:197], v[100:103]
	v_mfma_f32_16x16x32_bf16 v[96:99], v[178:181], v[194:197], v[96:99]
	v_mfma_f32_16x16x32_bf16 v[76:79], v[170:173], v[202:205], v[76:79]
	v_mfma_f32_16x16x32_bf16 v[72:75], v[178:181], v[202:205], v[72:75]
	v_mfma_f32_16x16x32_bf16 v[68:71], v[170:173], v[210:213], v[68:71]
	v_mfma_f32_16x16x32_bf16 v[64:67], v[178:181], v[210:213], v[64:67]
	s_setprio 0
	s_barrier
	s_add_i32 s46, s39, s27
	v_lshl_add_u64 v[214:215], s[20:21], 0, v[130:131]
	s_mov_b32 m0, s46
	ds_read_b128 v[182:185], v157 offset:16384
	ds_read_b128 v[186:189], v157 offset:17408
	ds_read_b128 v[190:193], v157 offset:18432
	ds_read_b128 v[194:197], v157 offset:19456
	ds_read_b128 v[198:201], v157 offset:20480
	ds_read_b128 v[202:205], v157 offset:21504
	ds_read_b128 v[206:209], v157 offset:22528
	ds_read_b128 v[210:213], v157 offset:23552
	global_load_lds_dwordx4 v[214:215], off
	s_add_i32 m0, s46, 0x2000
	s_add_u32 s46, s20, 0x160000
	v_lshl_add_u64 v[216:217], s[20:21], 0, v[134:135]
	s_addc_u32 s47, s21, 0
	s_add_i32 s48, s40, s27
	global_load_lds_dwordx4 v[216:217], off
	v_lshl_add_u64 v[218:219], s[46:47], 0, v[130:131]
	s_mov_b32 m0, s48
	v_lshl_add_u64 v[220:221], s[22:23], 0, v[132:133]
	global_load_lds_dwordx4 v[218:219], off
	v_lshl_add_u64 v[218:219], s[46:47], 0, v[134:135]
	s_add_i32 m0, s48, 0x2000
	s_nop 0
	global_load_lds_dwordx4 v[218:219], off
	v_lshl_add_u64 v[218:219], s[22:23], 0, v[128:129]
	s_mov_b32 m0, s30
	s_nop 0
	global_load_lds_dwordx4 v[218:219], off
	s_mov_b32 m0, s31
	s_nop 0
	global_load_lds_dwordx4 v[220:221], off
	s_waitcnt vmcnt(8)
	s_waitcnt lgkmcnt(0)
	s_barrier
	s_setprio 1
	s_waitcnt lgkmcnt(0)
	v_mfma_f32_16x16x32_bf16 v[60:63], v[144:147], v[182:185], v[60:63]
	v_mfma_f32_16x16x32_bf16 v[56:59], v[158:161], v[182:185], v[56:59]
	v_mfma_f32_16x16x32_bf16 v[52:55], v[144:147], v[190:193], v[52:55]
	v_mfma_f32_16x16x32_bf16 v[48:51], v[158:161], v[190:193], v[48:51]
	v_mfma_f32_16x16x32_bf16 v[28:31], v[144:147], v[198:201], v[28:31]
	v_mfma_f32_16x16x32_bf16 v[24:27], v[158:161], v[198:201], v[24:27]
	v_mfma_f32_16x16x32_bf16 v[20:23], v[144:147], v[206:209], v[20:23]
	v_mfma_f32_16x16x32_bf16 v[16:19], v[158:161], v[206:209], v[16:19]
	s_setprio 0
	s_setprio 1
	v_mfma_f32_16x16x32_bf16 v[60:63], v[148:151], v[186:189], v[60:63]
	v_mfma_f32_16x16x32_bf16 v[56:59], v[162:165], v[186:189], v[56:59]
	v_mfma_f32_16x16x32_bf16 v[52:55], v[148:151], v[194:197], v[52:55]
	v_mfma_f32_16x16x32_bf16 v[48:51], v[162:165], v[194:197], v[48:51]
	v_mfma_f32_16x16x32_bf16 v[28:31], v[148:151], v[202:205], v[28:31]
	v_mfma_f32_16x16x32_bf16 v[24:27], v[162:165], v[202:205], v[24:27]
	v_mfma_f32_16x16x32_bf16 v[20:23], v[148:151], v[210:213], v[20:23]
	v_mfma_f32_16x16x32_bf16 v[16:19], v[162:165], v[210:213], v[16:19]
	s_setprio 0
	s_setprio 1
	v_mfma_f32_16x16x32_bf16 v[44:47], v[166:169], v[182:185], v[44:47]
	v_mfma_f32_16x16x32_bf16 v[40:43], v[174:177], v[182:185], v[40:43]
	v_mfma_f32_16x16x32_bf16 v[36:39], v[166:169], v[190:193], v[36:39]
	v_mfma_f32_16x16x32_bf16 v[32:35], v[174:177], v[190:193], v[32:35]
	v_mfma_f32_16x16x32_bf16 v[12:15], v[166:169], v[198:201], v[12:15]
	v_mfma_f32_16x16x32_bf16 v[8:11], v[174:177], v[198:201], v[8:11]
	v_mfma_f32_16x16x32_bf16 v[4:7], v[166:169], v[206:209], v[4:7]
	v_mfma_f32_16x16x32_bf16 v[0:3], v[174:177], v[206:209], v[0:3]
	s_setprio 0
	s_setprio 1
	v_mfma_f32_16x16x32_bf16 v[44:47], v[170:173], v[186:189], v[44:47]
	v_mfma_f32_16x16x32_bf16 v[40:43], v[178:181], v[186:189], v[40:43]
	v_mfma_f32_16x16x32_bf16 v[36:39], v[170:173], v[194:197], v[36:39]
	v_mfma_f32_16x16x32_bf16 v[32:35], v[178:181], v[194:197], v[32:35]
	v_mfma_f32_16x16x32_bf16 v[12:15], v[170:173], v[202:205], v[12:15]
	v_mfma_f32_16x16x32_bf16 v[8:11], v[178:181], v[202:205], v[8:11]
	v_mfma_f32_16x16x32_bf16 v[4:7], v[170:173], v[210:213], v[4:7]
	v_mfma_f32_16x16x32_bf16 v[0:3], v[178:181], v[210:213], v[0:3]
	s_setprio 0
	s_barrier
	s_add_i32 s46, 0, 0x18000
	s_add_i32 s47, 0, 0x1c000
	v_add_u32_e32 v162, s46, v153
	v_add_u32_e32 v178, s47, v153
	ds_read_b128 v[144:147], v162
	ds_read_b128 v[148:151], v162 offset:1024
	ds_read_b128 v[158:161], v162 offset:2048
	ds_read_b128 v[162:165], v162 offset:3072
	ds_read_b128 v[166:169], v178
	ds_read_b128 v[170:173], v178 offset:1024
	ds_read_b128 v[174:177], v178 offset:2048
	ds_read_b128 v[178:181], v178 offset:3072
	s_add_u32 s22, s22, 0x160000
	s_addc_u32 s23, s23, 0
	s_mov_b32 m0, s33
	v_lshl_add_u64 v[222:223], s[22:23], 0, v[128:129]
	ds_read_b128 v[182:185], v157 offset:32768
	ds_read_b128 v[186:189], v157 offset:33792
	ds_read_b128 v[190:193], v157 offset:34816
	ds_read_b128 v[194:197], v157 offset:35840
	ds_read_b128 v[198:201], v157 offset:36864
	ds_read_b128 v[202:205], v157 offset:37888
	ds_read_b128 v[206:209], v157 offset:38912
	ds_read_b128 v[210:213], v157 offset:39936
	global_load_lds_dwordx4 v[222:223], off
	v_lshl_add_u64 v[222:223], s[22:23], 0, v[132:133]
	s_mov_b32 m0, s34
	s_nop 0
	global_load_lds_dwordx4 v[222:223], off
	s_waitcnt vmcnt(8)
	s_waitcnt lgkmcnt(0)
	s_barrier
	s_setprio 1
	s_waitcnt lgkmcnt(0)
	v_mfma_f32_16x16x32_bf16 v[124:127], v[144:147], v[182:185], v[124:127]
	v_mfma_f32_16x16x32_bf16 v[120:123], v[158:161], v[182:185], v[120:123]
	v_mfma_f32_16x16x32_bf16 v[116:119], v[144:147], v[190:193], v[116:119]
	v_mfma_f32_16x16x32_bf16 v[112:115], v[158:161], v[190:193], v[112:115]
	v_mfma_f32_16x16x32_bf16 v[92:95], v[144:147], v[198:201], v[92:95]
	v_mfma_f32_16x16x32_bf16 v[88:91], v[158:161], v[198:201], v[88:91]
	v_mfma_f32_16x16x32_bf16 v[84:87], v[144:147], v[206:209], v[84:87]
	v_mfma_f32_16x16x32_bf16 v[80:83], v[158:161], v[206:209], v[80:83]
	s_setprio 0
	s_setprio 1
	v_mfma_f32_16x16x32_bf16 v[124:127], v[148:151], v[186:189], v[124:127]
	v_mfma_f32_16x16x32_bf16 v[120:123], v[162:165], v[186:189], v[120:123]
	v_mfma_f32_16x16x32_bf16 v[116:119], v[148:151], v[194:197], v[116:119]
	v_mfma_f32_16x16x32_bf16 v[112:115], v[162:165], v[194:197], v[112:115]
	v_mfma_f32_16x16x32_bf16 v[92:95], v[148:151], v[202:205], v[92:95]
	v_mfma_f32_16x16x32_bf16 v[88:91], v[162:165], v[202:205], v[88:91]
	v_mfma_f32_16x16x32_bf16 v[84:87], v[148:151], v[210:213], v[84:87]
	v_mfma_f32_16x16x32_bf16 v[80:83], v[162:165], v[210:213], v[80:83]
	s_setprio 0
	s_setprio 1
	v_mfma_f32_16x16x32_bf16 v[108:111], v[166:169], v[182:185], v[108:111]
	v_mfma_f32_16x16x32_bf16 v[104:107], v[174:177], v[182:185], v[104:107]
	v_mfma_f32_16x16x32_bf16 v[100:103], v[166:169], v[190:193], v[100:103]
	v_mfma_f32_16x16x32_bf16 v[96:99], v[174:177], v[190:193], v[96:99]
	v_mfma_f32_16x16x32_bf16 v[76:79], v[166:169], v[198:201], v[76:79]
	v_mfma_f32_16x16x32_bf16 v[72:75], v[174:177], v[198:201], v[72:75]
	v_mfma_f32_16x16x32_bf16 v[68:71], v[166:169], v[206:209], v[68:71]
	v_mfma_f32_16x16x32_bf16 v[64:67], v[174:177], v[206:209], v[64:67]
	s_setprio 0
	s_setprio 1
	v_mfma_f32_16x16x32_bf16 v[108:111], v[170:173], v[186:189], v[108:111]
	v_mfma_f32_16x16x32_bf16 v[104:107], v[178:181], v[186:189], v[104:107]
	v_mfma_f32_16x16x32_bf16 v[100:103], v[170:173], v[194:197], v[100:103]
	v_mfma_f32_16x16x32_bf16 v[96:99], v[178:181], v[194:197], v[96:99]
	v_mfma_f32_16x16x32_bf16 v[76:79], v[170:173], v[202:205], v[76:79]
	v_mfma_f32_16x16x32_bf16 v[72:75], v[178:181], v[202:205], v[72:75]
	v_mfma_f32_16x16x32_bf16 v[68:71], v[170:173], v[210:213], v[68:71]
	v_mfma_f32_16x16x32_bf16 v[64:67], v[178:181], v[210:213], v[64:67]
	s_setprio 0
	s_barrier
	s_add_i32 s22, s46, s27
	v_lshl_add_u64 v[214:215], v[214:215], 0, s[12:13]
	s_mov_b32 m0, s22
	ds_read_b128 v[182:185], v157 offset:49152
	ds_read_b128 v[186:189], v157 offset:50176
	ds_read_b128 v[190:193], v157 offset:51200
	ds_read_b128 v[194:197], v157 offset:52224
	ds_read_b128 v[198:201], v157 offset:53248
	ds_read_b128 v[202:205], v157 offset:54272
	ds_read_b128 v[206:209], v157 offset:55296
	ds_read_b128 v[210:213], v157 offset:56320
	global_load_lds_dwordx4 v[214:215], off
	s_add_i32 m0, s22, 0x2000
	s_add_u32 s20, s20, 0x160080
	v_lshl_add_u64 v[214:215], v[216:217], 0, s[12:13]
	s_addc_u32 s21, s21, 0
	s_add_i32 s22, s47, s27
	global_load_lds_dwordx4 v[214:215], off
	v_lshl_add_u64 v[214:215], s[20:21], 0, v[130:131]
	s_mov_b32 m0, s22
	s_nop 0
	global_load_lds_dwordx4 v[214:215], off
	v_lshl_add_u64 v[214:215], s[20:21], 0, v[134:135]
	s_add_i32 m0, s22, 0x2000
	s_nop 0
	global_load_lds_dwordx4 v[214:215], off
	v_lshl_add_u64 v[214:215], v[218:219], 0, s[12:13]
	s_mov_b32 m0, s36
	s_nop 0
	global_load_lds_dwordx4 v[214:215], off
	v_lshl_add_u64 v[214:215], v[220:221], 0, s[12:13]
	s_mov_b32 m0, s37
	s_nop 0
	global_load_lds_dwordx4 v[214:215], off
	s_waitcnt vmcnt(8)
	s_waitcnt lgkmcnt(0)
	s_barrier
	s_setprio 1
	s_waitcnt lgkmcnt(0)
	v_mfma_f32_16x16x32_bf16 v[60:63], v[144:147], v[182:185], v[60:63]
	v_mfma_f32_16x16x32_bf16 v[56:59], v[158:161], v[182:185], v[56:59]
	v_mfma_f32_16x16x32_bf16 v[52:55], v[144:147], v[190:193], v[52:55]
	v_mfma_f32_16x16x32_bf16 v[48:51], v[158:161], v[190:193], v[48:51]
	v_mfma_f32_16x16x32_bf16 v[28:31], v[144:147], v[198:201], v[28:31]
	v_mfma_f32_16x16x32_bf16 v[24:27], v[158:161], v[198:201], v[24:27]
	v_mfma_f32_16x16x32_bf16 v[20:23], v[144:147], v[206:209], v[20:23]
	v_mfma_f32_16x16x32_bf16 v[16:19], v[158:161], v[206:209], v[16:19]
	s_setprio 0
	s_setprio 1
	v_mfma_f32_16x16x32_bf16 v[60:63], v[148:151], v[186:189], v[60:63]
	v_mfma_f32_16x16x32_bf16 v[56:59], v[162:165], v[186:189], v[56:59]
	v_mfma_f32_16x16x32_bf16 v[52:55], v[148:151], v[194:197], v[52:55]
	v_mfma_f32_16x16x32_bf16 v[48:51], v[162:165], v[194:197], v[48:51]
	v_mfma_f32_16x16x32_bf16 v[28:31], v[148:151], v[202:205], v[28:31]
	v_mfma_f32_16x16x32_bf16 v[24:27], v[162:165], v[202:205], v[24:27]
	v_mfma_f32_16x16x32_bf16 v[20:23], v[148:151], v[210:213], v[20:23]
	v_mfma_f32_16x16x32_bf16 v[16:19], v[162:165], v[210:213], v[16:19]
	s_setprio 0
	s_setprio 1
	v_mfma_f32_16x16x32_bf16 v[44:47], v[166:169], v[182:185], v[44:47]
	v_mfma_f32_16x16x32_bf16 v[40:43], v[174:177], v[182:185], v[40:43]
	v_mfma_f32_16x16x32_bf16 v[36:39], v[166:169], v[190:193], v[36:39]
	v_mfma_f32_16x16x32_bf16 v[32:35], v[174:177], v[190:193], v[32:35]
	v_mfma_f32_16x16x32_bf16 v[12:15], v[166:169], v[198:201], v[12:15]
	v_mfma_f32_16x16x32_bf16 v[8:11], v[174:177], v[198:201], v[8:11]
	v_mfma_f32_16x16x32_bf16 v[4:7], v[166:169], v[206:209], v[4:7]
	v_mfma_f32_16x16x32_bf16 v[0:3], v[174:177], v[206:209], v[0:3]
	s_setprio 0
	s_setprio 1
	v_mfma_f32_16x16x32_bf16 v[44:47], v[170:173], v[186:189], v[44:47]
	v_mfma_f32_16x16x32_bf16 v[40:43], v[178:181], v[186:189], v[40:43]
	v_mfma_f32_16x16x32_bf16 v[36:39], v[170:173], v[194:197], v[36:39]
	v_mfma_f32_16x16x32_bf16 v[32:35], v[178:181], v[194:197], v[32:35]
	v_mfma_f32_16x16x32_bf16 v[12:15], v[170:173], v[202:205], v[12:15]
	v_mfma_f32_16x16x32_bf16 v[8:11], v[178:181], v[202:205], v[8:11]
	v_mfma_f32_16x16x32_bf16 v[4:7], v[170:173], v[210:213], v[4:7]
	v_mfma_f32_16x16x32_bf16 v[0:3], v[178:181], v[210:213], v[0:3]
	s_setprio 0
	s_barrier
	s_add_i32 s45, s45, 2
	s_add_u32 s18, s18, 0x100
	s_addc_u32 s19, s19, 0
	s_add_u32 s0, s0, 0x100
	s_addc_u32 s1, s1, 0
	s_cmpk_gt_u32 s45, 0x55
	s_cbranch_scc0 .LBB0_3930
	s_and_b64 vcc, exec, s[14:15]
	s_cbranch_vccz .LBB0_3933
	s_barrier
